# m0trim2
# baseline (speedup 1.0000x reference)
; #define STAGE(P, BASE, LD, br, kt) do { const char* _g = (const char*)((BASE) + (size_t)(br) * (LD) + (size_t)(kt) * 64); \
;     for (int _i = 0; _i < 2; ++_i) { int _b = tidx * 16 + _i * 8192; int _r, _c; stage_rc(_b, _r, _c); \
;       __builtin_amdgcn_global_load_lds((const unsigned*)(_g + (unsigned)((_r * (LD) + _c) * 2)), (unsigned*)((char*)(P) + _b), 16, 0, 0); } } while (0)
; #define LDA(dst, b, h) for (int m = 0; m < 4; ++m) for (int k = 0; k < 2; ++k) \
;     dst[m][k] = *reinterpret_cast<const bf16x8*>((char*)SA(b, h) + lds_byte(wr * 64 + m * 16 + fr, k * 32 + fq * 8))
; #define LDB(dst, b, h) for (int n = 0; n < 2; ++n) for (int k = 0; k < 2; ++k) \
;     dst[n][k] = *reinterpret_cast<const bf16x8*>((char*)SB(b, h) + lds_byte(wc * 32 + n * 16 + fr, k * 32 + fq * 8))
; #define MMA(ai, bj, At_, Bt_) do { __builtin_amdgcn_s_setprio(1); \
;     for (int k = 0; k < 2; ++k) for (int m = 0; m < 4; ++m) for (int n = 0; n < 2; ++n) \
;       acc[ai][bj][m][n] = __builtin_amdgcn_mfma_f32_16x16x32_bf16(At_[m][k], Bt_[n][k], acc[ai][bj][m][n], 0, 0, 0); \
;     __builtin_amdgcn_s_setprio(0); } while (0)
; #define WAIT_V(n) asm volatile("s_waitcnt vmcnt(" #n ")" ::: "memory")
; #define WAIT_L(n) asm volatile("s_waitcnt lgkmcnt(" #n ")" ::: "memory")
; #define BAR __builtin_amdgcn_s_barrier()
; #define SCHED __builtin_amdgcn_sched_barrier(0)
; template <int EPI, int lda, int ldb, int N, int K>
; __device__ __forceinline__ void gemm_phase(const u16* __restrict__ A, const u16* __restrict__ Bt, const GemmEpi ep, int wv) {
;     ...
;     for (int t = 0; t < nt - 2; t += 2) {
;       LDB(B0, 0, 0); SCHED; LDA(At, 0, 0); STAGE(SA(1, 1), Ab, lda, brow + HALF, t + 1);
;       WAIT_L(8); BAR; WAIT_L(0); MMA(0, 0, At, B0); BAR; SCHED;
;       LDB(B1, 0, 1); STAGE(SB(0, 0), Bt, ldb, bcol, t + 2);
;       BAR; WAIT_L(0); MMA(0, 1, At, B1); BAR;
;       LDA(At, 0, 1); STAGE(SA(0, 0), Ab, lda, brow, t + 2);
;       BAR; WAIT_L(0); MMA(1, 0, At, B0); BAR; SCHED;
;       STAGE(SB(0, 1), Bt, ldb, bcol + HALF, t + 2);
;       WAIT_V(6); BAR; MMA(1, 1, At, B1); BAR;
.LBB0_53:
	ds_read_b128 v[172:175], v161
	ds_read_b128 v[176:179], v161 offset:1024
	ds_read_b128 v[180:183], v161 offset:2048
	ds_read_b128 v[184:187], v161 offset:3072
	v_add_u32_e32 v169, 0xc000, v148
	v_lshl_add_u64 v[236:237], v[136:137], 0, s[42:43]
	v_readfirstlane_b32 s45, v169
	v_add_u32_e32 v170, 0xe000, v148
	v_lshl_add_u64 v[162:163], v[236:237], 0, s[14:15]
	s_mov_b32 m0, s45
	v_lshl_add_u64 v[238:239], v[134:135], 0, s[42:43]
	ds_read_b128 v[164:167], v152
	ds_read_b128 v[188:191], v152 offset:1024
	ds_read_b128 v[192:195], v151
	ds_read_b128 v[196:199], v151 offset:1024
	ds_read_b128 v[200:203], v150
	ds_read_b128 v[204:207], v150 offset:1024
	ds_read_b128 v[208:211], v149
	ds_read_b128 v[212:215], v149 offset:1024
	global_load_lds_dwordx4 v[162:163], off
	s_bitset1_b32 m0, 13
	v_lshl_add_u64 v[162:163], v[238:239], 0, s[14:15]
	global_load_lds_dwordx4 v[162:163], off
	s_waitcnt lgkmcnt(8)
	s_barrier
	s_waitcnt lgkmcnt(0)
	s_waitcnt lgkmcnt(0)
	v_mfma_f32_16x16x32_bf16 v[124:127], v[172:175], v[164:167], v[124:127]
	v_mfma_f32_16x16x32_bf16 v[120:123], v[180:183], v[164:167], v[120:123]
	v_mfma_f32_16x16x32_bf16 v[116:119], v[172:175], v[192:195], v[116:119]
	v_mfma_f32_16x16x32_bf16 v[112:115], v[180:183], v[192:195], v[112:115]
	v_mfma_f32_16x16x32_bf16 v[108:111], v[172:175], v[200:203], v[108:111]
	v_mfma_f32_16x16x32_bf16 v[104:107], v[180:183], v[200:203], v[104:107]
	v_mfma_f32_16x16x32_bf16 v[100:103], v[172:175], v[208:211], v[100:103]
	v_mfma_f32_16x16x32_bf16 v[96:99], v[180:183], v[208:211], v[96:99]
	v_mfma_f32_16x16x32_bf16 v[124:127], v[176:179], v[188:191], v[124:127]
	v_mfma_f32_16x16x32_bf16 v[120:123], v[184:187], v[188:191], v[120:123]
	v_mfma_f32_16x16x32_bf16 v[116:119], v[176:179], v[196:199], v[116:119]
	v_mfma_f32_16x16x32_bf16 v[112:115], v[184:187], v[196:199], v[112:115]
	v_mfma_f32_16x16x32_bf16 v[108:111], v[176:179], v[204:207], v[108:111]
	v_mfma_f32_16x16x32_bf16 v[104:107], v[184:187], v[204:207], v[104:107]
	v_mfma_f32_16x16x32_bf16 v[100:103], v[176:179], v[212:215], v[100:103]
	v_mfma_f32_16x16x32_bf16 v[96:99], v[184:187], v[212:215], v[96:99]
	s_barrier
	v_add_u32_e32 v162, s54, v153
	v_lshl_add_u64 v[240:241], v[140:141], 0, s[42:43]
	v_readfirstlane_b32 s45, v162
	v_add_u32_e32 v163, 0x2000, v162
	v_lshl_add_u64 v[232:233], v[240:241], 0, s[16:17]
	s_mov_b32 m0, s45
	v_lshl_add_u64 v[242:243], v[138:139], 0, s[42:43]
	ds_read_b128 v[216:219], v160
	ds_read_b128 v[220:223], v160 offset:1024
	ds_read_b128 v[224:227], v160 offset:2048
	ds_read_b128 v[228:231], v160 offset:3072
	global_load_lds_dwordx4 v[232:233], off
	s_bitset1_b32 m0, 13
	v_lshl_add_u64 v[232:233], v[242:243], 0, s[16:17]
	global_load_lds_dwordx4 v[232:233], off
	s_barrier
	s_waitcnt lgkmcnt(0)
	s_waitcnt lgkmcnt(0)
	v_mfma_f32_16x16x32_bf16 v[92:95], v[216:219], v[164:167], v[92:95]
	v_mfma_f32_16x16x32_bf16 v[88:91], v[224:227], v[164:167], v[88:91]
	v_mfma_f32_16x16x32_bf16 v[84:87], v[216:219], v[192:195], v[84:87]
	v_mfma_f32_16x16x32_bf16 v[80:83], v[224:227], v[192:195], v[80:83]
	v_mfma_f32_16x16x32_bf16 v[76:79], v[216:219], v[200:203], v[76:79]
	v_mfma_f32_16x16x32_bf16 v[72:75], v[224:227], v[200:203], v[72:75]
	v_mfma_f32_16x16x32_bf16 v[68:71], v[216:219], v[208:211], v[68:71]
	v_mfma_f32_16x16x32_bf16 v[64:67], v[224:227], v[208:211], v[64:67]
	v_mfma_f32_16x16x32_bf16 v[92:95], v[220:223], v[188:191], v[92:95]
	v_mfma_f32_16x16x32_bf16 v[88:91], v[228:231], v[188:191], v[88:91]
	v_mfma_f32_16x16x32_bf16 v[84:87], v[220:223], v[196:199], v[84:87]
	v_mfma_f32_16x16x32_bf16 v[80:83], v[228:231], v[196:199], v[80:83]
	v_mfma_f32_16x16x32_bf16 v[76:79], v[220:223], v[204:207], v[76:79]
	v_mfma_f32_16x16x32_bf16 v[72:75], v[228:231], v[204:207], v[72:75]
	v_mfma_f32_16x16x32_bf16 v[68:71], v[220:223], v[212:215], v[68:71]
	v_mfma_f32_16x16x32_bf16 v[64:67], v[228:231], v[212:215], v[64:67]
	v_readfirstlane_b32 s45, v148
	v_lshl_add_u64 v[164:165], v[236:237], 0, s[18:19]
	s_mov_b32 m0, s45
	s_barrier
	ds_read_b128 v[188:191], v152 offset:16384
	ds_read_b128 v[192:195], v152 offset:17408
	ds_read_b128 v[196:199], v151 offset:16384
	ds_read_b128 v[200:203], v151 offset:17408
	ds_read_b128 v[204:207], v150 offset:16384
	ds_read_b128 v[208:211], v150 offset:17408
	ds_read_b128 v[212:215], v149 offset:16384
	ds_read_b128 v[232:235], v149 offset:17408
	global_load_lds_dwordx4 v[164:165], off
	s_bitset1_b32 m0, 13
	v_add_u32_e32 v164, 0x2000, v148
	v_lshl_add_u64 v[166:167], v[238:239], 0, s[18:19]
	global_load_lds_dwordx4 v[166:167], off
	s_barrier
	s_waitcnt lgkmcnt(0)
	s_waitcnt lgkmcnt(0)
	v_mfma_f32_16x16x32_bf16 v[60:63], v[172:175], v[188:191], v[60:63]
	v_mfma_f32_16x16x32_bf16 v[56:59], v[180:183], v[188:191], v[56:59]
	v_mfma_f32_16x16x32_bf16 v[52:55], v[172:175], v[196:199], v[52:55]
	v_mfma_f32_16x16x32_bf16 v[48:51], v[180:183], v[196:199], v[48:51]
	v_mfma_f32_16x16x32_bf16 v[44:47], v[172:175], v[204:207], v[44:47]
	v_mfma_f32_16x16x32_bf16 v[40:43], v[180:183], v[204:207], v[40:43]
	v_mfma_f32_16x16x32_bf16 v[36:39], v[172:175], v[212:215], v[36:39]
	v_mfma_f32_16x16x32_bf16 v[32:35], v[180:183], v[212:215], v[32:35]
	v_mfma_f32_16x16x32_bf16 v[60:63], v[176:179], v[192:195], v[60:63]
	v_mfma_f32_16x16x32_bf16 v[56:59], v[184:187], v[192:195], v[56:59]
	v_mfma_f32_16x16x32_bf16 v[52:55], v[176:179], v[200:203], v[52:55]
	v_mfma_f32_16x16x32_bf16 v[48:51], v[184:187], v[200:203], v[48:51]
	v_mfma_f32_16x16x32_bf16 v[44:47], v[176:179], v[208:211], v[44:47]
	v_mfma_f32_16x16x32_bf16 v[40:43], v[184:187], v[208:211], v[40:43]
	v_mfma_f32_16x16x32_bf16 v[36:39], v[176:179], v[232:235], v[36:39]
	v_mfma_f32_16x16x32_bf16 v[32:35], v[184:187], v[232:235], v[32:35]
	s_barrier
; #define STAGE(P, BASE, LD, br, kt) do { const char* _g = (const char*)((BASE) + (size_t)(br) * (LD) + (size_t)(kt) * 64); \
;     for (int _i = 0; _i < 2; ++_i) { int _b = tidx * 16 + _i * 8192; int _r, _c; stage_rc(_b, _r, _c); \
;       __builtin_amdgcn_global_load_lds((const unsigned*)(_g + (unsigned)((_r * (LD) + _c) * 2)), (unsigned*)((char*)(P) + _b), 16, 0, 0); } } while (0)
; #define LDA(dst, b, h) for (int m = 0; m < 4; ++m) for (int k = 0; k < 2; ++k) \
;     dst[m][k] = *reinterpret_cast<const bf16x8*>((char*)SA(b, h) + lds_byte(wr * 64 + m * 16 + fr, k * 32 + fq * 8))
; #define LDB(dst, b, h) for (int n = 0; n < 2; ++n) for (int k = 0; k < 2; ++k) \
;     dst[n][k] = *reinterpret_cast<const bf16x8*>((char*)SB(b, h) + lds_byte(wc * 32 + n * 16 + fr, k * 32 + fq * 8))
; #define MMA(ai, bj, At_, Bt_) do { __builtin_amdgcn_s_setprio(1); \
;     for (int k = 0; k < 2; ++k) for (int m = 0; m < 4; ++m) for (int n = 0; n < 2; ++n) \
;       acc[ai][bj][m][n] = __builtin_amdgcn_mfma_f32_16x16x32_bf16(At_[m][k], Bt_[n][k], acc[ai][bj][m][n], 0, 0, 0); \
;     __builtin_amdgcn_s_setprio(0); } while (0)
; #define WAIT_V(n) asm volatile("s_waitcnt vmcnt(" #n ")" ::: "memory")
; #define WAIT_L(n) asm volatile("s_waitcnt lgkmcnt(" #n ")" ::: "memory")
; #define BAR __builtin_amdgcn_s_barrier()
; #define SCHED __builtin_amdgcn_sched_barrier(0)
; template <int EPI, int lda, int ldb, int N, int K>
; __device__ __forceinline__ void gemm_phase(const u16* __restrict__ A, const u16* __restrict__ Bt, const GemmEpi ep, int wv) {
;     ...
;       WAIT_V(6); BAR; MMA(1, 1, At, B1); BAR;
;       LDB(B0, 1, 0); SCHED; LDA(At, 1, 0); STAGE(SA(0, 1), Ab, lda, brow + HALF, t + 2);
;       WAIT_L(8); BAR; WAIT_L(0); MMA(0, 0, At, B0); BAR; SCHED;
;       LDB(B1, 1, 1); STAGE(SB(1, 0), Bt, ldb, bcol, t + 3);
;       BAR; WAIT_L(0); MMA(0, 1, At, B1); BAR;
;       LDA(At, 1, 1); STAGE(SA(1, 0), Ab, lda, brow, t + 3);
;       BAR; WAIT_L(0); MMA(1, 0, At, B0); BAR; SCHED;
;       STAGE(SB(1, 1), Bt, ldb, bcol + HALF, t + 3);
;       WAIT_V(6); BAR; MMA(1, 1, At, B1); BAR;
	v_add_u32_e32 v165, s55, v153
	v_lshl_add_u64 v[166:167], v[240:241], 0, s[20:21]
	v_readfirstlane_b32 s45, v165
	s_mov_b32 m0, s45
	v_lshl_add_u64 v[172:173], v[242:243], 0, s[20:21]
	global_load_lds_dwordx4 v[166:167], off
	s_bitset1_b32 m0, 13
	v_add_u32_e32 v166, 0x2000, v165
	global_load_lds_dwordx4 v[172:173], off
	s_waitcnt vmcnt(6)
	s_barrier
	v_mfma_f32_16x16x32_bf16 v[28:31], v[216:219], v[188:191], v[28:31]
	v_mfma_f32_16x16x32_bf16 v[24:27], v[224:227], v[188:191], v[24:27]
	v_mfma_f32_16x16x32_bf16 v[20:23], v[216:219], v[196:199], v[20:23]
	v_mfma_f32_16x16x32_bf16 v[16:19], v[224:227], v[196:199], v[16:19]
	v_mfma_f32_16x16x32_bf16 v[12:15], v[216:219], v[204:207], v[12:15]
	v_mfma_f32_16x16x32_bf16 v[8:11], v[224:227], v[204:207], v[8:11]
	v_mfma_f32_16x16x32_bf16 v[4:7], v[216:219], v[212:215], v[4:7]
	v_mfma_f32_16x16x32_bf16 v[0:3], v[224:227], v[212:215], v[0:3]
	v_mfma_f32_16x16x32_bf16 v[28:31], v[220:223], v[192:195], v[28:31]
	v_mfma_f32_16x16x32_bf16 v[24:27], v[228:231], v[192:195], v[24:27]
	v_mfma_f32_16x16x32_bf16 v[20:23], v[220:223], v[200:203], v[20:23]
	v_mfma_f32_16x16x32_bf16 v[16:19], v[228:231], v[200:203], v[16:19]
	v_mfma_f32_16x16x32_bf16 v[12:15], v[220:223], v[208:211], v[12:15]
	v_mfma_f32_16x16x32_bf16 v[8:11], v[228:231], v[208:211], v[8:11]
	v_mfma_f32_16x16x32_bf16 v[4:7], v[220:223], v[232:235], v[4:7]
	v_mfma_f32_16x16x32_bf16 v[0:3], v[228:231], v[232:235], v[0:3]
	s_barrier
	ds_read_b128 v[172:175], v156
	ds_read_b128 v[176:179], v156 offset:1024
	ds_read_b128 v[180:183], v156 offset:2048
	ds_read_b128 v[184:187], v156 offset:3072
	v_add_u32_e32 v167, 0x4000, v148
	v_add_u32_e32 v168, 0x6000, v148
	v_readfirstlane_b32 s45, v167
	v_lshl_add_u64 v[220:221], v[236:237], 0, s[22:23]
	s_mov_b32 m0, s45
	ds_read_b128 v[188:191], v152 offset:32768
	ds_read_b128 v[192:195], v152 offset:33792
	ds_read_b128 v[196:199], v151 offset:32768
	ds_read_b128 v[200:203], v151 offset:33792
	ds_read_b128 v[204:207], v150 offset:32768
	ds_read_b128 v[208:211], v150 offset:33792
	ds_read_b128 v[212:215], v149 offset:32768
	ds_read_b128 v[216:219], v149 offset:33792
	global_load_lds_dwordx4 v[220:221], off
	s_bitset1_b32 m0, 13
	v_lshl_add_u64 v[220:221], v[238:239], 0, s[22:23]
	global_load_lds_dwordx4 v[220:221], off
	s_waitcnt lgkmcnt(8)
	s_barrier
	s_waitcnt lgkmcnt(0)
	s_waitcnt lgkmcnt(0)
	v_mfma_f32_16x16x32_bf16 v[124:127], v[172:175], v[188:191], v[124:127]
	v_mfma_f32_16x16x32_bf16 v[120:123], v[180:183], v[188:191], v[120:123]
	v_mfma_f32_16x16x32_bf16 v[116:119], v[172:175], v[196:199], v[116:119]
	v_mfma_f32_16x16x32_bf16 v[112:115], v[180:183], v[196:199], v[112:115]
	v_mfma_f32_16x16x32_bf16 v[108:111], v[172:175], v[204:207], v[108:111]
	v_mfma_f32_16x16x32_bf16 v[104:107], v[180:183], v[204:207], v[104:107]
	v_mfma_f32_16x16x32_bf16 v[100:103], v[172:175], v[212:215], v[100:103]
	v_mfma_f32_16x16x32_bf16 v[96:99], v[180:183], v[212:215], v[96:99]
	v_mfma_f32_16x16x32_bf16 v[124:127], v[176:179], v[192:195], v[124:127]
	v_mfma_f32_16x16x32_bf16 v[120:123], v[184:187], v[192:195], v[120:123]
	v_mfma_f32_16x16x32_bf16 v[116:119], v[176:179], v[200:203], v[116:119]
	v_mfma_f32_16x16x32_bf16 v[112:115], v[184:187], v[200:203], v[112:115]
	v_mfma_f32_16x16x32_bf16 v[108:111], v[176:179], v[208:211], v[108:111]
	v_mfma_f32_16x16x32_bf16 v[104:107], v[184:187], v[208:211], v[104:107]
	v_mfma_f32_16x16x32_bf16 v[100:103], v[176:179], v[216:219], v[100:103]
	v_mfma_f32_16x16x32_bf16 v[96:99], v[184:187], v[216:219], v[96:99]
	s_barrier
	v_readfirstlane_b32 s45, v155
	v_add_u32_e32 v171, 0x2000, v155
	v_lshl_add_u64 v[244:245], v[240:241], 0, s[24:25]
	s_mov_b32 m0, s45
	ds_read_b128 v[220:223], v154
	ds_read_b128 v[224:227], v154 offset:1024
	ds_read_b128 v[228:231], v154 offset:2048
	ds_read_b128 v[232:235], v154 offset:3072
	global_load_lds_dwordx4 v[244:245], off
	s_bitset1_b32 m0, 13
	v_lshl_add_u64 v[244:245], v[242:243], 0, s[24:25]
	global_load_lds_dwordx4 v[244:245], off
	s_barrier
	s_waitcnt lgkmcnt(0)
	s_waitcnt lgkmcnt(0)
	v_mfma_f32_16x16x32_bf16 v[92:95], v[220:223], v[188:191], v[92:95]
	v_mfma_f32_16x16x32_bf16 v[88:91], v[228:231], v[188:191], v[88:91]
	v_mfma_f32_16x16x32_bf16 v[84:87], v[220:223], v[196:199], v[84:87]
	v_mfma_f32_16x16x32_bf16 v[80:83], v[228:231], v[196:199], v[80:83]
	v_mfma_f32_16x16x32_bf16 v[76:79], v[220:223], v[204:207], v[76:79]
	v_mfma_f32_16x16x32_bf16 v[72:75], v[228:231], v[204:207], v[72:75]
	v_mfma_f32_16x16x32_bf16 v[68:71], v[220:223], v[212:215], v[68:71]
	v_mfma_f32_16x16x32_bf16 v[64:67], v[228:231], v[212:215], v[64:67]
	v_mfma_f32_16x16x32_bf16 v[92:95], v[224:227], v[192:195], v[92:95]
	v_mfma_f32_16x16x32_bf16 v[88:91], v[232:235], v[192:195], v[88:91]
	v_mfma_f32_16x16x32_bf16 v[84:87], v[224:227], v[200:203], v[84:87]
	v_mfma_f32_16x16x32_bf16 v[80:83], v[232:235], v[200:203], v[80:83]
	v_mfma_f32_16x16x32_bf16 v[76:79], v[224:227], v[208:211], v[76:79]
	v_mfma_f32_16x16x32_bf16 v[72:75], v[232:235], v[208:211], v[72:75]
	v_mfma_f32_16x16x32_bf16 v[68:71], v[224:227], v[216:219], v[68:71]
	v_mfma_f32_16x16x32_bf16 v[64:67], v[232:235], v[216:219], v[64:67]
	v_readfirstlane_b32 s45, v157
	v_lshl_add_u64 v[236:237], v[236:237], 0, s[26:27]
	s_mov_b32 m0, s45
	s_barrier
	ds_read_b128 v[188:191], v152 offset:49152
	ds_read_b128 v[192:195], v152 offset:50176
	ds_read_b128 v[196:199], v151 offset:49152
	ds_read_b128 v[200:203], v151 offset:50176
	ds_read_b128 v[204:207], v150 offset:49152
	ds_read_b128 v[208:211], v150 offset:50176
	ds_read_b128 v[212:215], v149 offset:49152
	ds_read_b128 v[216:219], v149 offset:50176
	global_load_lds_dwordx4 v[236:237], off
	s_bitset1_b32 m0, 13
	v_lshl_add_u64 v[236:237], v[238:239], 0, s[26:27]
	global_load_lds_dwordx4 v[236:237], off
	s_barrier
; #define STAGE(P, BASE, LD, br, kt) do { const char* _g = (const char*)((BASE) + (size_t)(br) * (LD) + (size_t)(kt) * 64); \
;     for (int _i = 0; _i < 2; ++_i) { int _b = tidx * 16 + _i * 8192; int _r, _c; stage_rc(_b, _r, _c); \
;       __builtin_amdgcn_global_load_lds((const unsigned*)(_g + (unsigned)((_r * (LD) + _c) * 2)), (unsigned*)((char*)(P) + _b), 16, 0, 0); } } while (0)
; #define LDA(dst, b, h) for (int m = 0; m < 4; ++m) for (int k = 0; k < 2; ++k) \
;     dst[m][k] = *reinterpret_cast<const bf16x8*>((char*)SA(b, h) + lds_byte(wr * 64 + m * 16 + fr, k * 32 + fq * 8))
; #define LDB(dst, b, h) for (int n = 0; n < 2; ++n) for (int k = 0; k < 2; ++k) \
;     dst[n][k] = *reinterpret_cast<const bf16x8*>((char*)SB(b, h) + lds_byte(wc * 32 + n * 16 + fr, k * 32 + fq * 8))
; #define MMA(ai, bj, At_, Bt_) do { __builtin_amdgcn_s_setprio(1); \
;     for (int k = 0; k < 2; ++k) for (int m = 0; m < 4; ++m) for (int n = 0; n < 2; ++n) \
;       acc[ai][bj][m][n] = __builtin_amdgcn_mfma_f32_16x16x32_bf16(At_[m][k], Bt_[n][k], acc[ai][bj][m][n], 0, 0, 0); \
;     __builtin_amdgcn_s_setprio(0); } while (0)
; #define WAIT_V(n) asm volatile("s_waitcnt vmcnt(" #n ")" ::: "memory")
; #define WAIT_L(n) asm volatile("s_waitcnt lgkmcnt(" #n ")" ::: "memory")
; #define BAR __builtin_amdgcn_s_barrier()
; #define SCHED __builtin_amdgcn_sched_barrier(0)
; template <int EPI, int lda, int ldb, int N, int K>
; __device__ __forceinline__ void gemm_phase(const u16* __restrict__ A, const u16* __restrict__ Bt, const GemmEpi ep, int wv) {
;     ...
;       BAR; WAIT_L(0); MMA(0, 1, At, B1); BAR;
;       LDA(At, 1, 1); STAGE(SA(1, 0), Ab, lda, brow, t + 3);
;       BAR; WAIT_L(0); MMA(1, 0, At, B0); BAR; SCHED;
;       STAGE(SB(1, 1), Bt, ldb, bcol + HALF, t + 3);
;       WAIT_V(6); BAR; MMA(1, 1, At, B1); BAR;
;     }
;     { LDB(B0, 0, 0); LDA(At, 0, 0); STAGE(SA(1, 1), Ab, lda, brow + HALF, nt - 1);
;       BAR; WAIT_L(0); MMA(0, 0, At, B0); BAR;
;       LDB(B1, 0, 1); BAR; WAIT_L(0); MMA(0, 1, At, B1); BAR;
;       LDA(At, 0, 1); WAIT_V(4); BAR; WAIT_L(0); MMA(1, 0, At, B0); MMA(1, 1, At, B1); BAR; }
	s_waitcnt lgkmcnt(0)
	s_waitcnt lgkmcnt(0)
	v_mfma_f32_16x16x32_bf16 v[60:63], v[172:175], v[188:191], v[60:63]
	v_mfma_f32_16x16x32_bf16 v[56:59], v[180:183], v[188:191], v[56:59]
	v_mfma_f32_16x16x32_bf16 v[52:55], v[172:175], v[196:199], v[52:55]
	v_mfma_f32_16x16x32_bf16 v[48:51], v[180:183], v[196:199], v[48:51]
	v_mfma_f32_16x16x32_bf16 v[44:47], v[172:175], v[204:207], v[44:47]
	v_mfma_f32_16x16x32_bf16 v[40:43], v[180:183], v[204:207], v[40:43]
	v_mfma_f32_16x16x32_bf16 v[36:39], v[172:175], v[212:215], v[36:39]
	v_mfma_f32_16x16x32_bf16 v[32:35], v[180:183], v[212:215], v[32:35]
	v_mfma_f32_16x16x32_bf16 v[60:63], v[176:179], v[192:195], v[60:63]
	v_mfma_f32_16x16x32_bf16 v[56:59], v[184:187], v[192:195], v[56:59]
	v_mfma_f32_16x16x32_bf16 v[52:55], v[176:179], v[200:203], v[52:55]
	v_mfma_f32_16x16x32_bf16 v[48:51], v[184:187], v[200:203], v[48:51]
	v_mfma_f32_16x16x32_bf16 v[44:47], v[176:179], v[208:211], v[44:47]
	v_mfma_f32_16x16x32_bf16 v[40:43], v[184:187], v[208:211], v[40:43]
	v_mfma_f32_16x16x32_bf16 v[36:39], v[176:179], v[216:219], v[36:39]
	v_mfma_f32_16x16x32_bf16 v[32:35], v[184:187], v[216:219], v[32:35]
	s_barrier
	v_readfirstlane_b32 s45, v159
	v_add_u32_e32 v171, 0x2000, v159
	v_lshl_add_u64 v[172:173], v[240:241], 0, s[34:35]
	s_mov_b32 m0, s45
	global_load_lds_dwordx4 v[172:173], off
	s_bitset1_b32 m0, 13
	v_lshl_add_u64 v[172:173], v[242:243], 0, s[34:35]
	global_load_lds_dwordx4 v[172:173], off
	s_waitcnt vmcnt(6)
	s_barrier
	v_mfma_f32_16x16x32_bf16 v[28:31], v[220:223], v[188:191], v[28:31]
	v_mfma_f32_16x16x32_bf16 v[24:27], v[228:231], v[188:191], v[24:27]
	v_mfma_f32_16x16x32_bf16 v[20:23], v[220:223], v[196:199], v[20:23]
	v_mfma_f32_16x16x32_bf16 v[16:19], v[228:231], v[196:199], v[16:19]
	v_mfma_f32_16x16x32_bf16 v[12:15], v[220:223], v[204:207], v[12:15]
	v_mfma_f32_16x16x32_bf16 v[8:11], v[228:231], v[204:207], v[8:11]
	v_mfma_f32_16x16x32_bf16 v[4:7], v[220:223], v[212:215], v[4:7]
	v_mfma_f32_16x16x32_bf16 v[0:3], v[228:231], v[212:215], v[0:3]
	v_mfma_f32_16x16x32_bf16 v[28:31], v[224:227], v[192:195], v[28:31]
	v_mfma_f32_16x16x32_bf16 v[24:27], v[232:235], v[192:195], v[24:27]
	v_mfma_f32_16x16x32_bf16 v[20:23], v[224:227], v[200:203], v[20:23]
	v_mfma_f32_16x16x32_bf16 v[16:19], v[232:235], v[200:203], v[16:19]
	v_mfma_f32_16x16x32_bf16 v[12:15], v[224:227], v[208:211], v[12:15]
	v_mfma_f32_16x16x32_bf16 v[8:11], v[232:235], v[208:211], v[8:11]
	v_mfma_f32_16x16x32_bf16 v[4:7], v[224:227], v[216:219], v[4:7]
	v_mfma_f32_16x16x32_bf16 v[0:3], v[232:235], v[216:219], v[0:3]
	s_add_i32 s44, s44, 2
	s_add_u32 s42, s42, 0x100
	s_addc_u32 s43, s43, 0
	s_cmp_gt_u32 s44, 27
	s_barrier
	s_cbranch_scc0 .LBB0_53
	s_add_i32 s42, s38, 0x80
	s_mul_hi_i32 s43, s42, 0x1080
	s_mulk_i32 s42, 0x1080
	s_add_u32 s42, s51, s42
	s_addc_u32 s43, s52, s43
	v_lshl_add_u64 v[158:159], s[42:43], 0, v[128:129]
	v_readfirstlane_b32 s44, v169
	v_lshl_add_u64 v[158:159], v[158:159], 0, s[36:37]
	s_mov_b32 m0, s44
	ds_read_b128 v[134:137], v161
	ds_read_b128 v[138:141], v161 offset:1024
	ds_read_b128 v[172:175], v161 offset:2048
	ds_read_b128 v[176:179], v161 offset:3072
	ds_read_b128 v[180:183], v152
	ds_read_b128 v[184:187], v152 offset:1024
	ds_read_b128 v[188:191], v151
	ds_read_b128 v[192:195], v151 offset:1024
	ds_read_b128 v[196:199], v150
	ds_read_b128 v[200:203], v150 offset:1024
	ds_read_b128 v[204:207], v149
	ds_read_b128 v[208:211], v149 offset:1024
	global_load_lds_dwordx4 v[158:159], off
	v_lshl_add_u64 v[158:159], s[42:43], 0, v[132:133]
	v_readfirstlane_b32 s42, v170
	v_lshl_add_u64 v[158:159], v[158:159], 0, s[36:37]
	s_mov_b32 m0, s42
	s_nop 0
	global_load_lds_dwordx4 v[158:159], off
	s_barrier
	s_waitcnt lgkmcnt(0)
	s_waitcnt lgkmcnt(0)
	v_mfma_f32_16x16x32_bf16 v[124:127], v[134:137], v[180:183], v[124:127]
	v_mfma_f32_16x16x32_bf16 v[120:123], v[172:175], v[180:183], v[120:123]
	v_mfma_f32_16x16x32_bf16 v[116:119], v[134:137], v[188:191], v[116:119]
	v_mfma_f32_16x16x32_bf16 v[112:115], v[172:175], v[188:191], v[112:115]
	v_mfma_f32_16x16x32_bf16 v[108:111], v[134:137], v[196:199], v[108:111]
	v_mfma_f32_16x16x32_bf16 v[104:107], v[172:175], v[196:199], v[104:107]
	v_mfma_f32_16x16x32_bf16 v[100:103], v[134:137], v[204:207], v[100:103]
	v_mfma_f32_16x16x32_bf16 v[96:99], v[172:175], v[204:207], v[96:99]
	v_mfma_f32_16x16x32_bf16 v[124:127], v[138:141], v[184:187], v[124:127]
	v_mfma_f32_16x16x32_bf16 v[120:123], v[176:179], v[184:187], v[120:123]
	v_mfma_f32_16x16x32_bf16 v[116:119], v[138:141], v[192:195], v[116:119]
	v_mfma_f32_16x16x32_bf16 v[112:115], v[176:179], v[192:195], v[112:115]
	v_mfma_f32_16x16x32_bf16 v[108:111], v[138:141], v[200:203], v[108:111]
	v_mfma_f32_16x16x32_bf16 v[104:107], v[176:179], v[200:203], v[104:107]
	v_mfma_f32_16x16x32_bf16 v[100:103], v[138:141], v[208:211], v[100:103]
	v_mfma_f32_16x16x32_bf16 v[96:99], v[176:179], v[208:211], v[96:99]
	s_barrier
	ds_read_b128 v[212:215], v160
	ds_read_b128 v[216:219], v160 offset:1024
	ds_read_b128 v[220:223], v160 offset:2048
	ds_read_b128 v[158:161], v160 offset:3072
	s_barrier
; #define LDA(dst, b, h) for (int m = 0; m < 4; ++m) for (int k = 0; k < 2; ++k) \
;     dst[m][k] = *reinterpret_cast<const bf16x8*>((char*)SA(b, h) + lds_byte(wr * 64 + m * 16 + fr, k * 32 + fq * 8))
; #define LDB(dst, b, h) for (int n = 0; n < 2; ++n) for (int k = 0; k < 2; ++k) \
;     dst[n][k] = *reinterpret_cast<const bf16x8*>((char*)SB(b, h) + lds_byte(wc * 32 + n * 16 + fr, k * 32 + fq * 8))
; #define MMA(ai, bj, At_, Bt_) do { __builtin_amdgcn_s_setprio(1); \
;     for (int k = 0; k < 2; ++k) for (int m = 0; m < 4; ++m) for (int n = 0; n < 2; ++n) \
;       acc[ai][bj][m][n] = __builtin_amdgcn_mfma_f32_16x16x32_bf16(At_[m][k], Bt_[n][k], acc[ai][bj][m][n], 0, 0, 0); \
;     __builtin_amdgcn_s_setprio(0); } while (0)
; #define WAIT_V(n) asm volatile("s_waitcnt vmcnt(" #n ")" ::: "memory")
; #define WAIT_L(n) asm volatile("s_waitcnt lgkmcnt(" #n ")" ::: "memory")
; #define BAR __builtin_amdgcn_s_barrier()
; template <int EPI, int lda, int ldb, int N, int K>
; __device__ __forceinline__ void gemm_phase(const u16* __restrict__ A, const u16* __restrict__ Bt, const GemmEpi ep, int wv) {
;     ...
;       BAR; WAIT_L(0); MMA(0, 0, At, B0); BAR;
;       LDB(B1, 0, 1); BAR; WAIT_L(0); MMA(0, 1, At, B1); BAR;
;       LDA(At, 0, 1); WAIT_V(4); BAR; WAIT_L(0); MMA(1, 0, At, B0); MMA(1, 1, At, B1); BAR; }
;     { LDB(B0, 1, 0); LDA(At, 1, 0); WAIT_V(2); BAR; WAIT_L(0); MMA(0, 0, At, B0); BAR;
;       LDB(B1, 1, 1); WAIT_V(0); BAR; WAIT_L(0); MMA(0, 1, At, B1); BAR;
	s_waitcnt lgkmcnt(0)
	s_waitcnt lgkmcnt(0)
	v_mfma_f32_16x16x32_bf16 v[92:95], v[212:215], v[180:183], v[92:95]
	v_mfma_f32_16x16x32_bf16 v[88:91], v[220:223], v[180:183], v[88:91]
	v_mfma_f32_16x16x32_bf16 v[76:79], v[212:215], v[196:199], v[76:79]
	v_mfma_f32_16x16x32_bf16 v[72:75], v[220:223], v[196:199], v[72:75]
	v_mfma_f32_16x16x32_bf16 v[84:87], v[212:215], v[188:191], v[84:87]
	v_mfma_f32_16x16x32_bf16 v[80:83], v[220:223], v[188:191], v[80:83]
	v_mfma_f32_16x16x32_bf16 v[68:71], v[212:215], v[204:207], v[68:71]
	v_mfma_f32_16x16x32_bf16 v[64:67], v[220:223], v[204:207], v[64:67]
	v_mfma_f32_16x16x32_bf16 v[92:95], v[216:219], v[184:187], v[92:95]
	v_mfma_f32_16x16x32_bf16 v[88:91], v[158:161], v[184:187], v[88:91]
	v_mfma_f32_16x16x32_bf16 v[76:79], v[216:219], v[200:203], v[76:79]
	v_mfma_f32_16x16x32_bf16 v[72:75], v[158:161], v[200:203], v[72:75]
	v_mfma_f32_16x16x32_bf16 v[180:183], v[216:219], v[192:195], v[84:87]
	v_mfma_f32_16x16x32_bf16 v[184:187], v[158:161], v[192:195], v[80:83]
	v_mfma_f32_16x16x32_bf16 v[188:191], v[216:219], v[208:211], v[68:71]
	v_mfma_f32_16x16x32_bf16 v[192:195], v[158:161], v[208:211], v[64:67]
	s_barrier
	s_nop 0
	ds_read_b128 v[64:67], v152 offset:16384
	ds_read_b128 v[68:71], v152 offset:17408
	ds_read_b128 v[80:83], v151 offset:16384
	ds_read_b128 v[84:87], v151 offset:17408
	ds_read_b128 v[196:199], v150 offset:16384
	ds_read_b128 v[200:203], v150 offset:17408
	ds_read_b128 v[204:207], v149 offset:16384
	ds_read_b128 v[208:211], v149 offset:17408
	s_waitcnt vmcnt(4)
	s_barrier
	s_waitcnt lgkmcnt(0)
	s_waitcnt lgkmcnt(0)
	v_mfma_f32_16x16x32_bf16 v[60:63], v[134:137], v[64:67], v[60:63]
	v_mfma_f32_16x16x32_bf16 v[56:59], v[172:175], v[64:67], v[56:59]
	v_mfma_f32_16x16x32_bf16 v[52:55], v[134:137], v[80:83], v[52:55]
	v_mfma_f32_16x16x32_bf16 v[48:51], v[172:175], v[80:83], v[48:51]
	v_mfma_f32_16x16x32_bf16 v[44:47], v[134:137], v[196:199], v[44:47]
	v_mfma_f32_16x16x32_bf16 v[40:43], v[172:175], v[196:199], v[40:43]
	v_mfma_f32_16x16x32_bf16 v[36:39], v[134:137], v[204:207], v[36:39]
	v_mfma_f32_16x16x32_bf16 v[32:35], v[172:175], v[204:207], v[32:35]
	v_mfma_f32_16x16x32_bf16 v[60:63], v[138:141], v[68:71], v[60:63]
	v_mfma_f32_16x16x32_bf16 v[56:59], v[176:179], v[68:71], v[56:59]
	v_mfma_f32_16x16x32_bf16 v[52:55], v[138:141], v[84:87], v[52:55]
	v_mfma_f32_16x16x32_bf16 v[48:51], v[176:179], v[84:87], v[48:51]
	v_mfma_f32_16x16x32_bf16 v[44:47], v[138:141], v[200:203], v[44:47]
	v_mfma_f32_16x16x32_bf16 v[40:43], v[176:179], v[200:203], v[40:43]
	v_mfma_f32_16x16x32_bf16 v[36:39], v[138:141], v[208:211], v[36:39]
	v_mfma_f32_16x16x32_bf16 v[32:35], v[176:179], v[208:211], v[32:35]
	v_mfma_f32_16x16x32_bf16 v[28:31], v[212:215], v[64:67], v[28:31]
	v_mfma_f32_16x16x32_bf16 v[24:27], v[220:223], v[64:67], v[24:27]
	v_mfma_f32_16x16x32_bf16 v[12:15], v[212:215], v[196:199], v[12:15]
	v_mfma_f32_16x16x32_bf16 v[8:11], v[220:223], v[196:199], v[8:11]
	v_mfma_f32_16x16x32_bf16 v[20:23], v[212:215], v[80:83], v[20:23]
	v_mfma_f32_16x16x32_bf16 v[16:19], v[220:223], v[80:83], v[16:19]
	v_mfma_f32_16x16x32_bf16 v[4:7], v[212:215], v[204:207], v[4:7]
	v_mfma_f32_16x16x32_bf16 v[0:3], v[220:223], v[204:207], v[0:3]
	v_mfma_f32_16x16x32_bf16 v[28:31], v[216:219], v[68:71], v[28:31]
	v_mfma_f32_16x16x32_bf16 v[24:27], v[158:161], v[68:71], v[24:27]
	v_mfma_f32_16x16x32_bf16 v[12:15], v[216:219], v[200:203], v[12:15]
	v_mfma_f32_16x16x32_bf16 v[8:11], v[158:161], v[200:203], v[8:11]
	v_mfma_f32_16x16x32_bf16 v[134:137], v[216:219], v[84:87], v[20:23]
	v_mfma_f32_16x16x32_bf16 v[138:141], v[158:161], v[84:87], v[16:19]
	v_mfma_f32_16x16x32_bf16 v[170:173], v[216:219], v[208:211], v[4:7]
	v_mfma_f32_16x16x32_bf16 v[158:161], v[158:161], v[208:211], v[0:3]
	s_barrier
	s_nop 0
	ds_read_b128 v[0:3], v156
	ds_read_b128 v[4:7], v156 offset:1024
	ds_read_b128 v[16:19], v156 offset:2048
	ds_read_b128 v[174:177], v156 offset:3072
	ds_read_b128 v[20:23], v152 offset:32768
	ds_read_b128 v[196:199], v152 offset:33792
	ds_read_b128 v[200:203], v151 offset:32768
	ds_read_b128 v[204:207], v151 offset:33792
	ds_read_b128 v[208:211], v150 offset:32768
	ds_read_b128 v[212:215], v150 offset:33792
	ds_read_b128 v[216:219], v149 offset:32768
	ds_read_b128 v[220:223], v149 offset:33792
	s_waitcnt vmcnt(2)
	s_barrier
; #define LDA(dst, b, h) for (int m = 0; m < 4; ++m) for (int k = 0; k < 2; ++k) \
;     dst[m][k] = *reinterpret_cast<const bf16x8*>((char*)SA(b, h) + lds_byte(wr * 64 + m * 16 + fr, k * 32 + fq * 8))
; #define LDB(dst, b, h) for (int n = 0; n < 2; ++n) for (int k = 0; k < 2; ++k) \
;     dst[n][k] = *reinterpret_cast<const bf16x8*>((char*)SB(b, h) + lds_byte(wc * 32 + n * 16 + fr, k * 32 + fq * 8))
; #define MMA(ai, bj, At_, Bt_) do { __builtin_amdgcn_s_setprio(1); \
;     for (int k = 0; k < 2; ++k) for (int m = 0; m < 4; ++m) for (int n = 0; n < 2; ++n) \
;       acc[ai][bj][m][n] = __builtin_amdgcn_mfma_f32_16x16x32_bf16(At_[m][k], Bt_[n][k], acc[ai][bj][m][n], 0, 0, 0); \
;     __builtin_amdgcn_s_setprio(0); } while (0)
; #define WAIT_V(n) asm volatile("s_waitcnt vmcnt(" #n ")" ::: "memory")
; #define WAIT_L(n) asm volatile("s_waitcnt lgkmcnt(" #n ")" ::: "memory")
; #define BAR __builtin_amdgcn_s_barrier()
; template <int EPI, int lda, int ldb, int N, int K>
; __device__ __forceinline__ void gemm_phase(const u16* __restrict__ A, const u16* __restrict__ Bt, const GemmEpi ep, int wv) {
;     ...
;       LDA(At, 0, 1); WAIT_V(4); BAR; WAIT_L(0); MMA(1, 0, At, B0); MMA(1, 1, At, B1); BAR; }
;     { LDB(B0, 1, 0); LDA(At, 1, 0); WAIT_V(2); BAR; WAIT_L(0); MMA(0, 0, At, B0); BAR;
;       LDB(B1, 1, 1); WAIT_V(0); BAR; WAIT_L(0); MMA(0, 1, At, B1); BAR;
;       LDA(At, 1, 1); BAR; WAIT_L(0); MMA(1, 0, At, B0); MMA(1, 1, At, B1); BAR; }
;     if (wr == 0) BAR;
	s_waitcnt lgkmcnt(0)
	s_waitcnt lgkmcnt(0)
	v_mfma_f32_16x16x32_bf16 v[64:67], v[0:3], v[20:23], v[124:127]
	v_mfma_f32_16x16x32_bf16 v[68:71], v[16:19], v[20:23], v[120:123]
	v_mfma_f32_16x16x32_bf16 v[80:83], v[0:3], v[200:203], v[116:119]
	v_mfma_f32_16x16x32_bf16 v[84:87], v[16:19], v[200:203], v[112:115]
	v_mfma_f32_16x16x32_bf16 v[108:111], v[0:3], v[208:211], v[108:111]
	v_mfma_f32_16x16x32_bf16 v[104:107], v[16:19], v[208:211], v[104:107]
	v_mfma_f32_16x16x32_bf16 v[120:123], v[0:3], v[216:219], v[100:103]
	v_mfma_f32_16x16x32_bf16 v[124:127], v[16:19], v[216:219], v[96:99]
	v_mfma_f32_16x16x32_bf16 v[116:119], v[4:7], v[196:199], v[64:67]
	v_mfma_f32_16x16x32_bf16 v[112:115], v[174:177], v[196:199], v[68:71]
	v_mfma_f32_16x16x32_bf16 v[100:103], v[4:7], v[204:207], v[80:83]
	v_mfma_f32_16x16x32_bf16 v[96:99], v[174:177], v[204:207], v[84:87]
	v_mfma_f32_16x16x32_bf16 v[84:87], v[4:7], v[212:215], v[108:111]
	v_mfma_f32_16x16x32_bf16 v[80:83], v[174:177], v[212:215], v[104:107]
	v_mfma_f32_16x16x32_bf16 v[68:71], v[4:7], v[220:223], v[120:123]
	v_mfma_f32_16x16x32_bf16 v[64:67], v[174:177], v[220:223], v[124:127]
	s_barrier
	ds_read_b128 v[224:227], v154
	ds_read_b128 v[228:231], v154 offset:1024
	ds_read_b128 v[232:235], v154 offset:2048
	ds_read_b128 v[154:157], v154 offset:3072
	s_waitcnt vmcnt(0)
	s_barrier
	s_waitcnt lgkmcnt(0)
	s_waitcnt lgkmcnt(0)
	v_mfma_f32_16x16x32_bf16 v[92:95], v[224:227], v[20:23], v[92:95]
	v_mfma_f32_16x16x32_bf16 v[20:23], v[232:235], v[20:23], v[88:91]
	v_mfma_f32_16x16x32_bf16 v[88:91], v[224:227], v[200:203], v[180:183]
	v_mfma_f32_16x16x32_bf16 v[104:107], v[232:235], v[200:203], v[184:187]
	v_mfma_f32_16x16x32_bf16 v[76:79], v[224:227], v[208:211], v[76:79]
	v_mfma_f32_16x16x32_bf16 v[72:75], v[232:235], v[208:211], v[72:75]
	v_mfma_f32_16x16x32_bf16 v[178:181], v[224:227], v[216:219], v[188:191]
	v_mfma_f32_16x16x32_bf16 v[182:185], v[232:235], v[216:219], v[192:195]
	v_mfma_f32_16x16x32_bf16 v[124:127], v[228:231], v[196:199], v[92:95]
	v_mfma_f32_16x16x32_bf16 v[120:123], v[154:157], v[196:199], v[20:23]
	v_mfma_f32_16x16x32_bf16 v[108:111], v[228:231], v[204:207], v[88:91]
	v_mfma_f32_16x16x32_bf16 v[104:107], v[154:157], v[204:207], v[104:107]
	v_mfma_f32_16x16x32_bf16 v[92:95], v[228:231], v[212:215], v[76:79]
	v_mfma_f32_16x16x32_bf16 v[88:91], v[154:157], v[212:215], v[72:75]
	v_mfma_f32_16x16x32_bf16 v[76:79], v[228:231], v[220:223], v[178:181]
	v_mfma_f32_16x16x32_bf16 v[72:75], v[154:157], v[220:223], v[182:185]
	s_barrier
	ds_read_b128 v[178:181], v152 offset:49152
	ds_read_b128 v[182:185], v152 offset:50176
	ds_read_b128 v[186:189], v151 offset:49152
	ds_read_b128 v[190:193], v151 offset:50176
	ds_read_b128 v[194:197], v150 offset:49152
	ds_read_b128 v[150:153], v150 offset:50176
	ds_read_b128 v[198:201], v149 offset:49152
	ds_read_b128 v[202:205], v149 offset:50176
	s_barrier
	s_waitcnt lgkmcnt(0)
	s_waitcnt lgkmcnt(0)
	v_mfma_f32_16x16x32_bf16 v[20:23], v[0:3], v[178:181], v[60:63]
	v_mfma_f32_16x16x32_bf16 v[56:59], v[16:19], v[178:181], v[56:59]
	v_mfma_f32_16x16x32_bf16 v[60:63], v[0:3], v[186:189], v[52:55]
	v_mfma_f32_16x16x32_bf16 v[206:209], v[16:19], v[186:189], v[48:51]
	v_mfma_f32_16x16x32_bf16 v[44:47], v[0:3], v[194:197], v[44:47]
	v_mfma_f32_16x16x32_bf16 v[40:43], v[16:19], v[194:197], v[40:43]
	v_mfma_f32_16x16x32_bf16 v[0:3], v[0:3], v[198:201], v[36:39]
	v_mfma_f32_16x16x32_bf16 v[210:213], v[16:19], v[198:201], v[32:35]
	v_mfma_f32_16x16x32_bf16 v[52:55], v[4:7], v[182:185], v[20:23]
	v_mfma_f32_16x16x32_bf16 v[48:51], v[174:177], v[182:185], v[56:59]
	v_mfma_f32_16x16x32_bf16 v[36:39], v[4:7], v[190:193], v[60:63]
	v_mfma_f32_16x16x32_bf16 v[32:35], v[174:177], v[190:193], v[206:209]
	v_mfma_f32_16x16x32_bf16 v[20:23], v[4:7], v[150:153], v[44:47]
	v_mfma_f32_16x16x32_bf16 v[16:19], v[174:177], v[150:153], v[40:43]
	v_mfma_f32_16x16x32_bf16 v[4:7], v[4:7], v[202:205], v[0:3]
	v_mfma_f32_16x16x32_bf16 v[0:3], v[174:177], v[202:205], v[210:213]
	v_mfma_f32_16x16x32_bf16 v[28:31], v[224:227], v[178:181], v[28:31]
	v_mfma_f32_16x16x32_bf16 v[24:27], v[232:235], v[178:181], v[24:27]
	v_mfma_f32_16x16x32_bf16 v[40:43], v[224:227], v[186:189], v[134:137]
	v_mfma_f32_16x16x32_bf16 v[134:137], v[232:235], v[186:189], v[138:141]
	v_mfma_f32_16x16x32_bf16 v[12:15], v[224:227], v[194:197], v[12:15]
	v_mfma_f32_16x16x32_bf16 v[8:11], v[232:235], v[194:197], v[8:11]
	v_mfma_f32_16x16x32_bf16 v[138:141], v[224:227], v[198:201], v[170:173]
	v_mfma_f32_16x16x32_bf16 v[158:161], v[232:235], v[198:201], v[158:161]
	v_mfma_f32_16x16x32_bf16 v[60:63], v[228:231], v[182:185], v[28:31]
	v_mfma_f32_16x16x32_bf16 v[56:59], v[154:157], v[182:185], v[24:27]
	v_mfma_f32_16x16x32_bf16 v[44:47], v[228:231], v[190:193], v[40:43]
	v_mfma_f32_16x16x32_bf16 v[40:43], v[154:157], v[190:193], v[134:137]
	v_mfma_f32_16x16x32_bf16 v[28:31], v[228:231], v[150:153], v[12:15]
	v_mfma_f32_16x16x32_bf16 v[24:27], v[154:157], v[150:153], v[8:11]
	v_mfma_f32_16x16x32_bf16 v[12:15], v[228:231], v[202:205], v[138:141]
	v_mfma_f32_16x16x32_bf16 v[8:11], v[154:157], v[202:205], v[158:161]
	v_cmp_gt_u32_e32 vcc, s56, v130
	s_barrier
	s_and_saveexec_b64 s[42:43], vcc
	s_cbranch_execz .LBB0_56
	s_barrier

; #define STAGE(P, BASE, LD, br, kt) do { const char* _g = (const char*)((BASE) + (size_t)(br) * (LD) + (size_t)(kt) * 64); \
;     for (int _i = 0; _i < 2; ++_i) { int _b = tidx * 16 + _i * 8192; int _r, _c; stage_rc(_b, _r, _c); \
;       __builtin_amdgcn_global_load_lds((const unsigned*)(_g + (unsigned)((_r * (LD) + _c) * 2)), (unsigned*)((char*)(P) + _b), 16, 0, 0); } } while (0)
; #define LDA(dst, b, h) for (int m = 0; m < 4; ++m) for (int k = 0; k < 2; ++k) \
;     dst[m][k] = *reinterpret_cast<const bf16x8*>((char*)SA(b, h) + lds_byte(wr * 64 + m * 16 + fr, k * 32 + fq * 8))
; #define LDB(dst, b, h) for (int n = 0; n < 2; ++n) for (int k = 0; k < 2; ++k) \
;     dst[n][k] = *reinterpret_cast<const bf16x8*>((char*)SB(b, h) + lds_byte(wc * 32 + n * 16 + fr, k * 32 + fq * 8))
; #define MMA(ai, bj, At_, Bt_) do { __builtin_amdgcn_s_setprio(1); \
;     for (int k = 0; k < 2; ++k) for (int m = 0; m < 4; ++m) for (int n = 0; n < 2; ++n) \
;       acc[ai][bj][m][n] = __builtin_amdgcn_mfma_f32_16x16x32_bf16(At_[m][k], Bt_[n][k], acc[ai][bj][m][n], 0, 0, 0); \
;     __builtin_amdgcn_s_setprio(0); } while (0)
; #define WAIT_V(n) asm volatile("s_waitcnt vmcnt(" #n ")" ::: "memory")
; #define WAIT_L(n) asm volatile("s_waitcnt lgkmcnt(" #n ")" ::: "memory")
; #define BAR __builtin_amdgcn_s_barrier()
; #define SCHED __builtin_amdgcn_sched_barrier(0)
; template <int EPI, int lda, int ldb, int N, int K>
; __device__ __forceinline__ void gemm_phase(const u16* __restrict__ A, const u16* __restrict__ Bt, const GemmEpi ep, int wv) {
;     ...
;     for (int t = 0; t < nt - 2; t += 2) {
;       LDB(B0, 0, 0); SCHED; LDA(At, 0, 0); STAGE(SA(1, 1), Ab, lda, brow + HALF, t + 1);
;       WAIT_L(8); BAR; WAIT_L(0); MMA(0, 0, At, B0); BAR; SCHED;
;       LDB(B1, 0, 1); STAGE(SB(0, 0), Bt, ldb, bcol, t + 2);
;       BAR; WAIT_L(0); MMA(0, 1, At, B1); BAR;
;       LDA(At, 0, 1); STAGE(SA(0, 0), Ab, lda, brow, t + 2);
;       BAR; WAIT_L(0); MMA(1, 0, At, B0); BAR; SCHED;
;       STAGE(SB(0, 1), Bt, ldb, bcol + HALF, t + 2);
;       WAIT_V(6); BAR; MMA(1, 1, At, B1); BAR;
.LBB0_224:
	ds_read_b128 v[168:171], v164
	ds_read_b128 v[174:177], v164 offset:1024
	ds_read_b128 v[178:181], v164 offset:2048
	ds_read_b128 v[182:185], v164 offset:3072
	v_add_u32_e32 v172, 0xc000, v147
	v_lshl_add_u64 v[238:239], v[136:137], 0, s[44:45]
	v_readfirstlane_b32 s66, v172
	v_add_u32_e32 v173, 0xe000, v147
	v_lshl_add_u64 v[166:167], v[238:239], 0, s[18:19]
	s_mov_b32 m0, s66
	v_lshl_add_u64 v[240:241], v[134:135], 0, s[44:45]
	ds_read_b128 v[186:189], v155
	ds_read_b128 v[190:193], v155 offset:1024
	ds_read_b128 v[194:197], v154
	ds_read_b128 v[198:201], v154 offset:1024
	ds_read_b128 v[202:205], v153
	ds_read_b128 v[206:209], v153 offset:1024
	ds_read_b128 v[210:213], v152
	ds_read_b128 v[214:217], v152 offset:1024
	global_load_lds_dwordx4 v[166:167], off
	s_bitset1_b32 m0, 13
	v_lshl_add_u64 v[166:167], v[240:241], 0, s[18:19]
	global_load_lds_dwordx4 v[166:167], off
	s_waitcnt lgkmcnt(8)
	s_barrier
	s_waitcnt lgkmcnt(0)
	s_waitcnt lgkmcnt(0)
	v_mfma_f32_16x16x32_bf16 v[124:127], v[168:171], v[186:189], v[124:127]
	v_mfma_f32_16x16x32_bf16 v[120:123], v[178:181], v[186:189], v[120:123]
	v_mfma_f32_16x16x32_bf16 v[116:119], v[168:171], v[194:197], v[116:119]
	v_mfma_f32_16x16x32_bf16 v[112:115], v[178:181], v[194:197], v[112:115]
	v_mfma_f32_16x16x32_bf16 v[108:111], v[168:171], v[202:205], v[108:111]
	v_mfma_f32_16x16x32_bf16 v[104:107], v[178:181], v[202:205], v[104:107]
	v_mfma_f32_16x16x32_bf16 v[100:103], v[168:171], v[210:213], v[100:103]
	v_mfma_f32_16x16x32_bf16 v[96:99], v[178:181], v[210:213], v[96:99]
	v_mfma_f32_16x16x32_bf16 v[124:127], v[174:177], v[190:193], v[124:127]
	v_mfma_f32_16x16x32_bf16 v[120:123], v[182:185], v[190:193], v[120:123]
	v_mfma_f32_16x16x32_bf16 v[116:119], v[174:177], v[198:201], v[116:119]
	v_mfma_f32_16x16x32_bf16 v[112:115], v[182:185], v[198:201], v[112:115]
	v_mfma_f32_16x16x32_bf16 v[108:111], v[174:177], v[206:209], v[108:111]
	v_mfma_f32_16x16x32_bf16 v[104:107], v[182:185], v[206:209], v[104:107]
	v_mfma_f32_16x16x32_bf16 v[100:103], v[174:177], v[214:217], v[100:103]
	v_mfma_f32_16x16x32_bf16 v[96:99], v[182:185], v[214:217], v[96:99]
	s_barrier
	v_add_u32_e32 v165, s55, v156
	v_lshl_add_u64 v[242:243], v[144:145], 0, s[44:45]
	v_readfirstlane_b32 s66, v165
	v_lshl_add_u64 v[166:167], v[242:243], 0, s[20:21]
	s_mov_b32 m0, s66
	ds_read_b128 v[218:221], v163
	ds_read_b128 v[222:225], v163 offset:1024
	ds_read_b128 v[226:229], v163 offset:2048
	ds_read_b128 v[230:233], v163 offset:3072
	global_load_lds_dwordx4 v[166:167], off
	s_bitset1_b32 m0, 13
	v_add_u32_e32 v166, 0x2000, v165
	v_lshl_add_u64 v[244:245], v[142:143], 0, s[44:45]
	v_lshl_add_u64 v[234:235], v[244:245], 0, s[20:21]
	global_load_lds_dwordx4 v[234:235], off
	s_barrier
	s_waitcnt lgkmcnt(0)
	s_waitcnt lgkmcnt(0)
	v_mfma_f32_16x16x32_bf16 v[92:95], v[218:221], v[186:189], v[92:95]
	v_mfma_f32_16x16x32_bf16 v[88:91], v[226:229], v[186:189], v[88:91]
	v_mfma_f32_16x16x32_bf16 v[84:87], v[218:221], v[194:197], v[84:87]
	v_mfma_f32_16x16x32_bf16 v[80:83], v[226:229], v[194:197], v[80:83]
	v_mfma_f32_16x16x32_bf16 v[76:79], v[218:221], v[202:205], v[76:79]
	v_mfma_f32_16x16x32_bf16 v[72:75], v[226:229], v[202:205], v[72:75]
	v_mfma_f32_16x16x32_bf16 v[68:71], v[218:221], v[210:213], v[68:71]
	v_mfma_f32_16x16x32_bf16 v[64:67], v[226:229], v[210:213], v[64:67]
	v_mfma_f32_16x16x32_bf16 v[92:95], v[222:225], v[190:193], v[92:95]
	v_mfma_f32_16x16x32_bf16 v[88:91], v[230:233], v[190:193], v[88:91]
	v_mfma_f32_16x16x32_bf16 v[84:87], v[222:225], v[198:201], v[84:87]
	v_mfma_f32_16x16x32_bf16 v[80:83], v[230:233], v[198:201], v[80:83]
	v_mfma_f32_16x16x32_bf16 v[76:79], v[222:225], v[206:209], v[76:79]
	v_mfma_f32_16x16x32_bf16 v[72:75], v[230:233], v[206:209], v[72:75]
	v_mfma_f32_16x16x32_bf16 v[68:71], v[222:225], v[214:217], v[68:71]
	v_mfma_f32_16x16x32_bf16 v[64:67], v[230:233], v[214:217], v[64:67]
	v_readfirstlane_b32 s66, v147
	v_add_u32_e32 v167, 0x2000, v147
	v_lshl_add_u64 v[234:235], v[238:239], 0, s[22:23]
	s_mov_b32 m0, s66
	s_barrier
	ds_read_b128 v[186:189], v155 offset:16384
	ds_read_b128 v[190:193], v155 offset:17408
	ds_read_b128 v[194:197], v154 offset:16384
	ds_read_b128 v[198:201], v154 offset:17408
	ds_read_b128 v[202:205], v153 offset:16384
	ds_read_b128 v[206:209], v153 offset:17408
	ds_read_b128 v[210:213], v152 offset:16384
	ds_read_b128 v[214:217], v152 offset:17408
	global_load_lds_dwordx4 v[234:235], off
	s_bitset1_b32 m0, 13
	v_lshl_add_u64 v[234:235], v[240:241], 0, s[22:23]
	global_load_lds_dwordx4 v[234:235], off
	s_barrier
	s_waitcnt lgkmcnt(0)
	s_waitcnt lgkmcnt(0)
	v_mfma_f32_16x16x32_bf16 v[60:63], v[168:171], v[186:189], v[60:63]
	v_mfma_f32_16x16x32_bf16 v[56:59], v[178:181], v[186:189], v[56:59]
	v_mfma_f32_16x16x32_bf16 v[52:55], v[168:171], v[194:197], v[52:55]
	v_mfma_f32_16x16x32_bf16 v[48:51], v[178:181], v[194:197], v[48:51]
	v_mfma_f32_16x16x32_bf16 v[44:47], v[168:171], v[202:205], v[44:47]
	v_mfma_f32_16x16x32_bf16 v[40:43], v[178:181], v[202:205], v[40:43]
	v_mfma_f32_16x16x32_bf16 v[36:39], v[168:171], v[210:213], v[36:39]
	v_mfma_f32_16x16x32_bf16 v[32:35], v[178:181], v[210:213], v[32:35]
	v_mfma_f32_16x16x32_bf16 v[60:63], v[174:177], v[190:193], v[60:63]
	v_mfma_f32_16x16x32_bf16 v[56:59], v[182:185], v[190:193], v[56:59]
	v_mfma_f32_16x16x32_bf16 v[52:55], v[174:177], v[198:201], v[52:55]
	v_mfma_f32_16x16x32_bf16 v[48:51], v[182:185], v[198:201], v[48:51]
	v_mfma_f32_16x16x32_bf16 v[44:47], v[174:177], v[206:209], v[44:47]
	v_mfma_f32_16x16x32_bf16 v[40:43], v[182:185], v[206:209], v[40:43]
	v_mfma_f32_16x16x32_bf16 v[36:39], v[174:177], v[214:217], v[36:39]
	v_mfma_f32_16x16x32_bf16 v[32:35], v[182:185], v[214:217], v[32:35]
	s_barrier
; #define STAGE(P, BASE, LD, br, kt) do { const char* _g = (const char*)((BASE) + (size_t)(br) * (LD) + (size_t)(kt) * 64); \
;     for (int _i = 0; _i < 2; ++_i) { int _b = tidx * 16 + _i * 8192; int _r, _c; stage_rc(_b, _r, _c); \
;       __builtin_amdgcn_global_load_lds((const unsigned*)(_g + (unsigned)((_r * (LD) + _c) * 2)), (unsigned*)((char*)(P) + _b), 16, 0, 0); } } while (0)
; #define LDA(dst, b, h) for (int m = 0; m < 4; ++m) for (int k = 0; k < 2; ++k) \
;     dst[m][k] = *reinterpret_cast<const bf16x8*>((char*)SA(b, h) + lds_byte(wr * 64 + m * 16 + fr, k * 32 + fq * 8))
; #define LDB(dst, b, h) for (int n = 0; n < 2; ++n) for (int k = 0; k < 2; ++k) \
;     dst[n][k] = *reinterpret_cast<const bf16x8*>((char*)SB(b, h) + lds_byte(wc * 32 + n * 16 + fr, k * 32 + fq * 8))
; #define MMA(ai, bj, At_, Bt_) do { __builtin_amdgcn_s_setprio(1); \
;     for (int k = 0; k < 2; ++k) for (int m = 0; m < 4; ++m) for (int n = 0; n < 2; ++n) \
;       acc[ai][bj][m][n] = __builtin_amdgcn_mfma_f32_16x16x32_bf16(At_[m][k], Bt_[n][k], acc[ai][bj][m][n], 0, 0, 0); \
;     __builtin_amdgcn_s_setprio(0); } while (0)
; #define WAIT_V(n) asm volatile("s_waitcnt vmcnt(" #n ")" ::: "memory")
; #define WAIT_L(n) asm volatile("s_waitcnt lgkmcnt(" #n ")" ::: "memory")
; #define BAR __builtin_amdgcn_s_barrier()
; #define SCHED __builtin_amdgcn_sched_barrier(0)
; template <int EPI, int lda, int ldb, int N, int K>
; __device__ __forceinline__ void gemm_phase(const u16* __restrict__ A, const u16* __restrict__ Bt, const GemmEpi ep, int wv) {
;     ...
;       WAIT_V(6); BAR; MMA(1, 1, At, B1); BAR;
;       LDB(B0, 1, 0); SCHED; LDA(At, 1, 0); STAGE(SA(0, 1), Ab, lda, brow + HALF, t + 2);
;       WAIT_L(8); BAR; WAIT_L(0); MMA(0, 0, At, B0); BAR; SCHED;
;       LDB(B1, 1, 1); STAGE(SB(1, 0), Bt, ldb, bcol, t + 3);
;       BAR; WAIT_L(0); MMA(0, 1, At, B1); BAR;
;       LDA(At, 1, 1); STAGE(SA(1, 0), Ab, lda, brow, t + 3);
;       BAR; WAIT_L(0); MMA(1, 0, At, B0); BAR; SCHED;
;       STAGE(SB(1, 1), Bt, ldb, bcol + HALF, t + 3);
;       WAIT_V(6); BAR; MMA(1, 1, At, B1); BAR;
	v_add_u32_e32 v168, s56, v156
	v_lshl_add_u64 v[246:247], v[140:141], 0, s[44:45]
	v_readfirstlane_b32 s66, v168
	v_add_u32_e32 v169, 0x2000, v168
	v_lshl_add_u64 v[170:171], v[246:247], 0, s[24:25]
	s_mov_b32 m0, s66
	v_lshl_add_u64 v[248:249], v[138:139], 0, s[44:45]
	global_load_lds_dwordx4 v[170:171], off
	s_bitset1_b32 m0, 13
	v_lshl_add_u64 v[170:171], v[248:249], 0, s[24:25]
	global_load_lds_dwordx4 v[170:171], off
	s_waitcnt vmcnt(6)
	s_barrier
	v_mfma_f32_16x16x32_bf16 v[28:31], v[218:221], v[186:189], v[28:31]
	v_mfma_f32_16x16x32_bf16 v[24:27], v[226:229], v[186:189], v[24:27]
	v_mfma_f32_16x16x32_bf16 v[20:23], v[218:221], v[194:197], v[20:23]
	v_mfma_f32_16x16x32_bf16 v[16:19], v[226:229], v[194:197], v[16:19]
	v_mfma_f32_16x16x32_bf16 v[12:15], v[218:221], v[202:205], v[12:15]
	v_mfma_f32_16x16x32_bf16 v[8:11], v[226:229], v[202:205], v[8:11]
	v_mfma_f32_16x16x32_bf16 v[4:7], v[218:221], v[210:213], v[4:7]
	v_mfma_f32_16x16x32_bf16 v[0:3], v[226:229], v[210:213], v[0:3]
	v_mfma_f32_16x16x32_bf16 v[28:31], v[222:225], v[190:193], v[28:31]
	v_mfma_f32_16x16x32_bf16 v[24:27], v[230:233], v[190:193], v[24:27]
	v_mfma_f32_16x16x32_bf16 v[20:23], v[222:225], v[198:201], v[20:23]
	v_mfma_f32_16x16x32_bf16 v[16:19], v[230:233], v[198:201], v[16:19]
	v_mfma_f32_16x16x32_bf16 v[12:15], v[222:225], v[206:209], v[12:15]
	v_mfma_f32_16x16x32_bf16 v[8:11], v[230:233], v[206:209], v[8:11]
	v_mfma_f32_16x16x32_bf16 v[4:7], v[222:225], v[214:217], v[4:7]
	v_mfma_f32_16x16x32_bf16 v[0:3], v[230:233], v[214:217], v[0:3]
	s_barrier
	ds_read_b128 v[174:177], v159
	ds_read_b128 v[178:181], v159 offset:1024
	ds_read_b128 v[182:185], v159 offset:2048
	ds_read_b128 v[186:189], v159 offset:3072
	v_add_u32_e32 v170, 0x4000, v147
	v_add_u32_e32 v171, 0x6000, v147
	v_readfirstlane_b32 s66, v170
	v_lshl_add_u64 v[222:223], v[238:239], 0, s[26:27]
	s_mov_b32 m0, s66
	ds_read_b128 v[190:193], v155 offset:32768
	ds_read_b128 v[194:197], v155 offset:33792
	ds_read_b128 v[198:201], v154 offset:32768
	ds_read_b128 v[202:205], v154 offset:33792
	ds_read_b128 v[206:209], v153 offset:32768
	ds_read_b128 v[210:213], v153 offset:33792
	ds_read_b128 v[214:217], v152 offset:32768
	ds_read_b128 v[218:221], v152 offset:33792
	global_load_lds_dwordx4 v[222:223], off
	s_bitset1_b32 m0, 13
	v_lshl_add_u64 v[222:223], v[240:241], 0, s[26:27]
	global_load_lds_dwordx4 v[222:223], off
	s_waitcnt lgkmcnt(8)
	s_barrier
	s_waitcnt lgkmcnt(0)
	s_waitcnt lgkmcnt(0)
	v_mfma_f32_16x16x32_bf16 v[124:127], v[174:177], v[190:193], v[124:127]
	v_mfma_f32_16x16x32_bf16 v[120:123], v[182:185], v[190:193], v[120:123]
	v_mfma_f32_16x16x32_bf16 v[116:119], v[174:177], v[198:201], v[116:119]
	v_mfma_f32_16x16x32_bf16 v[112:115], v[182:185], v[198:201], v[112:115]
	v_mfma_f32_16x16x32_bf16 v[108:111], v[174:177], v[206:209], v[108:111]
	v_mfma_f32_16x16x32_bf16 v[104:107], v[182:185], v[206:209], v[104:107]
	v_mfma_f32_16x16x32_bf16 v[100:103], v[174:177], v[214:217], v[100:103]
	v_mfma_f32_16x16x32_bf16 v[96:99], v[182:185], v[214:217], v[96:99]
	v_mfma_f32_16x16x32_bf16 v[124:127], v[178:181], v[194:197], v[124:127]
	v_mfma_f32_16x16x32_bf16 v[120:123], v[186:189], v[194:197], v[120:123]
	v_mfma_f32_16x16x32_bf16 v[116:119], v[178:181], v[202:205], v[116:119]
	v_mfma_f32_16x16x32_bf16 v[112:115], v[186:189], v[202:205], v[112:115]
	v_mfma_f32_16x16x32_bf16 v[108:111], v[178:181], v[210:213], v[108:111]
	v_mfma_f32_16x16x32_bf16 v[104:107], v[186:189], v[210:213], v[104:107]
	v_mfma_f32_16x16x32_bf16 v[100:103], v[178:181], v[218:221], v[100:103]
	v_mfma_f32_16x16x32_bf16 v[96:99], v[186:189], v[218:221], v[96:99]
	s_barrier
	v_readfirstlane_b32 s66, v158
	v_lshl_add_u64 v[242:243], v[242:243], 0, s[36:37]
	s_mov_b32 m0, s66
	ds_read_b128 v[222:225], v157
	ds_read_b128 v[226:229], v157 offset:1024
	ds_read_b128 v[230:233], v157 offset:2048
	ds_read_b128 v[234:237], v157 offset:3072
	global_load_lds_dwordx4 v[242:243], off
	s_bitset1_b32 m0, 13
	v_lshl_add_u64 v[242:243], v[244:245], 0, s[36:37]
	v_add_u32_e32 v244, 0x2000, v158
	global_load_lds_dwordx4 v[242:243], off
	s_barrier
	s_waitcnt lgkmcnt(0)
	s_waitcnt lgkmcnt(0)
	v_mfma_f32_16x16x32_bf16 v[92:95], v[222:225], v[190:193], v[92:95]
	v_mfma_f32_16x16x32_bf16 v[88:91], v[230:233], v[190:193], v[88:91]
	v_mfma_f32_16x16x32_bf16 v[84:87], v[222:225], v[198:201], v[84:87]
	v_mfma_f32_16x16x32_bf16 v[80:83], v[230:233], v[198:201], v[80:83]
	v_mfma_f32_16x16x32_bf16 v[76:79], v[222:225], v[206:209], v[76:79]
	v_mfma_f32_16x16x32_bf16 v[72:75], v[230:233], v[206:209], v[72:75]
	v_mfma_f32_16x16x32_bf16 v[68:71], v[222:225], v[214:217], v[68:71]
	v_mfma_f32_16x16x32_bf16 v[64:67], v[230:233], v[214:217], v[64:67]
	v_mfma_f32_16x16x32_bf16 v[92:95], v[226:229], v[194:197], v[92:95]
	v_mfma_f32_16x16x32_bf16 v[88:91], v[234:237], v[194:197], v[88:91]
	v_mfma_f32_16x16x32_bf16 v[84:87], v[226:229], v[202:205], v[84:87]
	v_mfma_f32_16x16x32_bf16 v[80:83], v[234:237], v[202:205], v[80:83]
	v_mfma_f32_16x16x32_bf16 v[76:79], v[226:229], v[210:213], v[76:79]
	v_mfma_f32_16x16x32_bf16 v[72:75], v[234:237], v[210:213], v[72:75]
	v_mfma_f32_16x16x32_bf16 v[68:71], v[226:229], v[218:221], v[68:71]
	v_mfma_f32_16x16x32_bf16 v[64:67], v[234:237], v[218:221], v[64:67]
	v_readfirstlane_b32 s66, v160
	v_lshl_add_u64 v[238:239], v[238:239], 0, s[38:39]
	s_mov_b32 m0, s66
	s_barrier
	ds_read_b128 v[190:193], v155 offset:49152
	ds_read_b128 v[194:197], v155 offset:50176
	ds_read_b128 v[198:201], v154 offset:49152
	ds_read_b128 v[202:205], v154 offset:50176
	ds_read_b128 v[206:209], v153 offset:49152
	ds_read_b128 v[210:213], v153 offset:50176
	ds_read_b128 v[214:217], v152 offset:49152
	ds_read_b128 v[218:221], v152 offset:50176
	global_load_lds_dwordx4 v[238:239], off
	s_bitset1_b32 m0, 13
	v_lshl_add_u64 v[238:239], v[240:241], 0, s[38:39]
	global_load_lds_dwordx4 v[238:239], off
	s_barrier
; #define STAGE(P, BASE, LD, br, kt) do { const char* _g = (const char*)((BASE) + (size_t)(br) * (LD) + (size_t)(kt) * 64); \
;     for (int _i = 0; _i < 2; ++_i) { int _b = tidx * 16 + _i * 8192; int _r, _c; stage_rc(_b, _r, _c); \
;       __builtin_amdgcn_global_load_lds((const unsigned*)(_g + (unsigned)((_r * (LD) + _c) * 2)), (unsigned*)((char*)(P) + _b), 16, 0, 0); } } while (0)
; #define LDA(dst, b, h) for (int m = 0; m < 4; ++m) for (int k = 0; k < 2; ++k) \
;     dst[m][k] = *reinterpret_cast<const bf16x8*>((char*)SA(b, h) + lds_byte(wr * 64 + m * 16 + fr, k * 32 + fq * 8))
; #define LDB(dst, b, h) for (int n = 0; n < 2; ++n) for (int k = 0; k < 2; ++k) \
;     dst[n][k] = *reinterpret_cast<const bf16x8*>((char*)SB(b, h) + lds_byte(wc * 32 + n * 16 + fr, k * 32 + fq * 8))
; #define MMA(ai, bj, At_, Bt_) do { __builtin_amdgcn_s_setprio(1); \
;     for (int k = 0; k < 2; ++k) for (int m = 0; m < 4; ++m) for (int n = 0; n < 2; ++n) \
;       acc[ai][bj][m][n] = __builtin_amdgcn_mfma_f32_16x16x32_bf16(At_[m][k], Bt_[n][k], acc[ai][bj][m][n], 0, 0, 0); \
;     __builtin_amdgcn_s_setprio(0); } while (0)
; #define WAIT_V(n) asm volatile("s_waitcnt vmcnt(" #n ")" ::: "memory")
; #define WAIT_L(n) asm volatile("s_waitcnt lgkmcnt(" #n ")" ::: "memory")
; #define BAR __builtin_amdgcn_s_barrier()
; #define SCHED __builtin_amdgcn_sched_barrier(0)
; template <int EPI, int lda, int ldb, int N, int K>
; __device__ __forceinline__ void gemm_phase(const u16* __restrict__ A, const u16* __restrict__ Bt, const GemmEpi ep, int wv) {
;     ...
;       BAR; WAIT_L(0); MMA(1, 0, At, B0); BAR; SCHED;
;       STAGE(SB(1, 1), Bt, ldb, bcol + HALF, t + 3);
;       WAIT_V(6); BAR; MMA(1, 1, At, B1); BAR;
;     }
;     { LDB(B0, 0, 0); LDA(At, 0, 0); STAGE(SA(1, 1), Ab, lda, brow + HALF, nt - 1);
;       BAR; WAIT_L(0); MMA(0, 0, At, B0); BAR;
;       LDB(B1, 0, 1); BAR; WAIT_L(0); MMA(0, 1, At, B1); BAR;
;       LDA(At, 0, 1); WAIT_V(4); BAR; WAIT_L(0); MMA(1, 0, At, B0); MMA(1, 1, At, B1); BAR; }
;     { LDB(B0, 1, 0); LDA(At, 1, 0); WAIT_V(2); BAR; WAIT_L(0); MMA(0, 0, At, B0); BAR;
	s_waitcnt lgkmcnt(0)
	s_waitcnt lgkmcnt(0)
	v_mfma_f32_16x16x32_bf16 v[60:63], v[174:177], v[190:193], v[60:63]
	v_mfma_f32_16x16x32_bf16 v[56:59], v[182:185], v[190:193], v[56:59]
	v_mfma_f32_16x16x32_bf16 v[52:55], v[174:177], v[198:201], v[52:55]
	v_mfma_f32_16x16x32_bf16 v[48:51], v[182:185], v[198:201], v[48:51]
	v_mfma_f32_16x16x32_bf16 v[44:47], v[174:177], v[206:209], v[44:47]
	v_mfma_f32_16x16x32_bf16 v[40:43], v[182:185], v[206:209], v[40:43]
	v_mfma_f32_16x16x32_bf16 v[36:39], v[174:177], v[214:217], v[36:39]
	v_mfma_f32_16x16x32_bf16 v[32:35], v[182:185], v[214:217], v[32:35]
	v_mfma_f32_16x16x32_bf16 v[60:63], v[178:181], v[194:197], v[60:63]
	v_mfma_f32_16x16x32_bf16 v[56:59], v[186:189], v[194:197], v[56:59]
	v_mfma_f32_16x16x32_bf16 v[52:55], v[178:181], v[202:205], v[52:55]
	v_mfma_f32_16x16x32_bf16 v[48:51], v[186:189], v[202:205], v[48:51]
	v_mfma_f32_16x16x32_bf16 v[44:47], v[178:181], v[210:213], v[44:47]
	v_mfma_f32_16x16x32_bf16 v[40:43], v[186:189], v[210:213], v[40:43]
	v_mfma_f32_16x16x32_bf16 v[36:39], v[178:181], v[218:221], v[36:39]
	v_mfma_f32_16x16x32_bf16 v[32:35], v[186:189], v[218:221], v[32:35]
	s_barrier
	v_readfirstlane_b32 s66, v162
	v_add_u32_e32 v176, 0x2000, v162
	v_lshl_add_u64 v[174:175], v[246:247], 0, s[42:43]
	s_mov_b32 m0, s66
	global_load_lds_dwordx4 v[174:175], off
	s_bitset1_b32 m0, 13
	v_lshl_add_u64 v[174:175], v[248:249], 0, s[42:43]
	global_load_lds_dwordx4 v[174:175], off
	s_waitcnt vmcnt(6)
	s_barrier
	v_mfma_f32_16x16x32_bf16 v[28:31], v[222:225], v[190:193], v[28:31]
	v_mfma_f32_16x16x32_bf16 v[24:27], v[230:233], v[190:193], v[24:27]
	v_mfma_f32_16x16x32_bf16 v[20:23], v[222:225], v[198:201], v[20:23]
	v_mfma_f32_16x16x32_bf16 v[16:19], v[230:233], v[198:201], v[16:19]
	v_mfma_f32_16x16x32_bf16 v[12:15], v[222:225], v[206:209], v[12:15]
	v_mfma_f32_16x16x32_bf16 v[8:11], v[230:233], v[206:209], v[8:11]
	v_mfma_f32_16x16x32_bf16 v[4:7], v[222:225], v[214:217], v[4:7]
	v_mfma_f32_16x16x32_bf16 v[0:3], v[230:233], v[214:217], v[0:3]
	v_mfma_f32_16x16x32_bf16 v[28:31], v[226:229], v[194:197], v[28:31]
	v_mfma_f32_16x16x32_bf16 v[24:27], v[234:237], v[194:197], v[24:27]
	v_mfma_f32_16x16x32_bf16 v[20:23], v[226:229], v[202:205], v[20:23]
	v_mfma_f32_16x16x32_bf16 v[16:19], v[234:237], v[202:205], v[16:19]
	v_mfma_f32_16x16x32_bf16 v[12:15], v[226:229], v[210:213], v[12:15]
	v_mfma_f32_16x16x32_bf16 v[8:11], v[234:237], v[210:213], v[8:11]
	v_mfma_f32_16x16x32_bf16 v[4:7], v[226:229], v[218:221], v[4:7]
	v_mfma_f32_16x16x32_bf16 v[0:3], v[234:237], v[218:221], v[0:3]
	s_add_i32 s65, s65, 2
	s_add_u32 s44, s44, 0x100
	s_addc_u32 s45, s45, 0
	s_cmpk_gt_u32 s65, 0x51
	s_barrier
	s_cbranch_scc0 .LBB0_224
	s_add_i32 s44, s14, 0x80
	s_mul_hi_i32 s45, s44, 0x2b00
	s_mulk_i32 s44, 0x2b00
	s_add_u32 s44, s48, s44
	s_addc_u32 s45, s49, s45
	s_add_u32 s44, s44, 0x2a80
	s_addc_u32 s45, s45, 0
	v_readfirstlane_b32 s65, v172
	v_lshl_add_u64 v[160:161], s[44:45], 0, v[128:129]
	s_mov_b32 m0, s65
	ds_read_b128 v[134:137], v164
	ds_read_b128 v[138:141], v164 offset:1024
	ds_read_b128 v[142:145], v164 offset:2048
	ds_read_b128 v[174:177], v164 offset:3072
	ds_read_b128 v[178:181], v155
	ds_read_b128 v[182:185], v155 offset:1024
	ds_read_b128 v[186:189], v154
	ds_read_b128 v[190:193], v154 offset:1024
	ds_read_b128 v[194:197], v153
	ds_read_b128 v[198:201], v153 offset:1024
	ds_read_b128 v[202:205], v152
	ds_read_b128 v[206:209], v152 offset:1024
	global_load_lds_dwordx4 v[160:161], off
	v_lshl_add_u64 v[160:161], s[44:45], 0, v[132:133]
	v_readfirstlane_b32 s44, v173
	s_mov_b32 m0, s44
	s_nop 0
	global_load_lds_dwordx4 v[160:161], off
	s_barrier
	s_waitcnt lgkmcnt(0)
	s_waitcnt lgkmcnt(0)
	v_mfma_f32_16x16x32_bf16 v[124:127], v[134:137], v[178:181], v[124:127]
	v_mfma_f32_16x16x32_bf16 v[120:123], v[142:145], v[178:181], v[120:123]
	v_mfma_f32_16x16x32_bf16 v[116:119], v[134:137], v[186:189], v[116:119]
	v_mfma_f32_16x16x32_bf16 v[112:115], v[142:145], v[186:189], v[112:115]
	v_mfma_f32_16x16x32_bf16 v[108:111], v[134:137], v[194:197], v[108:111]
	v_mfma_f32_16x16x32_bf16 v[104:107], v[142:145], v[194:197], v[104:107]
	v_mfma_f32_16x16x32_bf16 v[100:103], v[134:137], v[202:205], v[100:103]
	v_mfma_f32_16x16x32_bf16 v[96:99], v[142:145], v[202:205], v[96:99]
	v_mfma_f32_16x16x32_bf16 v[124:127], v[138:141], v[182:185], v[124:127]
	v_mfma_f32_16x16x32_bf16 v[120:123], v[174:177], v[182:185], v[120:123]
	v_mfma_f32_16x16x32_bf16 v[116:119], v[138:141], v[190:193], v[116:119]
	v_mfma_f32_16x16x32_bf16 v[112:115], v[174:177], v[190:193], v[112:115]
	v_mfma_f32_16x16x32_bf16 v[108:111], v[138:141], v[198:201], v[108:111]
	v_mfma_f32_16x16x32_bf16 v[104:107], v[174:177], v[198:201], v[104:107]
	v_mfma_f32_16x16x32_bf16 v[100:103], v[138:141], v[206:209], v[100:103]
	v_mfma_f32_16x16x32_bf16 v[96:99], v[174:177], v[206:209], v[96:99]
	s_barrier
	ds_read_b128 v[210:213], v163
	ds_read_b128 v[214:217], v163 offset:1024
	ds_read_b128 v[218:221], v163 offset:2048
	ds_read_b128 v[160:163], v163 offset:3072
	s_barrier
	s_waitcnt lgkmcnt(0)
	s_waitcnt lgkmcnt(0)
	v_mfma_f32_16x16x32_bf16 v[92:95], v[210:213], v[178:181], v[92:95]
	v_mfma_f32_16x16x32_bf16 v[88:91], v[218:221], v[178:181], v[88:91]
	v_mfma_f32_16x16x32_bf16 v[76:79], v[210:213], v[194:197], v[76:79]
	v_mfma_f32_16x16x32_bf16 v[72:75], v[218:221], v[194:197], v[72:75]
	v_mfma_f32_16x16x32_bf16 v[84:87], v[210:213], v[186:189], v[84:87]
	v_mfma_f32_16x16x32_bf16 v[80:83], v[218:221], v[186:189], v[80:83]
	v_mfma_f32_16x16x32_bf16 v[68:71], v[210:213], v[202:205], v[68:71]
	v_mfma_f32_16x16x32_bf16 v[64:67], v[218:221], v[202:205], v[64:67]
	v_mfma_f32_16x16x32_bf16 v[92:95], v[214:217], v[182:185], v[92:95]
	v_mfma_f32_16x16x32_bf16 v[88:91], v[160:163], v[182:185], v[88:91]
	v_mfma_f32_16x16x32_bf16 v[76:79], v[214:217], v[198:201], v[76:79]
	v_mfma_f32_16x16x32_bf16 v[72:75], v[160:163], v[198:201], v[72:75]
	v_mfma_f32_16x16x32_bf16 v[178:181], v[214:217], v[190:193], v[84:87]
	v_mfma_f32_16x16x32_bf16 v[182:185], v[160:163], v[190:193], v[80:83]
	v_mfma_f32_16x16x32_bf16 v[186:189], v[214:217], v[206:209], v[68:71]
	v_mfma_f32_16x16x32_bf16 v[190:193], v[160:163], v[206:209], v[64:67]
	s_barrier
; #define LDA(dst, b, h) for (int m = 0; m < 4; ++m) for (int k = 0; k < 2; ++k) \
;     dst[m][k] = *reinterpret_cast<const bf16x8*>((char*)SA(b, h) + lds_byte(wr * 64 + m * 16 + fr, k * 32 + fq * 8))
; #define LDB(dst, b, h) for (int n = 0; n < 2; ++n) for (int k = 0; k < 2; ++k) \
;     dst[n][k] = *reinterpret_cast<const bf16x8*>((char*)SB(b, h) + lds_byte(wc * 32 + n * 16 + fr, k * 32 + fq * 8))
; #define MMA(ai, bj, At_, Bt_) do { __builtin_amdgcn_s_setprio(1); \
;     for (int k = 0; k < 2; ++k) for (int m = 0; m < 4; ++m) for (int n = 0; n < 2; ++n) \
;       acc[ai][bj][m][n] = __builtin_amdgcn_mfma_f32_16x16x32_bf16(At_[m][k], Bt_[n][k], acc[ai][bj][m][n], 0, 0, 0); \
;     __builtin_amdgcn_s_setprio(0); } while (0)
; #define WAIT_V(n) asm volatile("s_waitcnt vmcnt(" #n ")" ::: "memory")
; #define WAIT_L(n) asm volatile("s_waitcnt lgkmcnt(" #n ")" ::: "memory")
; #define BAR __builtin_amdgcn_s_barrier()
; template <int EPI, int lda, int ldb, int N, int K>
; __device__ __forceinline__ void gemm_phase(const u16* __restrict__ A, const u16* __restrict__ Bt, const GemmEpi ep, int wv) {
;     ...
;       LDB(B1, 0, 1); BAR; WAIT_L(0); MMA(0, 1, At, B1); BAR;
;       LDA(At, 0, 1); WAIT_V(4); BAR; WAIT_L(0); MMA(1, 0, At, B0); MMA(1, 1, At, B1); BAR; }
;     { LDB(B0, 1, 0); LDA(At, 1, 0); WAIT_V(2); BAR; WAIT_L(0); MMA(0, 0, At, B0); BAR;
;       LDB(B1, 1, 1); WAIT_V(0); BAR; WAIT_L(0); MMA(0, 1, At, B1); BAR;
	s_nop 0
	ds_read_b128 v[64:67], v155 offset:16384
	ds_read_b128 v[68:71], v155 offset:17408
	ds_read_b128 v[80:83], v154 offset:16384
	ds_read_b128 v[84:87], v154 offset:17408
	ds_read_b128 v[194:197], v153 offset:16384
	ds_read_b128 v[198:201], v153 offset:17408
	ds_read_b128 v[202:205], v152 offset:16384
	ds_read_b128 v[206:209], v152 offset:17408
	s_waitcnt vmcnt(4)
	s_barrier
	s_waitcnt lgkmcnt(0)
	s_waitcnt lgkmcnt(0)
	v_mfma_f32_16x16x32_bf16 v[60:63], v[134:137], v[64:67], v[60:63]
	v_mfma_f32_16x16x32_bf16 v[56:59], v[142:145], v[64:67], v[56:59]
	v_mfma_f32_16x16x32_bf16 v[52:55], v[134:137], v[80:83], v[52:55]
	v_mfma_f32_16x16x32_bf16 v[48:51], v[142:145], v[80:83], v[48:51]
	v_mfma_f32_16x16x32_bf16 v[44:47], v[134:137], v[194:197], v[44:47]
	v_mfma_f32_16x16x32_bf16 v[40:43], v[142:145], v[194:197], v[40:43]
	v_mfma_f32_16x16x32_bf16 v[36:39], v[134:137], v[202:205], v[36:39]
	v_mfma_f32_16x16x32_bf16 v[32:35], v[142:145], v[202:205], v[32:35]
	v_mfma_f32_16x16x32_bf16 v[60:63], v[138:141], v[68:71], v[60:63]
	v_mfma_f32_16x16x32_bf16 v[56:59], v[174:177], v[68:71], v[56:59]
	v_mfma_f32_16x16x32_bf16 v[52:55], v[138:141], v[84:87], v[52:55]
	v_mfma_f32_16x16x32_bf16 v[48:51], v[174:177], v[84:87], v[48:51]
	v_mfma_f32_16x16x32_bf16 v[44:47], v[138:141], v[198:201], v[44:47]
	v_mfma_f32_16x16x32_bf16 v[40:43], v[174:177], v[198:201], v[40:43]
	v_mfma_f32_16x16x32_bf16 v[36:39], v[138:141], v[206:209], v[36:39]
	v_mfma_f32_16x16x32_bf16 v[32:35], v[174:177], v[206:209], v[32:35]
	v_mfma_f32_16x16x32_bf16 v[28:31], v[210:213], v[64:67], v[28:31]
	v_mfma_f32_16x16x32_bf16 v[16:19], v[218:221], v[80:83], v[16:19]
	v_mfma_f32_16x16x32_bf16 v[12:15], v[210:213], v[194:197], v[12:15]
	v_mfma_f32_16x16x32_bf16 v[0:3], v[218:221], v[202:205], v[0:3]
	v_mfma_f32_16x16x32_bf16 v[24:27], v[218:221], v[64:67], v[24:27]
	v_mfma_f32_16x16x32_bf16 v[20:23], v[210:213], v[80:83], v[20:23]
	v_mfma_f32_16x16x32_bf16 v[8:11], v[218:221], v[194:197], v[8:11]
	v_mfma_f32_16x16x32_bf16 v[4:7], v[210:213], v[202:205], v[4:7]
	v_mfma_f32_16x16x32_bf16 v[28:31], v[214:217], v[68:71], v[28:31]
	v_mfma_f32_16x16x32_bf16 v[16:19], v[160:163], v[84:87], v[16:19]
	v_mfma_f32_16x16x32_bf16 v[12:15], v[214:217], v[198:201], v[12:15]
	v_mfma_f32_16x16x32_bf16 v[0:3], v[160:163], v[206:209], v[0:3]
	v_mfma_f32_16x16x32_bf16 v[134:137], v[160:163], v[68:71], v[24:27]
	v_mfma_f32_16x16x32_bf16 v[138:141], v[214:217], v[84:87], v[20:23]
	v_mfma_f32_16x16x32_bf16 v[142:145], v[160:163], v[198:201], v[8:11]
	v_mfma_f32_16x16x32_bf16 v[172:175], v[214:217], v[206:209], v[4:7]
	s_barrier
	s_nop 0
	ds_read_b128 v[4:7], v159
	ds_read_b128 v[8:11], v159 offset:1024
	ds_read_b128 v[20:23], v159 offset:2048
	ds_read_b128 v[158:161], v159 offset:3072
	ds_read_b128 v[24:27], v155 offset:32768
	ds_read_b128 v[194:197], v155 offset:33792
	ds_read_b128 v[198:201], v154 offset:32768
	ds_read_b128 v[202:205], v154 offset:33792
	ds_read_b128 v[206:209], v153 offset:32768
	ds_read_b128 v[210:213], v153 offset:33792
	ds_read_b128 v[214:217], v152 offset:32768
	ds_read_b128 v[218:221], v152 offset:33792
	s_waitcnt vmcnt(2)
	s_barrier
	s_waitcnt lgkmcnt(0)
	s_waitcnt lgkmcnt(0)
	v_mfma_f32_16x16x32_bf16 v[64:67], v[4:7], v[24:27], v[124:127]
	v_mfma_f32_16x16x32_bf16 v[68:71], v[20:23], v[24:27], v[120:123]
	v_mfma_f32_16x16x32_bf16 v[80:83], v[4:7], v[198:201], v[116:119]
	v_mfma_f32_16x16x32_bf16 v[84:87], v[20:23], v[198:201], v[112:115]
	v_mfma_f32_16x16x32_bf16 v[108:111], v[4:7], v[206:209], v[108:111]
	v_mfma_f32_16x16x32_bf16 v[104:107], v[20:23], v[206:209], v[104:107]
	v_mfma_f32_16x16x32_bf16 v[120:123], v[4:7], v[214:217], v[100:103]
	v_mfma_f32_16x16x32_bf16 v[124:127], v[20:23], v[214:217], v[96:99]
	v_mfma_f32_16x16x32_bf16 v[116:119], v[8:11], v[194:197], v[64:67]
	v_mfma_f32_16x16x32_bf16 v[112:115], v[158:161], v[194:197], v[68:71]
	v_mfma_f32_16x16x32_bf16 v[100:103], v[8:11], v[202:205], v[80:83]
	v_mfma_f32_16x16x32_bf16 v[96:99], v[158:161], v[202:205], v[84:87]
	v_mfma_f32_16x16x32_bf16 v[84:87], v[8:11], v[210:213], v[108:111]
	v_mfma_f32_16x16x32_bf16 v[80:83], v[158:161], v[210:213], v[104:107]
	v_mfma_f32_16x16x32_bf16 v[68:71], v[8:11], v[218:221], v[120:123]
	v_mfma_f32_16x16x32_bf16 v[64:67], v[158:161], v[218:221], v[124:127]
	s_barrier
; #define LDA(dst, b, h) for (int m = 0; m < 4; ++m) for (int k = 0; k < 2; ++k) \
;     dst[m][k] = *reinterpret_cast<const bf16x8*>((char*)SA(b, h) + lds_byte(wr * 64 + m * 16 + fr, k * 32 + fq * 8))
; #define LDB(dst, b, h) for (int n = 0; n < 2; ++n) for (int k = 0; k < 2; ++k) \
;     dst[n][k] = *reinterpret_cast<const bf16x8*>((char*)SB(b, h) + lds_byte(wc * 32 + n * 16 + fr, k * 32 + fq * 8))
; #define MMA(ai, bj, At_, Bt_) do { __builtin_amdgcn_s_setprio(1); \
;     for (int k = 0; k < 2; ++k) for (int m = 0; m < 4; ++m) for (int n = 0; n < 2; ++n) \
;       acc[ai][bj][m][n] = __builtin_amdgcn_mfma_f32_16x16x32_bf16(At_[m][k], Bt_[n][k], acc[ai][bj][m][n], 0, 0, 0); \
;     __builtin_amdgcn_s_setprio(0); } while (0)
; #define WAIT_V(n) asm volatile("s_waitcnt vmcnt(" #n ")" ::: "memory")
; #define WAIT_L(n) asm volatile("s_waitcnt lgkmcnt(" #n ")" ::: "memory")
; #define BAR __builtin_amdgcn_s_barrier()
; template <int EPI, int lda, int ldb, int N, int K>
; __device__ __forceinline__ void gemm_phase(const u16* __restrict__ A, const u16* __restrict__ Bt, const GemmEpi ep, int wv) {
;     ...
;     { LDB(B0, 1, 0); LDA(At, 1, 0); WAIT_V(2); BAR; WAIT_L(0); MMA(0, 0, At, B0); BAR;
;       LDB(B1, 1, 1); WAIT_V(0); BAR; WAIT_L(0); MMA(0, 1, At, B1); BAR;
;       LDA(At, 1, 1); BAR; WAIT_L(0); MMA(1, 0, At, B0); MMA(1, 1, At, B1); BAR; }
;     if (wr == 0) BAR;
	ds_read_b128 v[222:225], v157
	ds_read_b128 v[226:229], v157 offset:1024
	ds_read_b128 v[230:233], v157 offset:2048
	ds_read_b128 v[234:237], v157 offset:3072
	s_waitcnt vmcnt(0)
	s_barrier
	s_waitcnt lgkmcnt(0)
	s_waitcnt lgkmcnt(0)
	v_mfma_f32_16x16x32_bf16 v[92:95], v[222:225], v[24:27], v[92:95]
	v_mfma_f32_16x16x32_bf16 v[24:27], v[230:233], v[24:27], v[88:91]
	v_mfma_f32_16x16x32_bf16 v[88:91], v[222:225], v[198:201], v[178:181]
	v_mfma_f32_16x16x32_bf16 v[104:107], v[230:233], v[198:201], v[182:185]
	v_mfma_f32_16x16x32_bf16 v[76:79], v[222:225], v[206:209], v[76:79]
	v_mfma_f32_16x16x32_bf16 v[72:75], v[230:233], v[206:209], v[72:75]
	v_mfma_f32_16x16x32_bf16 v[176:179], v[222:225], v[214:217], v[186:189]
	v_mfma_f32_16x16x32_bf16 v[180:183], v[230:233], v[214:217], v[190:193]
	v_mfma_f32_16x16x32_bf16 v[124:127], v[226:229], v[194:197], v[92:95]
	v_mfma_f32_16x16x32_bf16 v[120:123], v[234:237], v[194:197], v[24:27]
	v_mfma_f32_16x16x32_bf16 v[108:111], v[226:229], v[202:205], v[88:91]
	v_mfma_f32_16x16x32_bf16 v[104:107], v[234:237], v[202:205], v[104:107]
	v_mfma_f32_16x16x32_bf16 v[92:95], v[226:229], v[210:213], v[76:79]
	v_mfma_f32_16x16x32_bf16 v[88:91], v[234:237], v[210:213], v[72:75]
	v_mfma_f32_16x16x32_bf16 v[76:79], v[226:229], v[218:221], v[176:179]
	v_mfma_f32_16x16x32_bf16 v[72:75], v[234:237], v[218:221], v[180:183]
	s_barrier
	ds_read_b128 v[176:179], v155 offset:49152
	ds_read_b128 v[180:183], v155 offset:50176
	ds_read_b128 v[184:187], v154 offset:49152
	ds_read_b128 v[154:157], v154 offset:50176
	ds_read_b128 v[188:191], v153 offset:49152
	ds_read_b128 v[192:195], v153 offset:50176
	ds_read_b128 v[196:199], v152 offset:49152
	ds_read_b128 v[200:203], v152 offset:50176
	s_barrier
	s_waitcnt lgkmcnt(0)
	s_waitcnt lgkmcnt(0)
	v_mfma_f32_16x16x32_bf16 v[24:27], v[4:7], v[176:179], v[60:63]
	v_mfma_f32_16x16x32_bf16 v[60:63], v[20:23], v[176:179], v[56:59]
	v_mfma_f32_16x16x32_bf16 v[204:207], v[4:7], v[184:187], v[52:55]
	v_mfma_f32_16x16x32_bf16 v[48:51], v[20:23], v[184:187], v[48:51]
	v_mfma_f32_16x16x32_bf16 v[44:47], v[4:7], v[188:191], v[44:47]
	v_mfma_f32_16x16x32_bf16 v[208:211], v[20:23], v[188:191], v[40:43]
	v_mfma_f32_16x16x32_bf16 v[4:7], v[4:7], v[196:199], v[36:39]
	v_mfma_f32_16x16x32_bf16 v[32:35], v[20:23], v[196:199], v[32:35]
	v_mfma_f32_16x16x32_bf16 v[56:59], v[8:11], v[180:183], v[24:27]
	v_mfma_f32_16x16x32_bf16 v[52:55], v[158:161], v[180:183], v[60:63]
	v_mfma_f32_16x16x32_bf16 v[40:43], v[8:11], v[154:157], v[204:207]
	v_mfma_f32_16x16x32_bf16 v[36:39], v[158:161], v[154:157], v[48:51]
	v_mfma_f32_16x16x32_bf16 v[24:27], v[8:11], v[192:195], v[44:47]
	v_mfma_f32_16x16x32_bf16 v[20:23], v[158:161], v[192:195], v[208:211]
	v_mfma_f32_16x16x32_bf16 v[8:11], v[8:11], v[200:203], v[4:7]
	v_mfma_f32_16x16x32_bf16 v[4:7], v[158:161], v[200:203], v[32:35]
	v_mfma_f32_16x16x32_bf16 v[28:31], v[222:225], v[176:179], v[28:31]
	v_mfma_f32_16x16x32_bf16 v[32:35], v[230:233], v[176:179], v[134:137]
	v_mfma_f32_16x16x32_bf16 v[44:47], v[222:225], v[184:187], v[138:141]
	v_mfma_f32_16x16x32_bf16 v[16:19], v[230:233], v[184:187], v[16:19]
	v_mfma_f32_16x16x32_bf16 v[12:15], v[222:225], v[188:191], v[12:15]
	v_mfma_f32_16x16x32_bf16 v[134:137], v[230:233], v[188:191], v[142:145]
	v_mfma_f32_16x16x32_bf16 v[138:141], v[222:225], v[196:199], v[172:175]
	v_mfma_f32_16x16x32_bf16 v[0:3], v[230:233], v[196:199], v[0:3]
	v_mfma_f32_16x16x32_bf16 v[60:63], v[226:229], v[180:183], v[28:31]
	v_mfma_f32_16x16x32_bf16 v[48:51], v[234:237], v[180:183], v[32:35]
	v_mfma_f32_16x16x32_bf16 v[44:47], v[226:229], v[154:157], v[44:47]
	v_mfma_f32_16x16x32_bf16 v[32:35], v[234:237], v[154:157], v[16:19]
	v_mfma_f32_16x16x32_bf16 v[28:31], v[226:229], v[192:195], v[12:15]
	v_mfma_f32_16x16x32_bf16 v[16:19], v[234:237], v[192:195], v[134:137]
	v_mfma_f32_16x16x32_bf16 v[12:15], v[226:229], v[200:203], v[138:141]
	v_mfma_f32_16x16x32_bf16 v[0:3], v[234:237], v[200:203], v[0:3]
	v_cmp_gt_u32_e32 vcc, s62, v130
	s_barrier
	s_and_saveexec_b64 s[44:45], vcc
	s_cbranch_execz .LBB0_227
	s_barrier

; #define STAGE(P, BASE, LD, br, kt) do { const char* _g = (const char*)((BASE) + (size_t)(br) * (LD) + (size_t)(kt) * 64); \
;     for (int _i = 0; _i < 2; ++_i) { int _b = tidx * 16 + _i * 8192; int _r, _c; stage_rc(_b, _r, _c); \
;       __builtin_amdgcn_global_load_lds((const unsigned*)(_g + (unsigned)((_r * (LD) + _c) * 2)), (unsigned*)((char*)(P) + _b), 16, 0, 0); } } while (0)
; #define LDA(dst, b, h) for (int m = 0; m < 4; ++m) for (int k = 0; k < 2; ++k) \
;     dst[m][k] = *reinterpret_cast<const bf16x8*>((char*)SA(b, h) + lds_byte(wr * 64 + m * 16 + fr, k * 32 + fq * 8))
; #define LDB(dst, b, h) for (int n = 0; n < 2; ++n) for (int k = 0; k < 2; ++k) \
;     dst[n][k] = *reinterpret_cast<const bf16x8*>((char*)SB(b, h) + lds_byte(wc * 32 + n * 16 + fr, k * 32 + fq * 8))
; #define MMA(ai, bj, At_, Bt_) do { __builtin_amdgcn_s_setprio(1); \
;     for (int k = 0; k < 2; ++k) for (int m = 0; m < 4; ++m) for (int n = 0; n < 2; ++n) \
;       acc[ai][bj][m][n] = __builtin_amdgcn_mfma_f32_16x16x32_bf16(At_[m][k], Bt_[n][k], acc[ai][bj][m][n], 0, 0, 0); \
;     __builtin_amdgcn_s_setprio(0); } while (0)
; #define WAIT_V(n) asm volatile("s_waitcnt vmcnt(" #n ")" ::: "memory")
; #define WAIT_L(n) asm volatile("s_waitcnt lgkmcnt(" #n ")" ::: "memory")
; #define BAR __builtin_amdgcn_s_barrier()
; #define SCHED __builtin_amdgcn_sched_barrier(0)
; template <int EPI, int lda, int ldb, int N, int K>
; __device__ __forceinline__ void gemm_phase(const u16* __restrict__ A, const u16* __restrict__ Bt, const GemmEpi ep, int wv) {
;     ...
;     for (int t = 0; t < nt - 2; t += 2) {
;       LDB(B0, 0, 0); SCHED; LDA(At, 0, 0); STAGE(SA(1, 1), Ab, lda, brow + HALF, t + 1);
;       WAIT_L(8); BAR; WAIT_L(0); MMA(0, 0, At, B0); BAR; SCHED;
;       LDB(B1, 0, 1); STAGE(SB(0, 0), Bt, ldb, bcol, t + 2);
;       BAR; WAIT_L(0); MMA(0, 1, At, B1); BAR;
;       LDA(At, 0, 1); STAGE(SA(0, 0), Ab, lda, brow, t + 2);
;       BAR; WAIT_L(0); MMA(1, 0, At, B0); BAR; SCHED;
;       STAGE(SB(0, 1), Bt, ldb, bcol + HALF, t + 2);
;       WAIT_V(6); BAR; MMA(1, 1, At, B1); BAR;
.LBB0_340:
	ds_read_b128 v[166:169], v162
	ds_read_b128 v[172:175], v162 offset:1024
	ds_read_b128 v[176:179], v162 offset:2048
	ds_read_b128 v[180:183], v162 offset:3072
	v_add_u32_e32 v170, 0xc000, v149
	v_lshl_add_u64 v[236:237], v[138:139], 0, s[48:49]
	v_readfirstlane_b32 s51, v170
	v_add_u32_e32 v171, 0xe000, v149
	v_lshl_add_u64 v[164:165], v[236:237], 0, s[18:19]
	s_mov_b32 m0, s51
	v_lshl_add_u64 v[238:239], v[140:141], 0, s[48:49]
	ds_read_b128 v[184:187], v153
	ds_read_b128 v[188:191], v153 offset:1024
	ds_read_b128 v[192:195], v152
	ds_read_b128 v[196:199], v152 offset:1024
	ds_read_b128 v[200:203], v151
	ds_read_b128 v[204:207], v151 offset:1024
	ds_read_b128 v[208:211], v150
	ds_read_b128 v[212:215], v150 offset:1024
	global_load_lds_dwordx4 v[164:165], off
	s_bitset1_b32 m0, 13
	v_lshl_add_u64 v[164:165], v[238:239], 0, s[18:19]
	global_load_lds_dwordx4 v[164:165], off
	s_waitcnt lgkmcnt(8)
	s_barrier
	s_waitcnt lgkmcnt(0)
	s_waitcnt lgkmcnt(0)
	v_mfma_f32_16x16x32_bf16 v[124:127], v[184:187], v[166:169], v[124:127]
	v_mfma_f32_16x16x32_bf16 v[120:123], v[184:187], v[176:179], v[120:123]
	v_mfma_f32_16x16x32_bf16 v[116:119], v[192:195], v[166:169], v[116:119]
	v_mfma_f32_16x16x32_bf16 v[112:115], v[192:195], v[176:179], v[112:115]
	v_mfma_f32_16x16x32_bf16 v[108:111], v[200:203], v[166:169], v[108:111]
	v_mfma_f32_16x16x32_bf16 v[104:107], v[200:203], v[176:179], v[104:107]
	v_mfma_f32_16x16x32_bf16 v[100:103], v[208:211], v[166:169], v[100:103]
	v_mfma_f32_16x16x32_bf16 v[96:99], v[208:211], v[176:179], v[96:99]
	v_mfma_f32_16x16x32_bf16 v[124:127], v[188:191], v[172:175], v[124:127]
	v_mfma_f32_16x16x32_bf16 v[120:123], v[188:191], v[180:183], v[120:123]
	v_mfma_f32_16x16x32_bf16 v[116:119], v[196:199], v[172:175], v[116:119]
	v_mfma_f32_16x16x32_bf16 v[112:115], v[196:199], v[180:183], v[112:115]
	v_mfma_f32_16x16x32_bf16 v[108:111], v[204:207], v[172:175], v[108:111]
	v_mfma_f32_16x16x32_bf16 v[104:107], v[204:207], v[180:183], v[104:107]
	v_mfma_f32_16x16x32_bf16 v[100:103], v[212:215], v[172:175], v[100:103]
	v_mfma_f32_16x16x32_bf16 v[96:99], v[212:215], v[180:183], v[96:99]
	s_barrier
	v_add_u32_e32 v163, s62, v155
	v_lshl_add_u64 v[240:241], v[134:135], 0, s[48:49]
	v_readfirstlane_b32 s51, v163
	v_lshl_add_u64 v[164:165], v[240:241], 0, s[20:21]
	s_mov_b32 m0, s51
	ds_read_b128 v[216:219], v161
	ds_read_b128 v[220:223], v161 offset:1024
	ds_read_b128 v[224:227], v161 offset:2048
	ds_read_b128 v[228:231], v161 offset:3072
	global_load_lds_dwordx4 v[164:165], off
	s_bitset1_b32 m0, 13
	v_add_u32_e32 v164, 0x2000, v163
	v_lshl_add_u64 v[242:243], v[136:137], 0, s[48:49]
	v_lshl_add_u64 v[232:233], v[242:243], 0, s[20:21]
	global_load_lds_dwordx4 v[232:233], off
	s_barrier
	s_waitcnt lgkmcnt(0)
	s_waitcnt lgkmcnt(0)
	v_mfma_f32_16x16x32_bf16 v[92:95], v[184:187], v[216:219], v[92:95]
	v_mfma_f32_16x16x32_bf16 v[88:91], v[184:187], v[224:227], v[88:91]
	v_mfma_f32_16x16x32_bf16 v[84:87], v[192:195], v[216:219], v[84:87]
	v_mfma_f32_16x16x32_bf16 v[80:83], v[192:195], v[224:227], v[80:83]
	v_mfma_f32_16x16x32_bf16 v[76:79], v[200:203], v[216:219], v[76:79]
	v_mfma_f32_16x16x32_bf16 v[72:75], v[200:203], v[224:227], v[72:75]
	v_mfma_f32_16x16x32_bf16 v[68:71], v[208:211], v[216:219], v[68:71]
	v_mfma_f32_16x16x32_bf16 v[64:67], v[208:211], v[224:227], v[64:67]
	v_mfma_f32_16x16x32_bf16 v[92:95], v[188:191], v[220:223], v[92:95]
	v_mfma_f32_16x16x32_bf16 v[88:91], v[188:191], v[228:231], v[88:91]
	v_mfma_f32_16x16x32_bf16 v[84:87], v[196:199], v[220:223], v[84:87]
	v_mfma_f32_16x16x32_bf16 v[80:83], v[196:199], v[228:231], v[80:83]
	v_mfma_f32_16x16x32_bf16 v[76:79], v[204:207], v[220:223], v[76:79]
	v_mfma_f32_16x16x32_bf16 v[72:75], v[204:207], v[228:231], v[72:75]
	v_mfma_f32_16x16x32_bf16 v[68:71], v[212:215], v[220:223], v[68:71]
	v_mfma_f32_16x16x32_bf16 v[64:67], v[212:215], v[228:231], v[64:67]
	v_readfirstlane_b32 s51, v149
	v_add_u32_e32 v165, 0x2000, v149
	v_lshl_add_u64 v[232:233], v[236:237], 0, s[22:23]
	s_mov_b32 m0, s51
	s_barrier
	ds_read_b128 v[184:187], v153 offset:16384
	ds_read_b128 v[188:191], v153 offset:17408
	ds_read_b128 v[192:195], v152 offset:16384
	ds_read_b128 v[196:199], v152 offset:17408
	ds_read_b128 v[200:203], v151 offset:16384
	ds_read_b128 v[204:207], v151 offset:17408
	ds_read_b128 v[208:211], v150 offset:16384
	ds_read_b128 v[212:215], v150 offset:17408
	global_load_lds_dwordx4 v[232:233], off
	s_bitset1_b32 m0, 13
	v_lshl_add_u64 v[232:233], v[238:239], 0, s[22:23]
	global_load_lds_dwordx4 v[232:233], off
	s_barrier
	s_waitcnt lgkmcnt(0)
	s_waitcnt lgkmcnt(0)
	v_mfma_f32_16x16x32_bf16 v[60:63], v[184:187], v[166:169], v[60:63]
	v_mfma_f32_16x16x32_bf16 v[56:59], v[184:187], v[176:179], v[56:59]
	v_mfma_f32_16x16x32_bf16 v[52:55], v[192:195], v[166:169], v[52:55]
	v_mfma_f32_16x16x32_bf16 v[48:51], v[192:195], v[176:179], v[48:51]
	v_mfma_f32_16x16x32_bf16 v[44:47], v[200:203], v[166:169], v[44:47]
	v_mfma_f32_16x16x32_bf16 v[40:43], v[200:203], v[176:179], v[40:43]
	v_mfma_f32_16x16x32_bf16 v[36:39], v[208:211], v[166:169], v[36:39]
	v_mfma_f32_16x16x32_bf16 v[32:35], v[208:211], v[176:179], v[32:35]
	v_mfma_f32_16x16x32_bf16 v[60:63], v[188:191], v[172:175], v[60:63]
	v_mfma_f32_16x16x32_bf16 v[56:59], v[188:191], v[180:183], v[56:59]
	v_mfma_f32_16x16x32_bf16 v[52:55], v[196:199], v[172:175], v[52:55]
	v_mfma_f32_16x16x32_bf16 v[48:51], v[196:199], v[180:183], v[48:51]
	v_mfma_f32_16x16x32_bf16 v[44:47], v[204:207], v[172:175], v[44:47]
	v_mfma_f32_16x16x32_bf16 v[40:43], v[204:207], v[180:183], v[40:43]
	v_mfma_f32_16x16x32_bf16 v[36:39], v[212:215], v[172:175], v[36:39]
	v_mfma_f32_16x16x32_bf16 v[32:35], v[212:215], v[180:183], v[32:35]
	s_barrier
; #define STAGE(P, BASE, LD, br, kt) do { const char* _g = (const char*)((BASE) + (size_t)(br) * (LD) + (size_t)(kt) * 64); \
;     for (int _i = 0; _i < 2; ++_i) { int _b = tidx * 16 + _i * 8192; int _r, _c; stage_rc(_b, _r, _c); \
;       __builtin_amdgcn_global_load_lds((const unsigned*)(_g + (unsigned)((_r * (LD) + _c) * 2)), (unsigned*)((char*)(P) + _b), 16, 0, 0); } } while (0)
; #define LDA(dst, b, h) for (int m = 0; m < 4; ++m) for (int k = 0; k < 2; ++k) \
;     dst[m][k] = *reinterpret_cast<const bf16x8*>((char*)SA(b, h) + lds_byte(wr * 64 + m * 16 + fr, k * 32 + fq * 8))
; #define LDB(dst, b, h) for (int n = 0; n < 2; ++n) for (int k = 0; k < 2; ++k) \
;     dst[n][k] = *reinterpret_cast<const bf16x8*>((char*)SB(b, h) + lds_byte(wc * 32 + n * 16 + fr, k * 32 + fq * 8))
; #define MMA(ai, bj, At_, Bt_) do { __builtin_amdgcn_s_setprio(1); \
;     for (int k = 0; k < 2; ++k) for (int m = 0; m < 4; ++m) for (int n = 0; n < 2; ++n) \
;       acc[ai][bj][m][n] = __builtin_amdgcn_mfma_f32_16x16x32_bf16(At_[m][k], Bt_[n][k], acc[ai][bj][m][n], 0, 0, 0); \
;     __builtin_amdgcn_s_setprio(0); } while (0)
; #define WAIT_V(n) asm volatile("s_waitcnt vmcnt(" #n ")" ::: "memory")
; #define WAIT_L(n) asm volatile("s_waitcnt lgkmcnt(" #n ")" ::: "memory")
; #define BAR __builtin_amdgcn_s_barrier()
; #define SCHED __builtin_amdgcn_sched_barrier(0)
; template <int EPI, int lda, int ldb, int N, int K>
; __device__ __forceinline__ void gemm_phase(const u16* __restrict__ A, const u16* __restrict__ Bt, const GemmEpi ep, int wv) {
;     ...
;       WAIT_V(6); BAR; MMA(1, 1, At, B1); BAR;
;       LDB(B0, 1, 0); SCHED; LDA(At, 1, 0); STAGE(SA(0, 1), Ab, lda, brow + HALF, t + 2);
;       WAIT_L(8); BAR; WAIT_L(0); MMA(0, 0, At, B0); BAR; SCHED;
;       LDB(B1, 1, 1); STAGE(SB(1, 0), Bt, ldb, bcol, t + 3);
;       BAR; WAIT_L(0); MMA(0, 1, At, B1); BAR;
;       LDA(At, 1, 1); STAGE(SA(1, 0), Ab, lda, brow, t + 3);
;       BAR; WAIT_L(0); MMA(1, 0, At, B0); BAR; SCHED;
;       STAGE(SB(1, 1), Bt, ldb, bcol + HALF, t + 3);
;       WAIT_V(6); BAR; MMA(1, 1, At, B1); BAR;
	v_add_u32_e32 v166, s63, v155
	v_add_u32_e32 v167, 0x2000, v166
	v_readfirstlane_b32 s51, v166
	v_lshl_add_u64 v[168:169], v[240:241], 0, s[24:25]
	s_mov_b32 m0, s51
	global_load_lds_dwordx4 v[168:169], off
	s_bitset1_b32 m0, 13
	v_lshl_add_u64 v[168:169], v[242:243], 0, s[24:25]
	global_load_lds_dwordx4 v[168:169], off
	s_waitcnt vmcnt(6)
	s_barrier
	v_mfma_f32_16x16x32_bf16 v[28:31], v[184:187], v[216:219], v[28:31]
	v_mfma_f32_16x16x32_bf16 v[24:27], v[184:187], v[224:227], v[24:27]
	v_mfma_f32_16x16x32_bf16 v[20:23], v[192:195], v[216:219], v[20:23]
	v_mfma_f32_16x16x32_bf16 v[16:19], v[192:195], v[224:227], v[16:19]
	v_mfma_f32_16x16x32_bf16 v[12:15], v[200:203], v[216:219], v[12:15]
	v_mfma_f32_16x16x32_bf16 v[8:11], v[200:203], v[224:227], v[8:11]
	v_mfma_f32_16x16x32_bf16 v[4:7], v[208:211], v[216:219], v[4:7]
	v_mfma_f32_16x16x32_bf16 v[0:3], v[208:211], v[224:227], v[0:3]
	v_mfma_f32_16x16x32_bf16 v[28:31], v[188:191], v[220:223], v[28:31]
	v_mfma_f32_16x16x32_bf16 v[24:27], v[188:191], v[228:231], v[24:27]
	v_mfma_f32_16x16x32_bf16 v[20:23], v[196:199], v[220:223], v[20:23]
	v_mfma_f32_16x16x32_bf16 v[16:19], v[196:199], v[228:231], v[16:19]
	v_mfma_f32_16x16x32_bf16 v[12:15], v[204:207], v[220:223], v[12:15]
	v_mfma_f32_16x16x32_bf16 v[8:11], v[204:207], v[228:231], v[8:11]
	v_mfma_f32_16x16x32_bf16 v[4:7], v[212:215], v[220:223], v[4:7]
	v_mfma_f32_16x16x32_bf16 v[0:3], v[212:215], v[228:231], v[0:3]
	s_barrier
	ds_read_b128 v[172:175], v156
	ds_read_b128 v[176:179], v156 offset:1024
	ds_read_b128 v[180:183], v156 offset:2048
	ds_read_b128 v[184:187], v156 offset:3072
	v_add_u32_e32 v168, 0x4000, v149
	v_add_u32_e32 v169, 0x6000, v149
	v_readfirstlane_b32 s51, v168
	v_lshl_add_u64 v[220:221], v[236:237], 0, s[26:27]
	s_mov_b32 m0, s51
	ds_read_b128 v[188:191], v153 offset:32768
	ds_read_b128 v[192:195], v153 offset:33792
	ds_read_b128 v[196:199], v152 offset:32768
	ds_read_b128 v[200:203], v152 offset:33792
	ds_read_b128 v[204:207], v151 offset:32768
	ds_read_b128 v[208:211], v151 offset:33792
	ds_read_b128 v[212:215], v150 offset:32768
	ds_read_b128 v[216:219], v150 offset:33792
	global_load_lds_dwordx4 v[220:221], off
	s_bitset1_b32 m0, 13
	v_lshl_add_u64 v[220:221], v[238:239], 0, s[26:27]
	global_load_lds_dwordx4 v[220:221], off
	s_waitcnt lgkmcnt(8)
	s_barrier
	s_waitcnt lgkmcnt(0)
	s_waitcnt lgkmcnt(0)
	v_mfma_f32_16x16x32_bf16 v[124:127], v[188:191], v[172:175], v[124:127]
	v_mfma_f32_16x16x32_bf16 v[120:123], v[188:191], v[180:183], v[120:123]
	v_mfma_f32_16x16x32_bf16 v[116:119], v[196:199], v[172:175], v[116:119]
	v_mfma_f32_16x16x32_bf16 v[112:115], v[196:199], v[180:183], v[112:115]
	v_mfma_f32_16x16x32_bf16 v[108:111], v[204:207], v[172:175], v[108:111]
	v_mfma_f32_16x16x32_bf16 v[104:107], v[204:207], v[180:183], v[104:107]
	v_mfma_f32_16x16x32_bf16 v[100:103], v[212:215], v[172:175], v[100:103]
	v_mfma_f32_16x16x32_bf16 v[96:99], v[212:215], v[180:183], v[96:99]
	v_mfma_f32_16x16x32_bf16 v[124:127], v[192:195], v[176:179], v[124:127]
	v_mfma_f32_16x16x32_bf16 v[120:123], v[192:195], v[184:187], v[120:123]
	v_mfma_f32_16x16x32_bf16 v[116:119], v[200:203], v[176:179], v[116:119]
	v_mfma_f32_16x16x32_bf16 v[112:115], v[200:203], v[184:187], v[112:115]
	v_mfma_f32_16x16x32_bf16 v[108:111], v[208:211], v[176:179], v[108:111]
	v_mfma_f32_16x16x32_bf16 v[104:107], v[208:211], v[184:187], v[104:107]
	v_mfma_f32_16x16x32_bf16 v[100:103], v[216:219], v[176:179], v[100:103]
	v_mfma_f32_16x16x32_bf16 v[96:99], v[216:219], v[184:187], v[96:99]
	s_barrier
	v_readfirstlane_b32 s51, v157
	v_add_u32_e32 v246, 0x2000, v157
	v_lshl_add_u64 v[244:245], v[240:241], 0, s[36:37]
	s_mov_b32 m0, s51
	ds_read_b128 v[220:223], v154
	ds_read_b128 v[224:227], v154 offset:1024
	ds_read_b128 v[228:231], v154 offset:2048
	ds_read_b128 v[232:235], v154 offset:3072
	global_load_lds_dwordx4 v[244:245], off
	s_bitset1_b32 m0, 13
	v_lshl_add_u64 v[244:245], v[242:243], 0, s[36:37]
	global_load_lds_dwordx4 v[244:245], off
	s_barrier
	s_waitcnt lgkmcnt(0)
	s_waitcnt lgkmcnt(0)
	v_mfma_f32_16x16x32_bf16 v[92:95], v[188:191], v[220:223], v[92:95]
	v_mfma_f32_16x16x32_bf16 v[88:91], v[188:191], v[228:231], v[88:91]
	v_mfma_f32_16x16x32_bf16 v[84:87], v[196:199], v[220:223], v[84:87]
	v_mfma_f32_16x16x32_bf16 v[80:83], v[196:199], v[228:231], v[80:83]
	v_mfma_f32_16x16x32_bf16 v[76:79], v[204:207], v[220:223], v[76:79]
	v_mfma_f32_16x16x32_bf16 v[72:75], v[204:207], v[228:231], v[72:75]
	v_mfma_f32_16x16x32_bf16 v[68:71], v[212:215], v[220:223], v[68:71]
	v_mfma_f32_16x16x32_bf16 v[64:67], v[212:215], v[228:231], v[64:67]
	v_mfma_f32_16x16x32_bf16 v[92:95], v[192:195], v[224:227], v[92:95]
	v_mfma_f32_16x16x32_bf16 v[88:91], v[192:195], v[232:235], v[88:91]
	v_mfma_f32_16x16x32_bf16 v[84:87], v[200:203], v[224:227], v[84:87]
	v_mfma_f32_16x16x32_bf16 v[80:83], v[200:203], v[232:235], v[80:83]
	v_mfma_f32_16x16x32_bf16 v[76:79], v[208:211], v[224:227], v[76:79]
	v_mfma_f32_16x16x32_bf16 v[72:75], v[208:211], v[232:235], v[72:75]
	v_mfma_f32_16x16x32_bf16 v[68:71], v[216:219], v[224:227], v[68:71]
	v_mfma_f32_16x16x32_bf16 v[64:67], v[216:219], v[232:235], v[64:67]
	v_readfirstlane_b32 s51, v158
	v_lshl_add_u64 v[236:237], v[236:237], 0, s[38:39]
	s_mov_b32 m0, s51
	s_barrier
	ds_read_b128 v[188:191], v153 offset:49152
	ds_read_b128 v[192:195], v153 offset:50176
	ds_read_b128 v[196:199], v152 offset:49152
	ds_read_b128 v[200:203], v152 offset:50176
	ds_read_b128 v[204:207], v151 offset:49152
	ds_read_b128 v[208:211], v151 offset:50176
	ds_read_b128 v[212:215], v150 offset:49152
	ds_read_b128 v[216:219], v150 offset:50176
	global_load_lds_dwordx4 v[236:237], off
	s_bitset1_b32 m0, 13
	v_lshl_add_u64 v[236:237], v[238:239], 0, s[38:39]
	global_load_lds_dwordx4 v[236:237], off
	s_barrier
; #define STAGE(P, BASE, LD, br, kt) do { const char* _g = (const char*)((BASE) + (size_t)(br) * (LD) + (size_t)(kt) * 64); \
;     for (int _i = 0; _i < 2; ++_i) { int _b = tidx * 16 + _i * 8192; int _r, _c; stage_rc(_b, _r, _c); \
;       __builtin_amdgcn_global_load_lds((const unsigned*)(_g + (unsigned)((_r * (LD) + _c) * 2)), (unsigned*)((char*)(P) + _b), 16, 0, 0); } } while (0)
; #define LDA(dst, b, h) for (int m = 0; m < 4; ++m) for (int k = 0; k < 2; ++k) \
;     dst[m][k] = *reinterpret_cast<const bf16x8*>((char*)SA(b, h) + lds_byte(wr * 64 + m * 16 + fr, k * 32 + fq * 8))
; #define LDB(dst, b, h) for (int n = 0; n < 2; ++n) for (int k = 0; k < 2; ++k) \
;     dst[n][k] = *reinterpret_cast<const bf16x8*>((char*)SB(b, h) + lds_byte(wc * 32 + n * 16 + fr, k * 32 + fq * 8))
; #define MMA(ai, bj, At_, Bt_) do { __builtin_amdgcn_s_setprio(1); \
;     for (int k = 0; k < 2; ++k) for (int m = 0; m < 4; ++m) for (int n = 0; n < 2; ++n) \
;       acc[ai][bj][m][n] = __builtin_amdgcn_mfma_f32_16x16x32_bf16(At_[m][k], Bt_[n][k], acc[ai][bj][m][n], 0, 0, 0); \
;     __builtin_amdgcn_s_setprio(0); } while (0)
; #define WAIT_V(n) asm volatile("s_waitcnt vmcnt(" #n ")" ::: "memory")
; #define WAIT_L(n) asm volatile("s_waitcnt lgkmcnt(" #n ")" ::: "memory")
; #define BAR __builtin_amdgcn_s_barrier()
; #define SCHED __builtin_amdgcn_sched_barrier(0)
; template <int EPI, int lda, int ldb, int N, int K>
; __device__ __forceinline__ void gemm_phase(const u16* __restrict__ A, const u16* __restrict__ Bt, const GemmEpi ep, int wv) {
;     ...
;       BAR; WAIT_L(0); MMA(0, 1, At, B1); BAR;
;       LDA(At, 1, 1); STAGE(SA(1, 0), Ab, lda, brow, t + 3);
;       BAR; WAIT_L(0); MMA(1, 0, At, B0); BAR; SCHED;
;       STAGE(SB(1, 1), Bt, ldb, bcol + HALF, t + 3);
;       WAIT_V(6); BAR; MMA(1, 1, At, B1); BAR;
;     }
;     { LDB(B0, 0, 0); LDA(At, 0, 0); STAGE(SA(1, 1), Ab, lda, brow + HALF, nt - 1);
;       BAR; WAIT_L(0); MMA(0, 0, At, B0); BAR;
;       LDB(B1, 0, 1); BAR; WAIT_L(0); MMA(0, 1, At, B1); BAR;
;       LDA(At, 0, 1); WAIT_V(4); BAR; WAIT_L(0); MMA(1, 0, At, B0); MMA(1, 1, At, B1); BAR; }
	s_waitcnt lgkmcnt(0)
	s_waitcnt lgkmcnt(0)
	v_mfma_f32_16x16x32_bf16 v[60:63], v[188:191], v[172:175], v[60:63]
	v_mfma_f32_16x16x32_bf16 v[56:59], v[188:191], v[180:183], v[56:59]
	v_mfma_f32_16x16x32_bf16 v[52:55], v[196:199], v[172:175], v[52:55]
	v_mfma_f32_16x16x32_bf16 v[48:51], v[196:199], v[180:183], v[48:51]
	v_mfma_f32_16x16x32_bf16 v[44:47], v[204:207], v[172:175], v[44:47]
	v_mfma_f32_16x16x32_bf16 v[40:43], v[204:207], v[180:183], v[40:43]
	v_mfma_f32_16x16x32_bf16 v[36:39], v[212:215], v[172:175], v[36:39]
	v_mfma_f32_16x16x32_bf16 v[32:35], v[212:215], v[180:183], v[32:35]
	v_mfma_f32_16x16x32_bf16 v[60:63], v[192:195], v[176:179], v[60:63]
	v_mfma_f32_16x16x32_bf16 v[56:59], v[192:195], v[184:187], v[56:59]
	v_mfma_f32_16x16x32_bf16 v[52:55], v[200:203], v[176:179], v[52:55]
	v_mfma_f32_16x16x32_bf16 v[48:51], v[200:203], v[184:187], v[48:51]
	v_mfma_f32_16x16x32_bf16 v[44:47], v[208:211], v[176:179], v[44:47]
	v_mfma_f32_16x16x32_bf16 v[40:43], v[208:211], v[184:187], v[40:43]
	v_mfma_f32_16x16x32_bf16 v[36:39], v[216:219], v[176:179], v[36:39]
	v_mfma_f32_16x16x32_bf16 v[32:35], v[216:219], v[184:187], v[32:35]
	s_barrier
	v_readfirstlane_b32 s51, v160
	v_add_u32_e32 v174, 0x2000, v160
	v_lshl_add_u64 v[172:173], v[240:241], 0, s[42:43]
	s_mov_b32 m0, s51
	global_load_lds_dwordx4 v[172:173], off
	s_bitset1_b32 m0, 13
	v_lshl_add_u64 v[172:173], v[242:243], 0, s[42:43]
	global_load_lds_dwordx4 v[172:173], off
	s_waitcnt vmcnt(6)
	s_barrier
	v_mfma_f32_16x16x32_bf16 v[28:31], v[188:191], v[220:223], v[28:31]
	v_mfma_f32_16x16x32_bf16 v[24:27], v[188:191], v[228:231], v[24:27]
	v_mfma_f32_16x16x32_bf16 v[20:23], v[196:199], v[220:223], v[20:23]
	v_mfma_f32_16x16x32_bf16 v[16:19], v[196:199], v[228:231], v[16:19]
	v_mfma_f32_16x16x32_bf16 v[12:15], v[204:207], v[220:223], v[12:15]
	v_mfma_f32_16x16x32_bf16 v[8:11], v[204:207], v[228:231], v[8:11]
	v_mfma_f32_16x16x32_bf16 v[4:7], v[212:215], v[220:223], v[4:7]
	v_mfma_f32_16x16x32_bf16 v[0:3], v[212:215], v[228:231], v[0:3]
	v_mfma_f32_16x16x32_bf16 v[28:31], v[192:195], v[224:227], v[28:31]
	v_mfma_f32_16x16x32_bf16 v[24:27], v[192:195], v[232:235], v[24:27]
	v_mfma_f32_16x16x32_bf16 v[20:23], v[200:203], v[224:227], v[20:23]
	v_mfma_f32_16x16x32_bf16 v[16:19], v[200:203], v[232:235], v[16:19]
	v_mfma_f32_16x16x32_bf16 v[12:15], v[208:211], v[224:227], v[12:15]
	v_mfma_f32_16x16x32_bf16 v[8:11], v[208:211], v[232:235], v[8:11]
	v_mfma_f32_16x16x32_bf16 v[4:7], v[216:219], v[224:227], v[4:7]
	v_mfma_f32_16x16x32_bf16 v[0:3], v[216:219], v[232:235], v[0:3]
	s_add_i32 s50, s50, 2
	s_add_u32 s48, s48, 0x100
	s_addc_u32 s49, s49, 0
	s_cmp_gt_u32 s50, 27
	s_barrier
	s_cbranch_scc0 .LBB0_340
	s_add_i32 s48, s46, 0x80
	s_mul_hi_i32 s49, s48, 0x1080
	s_mulk_i32 s48, 0x1080
	s_add_u32 s48, s31, s48
	s_addc_u32 s49, s56, s49
	v_lshl_add_u64 v[158:159], s[48:49], 0, v[128:129]
	v_readfirstlane_b32 s50, v170
	v_lshl_add_u64 v[158:159], v[158:159], 0, s[44:45]
	s_mov_b32 m0, s50
	ds_read_b128 v[134:137], v162
	ds_read_b128 v[138:141], v162 offset:1024
	ds_read_b128 v[172:175], v162 offset:2048
	ds_read_b128 v[176:179], v162 offset:3072
	ds_read_b128 v[180:183], v153
	ds_read_b128 v[184:187], v153 offset:1024
	ds_read_b128 v[188:191], v152
	ds_read_b128 v[192:195], v152 offset:1024
	ds_read_b128 v[196:199], v151
	ds_read_b128 v[200:203], v151 offset:1024
	ds_read_b128 v[204:207], v150
	ds_read_b128 v[208:211], v150 offset:1024
	global_load_lds_dwordx4 v[158:159], off
	v_lshl_add_u64 v[158:159], s[48:49], 0, v[132:133]
	v_readfirstlane_b32 s48, v171
	v_lshl_add_u64 v[158:159], v[158:159], 0, s[44:45]
	s_mov_b32 m0, s48
	s_nop 0
	global_load_lds_dwordx4 v[158:159], off
	s_barrier
	s_waitcnt lgkmcnt(0)
	s_waitcnt lgkmcnt(0)
	v_mfma_f32_16x16x32_bf16 v[124:127], v[180:183], v[134:137], v[124:127]
	v_mfma_f32_16x16x32_bf16 v[120:123], v[180:183], v[172:175], v[120:123]
	v_mfma_f32_16x16x32_bf16 v[116:119], v[188:191], v[134:137], v[116:119]
	v_mfma_f32_16x16x32_bf16 v[112:115], v[188:191], v[172:175], v[112:115]
	v_mfma_f32_16x16x32_bf16 v[108:111], v[196:199], v[134:137], v[108:111]
	v_mfma_f32_16x16x32_bf16 v[104:107], v[196:199], v[172:175], v[104:107]
	v_mfma_f32_16x16x32_bf16 v[100:103], v[204:207], v[134:137], v[100:103]
	v_mfma_f32_16x16x32_bf16 v[96:99], v[204:207], v[172:175], v[96:99]
	v_mfma_f32_16x16x32_bf16 v[124:127], v[184:187], v[138:141], v[124:127]
	v_mfma_f32_16x16x32_bf16 v[120:123], v[184:187], v[176:179], v[120:123]
	v_mfma_f32_16x16x32_bf16 v[116:119], v[192:195], v[138:141], v[116:119]
	v_mfma_f32_16x16x32_bf16 v[112:115], v[192:195], v[176:179], v[112:115]
	v_mfma_f32_16x16x32_bf16 v[108:111], v[200:203], v[138:141], v[108:111]
	v_mfma_f32_16x16x32_bf16 v[104:107], v[200:203], v[176:179], v[104:107]
	v_mfma_f32_16x16x32_bf16 v[100:103], v[208:211], v[138:141], v[100:103]
	v_mfma_f32_16x16x32_bf16 v[96:99], v[208:211], v[176:179], v[96:99]
	s_barrier
	ds_read_b128 v[212:215], v161
	ds_read_b128 v[216:219], v161 offset:1024
	ds_read_b128 v[220:223], v161 offset:2048
	ds_read_b128 v[158:161], v161 offset:3072
	s_barrier
; #define LDA(dst, b, h) for (int m = 0; m < 4; ++m) for (int k = 0; k < 2; ++k) \
;     dst[m][k] = *reinterpret_cast<const bf16x8*>((char*)SA(b, h) + lds_byte(wr * 64 + m * 16 + fr, k * 32 + fq * 8))
; #define LDB(dst, b, h) for (int n = 0; n < 2; ++n) for (int k = 0; k < 2; ++k) \
;     dst[n][k] = *reinterpret_cast<const bf16x8*>((char*)SB(b, h) + lds_byte(wc * 32 + n * 16 + fr, k * 32 + fq * 8))
; #define MMA(ai, bj, At_, Bt_) do { __builtin_amdgcn_s_setprio(1); \
;     for (int k = 0; k < 2; ++k) for (int m = 0; m < 4; ++m) for (int n = 0; n < 2; ++n) \
;       acc[ai][bj][m][n] = __builtin_amdgcn_mfma_f32_16x16x32_bf16(At_[m][k], Bt_[n][k], acc[ai][bj][m][n], 0, 0, 0); \
;     __builtin_amdgcn_s_setprio(0); } while (0)
; #define WAIT_V(n) asm volatile("s_waitcnt vmcnt(" #n ")" ::: "memory")
; #define WAIT_L(n) asm volatile("s_waitcnt lgkmcnt(" #n ")" ::: "memory")
; #define BAR __builtin_amdgcn_s_barrier()
; template <int EPI, int lda, int ldb, int N, int K>
; __device__ __forceinline__ void gemm_phase(const u16* __restrict__ A, const u16* __restrict__ Bt, const GemmEpi ep, int wv) {
;     ...
;       BAR; WAIT_L(0); MMA(0, 0, At, B0); BAR;
;       LDB(B1, 0, 1); BAR; WAIT_L(0); MMA(0, 1, At, B1); BAR;
;       LDA(At, 0, 1); WAIT_V(4); BAR; WAIT_L(0); MMA(1, 0, At, B0); MMA(1, 1, At, B1); BAR; }
;     { LDB(B0, 1, 0); LDA(At, 1, 0); WAIT_V(2); BAR; WAIT_L(0); MMA(0, 0, At, B0); BAR;
;       LDB(B1, 1, 1); WAIT_V(0); BAR; WAIT_L(0); MMA(0, 1, At, B1); BAR;
	s_waitcnt lgkmcnt(0)
	s_waitcnt lgkmcnt(0)
	v_mfma_f32_16x16x32_bf16 v[92:95], v[180:183], v[212:215], v[92:95]
	v_mfma_f32_16x16x32_bf16 v[88:91], v[180:183], v[220:223], v[88:91]
	v_mfma_f32_16x16x32_bf16 v[76:79], v[196:199], v[212:215], v[76:79]
	v_mfma_f32_16x16x32_bf16 v[72:75], v[196:199], v[220:223], v[72:75]
	v_mfma_f32_16x16x32_bf16 v[68:71], v[204:207], v[212:215], v[68:71]
	v_mfma_f32_16x16x32_bf16 v[64:67], v[204:207], v[220:223], v[64:67]
	v_mfma_f32_16x16x32_bf16 v[84:87], v[188:191], v[212:215], v[84:87]
	v_mfma_f32_16x16x32_bf16 v[80:83], v[188:191], v[220:223], v[80:83]
	v_mfma_f32_16x16x32_bf16 v[92:95], v[184:187], v[216:219], v[92:95]
	v_mfma_f32_16x16x32_bf16 v[88:91], v[184:187], v[158:161], v[88:91]
	v_mfma_f32_16x16x32_bf16 v[76:79], v[200:203], v[216:219], v[76:79]
	v_mfma_f32_16x16x32_bf16 v[72:75], v[200:203], v[158:161], v[72:75]
	v_mfma_f32_16x16x32_bf16 v[68:71], v[208:211], v[216:219], v[68:71]
	v_mfma_f32_16x16x32_bf16 v[64:67], v[208:211], v[158:161], v[64:67]
	v_mfma_f32_16x16x32_bf16 v[180:183], v[192:195], v[216:219], v[84:87]
	v_mfma_f32_16x16x32_bf16 v[184:187], v[192:195], v[158:161], v[80:83]
	s_barrier
	s_nop 0
	ds_read_b128 v[80:83], v153 offset:16384
	ds_read_b128 v[84:87], v153 offset:17408
	ds_read_b128 v[188:191], v152 offset:16384
	ds_read_b128 v[192:195], v152 offset:17408
	ds_read_b128 v[196:199], v151 offset:16384
	ds_read_b128 v[200:203], v151 offset:17408
	ds_read_b128 v[204:207], v150 offset:16384
	ds_read_b128 v[208:211], v150 offset:17408
	s_waitcnt vmcnt(4)
	s_barrier
	s_waitcnt lgkmcnt(0)
	s_waitcnt lgkmcnt(0)
	v_mfma_f32_16x16x32_bf16 v[60:63], v[80:83], v[134:137], v[60:63]
	v_mfma_f32_16x16x32_bf16 v[44:47], v[196:199], v[134:137], v[44:47]
	v_mfma_f32_16x16x32_bf16 v[40:43], v[196:199], v[172:175], v[40:43]
	v_mfma_f32_16x16x32_bf16 v[36:39], v[204:207], v[134:137], v[36:39]
	v_mfma_f32_16x16x32_bf16 v[32:35], v[204:207], v[172:175], v[32:35]
	v_mfma_f32_16x16x32_bf16 v[56:59], v[80:83], v[172:175], v[56:59]
	v_mfma_f32_16x16x32_bf16 v[52:55], v[188:191], v[134:137], v[52:55]
	v_mfma_f32_16x16x32_bf16 v[48:51], v[188:191], v[172:175], v[48:51]
	v_mfma_f32_16x16x32_bf16 v[60:63], v[84:87], v[138:141], v[60:63]
	v_mfma_f32_16x16x32_bf16 v[44:47], v[200:203], v[138:141], v[44:47]
	v_mfma_f32_16x16x32_bf16 v[40:43], v[200:203], v[176:179], v[40:43]
	v_mfma_f32_16x16x32_bf16 v[36:39], v[208:211], v[138:141], v[36:39]
	v_mfma_f32_16x16x32_bf16 v[32:35], v[208:211], v[176:179], v[32:35]
	v_mfma_f32_16x16x32_bf16 v[134:137], v[84:87], v[176:179], v[56:59]
	v_mfma_f32_16x16x32_bf16 v[170:173], v[192:195], v[138:141], v[52:55]
	v_mfma_f32_16x16x32_bf16 v[224:227], v[192:195], v[176:179], v[48:51]
	v_mfma_f32_16x16x32_bf16 v[28:31], v[80:83], v[212:215], v[28:31]
	v_mfma_f32_16x16x32_bf16 v[20:23], v[188:191], v[212:215], v[20:23]
	v_mfma_f32_16x16x32_bf16 v[12:15], v[196:199], v[212:215], v[12:15]
	v_mfma_f32_16x16x32_bf16 v[4:7], v[204:207], v[212:215], v[4:7]
	v_mfma_f32_16x16x32_bf16 v[24:27], v[80:83], v[220:223], v[24:27]
	v_mfma_f32_16x16x32_bf16 v[16:19], v[188:191], v[220:223], v[16:19]
	v_mfma_f32_16x16x32_bf16 v[8:11], v[196:199], v[220:223], v[8:11]
	v_mfma_f32_16x16x32_bf16 v[0:3], v[204:207], v[220:223], v[0:3]
	v_mfma_f32_16x16x32_bf16 v[28:31], v[84:87], v[216:219], v[28:31]
	v_mfma_f32_16x16x32_bf16 v[20:23], v[192:195], v[216:219], v[20:23]
	v_mfma_f32_16x16x32_bf16 v[12:15], v[200:203], v[216:219], v[12:15]
	v_mfma_f32_16x16x32_bf16 v[4:7], v[208:211], v[216:219], v[4:7]
	v_mfma_f32_16x16x32_bf16 v[138:141], v[84:87], v[158:161], v[24:27]
	v_mfma_f32_16x16x32_bf16 v[174:177], v[192:195], v[158:161], v[16:19]
	v_mfma_f32_16x16x32_bf16 v[188:191], v[200:203], v[158:161], v[8:11]
	v_mfma_f32_16x16x32_bf16 v[158:161], v[208:211], v[158:161], v[0:3]
	s_barrier
	s_nop 0
	ds_read_b128 v[0:3], v156
	ds_read_b128 v[8:11], v156 offset:1024
	ds_read_b128 v[16:19], v156 offset:2048
	ds_read_b128 v[192:195], v156 offset:3072
	ds_read_b128 v[24:27], v153 offset:32768
	ds_read_b128 v[56:59], v153 offset:33792
	ds_read_b128 v[196:199], v152 offset:32768
	ds_read_b128 v[200:203], v152 offset:33792
	ds_read_b128 v[204:207], v151 offset:32768
	ds_read_b128 v[208:211], v151 offset:33792
	ds_read_b128 v[212:215], v150 offset:32768
	ds_read_b128 v[216:219], v150 offset:33792
	s_waitcnt vmcnt(2)
	s_barrier
; #define LDA(dst, b, h) for (int m = 0; m < 4; ++m) for (int k = 0; k < 2; ++k) \
;     dst[m][k] = *reinterpret_cast<const bf16x8*>((char*)SA(b, h) + lds_byte(wr * 64 + m * 16 + fr, k * 32 + fq * 8))
; #define LDB(dst, b, h) for (int n = 0; n < 2; ++n) for (int k = 0; k < 2; ++k) \
;     dst[n][k] = *reinterpret_cast<const bf16x8*>((char*)SB(b, h) + lds_byte(wc * 32 + n * 16 + fr, k * 32 + fq * 8))
; #define MMA(ai, bj, At_, Bt_) do { __builtin_amdgcn_s_setprio(1); \
;     for (int k = 0; k < 2; ++k) for (int m = 0; m < 4; ++m) for (int n = 0; n < 2; ++n) \
;       acc[ai][bj][m][n] = __builtin_amdgcn_mfma_f32_16x16x32_bf16(At_[m][k], Bt_[n][k], acc[ai][bj][m][n], 0, 0, 0); \
;     __builtin_amdgcn_s_setprio(0); } while (0)
; #define WAIT_V(n) asm volatile("s_waitcnt vmcnt(" #n ")" ::: "memory")
; #define WAIT_L(n) asm volatile("s_waitcnt lgkmcnt(" #n ")" ::: "memory")
; #define BAR __builtin_amdgcn_s_barrier()
; template <int EPI, int lda, int ldb, int N, int K>
; __device__ __forceinline__ void gemm_phase(const u16* __restrict__ A, const u16* __restrict__ Bt, const GemmEpi ep, int wv) {
;     ...
;       LDA(At, 0, 1); WAIT_V(4); BAR; WAIT_L(0); MMA(1, 0, At, B0); MMA(1, 1, At, B1); BAR; }
;     { LDB(B0, 1, 0); LDA(At, 1, 0); WAIT_V(2); BAR; WAIT_L(0); MMA(0, 0, At, B0); BAR;
;       LDB(B1, 1, 1); WAIT_V(0); BAR; WAIT_L(0); MMA(0, 1, At, B1); BAR;
;       LDA(At, 1, 1); BAR; WAIT_L(0); MMA(1, 0, At, B0); MMA(1, 1, At, B1); BAR; }
;     if (wr == 0) BAR;
	s_waitcnt lgkmcnt(0)
	s_waitcnt lgkmcnt(0)
	v_mfma_f32_16x16x32_bf16 v[48:51], v[24:27], v[0:3], v[124:127]
	v_mfma_f32_16x16x32_bf16 v[52:55], v[24:27], v[16:19], v[120:123]
	v_mfma_f32_16x16x32_bf16 v[80:83], v[196:199], v[0:3], v[116:119]
	v_mfma_f32_16x16x32_bf16 v[84:87], v[196:199], v[16:19], v[112:115]
	v_mfma_f32_16x16x32_bf16 v[108:111], v[204:207], v[0:3], v[108:111]
	v_mfma_f32_16x16x32_bf16 v[104:107], v[204:207], v[16:19], v[104:107]
	v_mfma_f32_16x16x32_bf16 v[112:115], v[212:215], v[0:3], v[100:103]
	v_mfma_f32_16x16x32_bf16 v[120:123], v[212:215], v[16:19], v[96:99]
	v_mfma_f32_16x16x32_bf16 v[124:127], v[56:59], v[8:11], v[48:51]
	v_mfma_f32_16x16x32_bf16 v[116:119], v[56:59], v[192:195], v[52:55]
	v_mfma_f32_16x16x32_bf16 v[100:103], v[200:203], v[8:11], v[80:83]
	v_mfma_f32_16x16x32_bf16 v[96:99], v[200:203], v[192:195], v[84:87]
	v_mfma_f32_16x16x32_bf16 v[84:87], v[208:211], v[8:11], v[108:111]
	v_mfma_f32_16x16x32_bf16 v[80:83], v[208:211], v[192:195], v[104:107]
	v_mfma_f32_16x16x32_bf16 v[52:55], v[216:219], v[8:11], v[112:115]
	v_mfma_f32_16x16x32_bf16 v[48:51], v[216:219], v[192:195], v[120:123]
	s_barrier
	ds_read_b128 v[220:223], v154
	ds_read_b128 v[228:231], v154 offset:1024
	ds_read_b128 v[232:235], v154 offset:2048
	ds_read_b128 v[154:157], v154 offset:3072
	s_waitcnt vmcnt(0)
	s_barrier
	s_waitcnt lgkmcnt(0)
	s_waitcnt lgkmcnt(0)
	v_mfma_f32_16x16x32_bf16 v[92:95], v[24:27], v[220:223], v[92:95]
	v_mfma_f32_16x16x32_bf16 v[24:27], v[24:27], v[232:235], v[88:91]
	v_mfma_f32_16x16x32_bf16 v[88:91], v[196:199], v[220:223], v[180:183]
	v_mfma_f32_16x16x32_bf16 v[104:107], v[196:199], v[232:235], v[184:187]
	v_mfma_f32_16x16x32_bf16 v[76:79], v[204:207], v[220:223], v[76:79]
	v_mfma_f32_16x16x32_bf16 v[72:75], v[204:207], v[232:235], v[72:75]
	v_mfma_f32_16x16x32_bf16 v[68:71], v[212:215], v[220:223], v[68:71]
	v_mfma_f32_16x16x32_bf16 v[64:67], v[212:215], v[232:235], v[64:67]
	v_mfma_f32_16x16x32_bf16 v[120:123], v[56:59], v[228:231], v[92:95]
	v_mfma_f32_16x16x32_bf16 v[112:115], v[56:59], v[154:157], v[24:27]
	v_mfma_f32_16x16x32_bf16 v[108:111], v[200:203], v[228:231], v[88:91]
	v_mfma_f32_16x16x32_bf16 v[104:107], v[200:203], v[154:157], v[104:107]
	v_mfma_f32_16x16x32_bf16 v[92:95], v[208:211], v[228:231], v[76:79]
	v_mfma_f32_16x16x32_bf16 v[88:91], v[208:211], v[154:157], v[72:75]
	v_mfma_f32_16x16x32_bf16 v[68:71], v[216:219], v[228:231], v[68:71]
	v_mfma_f32_16x16x32_bf16 v[56:59], v[216:219], v[154:157], v[64:67]
	s_barrier
	s_nop 0
	ds_read_b128 v[64:67], v153 offset:49152
	ds_read_b128 v[178:181], v153 offset:50176
	ds_read_b128 v[76:79], v152 offset:49152
	ds_read_b128 v[182:185], v152 offset:50176
	ds_read_b128 v[196:199], v151 offset:49152
	ds_read_b128 v[200:203], v151 offset:50176
	ds_read_b128 v[204:207], v150 offset:49152
	ds_read_b128 v[150:153], v150 offset:50176
	s_barrier
	s_waitcnt lgkmcnt(0)
	s_waitcnt lgkmcnt(0)
	v_mfma_f32_16x16x32_bf16 v[24:27], v[64:67], v[0:3], v[60:63]
	v_mfma_f32_16x16x32_bf16 v[60:63], v[64:67], v[16:19], v[134:137]
	v_mfma_f32_16x16x32_bf16 v[134:137], v[76:79], v[0:3], v[170:173]
	v_mfma_f32_16x16x32_bf16 v[170:173], v[76:79], v[16:19], v[224:227]
	v_mfma_f32_16x16x32_bf16 v[44:47], v[196:199], v[0:3], v[44:47]
	v_mfma_f32_16x16x32_bf16 v[208:211], v[196:199], v[16:19], v[40:43]
	v_mfma_f32_16x16x32_bf16 v[0:3], v[204:207], v[0:3], v[36:39]
	v_mfma_f32_16x16x32_bf16 v[36:39], v[204:207], v[16:19], v[32:35]
	v_mfma_f32_16x16x32_bf16 v[72:75], v[178:181], v[8:11], v[24:27]
	v_mfma_f32_16x16x32_bf16 v[60:63], v[178:181], v[192:195], v[60:63]
	v_mfma_f32_16x16x32_bf16 v[40:43], v[182:185], v[8:11], v[134:137]
	v_mfma_f32_16x16x32_bf16 v[32:35], v[182:185], v[192:195], v[170:173]
	v_mfma_f32_16x16x32_bf16 v[24:27], v[200:203], v[8:11], v[44:47]
	v_mfma_f32_16x16x32_bf16 v[16:19], v[200:203], v[192:195], v[208:211]
	v_mfma_f32_16x16x32_bf16 v[8:11], v[150:153], v[8:11], v[0:3]
	v_mfma_f32_16x16x32_bf16 v[0:3], v[150:153], v[192:195], v[36:39]
	v_mfma_f32_16x16x32_bf16 v[28:31], v[64:67], v[220:223], v[28:31]
	v_mfma_f32_16x16x32_bf16 v[36:39], v[64:67], v[232:235], v[138:141]
	v_mfma_f32_16x16x32_bf16 v[20:23], v[76:79], v[220:223], v[20:23]
	v_mfma_f32_16x16x32_bf16 v[134:137], v[76:79], v[232:235], v[174:177]
	v_mfma_f32_16x16x32_bf16 v[12:15], v[196:199], v[220:223], v[12:15]
	v_mfma_f32_16x16x32_bf16 v[138:141], v[196:199], v[232:235], v[188:191]
	v_mfma_f32_16x16x32_bf16 v[4:7], v[204:207], v[220:223], v[4:7]
	v_mfma_f32_16x16x32_bf16 v[158:161], v[204:207], v[232:235], v[158:161]
	v_mfma_f32_16x16x32_bf16 v[76:79], v[178:181], v[228:231], v[28:31]
	v_mfma_f32_16x16x32_bf16 v[64:67], v[178:181], v[154:157], v[36:39]
	v_mfma_f32_16x16x32_bf16 v[44:47], v[182:185], v[228:231], v[20:23]
	v_mfma_f32_16x16x32_bf16 v[36:39], v[182:185], v[154:157], v[134:137]
	v_mfma_f32_16x16x32_bf16 v[28:31], v[200:203], v[228:231], v[12:15]
	v_mfma_f32_16x16x32_bf16 v[20:23], v[200:203], v[154:157], v[138:141]
	v_mfma_f32_16x16x32_bf16 v[12:15], v[150:153], v[228:231], v[4:7]
	v_mfma_f32_16x16x32_bf16 v[4:7], v[150:153], v[154:157], v[158:161]
	v_cmp_gt_u32_e32 vcc, s64, v130
	s_barrier
	s_and_saveexec_b64 s[48:49], vcc
	s_cbranch_execz .LBB0_343
	s_barrier

; #define STAGE(P, BASE, LD, br, kt) do { const char* _g = (const char*)((BASE) + (size_t)(br) * (LD) + (size_t)(kt) * 64); \
;     for (int _i = 0; _i < 2; ++_i) { int _b = tidx * 16 + _i * 8192; int _r, _c; stage_rc(_b, _r, _c); \
;       __builtin_amdgcn_global_load_lds((const unsigned*)(_g + (unsigned)((_r * (LD) + _c) * 2)), (unsigned*)((char*)(P) + _b), 16, 0, 0); } } while (0)
; #define LDA(dst, b, h) for (int m = 0; m < 4; ++m) for (int k = 0; k < 2; ++k) \
;     dst[m][k] = *reinterpret_cast<const bf16x8*>((char*)SA(b, h) + lds_byte(wr * 64 + m * 16 + fr, k * 32 + fq * 8))
; #define LDB(dst, b, h) for (int n = 0; n < 2; ++n) for (int k = 0; k < 2; ++k) \
;     dst[n][k] = *reinterpret_cast<const bf16x8*>((char*)SB(b, h) + lds_byte(wc * 32 + n * 16 + fr, k * 32 + fq * 8))
; #define MMA(ai, bj, At_, Bt_) do { __builtin_amdgcn_s_setprio(1); \
;     for (int k = 0; k < 2; ++k) for (int m = 0; m < 4; ++m) for (int n = 0; n < 2; ++n) \
;       acc[ai][bj][m][n] = __builtin_amdgcn_mfma_f32_16x16x32_bf16(At_[m][k], Bt_[n][k], acc[ai][bj][m][n], 0, 0, 0); \
;     __builtin_amdgcn_s_setprio(0); } while (0)
; #define WAIT_V(n) asm volatile("s_waitcnt vmcnt(" #n ")" ::: "memory")
; #define WAIT_L(n) asm volatile("s_waitcnt lgkmcnt(" #n ")" ::: "memory")
; #define BAR __builtin_amdgcn_s_barrier()
; #define SCHED __builtin_amdgcn_sched_barrier(0)
; template <int EPI, int lda, int ldb, int N, int K>
; __device__ __forceinline__ void gemm_phase(const u16* __restrict__ A, const u16* __restrict__ Bt, const GemmEpi ep, int wv) {
;     ...
;     for (int t = 0; t < nt - 2; t += 2) {
;       LDB(B0, 0, 0); SCHED; LDA(At, 0, 0); STAGE(SA(1, 1), Ab, lda, brow + HALF, t + 1);
;       WAIT_L(8); BAR; WAIT_L(0); MMA(0, 0, At, B0); BAR; SCHED;
;       LDB(B1, 0, 1); STAGE(SB(0, 0), Bt, ldb, bcol, t + 2);
;       BAR; WAIT_L(0); MMA(0, 1, At, B1); BAR;
;       LDA(At, 0, 1); STAGE(SA(0, 0), Ab, lda, brow, t + 2);
;       BAR; WAIT_L(0); MMA(1, 0, At, B0); BAR; SCHED;
;       STAGE(SB(0, 1), Bt, ldb, bcol + HALF, t + 2);
;       WAIT_V(6); BAR; MMA(1, 1, At, B1); BAR;
.LBB0_654:
	ds_read_b128 v[164:167], v160
	ds_read_b128 v[170:173], v160 offset:1024
	ds_read_b128 v[174:177], v160 offset:2048
	ds_read_b128 v[178:181], v160 offset:3072
	v_add_u32_e32 v168, 0xc000, v143
	v_lshl_add_u64 v[234:235], v[138:139], 0, s[52:53]
	v_readfirstlane_b32 s55, v168
	v_add_u32_e32 v169, 0xe000, v143
	v_lshl_add_u64 v[162:163], v[234:235], 0, s[20:21]
	s_mov_b32 m0, s55
	v_lshl_add_u64 v[236:237], v[140:141], 0, s[52:53]
	ds_read_b128 v[182:185], v151
	ds_read_b128 v[186:189], v151 offset:1024
	ds_read_b128 v[190:193], v150
	ds_read_b128 v[194:197], v150 offset:1024
	ds_read_b128 v[198:201], v149
	ds_read_b128 v[202:205], v149 offset:1024
	ds_read_b128 v[206:209], v148
	ds_read_b128 v[210:213], v148 offset:1024
	global_load_lds_dwordx4 v[162:163], off
	s_bitset1_b32 m0, 13
	v_lshl_add_u64 v[162:163], v[236:237], 0, s[20:21]
	global_load_lds_dwordx4 v[162:163], off
	s_waitcnt lgkmcnt(8)
	s_barrier
	s_waitcnt lgkmcnt(0)
	s_waitcnt lgkmcnt(0)
	v_mfma_f32_16x16x32_bf16 v[124:127], v[164:167], v[182:185], v[124:127]
	v_mfma_f32_16x16x32_bf16 v[120:123], v[174:177], v[182:185], v[120:123]
	v_mfma_f32_16x16x32_bf16 v[116:119], v[164:167], v[190:193], v[116:119]
	v_mfma_f32_16x16x32_bf16 v[112:115], v[174:177], v[190:193], v[112:115]
	v_mfma_f32_16x16x32_bf16 v[108:111], v[164:167], v[198:201], v[108:111]
	v_mfma_f32_16x16x32_bf16 v[104:107], v[174:177], v[198:201], v[104:107]
	v_mfma_f32_16x16x32_bf16 v[100:103], v[164:167], v[206:209], v[100:103]
	v_mfma_f32_16x16x32_bf16 v[96:99], v[174:177], v[206:209], v[96:99]
	v_mfma_f32_16x16x32_bf16 v[124:127], v[170:173], v[186:189], v[124:127]
	v_mfma_f32_16x16x32_bf16 v[120:123], v[178:181], v[186:189], v[120:123]
	v_mfma_f32_16x16x32_bf16 v[116:119], v[170:173], v[194:197], v[116:119]
	v_mfma_f32_16x16x32_bf16 v[112:115], v[178:181], v[194:197], v[112:115]
	v_mfma_f32_16x16x32_bf16 v[108:111], v[170:173], v[202:205], v[108:111]
	v_mfma_f32_16x16x32_bf16 v[104:107], v[178:181], v[202:205], v[104:107]
	v_mfma_f32_16x16x32_bf16 v[100:103], v[170:173], v[210:213], v[100:103]
	v_mfma_f32_16x16x32_bf16 v[96:99], v[178:181], v[210:213], v[96:99]
	s_barrier
	v_add_u32_e32 v161, s65, v153
	v_lshl_add_u64 v[238:239], v[134:135], 0, s[52:53]
	v_readfirstlane_b32 s55, v161
	v_lshl_add_u64 v[162:163], v[238:239], 0, s[22:23]
	s_mov_b32 m0, s55
	ds_read_b128 v[214:217], v159
	ds_read_b128 v[218:221], v159 offset:1024
	ds_read_b128 v[222:225], v159 offset:2048
	ds_read_b128 v[226:229], v159 offset:3072
	global_load_lds_dwordx4 v[162:163], off
	s_bitset1_b32 m0, 13
	v_add_u32_e32 v162, 0x2000, v161
	v_lshl_add_u64 v[240:241], v[136:137], 0, s[52:53]
	v_lshl_add_u64 v[230:231], v[240:241], 0, s[22:23]
	global_load_lds_dwordx4 v[230:231], off
	s_barrier
	s_waitcnt lgkmcnt(0)
	s_waitcnt lgkmcnt(0)
	v_mfma_f32_16x16x32_bf16 v[92:95], v[214:217], v[182:185], v[92:95]
	v_mfma_f32_16x16x32_bf16 v[88:91], v[222:225], v[182:185], v[88:91]
	v_mfma_f32_16x16x32_bf16 v[84:87], v[214:217], v[190:193], v[84:87]
	v_mfma_f32_16x16x32_bf16 v[80:83], v[222:225], v[190:193], v[80:83]
	v_mfma_f32_16x16x32_bf16 v[76:79], v[214:217], v[198:201], v[76:79]
	v_mfma_f32_16x16x32_bf16 v[72:75], v[222:225], v[198:201], v[72:75]
	v_mfma_f32_16x16x32_bf16 v[68:71], v[214:217], v[206:209], v[68:71]
	v_mfma_f32_16x16x32_bf16 v[64:67], v[222:225], v[206:209], v[64:67]
	v_mfma_f32_16x16x32_bf16 v[92:95], v[218:221], v[186:189], v[92:95]
	v_mfma_f32_16x16x32_bf16 v[88:91], v[226:229], v[186:189], v[88:91]
	v_mfma_f32_16x16x32_bf16 v[84:87], v[218:221], v[194:197], v[84:87]
	v_mfma_f32_16x16x32_bf16 v[80:83], v[226:229], v[194:197], v[80:83]
	v_mfma_f32_16x16x32_bf16 v[76:79], v[218:221], v[202:205], v[76:79]
	v_mfma_f32_16x16x32_bf16 v[72:75], v[226:229], v[202:205], v[72:75]
	v_mfma_f32_16x16x32_bf16 v[68:71], v[218:221], v[210:213], v[68:71]
	v_mfma_f32_16x16x32_bf16 v[64:67], v[226:229], v[210:213], v[64:67]
	v_readfirstlane_b32 s55, v143
	v_add_u32_e32 v163, 0x2000, v143
	v_lshl_add_u64 v[230:231], v[234:235], 0, s[24:25]
	s_mov_b32 m0, s55
	s_barrier
	ds_read_b128 v[182:185], v151 offset:16384
	ds_read_b128 v[186:189], v151 offset:17408
	ds_read_b128 v[190:193], v150 offset:16384
	ds_read_b128 v[194:197], v150 offset:17408
	ds_read_b128 v[198:201], v149 offset:16384
	ds_read_b128 v[202:205], v149 offset:17408
	ds_read_b128 v[206:209], v148 offset:16384
	ds_read_b128 v[210:213], v148 offset:17408
	global_load_lds_dwordx4 v[230:231], off
	s_bitset1_b32 m0, 13
	v_lshl_add_u64 v[230:231], v[236:237], 0, s[24:25]
	global_load_lds_dwordx4 v[230:231], off
	s_barrier
	s_waitcnt lgkmcnt(0)
	s_waitcnt lgkmcnt(0)
	v_mfma_f32_16x16x32_bf16 v[60:63], v[164:167], v[182:185], v[60:63]
	v_mfma_f32_16x16x32_bf16 v[56:59], v[174:177], v[182:185], v[56:59]
	v_mfma_f32_16x16x32_bf16 v[52:55], v[164:167], v[190:193], v[52:55]
	v_mfma_f32_16x16x32_bf16 v[48:51], v[174:177], v[190:193], v[48:51]
	v_mfma_f32_16x16x32_bf16 v[44:47], v[164:167], v[198:201], v[44:47]
	v_mfma_f32_16x16x32_bf16 v[40:43], v[174:177], v[198:201], v[40:43]
	v_mfma_f32_16x16x32_bf16 v[36:39], v[164:167], v[206:209], v[36:39]
	v_mfma_f32_16x16x32_bf16 v[32:35], v[174:177], v[206:209], v[32:35]
	v_mfma_f32_16x16x32_bf16 v[60:63], v[170:173], v[186:189], v[60:63]
	v_mfma_f32_16x16x32_bf16 v[56:59], v[178:181], v[186:189], v[56:59]
	v_mfma_f32_16x16x32_bf16 v[52:55], v[170:173], v[194:197], v[52:55]
	v_mfma_f32_16x16x32_bf16 v[48:51], v[178:181], v[194:197], v[48:51]
	v_mfma_f32_16x16x32_bf16 v[44:47], v[170:173], v[202:205], v[44:47]
	v_mfma_f32_16x16x32_bf16 v[40:43], v[178:181], v[202:205], v[40:43]
	v_mfma_f32_16x16x32_bf16 v[36:39], v[170:173], v[210:213], v[36:39]
	v_mfma_f32_16x16x32_bf16 v[32:35], v[178:181], v[210:213], v[32:35]
	s_barrier
; #define STAGE(P, BASE, LD, br, kt) do { const char* _g = (const char*)((BASE) + (size_t)(br) * (LD) + (size_t)(kt) * 64); \
;     for (int _i = 0; _i < 2; ++_i) { int _b = tidx * 16 + _i * 8192; int _r, _c; stage_rc(_b, _r, _c); \
;       __builtin_amdgcn_global_load_lds((const unsigned*)(_g + (unsigned)((_r * (LD) + _c) * 2)), (unsigned*)((char*)(P) + _b), 16, 0, 0); } } while (0)
; #define LDA(dst, b, h) for (int m = 0; m < 4; ++m) for (int k = 0; k < 2; ++k) \
;     dst[m][k] = *reinterpret_cast<const bf16x8*>((char*)SA(b, h) + lds_byte(wr * 64 + m * 16 + fr, k * 32 + fq * 8))
; #define LDB(dst, b, h) for (int n = 0; n < 2; ++n) for (int k = 0; k < 2; ++k) \
;     dst[n][k] = *reinterpret_cast<const bf16x8*>((char*)SB(b, h) + lds_byte(wc * 32 + n * 16 + fr, k * 32 + fq * 8))
; #define MMA(ai, bj, At_, Bt_) do { __builtin_amdgcn_s_setprio(1); \
;     for (int k = 0; k < 2; ++k) for (int m = 0; m < 4; ++m) for (int n = 0; n < 2; ++n) \
;       acc[ai][bj][m][n] = __builtin_amdgcn_mfma_f32_16x16x32_bf16(At_[m][k], Bt_[n][k], acc[ai][bj][m][n], 0, 0, 0); \
;     __builtin_amdgcn_s_setprio(0); } while (0)
; #define WAIT_V(n) asm volatile("s_waitcnt vmcnt(" #n ")" ::: "memory")
; #define WAIT_L(n) asm volatile("s_waitcnt lgkmcnt(" #n ")" ::: "memory")
; #define BAR __builtin_amdgcn_s_barrier()
; #define SCHED __builtin_amdgcn_sched_barrier(0)
; template <int EPI, int lda, int ldb, int N, int K>
; __device__ __forceinline__ void gemm_phase(const u16* __restrict__ A, const u16* __restrict__ Bt, const GemmEpi ep, int wv) {
;     ...
;       WAIT_V(6); BAR; MMA(1, 1, At, B1); BAR;
;       LDB(B0, 1, 0); SCHED; LDA(At, 1, 0); STAGE(SA(0, 1), Ab, lda, brow + HALF, t + 2);
;       WAIT_L(8); BAR; WAIT_L(0); MMA(0, 0, At, B0); BAR; SCHED;
;       LDB(B1, 1, 1); STAGE(SB(1, 0), Bt, ldb, bcol, t + 3);
;       BAR; WAIT_L(0); MMA(0, 1, At, B1); BAR;
;       LDA(At, 1, 1); STAGE(SA(1, 0), Ab, lda, brow, t + 3);
;       BAR; WAIT_L(0); MMA(1, 0, At, B0); BAR; SCHED;
;       STAGE(SB(1, 1), Bt, ldb, bcol + HALF, t + 3);
;       WAIT_V(6); BAR; MMA(1, 1, At, B1); BAR;
	v_add_u32_e32 v164, s66, v153
	v_add_u32_e32 v165, 0x2000, v164
	v_readfirstlane_b32 s55, v164
	v_lshl_add_u64 v[166:167], v[238:239], 0, s[26:27]
	s_mov_b32 m0, s55
	global_load_lds_dwordx4 v[166:167], off
	s_bitset1_b32 m0, 13
	v_lshl_add_u64 v[166:167], v[240:241], 0, s[26:27]
	global_load_lds_dwordx4 v[166:167], off
	s_waitcnt vmcnt(6)
	s_barrier
	v_mfma_f32_16x16x32_bf16 v[28:31], v[214:217], v[182:185], v[28:31]
	v_mfma_f32_16x16x32_bf16 v[24:27], v[222:225], v[182:185], v[24:27]
	v_mfma_f32_16x16x32_bf16 v[20:23], v[214:217], v[190:193], v[20:23]
	v_mfma_f32_16x16x32_bf16 v[16:19], v[222:225], v[190:193], v[16:19]
	v_mfma_f32_16x16x32_bf16 v[12:15], v[214:217], v[198:201], v[12:15]
	v_mfma_f32_16x16x32_bf16 v[8:11], v[222:225], v[198:201], v[8:11]
	v_mfma_f32_16x16x32_bf16 v[4:7], v[214:217], v[206:209], v[4:7]
	v_mfma_f32_16x16x32_bf16 v[0:3], v[222:225], v[206:209], v[0:3]
	v_mfma_f32_16x16x32_bf16 v[28:31], v[218:221], v[186:189], v[28:31]
	v_mfma_f32_16x16x32_bf16 v[24:27], v[226:229], v[186:189], v[24:27]
	v_mfma_f32_16x16x32_bf16 v[20:23], v[218:221], v[194:197], v[20:23]
	v_mfma_f32_16x16x32_bf16 v[16:19], v[226:229], v[194:197], v[16:19]
	v_mfma_f32_16x16x32_bf16 v[12:15], v[218:221], v[202:205], v[12:15]
	v_mfma_f32_16x16x32_bf16 v[8:11], v[226:229], v[202:205], v[8:11]
	v_mfma_f32_16x16x32_bf16 v[4:7], v[218:221], v[210:213], v[4:7]
	v_mfma_f32_16x16x32_bf16 v[0:3], v[226:229], v[210:213], v[0:3]
	s_barrier
	ds_read_b128 v[170:173], v154
	ds_read_b128 v[174:177], v154 offset:1024
	ds_read_b128 v[178:181], v154 offset:2048
	ds_read_b128 v[182:185], v154 offset:3072
	v_add_u32_e32 v166, 0x4000, v143
	v_add_u32_e32 v167, 0x6000, v143
	v_readfirstlane_b32 s55, v166
	v_lshl_add_u64 v[218:219], v[234:235], 0, s[42:43]
	s_mov_b32 m0, s55
	ds_read_b128 v[186:189], v151 offset:32768
	ds_read_b128 v[190:193], v151 offset:33792
	ds_read_b128 v[194:197], v150 offset:32768
	ds_read_b128 v[198:201], v150 offset:33792
	ds_read_b128 v[202:205], v149 offset:32768
	ds_read_b128 v[206:209], v149 offset:33792
	ds_read_b128 v[210:213], v148 offset:32768
	ds_read_b128 v[214:217], v148 offset:33792
	global_load_lds_dwordx4 v[218:219], off
	s_bitset1_b32 m0, 13
	v_lshl_add_u64 v[218:219], v[236:237], 0, s[42:43]
	global_load_lds_dwordx4 v[218:219], off
	s_waitcnt lgkmcnt(8)
	s_barrier
	s_waitcnt lgkmcnt(0)
	s_waitcnt lgkmcnt(0)
	v_mfma_f32_16x16x32_bf16 v[124:127], v[170:173], v[186:189], v[124:127]
	v_mfma_f32_16x16x32_bf16 v[120:123], v[178:181], v[186:189], v[120:123]
	v_mfma_f32_16x16x32_bf16 v[116:119], v[170:173], v[194:197], v[116:119]
	v_mfma_f32_16x16x32_bf16 v[112:115], v[178:181], v[194:197], v[112:115]
	v_mfma_f32_16x16x32_bf16 v[108:111], v[170:173], v[202:205], v[108:111]
	v_mfma_f32_16x16x32_bf16 v[104:107], v[178:181], v[202:205], v[104:107]
	v_mfma_f32_16x16x32_bf16 v[100:103], v[170:173], v[210:213], v[100:103]
	v_mfma_f32_16x16x32_bf16 v[96:99], v[178:181], v[210:213], v[96:99]
	v_mfma_f32_16x16x32_bf16 v[124:127], v[174:177], v[190:193], v[124:127]
	v_mfma_f32_16x16x32_bf16 v[120:123], v[182:185], v[190:193], v[120:123]
	v_mfma_f32_16x16x32_bf16 v[116:119], v[174:177], v[198:201], v[116:119]
	v_mfma_f32_16x16x32_bf16 v[112:115], v[182:185], v[198:201], v[112:115]
	v_mfma_f32_16x16x32_bf16 v[108:111], v[174:177], v[206:209], v[108:111]
	v_mfma_f32_16x16x32_bf16 v[104:107], v[182:185], v[206:209], v[104:107]
	v_mfma_f32_16x16x32_bf16 v[100:103], v[174:177], v[214:217], v[100:103]
	v_mfma_f32_16x16x32_bf16 v[96:99], v[182:185], v[214:217], v[96:99]
	s_barrier
	v_readfirstlane_b32 s55, v155
	v_add_u32_e32 v244, 0x2000, v155
	v_lshl_add_u64 v[242:243], v[238:239], 0, s[44:45]
	s_mov_b32 m0, s55
	ds_read_b128 v[218:221], v152
	ds_read_b128 v[222:225], v152 offset:1024
	ds_read_b128 v[226:229], v152 offset:2048
	ds_read_b128 v[230:233], v152 offset:3072
	global_load_lds_dwordx4 v[242:243], off
	s_bitset1_b32 m0, 13
	v_lshl_add_u64 v[242:243], v[240:241], 0, s[44:45]
	global_load_lds_dwordx4 v[242:243], off
	s_barrier
	s_waitcnt lgkmcnt(0)
	s_waitcnt lgkmcnt(0)
	v_mfma_f32_16x16x32_bf16 v[92:95], v[218:221], v[186:189], v[92:95]
	v_mfma_f32_16x16x32_bf16 v[88:91], v[226:229], v[186:189], v[88:91]
	v_mfma_f32_16x16x32_bf16 v[84:87], v[218:221], v[194:197], v[84:87]
	v_mfma_f32_16x16x32_bf16 v[80:83], v[226:229], v[194:197], v[80:83]
	v_mfma_f32_16x16x32_bf16 v[76:79], v[218:221], v[202:205], v[76:79]
	v_mfma_f32_16x16x32_bf16 v[72:75], v[226:229], v[202:205], v[72:75]
	v_mfma_f32_16x16x32_bf16 v[68:71], v[218:221], v[210:213], v[68:71]
	v_mfma_f32_16x16x32_bf16 v[64:67], v[226:229], v[210:213], v[64:67]
	v_mfma_f32_16x16x32_bf16 v[92:95], v[222:225], v[190:193], v[92:95]
	v_mfma_f32_16x16x32_bf16 v[88:91], v[230:233], v[190:193], v[88:91]
	v_mfma_f32_16x16x32_bf16 v[84:87], v[222:225], v[198:201], v[84:87]
	v_mfma_f32_16x16x32_bf16 v[80:83], v[230:233], v[198:201], v[80:83]
	v_mfma_f32_16x16x32_bf16 v[76:79], v[222:225], v[206:209], v[76:79]
	v_mfma_f32_16x16x32_bf16 v[72:75], v[230:233], v[206:209], v[72:75]
	v_mfma_f32_16x16x32_bf16 v[68:71], v[222:225], v[214:217], v[68:71]
	v_mfma_f32_16x16x32_bf16 v[64:67], v[230:233], v[214:217], v[64:67]
	v_readfirstlane_b32 s55, v156
	v_lshl_add_u64 v[234:235], v[234:235], 0, s[46:47]
	s_mov_b32 m0, s55
	s_barrier
	ds_read_b128 v[186:189], v151 offset:49152
	ds_read_b128 v[190:193], v151 offset:50176
	ds_read_b128 v[194:197], v150 offset:49152
	ds_read_b128 v[198:201], v150 offset:50176
	ds_read_b128 v[202:205], v149 offset:49152
	ds_read_b128 v[206:209], v149 offset:50176
	ds_read_b128 v[210:213], v148 offset:49152
	ds_read_b128 v[214:217], v148 offset:50176
	global_load_lds_dwordx4 v[234:235], off
	s_bitset1_b32 m0, 13
	v_lshl_add_u64 v[234:235], v[236:237], 0, s[46:47]
	global_load_lds_dwordx4 v[234:235], off
	s_barrier
; #define STAGE(P, BASE, LD, br, kt) do { const char* _g = (const char*)((BASE) + (size_t)(br) * (LD) + (size_t)(kt) * 64); \
;     for (int _i = 0; _i < 2; ++_i) { int _b = tidx * 16 + _i * 8192; int _r, _c; stage_rc(_b, _r, _c); \
;       __builtin_amdgcn_global_load_lds((const unsigned*)(_g + (unsigned)((_r * (LD) + _c) * 2)), (unsigned*)((char*)(P) + _b), 16, 0, 0); } } while (0)
; #define LDA(dst, b, h) for (int m = 0; m < 4; ++m) for (int k = 0; k < 2; ++k) \
;     dst[m][k] = *reinterpret_cast<const bf16x8*>((char*)SA(b, h) + lds_byte(wr * 64 + m * 16 + fr, k * 32 + fq * 8))
; #define LDB(dst, b, h) for (int n = 0; n < 2; ++n) for (int k = 0; k < 2; ++k) \
;     dst[n][k] = *reinterpret_cast<const bf16x8*>((char*)SB(b, h) + lds_byte(wc * 32 + n * 16 + fr, k * 32 + fq * 8))
; #define MMA(ai, bj, At_, Bt_) do { __builtin_amdgcn_s_setprio(1); \
;     for (int k = 0; k < 2; ++k) for (int m = 0; m < 4; ++m) for (int n = 0; n < 2; ++n) \
;       acc[ai][bj][m][n] = __builtin_amdgcn_mfma_f32_16x16x32_bf16(At_[m][k], Bt_[n][k], acc[ai][bj][m][n], 0, 0, 0); \
;     __builtin_amdgcn_s_setprio(0); } while (0)
; #define WAIT_V(n) asm volatile("s_waitcnt vmcnt(" #n ")" ::: "memory")
; #define WAIT_L(n) asm volatile("s_waitcnt lgkmcnt(" #n ")" ::: "memory")
; #define BAR __builtin_amdgcn_s_barrier()
; #define SCHED __builtin_amdgcn_sched_barrier(0)
; template <int EPI, int lda, int ldb, int N, int K>
; __device__ __forceinline__ void gemm_phase(const u16* __restrict__ A, const u16* __restrict__ Bt, const GemmEpi ep, int wv) {
;     ...
;       BAR; WAIT_L(0); MMA(1, 0, At, B0); BAR; SCHED;
;       STAGE(SB(1, 1), Bt, ldb, bcol + HALF, t + 3);
;       WAIT_V(6); BAR; MMA(1, 1, At, B1); BAR;
;     }
;     { LDB(B0, 0, 0); LDA(At, 0, 0); STAGE(SA(1, 1), Ab, lda, brow + HALF, nt - 1);
;       BAR; WAIT_L(0); MMA(0, 0, At, B0); BAR;
;       LDB(B1, 0, 1); BAR; WAIT_L(0); MMA(0, 1, At, B1); BAR;
;       LDA(At, 0, 1); WAIT_V(4); BAR; WAIT_L(0); MMA(1, 0, At, B0); MMA(1, 1, At, B1); BAR; }
;     { LDB(B0, 1, 0); LDA(At, 1, 0); WAIT_V(2); BAR; WAIT_L(0); MMA(0, 0, At, B0); BAR;
	s_waitcnt lgkmcnt(0)
	s_waitcnt lgkmcnt(0)
	v_mfma_f32_16x16x32_bf16 v[60:63], v[170:173], v[186:189], v[60:63]
	v_mfma_f32_16x16x32_bf16 v[56:59], v[178:181], v[186:189], v[56:59]
	v_mfma_f32_16x16x32_bf16 v[52:55], v[170:173], v[194:197], v[52:55]
	v_mfma_f32_16x16x32_bf16 v[48:51], v[178:181], v[194:197], v[48:51]
	v_mfma_f32_16x16x32_bf16 v[44:47], v[170:173], v[202:205], v[44:47]
	v_mfma_f32_16x16x32_bf16 v[40:43], v[178:181], v[202:205], v[40:43]
	v_mfma_f32_16x16x32_bf16 v[36:39], v[170:173], v[210:213], v[36:39]
	v_mfma_f32_16x16x32_bf16 v[32:35], v[178:181], v[210:213], v[32:35]
	v_mfma_f32_16x16x32_bf16 v[60:63], v[174:177], v[190:193], v[60:63]
	v_mfma_f32_16x16x32_bf16 v[56:59], v[182:185], v[190:193], v[56:59]
	v_mfma_f32_16x16x32_bf16 v[52:55], v[174:177], v[198:201], v[52:55]
	v_mfma_f32_16x16x32_bf16 v[48:51], v[182:185], v[198:201], v[48:51]
	v_mfma_f32_16x16x32_bf16 v[44:47], v[174:177], v[206:209], v[44:47]
	v_mfma_f32_16x16x32_bf16 v[40:43], v[182:185], v[206:209], v[40:43]
	v_mfma_f32_16x16x32_bf16 v[36:39], v[174:177], v[214:217], v[36:39]
	v_mfma_f32_16x16x32_bf16 v[32:35], v[182:185], v[214:217], v[32:35]
	s_barrier
	v_readfirstlane_b32 s55, v158
	v_add_u32_e32 v172, 0x2000, v158
	v_lshl_add_u64 v[170:171], v[238:239], 0, s[48:49]
	s_mov_b32 m0, s55
	global_load_lds_dwordx4 v[170:171], off
	s_bitset1_b32 m0, 13
	v_lshl_add_u64 v[170:171], v[240:241], 0, s[48:49]
	global_load_lds_dwordx4 v[170:171], off
	s_waitcnt vmcnt(6)
	s_barrier
	v_mfma_f32_16x16x32_bf16 v[28:31], v[218:221], v[186:189], v[28:31]
	v_mfma_f32_16x16x32_bf16 v[24:27], v[226:229], v[186:189], v[24:27]
	v_mfma_f32_16x16x32_bf16 v[20:23], v[218:221], v[194:197], v[20:23]
	v_mfma_f32_16x16x32_bf16 v[16:19], v[226:229], v[194:197], v[16:19]
	v_mfma_f32_16x16x32_bf16 v[12:15], v[218:221], v[202:205], v[12:15]
	v_mfma_f32_16x16x32_bf16 v[8:11], v[226:229], v[202:205], v[8:11]
	v_mfma_f32_16x16x32_bf16 v[4:7], v[218:221], v[210:213], v[4:7]
	v_mfma_f32_16x16x32_bf16 v[0:3], v[226:229], v[210:213], v[0:3]
	v_mfma_f32_16x16x32_bf16 v[28:31], v[222:225], v[190:193], v[28:31]
	v_mfma_f32_16x16x32_bf16 v[24:27], v[230:233], v[190:193], v[24:27]
	v_mfma_f32_16x16x32_bf16 v[20:23], v[222:225], v[198:201], v[20:23]
	v_mfma_f32_16x16x32_bf16 v[16:19], v[230:233], v[198:201], v[16:19]
	v_mfma_f32_16x16x32_bf16 v[12:15], v[222:225], v[206:209], v[12:15]
	v_mfma_f32_16x16x32_bf16 v[8:11], v[230:233], v[206:209], v[8:11]
	v_mfma_f32_16x16x32_bf16 v[4:7], v[222:225], v[214:217], v[4:7]
	v_mfma_f32_16x16x32_bf16 v[0:3], v[230:233], v[214:217], v[0:3]
	s_add_i32 s54, s54, 2
	s_add_u32 s52, s52, 0x100
	s_addc_u32 s53, s53, 0
	s_cmp_gt_u32 s54, 27
	s_barrier
	s_cbranch_scc0 .LBB0_654
	s_lshl_b64 s[52:53], s[16:17], 12
	s_add_u32 s52, s14, s52
	s_addc_u32 s53, s15, s53
	s_add_u32 s52, s52, 0x80000
	s_addc_u32 s53, s53, 0
	v_lshl_add_u64 v[156:157], s[52:53], 0, v[128:129]
	v_readfirstlane_b32 s54, v168
	v_lshl_add_u64 v[156:157], v[156:157], 0, s[50:51]
	s_mov_b32 m0, s54
	ds_read_b128 v[134:137], v160
	ds_read_b128 v[138:141], v160 offset:1024
	ds_read_b128 v[170:173], v160 offset:2048
	ds_read_b128 v[174:177], v160 offset:3072
	ds_read_b128 v[178:181], v151
	ds_read_b128 v[182:185], v151 offset:1024
	ds_read_b128 v[186:189], v150
	ds_read_b128 v[190:193], v150 offset:1024
	ds_read_b128 v[194:197], v149
	ds_read_b128 v[198:201], v149 offset:1024
	ds_read_b128 v[202:205], v148
	ds_read_b128 v[206:209], v148 offset:1024
	global_load_lds_dwordx4 v[156:157], off
	v_lshl_add_u64 v[156:157], s[52:53], 0, v[132:133]
	v_readfirstlane_b32 s52, v169
	v_lshl_add_u64 v[156:157], v[156:157], 0, s[50:51]
	s_mov_b32 m0, s52
	s_nop 0
	global_load_lds_dwordx4 v[156:157], off
	s_barrier
	s_waitcnt lgkmcnt(0)
	s_waitcnt lgkmcnt(0)
	v_mfma_f32_16x16x32_bf16 v[124:127], v[134:137], v[178:181], v[124:127]
	v_mfma_f32_16x16x32_bf16 v[120:123], v[170:173], v[178:181], v[120:123]
	v_mfma_f32_16x16x32_bf16 v[116:119], v[134:137], v[186:189], v[116:119]
	v_mfma_f32_16x16x32_bf16 v[112:115], v[170:173], v[186:189], v[112:115]
	v_mfma_f32_16x16x32_bf16 v[108:111], v[134:137], v[194:197], v[108:111]
	v_mfma_f32_16x16x32_bf16 v[104:107], v[170:173], v[194:197], v[104:107]
	v_mfma_f32_16x16x32_bf16 v[100:103], v[134:137], v[202:205], v[100:103]
	v_mfma_f32_16x16x32_bf16 v[96:99], v[170:173], v[202:205], v[96:99]
	v_mfma_f32_16x16x32_bf16 v[124:127], v[138:141], v[182:185], v[124:127]
	v_mfma_f32_16x16x32_bf16 v[120:123], v[174:177], v[182:185], v[120:123]
	v_mfma_f32_16x16x32_bf16 v[116:119], v[138:141], v[190:193], v[116:119]
	v_mfma_f32_16x16x32_bf16 v[112:115], v[174:177], v[190:193], v[112:115]
	v_mfma_f32_16x16x32_bf16 v[108:111], v[138:141], v[198:201], v[108:111]
	v_mfma_f32_16x16x32_bf16 v[104:107], v[174:177], v[198:201], v[104:107]
	v_mfma_f32_16x16x32_bf16 v[100:103], v[138:141], v[206:209], v[100:103]
	v_mfma_f32_16x16x32_bf16 v[96:99], v[174:177], v[206:209], v[96:99]
	s_barrier
	ds_read_b128 v[210:213], v159
	ds_read_b128 v[214:217], v159 offset:1024
	ds_read_b128 v[218:221], v159 offset:2048
	ds_read_b128 v[156:159], v159 offset:3072
	s_barrier
; #define LDA(dst, b, h) for (int m = 0; m < 4; ++m) for (int k = 0; k < 2; ++k) \
;     dst[m][k] = *reinterpret_cast<const bf16x8*>((char*)SA(b, h) + lds_byte(wr * 64 + m * 16 + fr, k * 32 + fq * 8))
; #define LDB(dst, b, h) for (int n = 0; n < 2; ++n) for (int k = 0; k < 2; ++k) \
;     dst[n][k] = *reinterpret_cast<const bf16x8*>((char*)SB(b, h) + lds_byte(wc * 32 + n * 16 + fr, k * 32 + fq * 8))
; #define MMA(ai, bj, At_, Bt_) do { __builtin_amdgcn_s_setprio(1); \
;     for (int k = 0; k < 2; ++k) for (int m = 0; m < 4; ++m) for (int n = 0; n < 2; ++n) \
;       acc[ai][bj][m][n] = __builtin_amdgcn_mfma_f32_16x16x32_bf16(At_[m][k], Bt_[n][k], acc[ai][bj][m][n], 0, 0, 0); \
;     __builtin_amdgcn_s_setprio(0); } while (0)
; #define WAIT_V(n) asm volatile("s_waitcnt vmcnt(" #n ")" ::: "memory")
; #define WAIT_L(n) asm volatile("s_waitcnt lgkmcnt(" #n ")" ::: "memory")
; #define BAR __builtin_amdgcn_s_barrier()
; template <int EPI, int lda, int ldb, int N, int K>
; __device__ __forceinline__ void gemm_phase(const u16* __restrict__ A, const u16* __restrict__ Bt, const GemmEpi ep, int wv) {
;     ...
;       BAR; WAIT_L(0); MMA(0, 0, At, B0); BAR;
;       LDB(B1, 0, 1); BAR; WAIT_L(0); MMA(0, 1, At, B1); BAR;
;       LDA(At, 0, 1); WAIT_V(4); BAR; WAIT_L(0); MMA(1, 0, At, B0); MMA(1, 1, At, B1); BAR; }
;     { LDB(B0, 1, 0); LDA(At, 1, 0); WAIT_V(2); BAR; WAIT_L(0); MMA(0, 0, At, B0); BAR;
;       LDB(B1, 1, 1); WAIT_V(0); BAR; WAIT_L(0); MMA(0, 1, At, B1); BAR;
	s_waitcnt lgkmcnt(0)
	s_waitcnt lgkmcnt(0)
	v_mfma_f32_16x16x32_bf16 v[92:95], v[210:213], v[178:181], v[92:95]
	v_mfma_f32_16x16x32_bf16 v[88:91], v[218:221], v[178:181], v[88:91]
	v_mfma_f32_16x16x32_bf16 v[76:79], v[210:213], v[194:197], v[76:79]
	v_mfma_f32_16x16x32_bf16 v[72:75], v[218:221], v[194:197], v[72:75]
	v_mfma_f32_16x16x32_bf16 v[84:87], v[210:213], v[186:189], v[84:87]
	v_mfma_f32_16x16x32_bf16 v[80:83], v[218:221], v[186:189], v[80:83]
	v_mfma_f32_16x16x32_bf16 v[68:71], v[210:213], v[202:205], v[68:71]
	v_mfma_f32_16x16x32_bf16 v[64:67], v[218:221], v[202:205], v[64:67]
	v_mfma_f32_16x16x32_bf16 v[92:95], v[214:217], v[182:185], v[92:95]
	v_mfma_f32_16x16x32_bf16 v[88:91], v[156:159], v[182:185], v[88:91]
	v_mfma_f32_16x16x32_bf16 v[76:79], v[214:217], v[198:201], v[76:79]
	v_mfma_f32_16x16x32_bf16 v[72:75], v[156:159], v[198:201], v[72:75]
	v_mfma_f32_16x16x32_bf16 v[178:181], v[214:217], v[190:193], v[84:87]
	v_mfma_f32_16x16x32_bf16 v[182:185], v[156:159], v[190:193], v[80:83]
	v_mfma_f32_16x16x32_bf16 v[186:189], v[214:217], v[206:209], v[68:71]
	v_mfma_f32_16x16x32_bf16 v[190:193], v[156:159], v[206:209], v[64:67]
	s_barrier
	s_nop 0
	ds_read_b128 v[64:67], v151 offset:16384
	ds_read_b128 v[68:71], v151 offset:17408
	ds_read_b128 v[80:83], v150 offset:16384
	ds_read_b128 v[84:87], v150 offset:17408
	ds_read_b128 v[194:197], v149 offset:16384
	ds_read_b128 v[198:201], v149 offset:17408
	ds_read_b128 v[202:205], v148 offset:16384
	ds_read_b128 v[206:209], v148 offset:17408
	s_waitcnt vmcnt(4)
	s_barrier
	s_waitcnt lgkmcnt(0)
	s_waitcnt lgkmcnt(0)
	v_mfma_f32_16x16x32_bf16 v[60:63], v[134:137], v[64:67], v[60:63]
	v_mfma_f32_16x16x32_bf16 v[56:59], v[170:173], v[64:67], v[56:59]
	v_mfma_f32_16x16x32_bf16 v[52:55], v[134:137], v[80:83], v[52:55]
	v_mfma_f32_16x16x32_bf16 v[48:51], v[170:173], v[80:83], v[48:51]
	v_mfma_f32_16x16x32_bf16 v[44:47], v[134:137], v[194:197], v[44:47]
	v_mfma_f32_16x16x32_bf16 v[40:43], v[170:173], v[194:197], v[40:43]
	v_mfma_f32_16x16x32_bf16 v[36:39], v[134:137], v[202:205], v[36:39]
	v_mfma_f32_16x16x32_bf16 v[32:35], v[170:173], v[202:205], v[32:35]
	v_mfma_f32_16x16x32_bf16 v[60:63], v[138:141], v[68:71], v[60:63]
	v_mfma_f32_16x16x32_bf16 v[56:59], v[174:177], v[68:71], v[56:59]
	v_mfma_f32_16x16x32_bf16 v[52:55], v[138:141], v[84:87], v[52:55]
	v_mfma_f32_16x16x32_bf16 v[48:51], v[174:177], v[84:87], v[48:51]
	v_mfma_f32_16x16x32_bf16 v[44:47], v[138:141], v[198:201], v[44:47]
	v_mfma_f32_16x16x32_bf16 v[40:43], v[174:177], v[198:201], v[40:43]
	v_mfma_f32_16x16x32_bf16 v[36:39], v[138:141], v[206:209], v[36:39]
	v_mfma_f32_16x16x32_bf16 v[32:35], v[174:177], v[206:209], v[32:35]
	v_mfma_f32_16x16x32_bf16 v[28:31], v[210:213], v[64:67], v[28:31]
	v_mfma_f32_16x16x32_bf16 v[20:23], v[210:213], v[80:83], v[20:23]
	v_mfma_f32_16x16x32_bf16 v[12:15], v[210:213], v[194:197], v[12:15]
	v_mfma_f32_16x16x32_bf16 v[4:7], v[210:213], v[202:205], v[4:7]
	v_mfma_f32_16x16x32_bf16 v[24:27], v[218:221], v[64:67], v[24:27]
	v_mfma_f32_16x16x32_bf16 v[16:19], v[218:221], v[80:83], v[16:19]
	v_mfma_f32_16x16x32_bf16 v[8:11], v[218:221], v[194:197], v[8:11]
	v_mfma_f32_16x16x32_bf16 v[0:3], v[218:221], v[202:205], v[0:3]
	v_mfma_f32_16x16x32_bf16 v[28:31], v[214:217], v[68:71], v[28:31]
	v_mfma_f32_16x16x32_bf16 v[20:23], v[214:217], v[84:87], v[20:23]
	v_mfma_f32_16x16x32_bf16 v[12:15], v[214:217], v[198:201], v[12:15]
	v_mfma_f32_16x16x32_bf16 v[4:7], v[214:217], v[206:209], v[4:7]
	v_mfma_f32_16x16x32_bf16 v[134:137], v[156:159], v[68:71], v[24:27]
	v_mfma_f32_16x16x32_bf16 v[138:141], v[156:159], v[84:87], v[16:19]
	v_mfma_f32_16x16x32_bf16 v[168:171], v[156:159], v[198:201], v[8:11]
	v_mfma_f32_16x16x32_bf16 v[156:159], v[156:159], v[206:209], v[0:3]
	s_barrier
	s_nop 0
	ds_read_b128 v[0:3], v154
	ds_read_b128 v[8:11], v154 offset:1024
	ds_read_b128 v[16:19], v154 offset:2048
	ds_read_b128 v[172:175], v154 offset:3072
	ds_read_b128 v[24:27], v151 offset:32768
	ds_read_b128 v[194:197], v151 offset:33792
	ds_read_b128 v[198:201], v150 offset:32768
	ds_read_b128 v[202:205], v150 offset:33792
	ds_read_b128 v[206:209], v149 offset:32768
	ds_read_b128 v[210:213], v149 offset:33792
	ds_read_b128 v[214:217], v148 offset:32768
	ds_read_b128 v[218:221], v148 offset:33792
	s_waitcnt vmcnt(2)
	s_barrier
; #define LDA(dst, b, h) for (int m = 0; m < 4; ++m) for (int k = 0; k < 2; ++k) \
;     dst[m][k] = *reinterpret_cast<const bf16x8*>((char*)SA(b, h) + lds_byte(wr * 64 + m * 16 + fr, k * 32 + fq * 8))
; #define LDB(dst, b, h) for (int n = 0; n < 2; ++n) for (int k = 0; k < 2; ++k) \
;     dst[n][k] = *reinterpret_cast<const bf16x8*>((char*)SB(b, h) + lds_byte(wc * 32 + n * 16 + fr, k * 32 + fq * 8))
; #define MMA(ai, bj, At_, Bt_) do { __builtin_amdgcn_s_setprio(1); \
;     for (int k = 0; k < 2; ++k) for (int m = 0; m < 4; ++m) for (int n = 0; n < 2; ++n) \
;       acc[ai][bj][m][n] = __builtin_amdgcn_mfma_f32_16x16x32_bf16(At_[m][k], Bt_[n][k], acc[ai][bj][m][n], 0, 0, 0); \
;     __builtin_amdgcn_s_setprio(0); } while (0)
; #define WAIT_V(n) asm volatile("s_waitcnt vmcnt(" #n ")" ::: "memory")
; #define WAIT_L(n) asm volatile("s_waitcnt lgkmcnt(" #n ")" ::: "memory")
; #define BAR __builtin_amdgcn_s_barrier()
; template <int EPI, int lda, int ldb, int N, int K>
; __device__ __forceinline__ void gemm_phase(const u16* __restrict__ A, const u16* __restrict__ Bt, const GemmEpi ep, int wv) {
;     ...
;       LDA(At, 0, 1); WAIT_V(4); BAR; WAIT_L(0); MMA(1, 0, At, B0); MMA(1, 1, At, B1); BAR; }
;     { LDB(B0, 1, 0); LDA(At, 1, 0); WAIT_V(2); BAR; WAIT_L(0); MMA(0, 0, At, B0); BAR;
;       LDB(B1, 1, 1); WAIT_V(0); BAR; WAIT_L(0); MMA(0, 1, At, B1); BAR;
;       LDA(At, 1, 1); BAR; WAIT_L(0); MMA(1, 0, At, B0); MMA(1, 1, At, B1); BAR; }
;     if (wr == 0) BAR;
	s_waitcnt lgkmcnt(0)
	s_waitcnt lgkmcnt(0)
	v_mfma_f32_16x16x32_bf16 v[64:67], v[0:3], v[24:27], v[124:127]
	v_mfma_f32_16x16x32_bf16 v[68:71], v[16:19], v[24:27], v[120:123]
	v_mfma_f32_16x16x32_bf16 v[80:83], v[0:3], v[198:201], v[116:119]
	v_mfma_f32_16x16x32_bf16 v[84:87], v[16:19], v[198:201], v[112:115]
	v_mfma_f32_16x16x32_bf16 v[108:111], v[0:3], v[206:209], v[108:111]
	v_mfma_f32_16x16x32_bf16 v[104:107], v[16:19], v[206:209], v[104:107]
	v_mfma_f32_16x16x32_bf16 v[120:123], v[0:3], v[214:217], v[100:103]
	v_mfma_f32_16x16x32_bf16 v[124:127], v[16:19], v[214:217], v[96:99]
	v_mfma_f32_16x16x32_bf16 v[116:119], v[8:11], v[194:197], v[64:67]
	v_mfma_f32_16x16x32_bf16 v[112:115], v[172:175], v[194:197], v[68:71]
	v_mfma_f32_16x16x32_bf16 v[100:103], v[8:11], v[202:205], v[80:83]
	v_mfma_f32_16x16x32_bf16 v[96:99], v[172:175], v[202:205], v[84:87]
	v_mfma_f32_16x16x32_bf16 v[84:87], v[8:11], v[210:213], v[108:111]
	v_mfma_f32_16x16x32_bf16 v[80:83], v[172:175], v[210:213], v[104:107]
	v_mfma_f32_16x16x32_bf16 v[68:71], v[8:11], v[218:221], v[120:123]
	v_mfma_f32_16x16x32_bf16 v[64:67], v[172:175], v[218:221], v[124:127]
	s_barrier
	ds_read_b128 v[222:225], v152
	ds_read_b128 v[226:229], v152 offset:1024
	ds_read_b128 v[230:233], v152 offset:2048
	ds_read_b128 v[152:155], v152 offset:3072
	s_waitcnt vmcnt(0)
	s_barrier
	s_waitcnt lgkmcnt(0)
	s_waitcnt lgkmcnt(0)
	v_mfma_f32_16x16x32_bf16 v[92:95], v[222:225], v[24:27], v[92:95]
	v_mfma_f32_16x16x32_bf16 v[24:27], v[230:233], v[24:27], v[88:91]
	v_mfma_f32_16x16x32_bf16 v[88:91], v[222:225], v[198:201], v[178:181]
	v_mfma_f32_16x16x32_bf16 v[104:107], v[230:233], v[198:201], v[182:185]
	v_mfma_f32_16x16x32_bf16 v[76:79], v[222:225], v[206:209], v[76:79]
	v_mfma_f32_16x16x32_bf16 v[72:75], v[230:233], v[206:209], v[72:75]
	v_mfma_f32_16x16x32_bf16 v[176:179], v[222:225], v[214:217], v[186:189]
	v_mfma_f32_16x16x32_bf16 v[180:183], v[230:233], v[214:217], v[190:193]
	v_mfma_f32_16x16x32_bf16 v[124:127], v[226:229], v[194:197], v[92:95]
	v_mfma_f32_16x16x32_bf16 v[120:123], v[152:155], v[194:197], v[24:27]
	v_mfma_f32_16x16x32_bf16 v[108:111], v[226:229], v[202:205], v[88:91]
	v_mfma_f32_16x16x32_bf16 v[104:107], v[152:155], v[202:205], v[104:107]
	v_mfma_f32_16x16x32_bf16 v[92:95], v[226:229], v[210:213], v[76:79]
	v_mfma_f32_16x16x32_bf16 v[88:91], v[152:155], v[210:213], v[72:75]
	v_mfma_f32_16x16x32_bf16 v[76:79], v[226:229], v[218:221], v[176:179]
	v_mfma_f32_16x16x32_bf16 v[72:75], v[152:155], v[218:221], v[180:183]
	s_barrier
	ds_read_b128 v[176:179], v151 offset:49152
	ds_read_b128 v[180:183], v151 offset:50176
	ds_read_b128 v[184:187], v150 offset:49152
	ds_read_b128 v[188:191], v150 offset:50176
	ds_read_b128 v[192:195], v149 offset:49152
	ds_read_b128 v[196:199], v149 offset:50176
	ds_read_b128 v[200:203], v148 offset:49152
	ds_read_b128 v[148:151], v148 offset:50176
	s_barrier
	s_waitcnt lgkmcnt(0)
	s_waitcnt lgkmcnt(0)
	v_mfma_f32_16x16x32_bf16 v[24:27], v[0:3], v[176:179], v[60:63]
	v_mfma_f32_16x16x32_bf16 v[60:63], v[16:19], v[176:179], v[56:59]
	v_mfma_f32_16x16x32_bf16 v[52:55], v[0:3], v[184:187], v[52:55]
	v_mfma_f32_16x16x32_bf16 v[204:207], v[16:19], v[184:187], v[48:51]
	v_mfma_f32_16x16x32_bf16 v[44:47], v[0:3], v[192:195], v[44:47]
	v_mfma_f32_16x16x32_bf16 v[208:211], v[16:19], v[192:195], v[40:43]
	v_mfma_f32_16x16x32_bf16 v[0:3], v[0:3], v[200:203], v[36:39]
	v_mfma_f32_16x16x32_bf16 v[36:39], v[16:19], v[200:203], v[32:35]
	v_mfma_f32_16x16x32_bf16 v[56:59], v[8:11], v[180:183], v[24:27]
	v_mfma_f32_16x16x32_bf16 v[48:51], v[172:175], v[180:183], v[60:63]
	v_mfma_f32_16x16x32_bf16 v[40:43], v[8:11], v[188:191], v[52:55]
	v_mfma_f32_16x16x32_bf16 v[32:35], v[172:175], v[188:191], v[204:207]
	v_mfma_f32_16x16x32_bf16 v[24:27], v[8:11], v[196:199], v[44:47]
	v_mfma_f32_16x16x32_bf16 v[16:19], v[172:175], v[196:199], v[208:211]
	v_mfma_f32_16x16x32_bf16 v[8:11], v[8:11], v[148:151], v[0:3]
	v_mfma_f32_16x16x32_bf16 v[0:3], v[172:175], v[148:151], v[36:39]
	v_mfma_f32_16x16x32_bf16 v[28:31], v[222:225], v[176:179], v[28:31]
	v_mfma_f32_16x16x32_bf16 v[36:39], v[230:233], v[176:179], v[134:137]
	v_mfma_f32_16x16x32_bf16 v[20:23], v[222:225], v[184:187], v[20:23]
	v_mfma_f32_16x16x32_bf16 v[134:137], v[230:233], v[184:187], v[138:141]
	v_mfma_f32_16x16x32_bf16 v[12:15], v[222:225], v[192:195], v[12:15]
	v_mfma_f32_16x16x32_bf16 v[138:141], v[230:233], v[192:195], v[168:171]
	v_mfma_f32_16x16x32_bf16 v[4:7], v[222:225], v[200:203], v[4:7]
	v_mfma_f32_16x16x32_bf16 v[156:159], v[230:233], v[200:203], v[156:159]
	v_mfma_f32_16x16x32_bf16 v[60:63], v[226:229], v[180:183], v[28:31]
	v_mfma_f32_16x16x32_bf16 v[52:55], v[152:155], v[180:183], v[36:39]
	v_mfma_f32_16x16x32_bf16 v[44:47], v[226:229], v[188:191], v[20:23]
	v_mfma_f32_16x16x32_bf16 v[36:39], v[152:155], v[188:191], v[134:137]
	v_mfma_f32_16x16x32_bf16 v[28:31], v[226:229], v[196:199], v[12:15]
	v_mfma_f32_16x16x32_bf16 v[20:23], v[152:155], v[196:199], v[138:141]
	v_mfma_f32_16x16x32_bf16 v[12:15], v[226:229], v[148:151], v[4:7]
	v_mfma_f32_16x16x32_bf16 v[4:7], v[152:155], v[148:151], v[156:159]
	v_cmp_gt_u32_e32 vcc, s70, v130
	s_barrier
	s_and_saveexec_b64 s[52:53], vcc
	s_cbranch_execz .LBB0_657
	s_barrier

; #define STAGE(P, BASE, LD, br, kt) do { const char* _g = (const char*)((BASE) + (size_t)(br) * (LD) + (size_t)(kt) * 64); \
;     for (int _i = 0; _i < 2; ++_i) { int _b = tidx * 16 + _i * 8192; int _r, _c; stage_rc(_b, _r, _c); \
;       __builtin_amdgcn_global_load_lds((const unsigned*)(_g + (unsigned)((_r * (LD) + _c) * 2)), (unsigned*)((char*)(P) + _b), 16, 0, 0); } } while (0)
; #define LDA(dst, b, h) for (int m = 0; m < 4; ++m) for (int k = 0; k < 2; ++k) \
;     dst[m][k] = *reinterpret_cast<const bf16x8*>((char*)SA(b, h) + lds_byte(wr * 64 + m * 16 + fr, k * 32 + fq * 8))
; #define LDB(dst, b, h) for (int n = 0; n < 2; ++n) for (int k = 0; k < 2; ++k) \
;     dst[n][k] = *reinterpret_cast<const bf16x8*>((char*)SB(b, h) + lds_byte(wc * 32 + n * 16 + fr, k * 32 + fq * 8))
; #define MMA(ai, bj, At_, Bt_) do { __builtin_amdgcn_s_setprio(1); \
;     for (int k = 0; k < 2; ++k) for (int m = 0; m < 4; ++m) for (int n = 0; n < 2; ++n) \
;       acc[ai][bj][m][n] = __builtin_amdgcn_mfma_f32_16x16x32_bf16(At_[m][k], Bt_[n][k], acc[ai][bj][m][n], 0, 0, 0); \
;     __builtin_amdgcn_s_setprio(0); } while (0)
; #define WAIT_V(n) asm volatile("s_waitcnt vmcnt(" #n ")" ::: "memory")
; #define WAIT_L(n) asm volatile("s_waitcnt lgkmcnt(" #n ")" ::: "memory")
; #define BAR __builtin_amdgcn_s_barrier()
; #define SCHED __builtin_amdgcn_sched_barrier(0)
; template <int EPI, int lda, int ldb, int N, int K>
; __device__ __forceinline__ void gemm_phase(const u16* __restrict__ A, const u16* __restrict__ Bt, const GemmEpi ep, int wv) {
;     ...
;     for (int t = 0; t < nt - 2; t += 2) {
;       LDB(B0, 0, 0); SCHED; LDA(At, 0, 0); STAGE(SA(1, 1), Ab, lda, brow + HALF, t + 1);
;       WAIT_L(8); BAR; WAIT_L(0); MMA(0, 0, At, B0); BAR; SCHED;
;       LDB(B1, 0, 1); STAGE(SB(0, 0), Bt, ldb, bcol, t + 2);
;       BAR; WAIT_L(0); MMA(0, 1, At, B1); BAR;
;       LDA(At, 0, 1); STAGE(SA(0, 0), Ab, lda, brow, t + 2);
;       BAR; WAIT_L(0); MMA(1, 0, At, B0); BAR; SCHED;
;       STAGE(SB(0, 1), Bt, ldb, bcol + HALF, t + 2);
;       WAIT_V(6); BAR; MMA(1, 1, At, B1); BAR;
.LBB0_770:
	ds_read_b128 v[172:175], v161
	ds_read_b128 v[176:179], v161 offset:1024
	ds_read_b128 v[180:183], v161 offset:2048
	ds_read_b128 v[184:187], v161 offset:3072
	v_add_u32_e32 v169, 0xc000, v148
	v_lshl_add_u64 v[236:237], v[136:137], 0, s[50:51]
	v_readfirstlane_b32 s53, v169
	v_add_u32_e32 v170, 0xe000, v148
	v_lshl_add_u64 v[162:163], v[236:237], 0, s[18:19]
	s_mov_b32 m0, s53
	v_lshl_add_u64 v[238:239], v[134:135], 0, s[50:51]
	ds_read_b128 v[164:167], v152
	ds_read_b128 v[188:191], v152 offset:1024
	ds_read_b128 v[192:195], v151
	ds_read_b128 v[196:199], v151 offset:1024
	ds_read_b128 v[200:203], v150
	ds_read_b128 v[204:207], v150 offset:1024
	ds_read_b128 v[208:211], v149
	ds_read_b128 v[212:215], v149 offset:1024
	global_load_lds_dwordx4 v[162:163], off
	s_bitset1_b32 m0, 13
	v_lshl_add_u64 v[162:163], v[238:239], 0, s[18:19]
	global_load_lds_dwordx4 v[162:163], off
	s_waitcnt lgkmcnt(8)
	s_barrier
	s_waitcnt lgkmcnt(0)
	s_waitcnt lgkmcnt(0)
	v_mfma_f32_16x16x32_bf16 v[124:127], v[172:175], v[164:167], v[124:127]
	v_mfma_f32_16x16x32_bf16 v[120:123], v[180:183], v[164:167], v[120:123]
	v_mfma_f32_16x16x32_bf16 v[116:119], v[172:175], v[192:195], v[116:119]
	v_mfma_f32_16x16x32_bf16 v[112:115], v[180:183], v[192:195], v[112:115]
	v_mfma_f32_16x16x32_bf16 v[108:111], v[172:175], v[200:203], v[108:111]
	v_mfma_f32_16x16x32_bf16 v[104:107], v[180:183], v[200:203], v[104:107]
	v_mfma_f32_16x16x32_bf16 v[100:103], v[172:175], v[208:211], v[100:103]
	v_mfma_f32_16x16x32_bf16 v[96:99], v[180:183], v[208:211], v[96:99]
	v_mfma_f32_16x16x32_bf16 v[124:127], v[176:179], v[188:191], v[124:127]
	v_mfma_f32_16x16x32_bf16 v[120:123], v[184:187], v[188:191], v[120:123]
	v_mfma_f32_16x16x32_bf16 v[116:119], v[176:179], v[196:199], v[116:119]
	v_mfma_f32_16x16x32_bf16 v[112:115], v[184:187], v[196:199], v[112:115]
	v_mfma_f32_16x16x32_bf16 v[108:111], v[176:179], v[204:207], v[108:111]
	v_mfma_f32_16x16x32_bf16 v[104:107], v[184:187], v[204:207], v[104:107]
	v_mfma_f32_16x16x32_bf16 v[100:103], v[176:179], v[212:215], v[100:103]
	v_mfma_f32_16x16x32_bf16 v[96:99], v[184:187], v[212:215], v[96:99]
	s_barrier
	v_add_u32_e32 v162, s64, v153
	v_lshl_add_u64 v[240:241], v[140:141], 0, s[50:51]
	v_readfirstlane_b32 s53, v162
	v_add_u32_e32 v163, 0x2000, v162
	v_lshl_add_u64 v[232:233], v[240:241], 0, s[20:21]
	s_mov_b32 m0, s53
	v_lshl_add_u64 v[242:243], v[138:139], 0, s[50:51]
	ds_read_b128 v[216:219], v160
	ds_read_b128 v[220:223], v160 offset:1024
	ds_read_b128 v[224:227], v160 offset:2048
	ds_read_b128 v[228:231], v160 offset:3072
	global_load_lds_dwordx4 v[232:233], off
	s_bitset1_b32 m0, 13
	v_lshl_add_u64 v[232:233], v[242:243], 0, s[20:21]
	global_load_lds_dwordx4 v[232:233], off
	s_barrier
	s_waitcnt lgkmcnt(0)
	s_waitcnt lgkmcnt(0)
	v_mfma_f32_16x16x32_bf16 v[92:95], v[216:219], v[164:167], v[92:95]
	v_mfma_f32_16x16x32_bf16 v[88:91], v[224:227], v[164:167], v[88:91]
	v_mfma_f32_16x16x32_bf16 v[84:87], v[216:219], v[192:195], v[84:87]
	v_mfma_f32_16x16x32_bf16 v[80:83], v[224:227], v[192:195], v[80:83]
	v_mfma_f32_16x16x32_bf16 v[76:79], v[216:219], v[200:203], v[76:79]
	v_mfma_f32_16x16x32_bf16 v[72:75], v[224:227], v[200:203], v[72:75]
	v_mfma_f32_16x16x32_bf16 v[68:71], v[216:219], v[208:211], v[68:71]
	v_mfma_f32_16x16x32_bf16 v[64:67], v[224:227], v[208:211], v[64:67]
	v_mfma_f32_16x16x32_bf16 v[92:95], v[220:223], v[188:191], v[92:95]
	v_mfma_f32_16x16x32_bf16 v[88:91], v[228:231], v[188:191], v[88:91]
	v_mfma_f32_16x16x32_bf16 v[84:87], v[220:223], v[196:199], v[84:87]
	v_mfma_f32_16x16x32_bf16 v[80:83], v[228:231], v[196:199], v[80:83]
	v_mfma_f32_16x16x32_bf16 v[76:79], v[220:223], v[204:207], v[76:79]
	v_mfma_f32_16x16x32_bf16 v[72:75], v[228:231], v[204:207], v[72:75]
	v_mfma_f32_16x16x32_bf16 v[68:71], v[220:223], v[212:215], v[68:71]
	v_mfma_f32_16x16x32_bf16 v[64:67], v[228:231], v[212:215], v[64:67]
	v_readfirstlane_b32 s53, v148
	v_lshl_add_u64 v[164:165], v[236:237], 0, s[22:23]
	s_mov_b32 m0, s53
	s_barrier
	ds_read_b128 v[188:191], v152 offset:16384
	ds_read_b128 v[192:195], v152 offset:17408
	ds_read_b128 v[196:199], v151 offset:16384
	ds_read_b128 v[200:203], v151 offset:17408
	ds_read_b128 v[204:207], v150 offset:16384
	ds_read_b128 v[208:211], v150 offset:17408
	ds_read_b128 v[212:215], v149 offset:16384
	ds_read_b128 v[232:235], v149 offset:17408
	global_load_lds_dwordx4 v[164:165], off
	s_bitset1_b32 m0, 13
	v_add_u32_e32 v164, 0x2000, v148
	v_lshl_add_u64 v[166:167], v[238:239], 0, s[22:23]
	global_load_lds_dwordx4 v[166:167], off
	s_barrier
	s_waitcnt lgkmcnt(0)
	s_waitcnt lgkmcnt(0)
	v_mfma_f32_16x16x32_bf16 v[60:63], v[172:175], v[188:191], v[60:63]
	v_mfma_f32_16x16x32_bf16 v[56:59], v[180:183], v[188:191], v[56:59]
	v_mfma_f32_16x16x32_bf16 v[52:55], v[172:175], v[196:199], v[52:55]
	v_mfma_f32_16x16x32_bf16 v[48:51], v[180:183], v[196:199], v[48:51]
	v_mfma_f32_16x16x32_bf16 v[44:47], v[172:175], v[204:207], v[44:47]
	v_mfma_f32_16x16x32_bf16 v[40:43], v[180:183], v[204:207], v[40:43]
	v_mfma_f32_16x16x32_bf16 v[36:39], v[172:175], v[212:215], v[36:39]
	v_mfma_f32_16x16x32_bf16 v[32:35], v[180:183], v[212:215], v[32:35]
	v_mfma_f32_16x16x32_bf16 v[60:63], v[176:179], v[192:195], v[60:63]
	v_mfma_f32_16x16x32_bf16 v[56:59], v[184:187], v[192:195], v[56:59]
	v_mfma_f32_16x16x32_bf16 v[52:55], v[176:179], v[200:203], v[52:55]
	v_mfma_f32_16x16x32_bf16 v[48:51], v[184:187], v[200:203], v[48:51]
	v_mfma_f32_16x16x32_bf16 v[44:47], v[176:179], v[208:211], v[44:47]
	v_mfma_f32_16x16x32_bf16 v[40:43], v[184:187], v[208:211], v[40:43]
	v_mfma_f32_16x16x32_bf16 v[36:39], v[176:179], v[232:235], v[36:39]
	v_mfma_f32_16x16x32_bf16 v[32:35], v[184:187], v[232:235], v[32:35]
	s_barrier
; #define STAGE(P, BASE, LD, br, kt) do { const char* _g = (const char*)((BASE) + (size_t)(br) * (LD) + (size_t)(kt) * 64); \
;     for (int _i = 0; _i < 2; ++_i) { int _b = tidx * 16 + _i * 8192; int _r, _c; stage_rc(_b, _r, _c); \
;       __builtin_amdgcn_global_load_lds((const unsigned*)(_g + (unsigned)((_r * (LD) + _c) * 2)), (unsigned*)((char*)(P) + _b), 16, 0, 0); } } while (0)
; #define LDA(dst, b, h) for (int m = 0; m < 4; ++m) for (int k = 0; k < 2; ++k) \
;     dst[m][k] = *reinterpret_cast<const bf16x8*>((char*)SA(b, h) + lds_byte(wr * 64 + m * 16 + fr, k * 32 + fq * 8))
; #define LDB(dst, b, h) for (int n = 0; n < 2; ++n) for (int k = 0; k < 2; ++k) \
;     dst[n][k] = *reinterpret_cast<const bf16x8*>((char*)SB(b, h) + lds_byte(wc * 32 + n * 16 + fr, k * 32 + fq * 8))
; #define MMA(ai, bj, At_, Bt_) do { __builtin_amdgcn_s_setprio(1); \
;     for (int k = 0; k < 2; ++k) for (int m = 0; m < 4; ++m) for (int n = 0; n < 2; ++n) \
;       acc[ai][bj][m][n] = __builtin_amdgcn_mfma_f32_16x16x32_bf16(At_[m][k], Bt_[n][k], acc[ai][bj][m][n], 0, 0, 0); \
;     __builtin_amdgcn_s_setprio(0); } while (0)
; #define WAIT_V(n) asm volatile("s_waitcnt vmcnt(" #n ")" ::: "memory")
; #define WAIT_L(n) asm volatile("s_waitcnt lgkmcnt(" #n ")" ::: "memory")
; #define BAR __builtin_amdgcn_s_barrier()
; #define SCHED __builtin_amdgcn_sched_barrier(0)
; template <int EPI, int lda, int ldb, int N, int K>
; __device__ __forceinline__ void gemm_phase(const u16* __restrict__ A, const u16* __restrict__ Bt, const GemmEpi ep, int wv) {
;     ...
;       WAIT_V(6); BAR; MMA(1, 1, At, B1); BAR;
;       LDB(B0, 1, 0); SCHED; LDA(At, 1, 0); STAGE(SA(0, 1), Ab, lda, brow + HALF, t + 2);
;       WAIT_L(8); BAR; WAIT_L(0); MMA(0, 0, At, B0); BAR; SCHED;
;       LDB(B1, 1, 1); STAGE(SB(1, 0), Bt, ldb, bcol, t + 3);
;       BAR; WAIT_L(0); MMA(0, 1, At, B1); BAR;
;       LDA(At, 1, 1); STAGE(SA(1, 0), Ab, lda, brow, t + 3);
;       BAR; WAIT_L(0); MMA(1, 0, At, B0); BAR; SCHED;
;       STAGE(SB(1, 1), Bt, ldb, bcol + HALF, t + 3);
;       WAIT_V(6); BAR; MMA(1, 1, At, B1); BAR;
	v_add_u32_e32 v165, s65, v153
	v_lshl_add_u64 v[166:167], v[240:241], 0, s[24:25]
	v_readfirstlane_b32 s53, v165
	s_mov_b32 m0, s53
	v_lshl_add_u64 v[172:173], v[242:243], 0, s[24:25]
	global_load_lds_dwordx4 v[166:167], off
	s_bitset1_b32 m0, 13
	v_add_u32_e32 v166, 0x2000, v165
	global_load_lds_dwordx4 v[172:173], off
	s_waitcnt vmcnt(6)
	s_barrier
	v_mfma_f32_16x16x32_bf16 v[28:31], v[216:219], v[188:191], v[28:31]
	v_mfma_f32_16x16x32_bf16 v[24:27], v[224:227], v[188:191], v[24:27]
	v_mfma_f32_16x16x32_bf16 v[20:23], v[216:219], v[196:199], v[20:23]
	v_mfma_f32_16x16x32_bf16 v[16:19], v[224:227], v[196:199], v[16:19]
	v_mfma_f32_16x16x32_bf16 v[12:15], v[216:219], v[204:207], v[12:15]
	v_mfma_f32_16x16x32_bf16 v[8:11], v[224:227], v[204:207], v[8:11]
	v_mfma_f32_16x16x32_bf16 v[4:7], v[216:219], v[212:215], v[4:7]
	v_mfma_f32_16x16x32_bf16 v[0:3], v[224:227], v[212:215], v[0:3]
	v_mfma_f32_16x16x32_bf16 v[28:31], v[220:223], v[192:195], v[28:31]
	v_mfma_f32_16x16x32_bf16 v[24:27], v[228:231], v[192:195], v[24:27]
	v_mfma_f32_16x16x32_bf16 v[20:23], v[220:223], v[200:203], v[20:23]
	v_mfma_f32_16x16x32_bf16 v[16:19], v[228:231], v[200:203], v[16:19]
	v_mfma_f32_16x16x32_bf16 v[12:15], v[220:223], v[208:211], v[12:15]
	v_mfma_f32_16x16x32_bf16 v[8:11], v[228:231], v[208:211], v[8:11]
	v_mfma_f32_16x16x32_bf16 v[4:7], v[220:223], v[232:235], v[4:7]
	v_mfma_f32_16x16x32_bf16 v[0:3], v[228:231], v[232:235], v[0:3]
	s_barrier
	ds_read_b128 v[172:175], v156
	ds_read_b128 v[176:179], v156 offset:1024
	ds_read_b128 v[180:183], v156 offset:2048
	ds_read_b128 v[184:187], v156 offset:3072
	v_add_u32_e32 v167, 0x4000, v148
	v_add_u32_e32 v168, 0x6000, v148
	v_readfirstlane_b32 s53, v167
	v_lshl_add_u64 v[220:221], v[236:237], 0, s[26:27]
	s_mov_b32 m0, s53
	ds_read_b128 v[188:191], v152 offset:32768
	ds_read_b128 v[192:195], v152 offset:33792
	ds_read_b128 v[196:199], v151 offset:32768
	ds_read_b128 v[200:203], v151 offset:33792
	ds_read_b128 v[204:207], v150 offset:32768
	ds_read_b128 v[208:211], v150 offset:33792
	ds_read_b128 v[212:215], v149 offset:32768
	ds_read_b128 v[216:219], v149 offset:33792
	global_load_lds_dwordx4 v[220:221], off
	s_bitset1_b32 m0, 13
	v_lshl_add_u64 v[220:221], v[238:239], 0, s[26:27]
	global_load_lds_dwordx4 v[220:221], off
	s_waitcnt lgkmcnt(8)
	s_barrier
	s_waitcnt lgkmcnt(0)
	s_waitcnt lgkmcnt(0)
	v_mfma_f32_16x16x32_bf16 v[124:127], v[172:175], v[188:191], v[124:127]
	v_mfma_f32_16x16x32_bf16 v[120:123], v[180:183], v[188:191], v[120:123]
	v_mfma_f32_16x16x32_bf16 v[116:119], v[172:175], v[196:199], v[116:119]
	v_mfma_f32_16x16x32_bf16 v[112:115], v[180:183], v[196:199], v[112:115]
	v_mfma_f32_16x16x32_bf16 v[108:111], v[172:175], v[204:207], v[108:111]
	v_mfma_f32_16x16x32_bf16 v[104:107], v[180:183], v[204:207], v[104:107]
	v_mfma_f32_16x16x32_bf16 v[100:103], v[172:175], v[212:215], v[100:103]
	v_mfma_f32_16x16x32_bf16 v[96:99], v[180:183], v[212:215], v[96:99]
	v_mfma_f32_16x16x32_bf16 v[124:127], v[176:179], v[192:195], v[124:127]
	v_mfma_f32_16x16x32_bf16 v[120:123], v[184:187], v[192:195], v[120:123]
	v_mfma_f32_16x16x32_bf16 v[116:119], v[176:179], v[200:203], v[116:119]
	v_mfma_f32_16x16x32_bf16 v[112:115], v[184:187], v[200:203], v[112:115]
	v_mfma_f32_16x16x32_bf16 v[108:111], v[176:179], v[208:211], v[108:111]
	v_mfma_f32_16x16x32_bf16 v[104:107], v[184:187], v[208:211], v[104:107]
	v_mfma_f32_16x16x32_bf16 v[100:103], v[176:179], v[216:219], v[100:103]
	v_mfma_f32_16x16x32_bf16 v[96:99], v[184:187], v[216:219], v[96:99]
	s_barrier
	v_readfirstlane_b32 s53, v155
	v_add_u32_e32 v171, 0x2000, v155
	v_lshl_add_u64 v[244:245], v[240:241], 0, s[40:41]
	s_mov_b32 m0, s53
	ds_read_b128 v[220:223], v154
	ds_read_b128 v[224:227], v154 offset:1024
	ds_read_b128 v[228:231], v154 offset:2048
	ds_read_b128 v[232:235], v154 offset:3072
	global_load_lds_dwordx4 v[244:245], off
	s_bitset1_b32 m0, 13
	v_lshl_add_u64 v[244:245], v[242:243], 0, s[40:41]
	global_load_lds_dwordx4 v[244:245], off
	s_barrier
	s_waitcnt lgkmcnt(0)
	s_waitcnt lgkmcnt(0)
	v_mfma_f32_16x16x32_bf16 v[92:95], v[220:223], v[188:191], v[92:95]
	v_mfma_f32_16x16x32_bf16 v[88:91], v[228:231], v[188:191], v[88:91]
	v_mfma_f32_16x16x32_bf16 v[84:87], v[220:223], v[196:199], v[84:87]
	v_mfma_f32_16x16x32_bf16 v[80:83], v[228:231], v[196:199], v[80:83]
	v_mfma_f32_16x16x32_bf16 v[76:79], v[220:223], v[204:207], v[76:79]
	v_mfma_f32_16x16x32_bf16 v[72:75], v[228:231], v[204:207], v[72:75]
	v_mfma_f32_16x16x32_bf16 v[68:71], v[220:223], v[212:215], v[68:71]
	v_mfma_f32_16x16x32_bf16 v[64:67], v[228:231], v[212:215], v[64:67]
	v_mfma_f32_16x16x32_bf16 v[92:95], v[224:227], v[192:195], v[92:95]
	v_mfma_f32_16x16x32_bf16 v[88:91], v[232:235], v[192:195], v[88:91]
	v_mfma_f32_16x16x32_bf16 v[84:87], v[224:227], v[200:203], v[84:87]
	v_mfma_f32_16x16x32_bf16 v[80:83], v[232:235], v[200:203], v[80:83]
	v_mfma_f32_16x16x32_bf16 v[76:79], v[224:227], v[208:211], v[76:79]
	v_mfma_f32_16x16x32_bf16 v[72:75], v[232:235], v[208:211], v[72:75]
	v_mfma_f32_16x16x32_bf16 v[68:71], v[224:227], v[216:219], v[68:71]
	v_mfma_f32_16x16x32_bf16 v[64:67], v[232:235], v[216:219], v[64:67]
	v_readfirstlane_b32 s53, v157
	v_lshl_add_u64 v[236:237], v[236:237], 0, s[42:43]
	s_mov_b32 m0, s53
	s_barrier
	ds_read_b128 v[188:191], v152 offset:49152
	ds_read_b128 v[192:195], v152 offset:50176
	ds_read_b128 v[196:199], v151 offset:49152
	ds_read_b128 v[200:203], v151 offset:50176
	ds_read_b128 v[204:207], v150 offset:49152
	ds_read_b128 v[208:211], v150 offset:50176
	ds_read_b128 v[212:215], v149 offset:49152
	ds_read_b128 v[216:219], v149 offset:50176
	global_load_lds_dwordx4 v[236:237], off
	s_bitset1_b32 m0, 13
	v_lshl_add_u64 v[236:237], v[238:239], 0, s[42:43]
	global_load_lds_dwordx4 v[236:237], off
	s_barrier
; #define STAGE(P, BASE, LD, br, kt) do { const char* _g = (const char*)((BASE) + (size_t)(br) * (LD) + (size_t)(kt) * 64); \
;     for (int _i = 0; _i < 2; ++_i) { int _b = tidx * 16 + _i * 8192; int _r, _c; stage_rc(_b, _r, _c); \
;       __builtin_amdgcn_global_load_lds((const unsigned*)(_g + (unsigned)((_r * (LD) + _c) * 2)), (unsigned*)((char*)(P) + _b), 16, 0, 0); } } while (0)
; #define LDA(dst, b, h) for (int m = 0; m < 4; ++m) for (int k = 0; k < 2; ++k) \
;     dst[m][k] = *reinterpret_cast<const bf16x8*>((char*)SA(b, h) + lds_byte(wr * 64 + m * 16 + fr, k * 32 + fq * 8))
; #define LDB(dst, b, h) for (int n = 0; n < 2; ++n) for (int k = 0; k < 2; ++k) \
;     dst[n][k] = *reinterpret_cast<const bf16x8*>((char*)SB(b, h) + lds_byte(wc * 32 + n * 16 + fr, k * 32 + fq * 8))
; #define MMA(ai, bj, At_, Bt_) do { __builtin_amdgcn_s_setprio(1); \
;     for (int k = 0; k < 2; ++k) for (int m = 0; m < 4; ++m) for (int n = 0; n < 2; ++n) \
;       acc[ai][bj][m][n] = __builtin_amdgcn_mfma_f32_16x16x32_bf16(At_[m][k], Bt_[n][k], acc[ai][bj][m][n], 0, 0, 0); \
;     __builtin_amdgcn_s_setprio(0); } while (0)
; #define WAIT_V(n) asm volatile("s_waitcnt vmcnt(" #n ")" ::: "memory")
; #define WAIT_L(n) asm volatile("s_waitcnt lgkmcnt(" #n ")" ::: "memory")
; #define BAR __builtin_amdgcn_s_barrier()
; #define SCHED __builtin_amdgcn_sched_barrier(0)
; template <int EPI, int lda, int ldb, int N, int K>
; __device__ __forceinline__ void gemm_phase(const u16* __restrict__ A, const u16* __restrict__ Bt, const GemmEpi ep, int wv) {
;     ...
;       BAR; WAIT_L(0); MMA(0, 1, At, B1); BAR;
;       LDA(At, 1, 1); STAGE(SA(1, 0), Ab, lda, brow, t + 3);
;       BAR; WAIT_L(0); MMA(1, 0, At, B0); BAR; SCHED;
;       STAGE(SB(1, 1), Bt, ldb, bcol + HALF, t + 3);
;       WAIT_V(6); BAR; MMA(1, 1, At, B1); BAR;
;     }
;     { LDB(B0, 0, 0); LDA(At, 0, 0); STAGE(SA(1, 1), Ab, lda, brow + HALF, nt - 1);
;       BAR; WAIT_L(0); MMA(0, 0, At, B0); BAR;
;       LDB(B1, 0, 1); BAR; WAIT_L(0); MMA(0, 1, At, B1); BAR;
;       LDA(At, 0, 1); WAIT_V(4); BAR; WAIT_L(0); MMA(1, 0, At, B0); MMA(1, 1, At, B1); BAR; }
	s_waitcnt lgkmcnt(0)
	s_waitcnt lgkmcnt(0)
	v_mfma_f32_16x16x32_bf16 v[60:63], v[172:175], v[188:191], v[60:63]
	v_mfma_f32_16x16x32_bf16 v[56:59], v[180:183], v[188:191], v[56:59]
	v_mfma_f32_16x16x32_bf16 v[52:55], v[172:175], v[196:199], v[52:55]
	v_mfma_f32_16x16x32_bf16 v[48:51], v[180:183], v[196:199], v[48:51]
	v_mfma_f32_16x16x32_bf16 v[44:47], v[172:175], v[204:207], v[44:47]
	v_mfma_f32_16x16x32_bf16 v[40:43], v[180:183], v[204:207], v[40:43]
	v_mfma_f32_16x16x32_bf16 v[36:39], v[172:175], v[212:215], v[36:39]
	v_mfma_f32_16x16x32_bf16 v[32:35], v[180:183], v[212:215], v[32:35]
	v_mfma_f32_16x16x32_bf16 v[60:63], v[176:179], v[192:195], v[60:63]
	v_mfma_f32_16x16x32_bf16 v[56:59], v[184:187], v[192:195], v[56:59]
	v_mfma_f32_16x16x32_bf16 v[52:55], v[176:179], v[200:203], v[52:55]
	v_mfma_f32_16x16x32_bf16 v[48:51], v[184:187], v[200:203], v[48:51]
	v_mfma_f32_16x16x32_bf16 v[44:47], v[176:179], v[208:211], v[44:47]
	v_mfma_f32_16x16x32_bf16 v[40:43], v[184:187], v[208:211], v[40:43]
	v_mfma_f32_16x16x32_bf16 v[36:39], v[176:179], v[216:219], v[36:39]
	v_mfma_f32_16x16x32_bf16 v[32:35], v[184:187], v[216:219], v[32:35]
	s_barrier
	v_readfirstlane_b32 s53, v159
	v_add_u32_e32 v171, 0x2000, v159
	v_lshl_add_u64 v[172:173], v[240:241], 0, s[44:45]
	s_mov_b32 m0, s53
	global_load_lds_dwordx4 v[172:173], off
	s_bitset1_b32 m0, 13
	v_lshl_add_u64 v[172:173], v[242:243], 0, s[44:45]
	global_load_lds_dwordx4 v[172:173], off
	s_waitcnt vmcnt(6)
	s_barrier
	v_mfma_f32_16x16x32_bf16 v[28:31], v[220:223], v[188:191], v[28:31]
	v_mfma_f32_16x16x32_bf16 v[24:27], v[228:231], v[188:191], v[24:27]
	v_mfma_f32_16x16x32_bf16 v[20:23], v[220:223], v[196:199], v[20:23]
	v_mfma_f32_16x16x32_bf16 v[16:19], v[228:231], v[196:199], v[16:19]
	v_mfma_f32_16x16x32_bf16 v[12:15], v[220:223], v[204:207], v[12:15]
	v_mfma_f32_16x16x32_bf16 v[8:11], v[228:231], v[204:207], v[8:11]
	v_mfma_f32_16x16x32_bf16 v[4:7], v[220:223], v[212:215], v[4:7]
	v_mfma_f32_16x16x32_bf16 v[0:3], v[228:231], v[212:215], v[0:3]
	v_mfma_f32_16x16x32_bf16 v[28:31], v[224:227], v[192:195], v[28:31]
	v_mfma_f32_16x16x32_bf16 v[24:27], v[232:235], v[192:195], v[24:27]
	v_mfma_f32_16x16x32_bf16 v[20:23], v[224:227], v[200:203], v[20:23]
	v_mfma_f32_16x16x32_bf16 v[16:19], v[232:235], v[200:203], v[16:19]
	v_mfma_f32_16x16x32_bf16 v[12:15], v[224:227], v[208:211], v[12:15]
	v_mfma_f32_16x16x32_bf16 v[8:11], v[232:235], v[208:211], v[8:11]
	v_mfma_f32_16x16x32_bf16 v[4:7], v[224:227], v[216:219], v[4:7]
	v_mfma_f32_16x16x32_bf16 v[0:3], v[232:235], v[216:219], v[0:3]
	s_add_i32 s52, s52, 2
	s_add_u32 s50, s50, 0x100
	s_addc_u32 s51, s51, 0
	s_cmp_gt_u32 s52, 27
	s_barrier
	s_cbranch_scc0 .LBB0_770
	s_add_i32 s50, s48, 0x80
	s_mul_hi_i32 s51, s50, 0x1080
	s_mulk_i32 s50, 0x1080
	s_add_u32 s50, s61, s50
	s_addc_u32 s51, s62, s51
	v_lshl_add_u64 v[158:159], s[50:51], 0, v[128:129]
	v_readfirstlane_b32 s52, v169
	v_lshl_add_u64 v[158:159], v[158:159], 0, s[46:47]
	s_mov_b32 m0, s52
	ds_read_b128 v[134:137], v161
	ds_read_b128 v[138:141], v161 offset:1024
	ds_read_b128 v[172:175], v161 offset:2048
	ds_read_b128 v[176:179], v161 offset:3072
	ds_read_b128 v[180:183], v152
	ds_read_b128 v[184:187], v152 offset:1024
	ds_read_b128 v[188:191], v151
	ds_read_b128 v[192:195], v151 offset:1024
	ds_read_b128 v[196:199], v150
	ds_read_b128 v[200:203], v150 offset:1024
	ds_read_b128 v[204:207], v149
	ds_read_b128 v[208:211], v149 offset:1024
	global_load_lds_dwordx4 v[158:159], off
	v_lshl_add_u64 v[158:159], s[50:51], 0, v[132:133]
	v_readfirstlane_b32 s50, v170
	v_lshl_add_u64 v[158:159], v[158:159], 0, s[46:47]
	s_mov_b32 m0, s50
	s_nop 0
	global_load_lds_dwordx4 v[158:159], off
	s_barrier
	s_waitcnt lgkmcnt(0)
	s_waitcnt lgkmcnt(0)
	v_mfma_f32_16x16x32_bf16 v[124:127], v[134:137], v[180:183], v[124:127]
	v_mfma_f32_16x16x32_bf16 v[120:123], v[172:175], v[180:183], v[120:123]
	v_mfma_f32_16x16x32_bf16 v[116:119], v[134:137], v[188:191], v[116:119]
	v_mfma_f32_16x16x32_bf16 v[112:115], v[172:175], v[188:191], v[112:115]
	v_mfma_f32_16x16x32_bf16 v[108:111], v[134:137], v[196:199], v[108:111]
	v_mfma_f32_16x16x32_bf16 v[104:107], v[172:175], v[196:199], v[104:107]
	v_mfma_f32_16x16x32_bf16 v[100:103], v[134:137], v[204:207], v[100:103]
	v_mfma_f32_16x16x32_bf16 v[96:99], v[172:175], v[204:207], v[96:99]
	v_mfma_f32_16x16x32_bf16 v[124:127], v[138:141], v[184:187], v[124:127]
	v_mfma_f32_16x16x32_bf16 v[120:123], v[176:179], v[184:187], v[120:123]
	v_mfma_f32_16x16x32_bf16 v[116:119], v[138:141], v[192:195], v[116:119]
	v_mfma_f32_16x16x32_bf16 v[112:115], v[176:179], v[192:195], v[112:115]
	v_mfma_f32_16x16x32_bf16 v[108:111], v[138:141], v[200:203], v[108:111]
	v_mfma_f32_16x16x32_bf16 v[104:107], v[176:179], v[200:203], v[104:107]
	v_mfma_f32_16x16x32_bf16 v[100:103], v[138:141], v[208:211], v[100:103]
	v_mfma_f32_16x16x32_bf16 v[96:99], v[176:179], v[208:211], v[96:99]
	s_barrier
	ds_read_b128 v[212:215], v160
	ds_read_b128 v[216:219], v160 offset:1024
	ds_read_b128 v[220:223], v160 offset:2048
	ds_read_b128 v[158:161], v160 offset:3072
	s_barrier
; #define LDA(dst, b, h) for (int m = 0; m < 4; ++m) for (int k = 0; k < 2; ++k) \
;     dst[m][k] = *reinterpret_cast<const bf16x8*>((char*)SA(b, h) + lds_byte(wr * 64 + m * 16 + fr, k * 32 + fq * 8))
; #define LDB(dst, b, h) for (int n = 0; n < 2; ++n) for (int k = 0; k < 2; ++k) \
;     dst[n][k] = *reinterpret_cast<const bf16x8*>((char*)SB(b, h) + lds_byte(wc * 32 + n * 16 + fr, k * 32 + fq * 8))
; #define MMA(ai, bj, At_, Bt_) do { __builtin_amdgcn_s_setprio(1); \
;     for (int k = 0; k < 2; ++k) for (int m = 0; m < 4; ++m) for (int n = 0; n < 2; ++n) \
;       acc[ai][bj][m][n] = __builtin_amdgcn_mfma_f32_16x16x32_bf16(At_[m][k], Bt_[n][k], acc[ai][bj][m][n], 0, 0, 0); \
;     __builtin_amdgcn_s_setprio(0); } while (0)
; #define WAIT_V(n) asm volatile("s_waitcnt vmcnt(" #n ")" ::: "memory")
; #define WAIT_L(n) asm volatile("s_waitcnt lgkmcnt(" #n ")" ::: "memory")
; #define BAR __builtin_amdgcn_s_barrier()
; template <int EPI, int lda, int ldb, int N, int K>
; __device__ __forceinline__ void gemm_phase(const u16* __restrict__ A, const u16* __restrict__ Bt, const GemmEpi ep, int wv) {
;     ...
;       LDB(B1, 0, 1); BAR; WAIT_L(0); MMA(0, 1, At, B1); BAR;
;       LDA(At, 0, 1); WAIT_V(4); BAR; WAIT_L(0); MMA(1, 0, At, B0); MMA(1, 1, At, B1); BAR; }
;     { LDB(B0, 1, 0); LDA(At, 1, 0); WAIT_V(2); BAR; WAIT_L(0); MMA(0, 0, At, B0); BAR;
	s_waitcnt lgkmcnt(0)
	s_waitcnt lgkmcnt(0)
	v_mfma_f32_16x16x32_bf16 v[92:95], v[212:215], v[180:183], v[92:95]
	v_mfma_f32_16x16x32_bf16 v[88:91], v[220:223], v[180:183], v[88:91]
	v_mfma_f32_16x16x32_bf16 v[76:79], v[212:215], v[196:199], v[76:79]
	v_mfma_f32_16x16x32_bf16 v[72:75], v[220:223], v[196:199], v[72:75]
	v_mfma_f32_16x16x32_bf16 v[84:87], v[212:215], v[188:191], v[84:87]
	v_mfma_f32_16x16x32_bf16 v[80:83], v[220:223], v[188:191], v[80:83]
	v_mfma_f32_16x16x32_bf16 v[68:71], v[212:215], v[204:207], v[68:71]
	v_mfma_f32_16x16x32_bf16 v[64:67], v[220:223], v[204:207], v[64:67]
	v_mfma_f32_16x16x32_bf16 v[92:95], v[216:219], v[184:187], v[92:95]
	v_mfma_f32_16x16x32_bf16 v[88:91], v[158:161], v[184:187], v[88:91]
	v_mfma_f32_16x16x32_bf16 v[76:79], v[216:219], v[200:203], v[76:79]
	v_mfma_f32_16x16x32_bf16 v[72:75], v[158:161], v[200:203], v[72:75]
	v_mfma_f32_16x16x32_bf16 v[180:183], v[216:219], v[192:195], v[84:87]
	v_mfma_f32_16x16x32_bf16 v[184:187], v[158:161], v[192:195], v[80:83]
	v_mfma_f32_16x16x32_bf16 v[188:191], v[216:219], v[208:211], v[68:71]
	v_mfma_f32_16x16x32_bf16 v[192:195], v[158:161], v[208:211], v[64:67]
	s_barrier
	s_nop 0
	ds_read_b128 v[64:67], v152 offset:16384
	ds_read_b128 v[68:71], v152 offset:17408
	ds_read_b128 v[80:83], v151 offset:16384
	ds_read_b128 v[84:87], v151 offset:17408
	ds_read_b128 v[196:199], v150 offset:16384
	ds_read_b128 v[200:203], v150 offset:17408
	ds_read_b128 v[204:207], v149 offset:16384
	ds_read_b128 v[208:211], v149 offset:17408
	s_waitcnt vmcnt(4)
	s_barrier
	s_waitcnt lgkmcnt(0)
	s_waitcnt lgkmcnt(0)
	v_mfma_f32_16x16x32_bf16 v[60:63], v[134:137], v[64:67], v[60:63]
	v_mfma_f32_16x16x32_bf16 v[56:59], v[172:175], v[64:67], v[56:59]
	v_mfma_f32_16x16x32_bf16 v[52:55], v[134:137], v[80:83], v[52:55]
	v_mfma_f32_16x16x32_bf16 v[48:51], v[172:175], v[80:83], v[48:51]
	v_mfma_f32_16x16x32_bf16 v[44:47], v[134:137], v[196:199], v[44:47]
	v_mfma_f32_16x16x32_bf16 v[40:43], v[172:175], v[196:199], v[40:43]
	v_mfma_f32_16x16x32_bf16 v[36:39], v[134:137], v[204:207], v[36:39]
	v_mfma_f32_16x16x32_bf16 v[32:35], v[172:175], v[204:207], v[32:35]
	v_mfma_f32_16x16x32_bf16 v[60:63], v[138:141], v[68:71], v[60:63]
	v_mfma_f32_16x16x32_bf16 v[56:59], v[176:179], v[68:71], v[56:59]
	v_mfma_f32_16x16x32_bf16 v[52:55], v[138:141], v[84:87], v[52:55]
	v_mfma_f32_16x16x32_bf16 v[48:51], v[176:179], v[84:87], v[48:51]
	v_mfma_f32_16x16x32_bf16 v[44:47], v[138:141], v[200:203], v[44:47]
	v_mfma_f32_16x16x32_bf16 v[40:43], v[176:179], v[200:203], v[40:43]
	v_mfma_f32_16x16x32_bf16 v[36:39], v[138:141], v[208:211], v[36:39]
	v_mfma_f32_16x16x32_bf16 v[32:35], v[176:179], v[208:211], v[32:35]
	v_mfma_f32_16x16x32_bf16 v[28:31], v[212:215], v[64:67], v[28:31]
	v_mfma_f32_16x16x32_bf16 v[24:27], v[220:223], v[64:67], v[24:27]
	v_mfma_f32_16x16x32_bf16 v[12:15], v[212:215], v[196:199], v[12:15]
	v_mfma_f32_16x16x32_bf16 v[8:11], v[220:223], v[196:199], v[8:11]
	v_mfma_f32_16x16x32_bf16 v[20:23], v[212:215], v[80:83], v[20:23]
	v_mfma_f32_16x16x32_bf16 v[16:19], v[220:223], v[80:83], v[16:19]
	v_mfma_f32_16x16x32_bf16 v[4:7], v[212:215], v[204:207], v[4:7]
	v_mfma_f32_16x16x32_bf16 v[0:3], v[220:223], v[204:207], v[0:3]
	v_mfma_f32_16x16x32_bf16 v[28:31], v[216:219], v[68:71], v[28:31]
	v_mfma_f32_16x16x32_bf16 v[24:27], v[158:161], v[68:71], v[24:27]
	v_mfma_f32_16x16x32_bf16 v[12:15], v[216:219], v[200:203], v[12:15]
	v_mfma_f32_16x16x32_bf16 v[8:11], v[158:161], v[200:203], v[8:11]
	v_mfma_f32_16x16x32_bf16 v[134:137], v[216:219], v[84:87], v[20:23]
	v_mfma_f32_16x16x32_bf16 v[138:141], v[158:161], v[84:87], v[16:19]
	v_mfma_f32_16x16x32_bf16 v[170:173], v[216:219], v[208:211], v[4:7]
	v_mfma_f32_16x16x32_bf16 v[158:161], v[158:161], v[208:211], v[0:3]
	s_barrier
	s_nop 0
	ds_read_b128 v[0:3], v156
	ds_read_b128 v[4:7], v156 offset:1024
	ds_read_b128 v[16:19], v156 offset:2048
	ds_read_b128 v[174:177], v156 offset:3072
	ds_read_b128 v[20:23], v152 offset:32768
	ds_read_b128 v[196:199], v152 offset:33792
	ds_read_b128 v[200:203], v151 offset:32768
	ds_read_b128 v[204:207], v151 offset:33792
	ds_read_b128 v[208:211], v150 offset:32768
	ds_read_b128 v[212:215], v150 offset:33792
	ds_read_b128 v[216:219], v149 offset:32768
	ds_read_b128 v[220:223], v149 offset:33792
	s_waitcnt vmcnt(2)
	s_barrier
; #define LDA(dst, b, h) for (int m = 0; m < 4; ++m) for (int k = 0; k < 2; ++k) \
;     dst[m][k] = *reinterpret_cast<const bf16x8*>((char*)SA(b, h) + lds_byte(wr * 64 + m * 16 + fr, k * 32 + fq * 8))
; #define LDB(dst, b, h) for (int n = 0; n < 2; ++n) for (int k = 0; k < 2; ++k) \
;     dst[n][k] = *reinterpret_cast<const bf16x8*>((char*)SB(b, h) + lds_byte(wc * 32 + n * 16 + fr, k * 32 + fq * 8))
; #define MMA(ai, bj, At_, Bt_) do { __builtin_amdgcn_s_setprio(1); \
;     for (int k = 0; k < 2; ++k) for (int m = 0; m < 4; ++m) for (int n = 0; n < 2; ++n) \
;       acc[ai][bj][m][n] = __builtin_amdgcn_mfma_f32_16x16x32_bf16(At_[m][k], Bt_[n][k], acc[ai][bj][m][n], 0, 0, 0); \
;     __builtin_amdgcn_s_setprio(0); } while (0)
; #define WAIT_V(n) asm volatile("s_waitcnt vmcnt(" #n ")" ::: "memory")
; #define WAIT_L(n) asm volatile("s_waitcnt lgkmcnt(" #n ")" ::: "memory")
; #define BAR __builtin_amdgcn_s_barrier()
; template <int EPI, int lda, int ldb, int N, int K>
; __device__ __forceinline__ void gemm_phase(const u16* __restrict__ A, const u16* __restrict__ Bt, const GemmEpi ep, int wv) {
;     ...
;     { LDB(B0, 1, 0); LDA(At, 1, 0); WAIT_V(2); BAR; WAIT_L(0); MMA(0, 0, At, B0); BAR;
;       LDB(B1, 1, 1); WAIT_V(0); BAR; WAIT_L(0); MMA(0, 1, At, B1); BAR;
;       LDA(At, 1, 1); BAR; WAIT_L(0); MMA(1, 0, At, B0); MMA(1, 1, At, B1); BAR; }
;     if (wr == 0) BAR;
	s_waitcnt lgkmcnt(0)
	s_waitcnt lgkmcnt(0)
	v_mfma_f32_16x16x32_bf16 v[64:67], v[0:3], v[20:23], v[124:127]
	v_mfma_f32_16x16x32_bf16 v[68:71], v[16:19], v[20:23], v[120:123]
	v_mfma_f32_16x16x32_bf16 v[80:83], v[0:3], v[200:203], v[116:119]
	v_mfma_f32_16x16x32_bf16 v[84:87], v[16:19], v[200:203], v[112:115]
	v_mfma_f32_16x16x32_bf16 v[108:111], v[0:3], v[208:211], v[108:111]
	v_mfma_f32_16x16x32_bf16 v[104:107], v[16:19], v[208:211], v[104:107]
	v_mfma_f32_16x16x32_bf16 v[120:123], v[0:3], v[216:219], v[100:103]
	v_mfma_f32_16x16x32_bf16 v[124:127], v[16:19], v[216:219], v[96:99]
	v_mfma_f32_16x16x32_bf16 v[116:119], v[4:7], v[196:199], v[64:67]
	v_mfma_f32_16x16x32_bf16 v[112:115], v[174:177], v[196:199], v[68:71]
	v_mfma_f32_16x16x32_bf16 v[100:103], v[4:7], v[204:207], v[80:83]
	v_mfma_f32_16x16x32_bf16 v[96:99], v[174:177], v[204:207], v[84:87]
	v_mfma_f32_16x16x32_bf16 v[84:87], v[4:7], v[212:215], v[108:111]
	v_mfma_f32_16x16x32_bf16 v[80:83], v[174:177], v[212:215], v[104:107]
	v_mfma_f32_16x16x32_bf16 v[68:71], v[4:7], v[220:223], v[120:123]
	v_mfma_f32_16x16x32_bf16 v[64:67], v[174:177], v[220:223], v[124:127]
	s_barrier
	ds_read_b128 v[224:227], v154
	ds_read_b128 v[228:231], v154 offset:1024
	ds_read_b128 v[232:235], v154 offset:2048
	ds_read_b128 v[154:157], v154 offset:3072
	s_waitcnt vmcnt(0)
	s_barrier
	s_waitcnt lgkmcnt(0)
	s_waitcnt lgkmcnt(0)
	v_mfma_f32_16x16x32_bf16 v[92:95], v[224:227], v[20:23], v[92:95]
	v_mfma_f32_16x16x32_bf16 v[20:23], v[232:235], v[20:23], v[88:91]
	v_mfma_f32_16x16x32_bf16 v[88:91], v[224:227], v[200:203], v[180:183]
	v_mfma_f32_16x16x32_bf16 v[104:107], v[232:235], v[200:203], v[184:187]
	v_mfma_f32_16x16x32_bf16 v[76:79], v[224:227], v[208:211], v[76:79]
	v_mfma_f32_16x16x32_bf16 v[72:75], v[232:235], v[208:211], v[72:75]
	v_mfma_f32_16x16x32_bf16 v[178:181], v[224:227], v[216:219], v[188:191]
	v_mfma_f32_16x16x32_bf16 v[182:185], v[232:235], v[216:219], v[192:195]
	v_mfma_f32_16x16x32_bf16 v[124:127], v[228:231], v[196:199], v[92:95]
	v_mfma_f32_16x16x32_bf16 v[120:123], v[154:157], v[196:199], v[20:23]
	v_mfma_f32_16x16x32_bf16 v[108:111], v[228:231], v[204:207], v[88:91]
	v_mfma_f32_16x16x32_bf16 v[104:107], v[154:157], v[204:207], v[104:107]
	v_mfma_f32_16x16x32_bf16 v[92:95], v[228:231], v[212:215], v[76:79]
	v_mfma_f32_16x16x32_bf16 v[88:91], v[154:157], v[212:215], v[72:75]
	v_mfma_f32_16x16x32_bf16 v[76:79], v[228:231], v[220:223], v[178:181]
	v_mfma_f32_16x16x32_bf16 v[72:75], v[154:157], v[220:223], v[182:185]
	s_barrier
	ds_read_b128 v[178:181], v152 offset:49152
	ds_read_b128 v[182:185], v152 offset:50176
	ds_read_b128 v[186:189], v151 offset:49152
	ds_read_b128 v[190:193], v151 offset:50176
	ds_read_b128 v[194:197], v150 offset:49152
	ds_read_b128 v[150:153], v150 offset:50176
	ds_read_b128 v[198:201], v149 offset:49152
	ds_read_b128 v[202:205], v149 offset:50176
	s_barrier
	s_waitcnt lgkmcnt(0)
	s_waitcnt lgkmcnt(0)
	v_mfma_f32_16x16x32_bf16 v[20:23], v[0:3], v[178:181], v[60:63]
	v_mfma_f32_16x16x32_bf16 v[56:59], v[16:19], v[178:181], v[56:59]
	v_mfma_f32_16x16x32_bf16 v[60:63], v[0:3], v[186:189], v[52:55]
	v_mfma_f32_16x16x32_bf16 v[206:209], v[16:19], v[186:189], v[48:51]
	v_mfma_f32_16x16x32_bf16 v[44:47], v[0:3], v[194:197], v[44:47]
	v_mfma_f32_16x16x32_bf16 v[40:43], v[16:19], v[194:197], v[40:43]
	v_mfma_f32_16x16x32_bf16 v[0:3], v[0:3], v[198:201], v[36:39]
	v_mfma_f32_16x16x32_bf16 v[210:213], v[16:19], v[198:201], v[32:35]
	v_mfma_f32_16x16x32_bf16 v[52:55], v[4:7], v[182:185], v[20:23]
	v_mfma_f32_16x16x32_bf16 v[48:51], v[174:177], v[182:185], v[56:59]
	v_mfma_f32_16x16x32_bf16 v[36:39], v[4:7], v[190:193], v[60:63]
	v_mfma_f32_16x16x32_bf16 v[32:35], v[174:177], v[190:193], v[206:209]
	v_mfma_f32_16x16x32_bf16 v[20:23], v[4:7], v[150:153], v[44:47]
	v_mfma_f32_16x16x32_bf16 v[16:19], v[174:177], v[150:153], v[40:43]
	v_mfma_f32_16x16x32_bf16 v[4:7], v[4:7], v[202:205], v[0:3]
	v_mfma_f32_16x16x32_bf16 v[0:3], v[174:177], v[202:205], v[210:213]
	v_mfma_f32_16x16x32_bf16 v[28:31], v[224:227], v[178:181], v[28:31]
	v_mfma_f32_16x16x32_bf16 v[24:27], v[232:235], v[178:181], v[24:27]
	v_mfma_f32_16x16x32_bf16 v[40:43], v[224:227], v[186:189], v[134:137]
	v_mfma_f32_16x16x32_bf16 v[134:137], v[232:235], v[186:189], v[138:141]
	v_mfma_f32_16x16x32_bf16 v[12:15], v[224:227], v[194:197], v[12:15]
	v_mfma_f32_16x16x32_bf16 v[8:11], v[232:235], v[194:197], v[8:11]
	v_mfma_f32_16x16x32_bf16 v[138:141], v[224:227], v[198:201], v[170:173]
	v_mfma_f32_16x16x32_bf16 v[158:161], v[232:235], v[198:201], v[158:161]
	v_mfma_f32_16x16x32_bf16 v[60:63], v[228:231], v[182:185], v[28:31]
	v_mfma_f32_16x16x32_bf16 v[56:59], v[154:157], v[182:185], v[24:27]
	v_mfma_f32_16x16x32_bf16 v[44:47], v[228:231], v[190:193], v[40:43]
	v_mfma_f32_16x16x32_bf16 v[40:43], v[154:157], v[190:193], v[134:137]
	v_mfma_f32_16x16x32_bf16 v[28:31], v[228:231], v[150:153], v[12:15]
	v_mfma_f32_16x16x32_bf16 v[24:27], v[154:157], v[150:153], v[8:11]
	v_mfma_f32_16x16x32_bf16 v[12:15], v[228:231], v[202:205], v[138:141]
	v_mfma_f32_16x16x32_bf16 v[8:11], v[154:157], v[202:205], v[158:161]
	v_cmp_gt_u32_e32 vcc, s66, v130
	s_barrier
	s_and_saveexec_b64 s[50:51], vcc
	s_cbranch_execz .LBB0_773
	s_barrier

; #define STAGE(P, BASE, LD, br, kt) do { const char* _g = (const char*)((BASE) + (size_t)(br) * (LD) + (size_t)(kt) * 64); \
;     for (int _i = 0; _i < 2; ++_i) { int _b = tidx * 16 + _i * 8192; int _r, _c; stage_rc(_b, _r, _c); \
;       __builtin_amdgcn_global_load_lds((const unsigned*)(_g + (unsigned)((_r * (LD) + _c) * 2)), (unsigned*)((char*)(P) + _b), 16, 0, 0); } } while (0)
; #define LDA(dst, b, h) for (int m = 0; m < 4; ++m) for (int k = 0; k < 2; ++k) \
;     dst[m][k] = *reinterpret_cast<const bf16x8*>((char*)SA(b, h) + lds_byte(wr * 64 + m * 16 + fr, k * 32 + fq * 8))
; #define LDB(dst, b, h) for (int n = 0; n < 2; ++n) for (int k = 0; k < 2; ++k) \
;     dst[n][k] = *reinterpret_cast<const bf16x8*>((char*)SB(b, h) + lds_byte(wc * 32 + n * 16 + fr, k * 32 + fq * 8))
; #define MMA(ai, bj, At_, Bt_) do { __builtin_amdgcn_s_setprio(1); \
;     for (int k = 0; k < 2; ++k) for (int m = 0; m < 4; ++m) for (int n = 0; n < 2; ++n) \
;       acc[ai][bj][m][n] = __builtin_amdgcn_mfma_f32_16x16x32_bf16(At_[m][k], Bt_[n][k], acc[ai][bj][m][n], 0, 0, 0); \
;     __builtin_amdgcn_s_setprio(0); } while (0)
; #define WAIT_L(n) asm volatile("s_waitcnt lgkmcnt(" #n ")" ::: "memory")
; #define BAR __builtin_amdgcn_s_barrier()
; #define SCHED __builtin_amdgcn_sched_barrier(0)
; template <int EPI, int lda, int ldb, int N, int K>
; __device__ __forceinline__ void gemm_phase(const u16* __restrict__ A, const u16* __restrict__ Bt, const GemmEpi ep, int wv) {
;     ...
;       LDB(B0, 0, 0); SCHED; LDA(At, 0, 0); STAGE(SA(1, 1), Ab, lda, brow + HALF, t + 1);
;       WAIT_L(8); BAR; WAIT_L(0); MMA(0, 0, At, B0); BAR; SCHED;
;       LDB(B1, 0, 1); STAGE(SB(0, 0), Bt, ldb, bcol, t + 2);
;       BAR; WAIT_L(0); MMA(0, 1, At, B1); BAR;
;       LDA(At, 0, 1); STAGE(SA(0, 0), Ab, lda, brow, t + 2);
;       BAR; WAIT_L(0); MMA(1, 0, At, B0); BAR; SCHED;
.LBB0_838:
	ds_read_b128 v[168:171], v164
	ds_read_b128 v[174:177], v164 offset:1024
	ds_read_b128 v[178:181], v164 offset:2048
	ds_read_b128 v[182:185], v164 offset:3072
	v_add_u32_e32 v172, 0xc000, v147
	v_lshl_add_u64 v[238:239], v[136:137], 0, s[50:51]
	v_readfirstlane_b32 s73, v172
	v_add_u32_e32 v173, 0xe000, v147
	v_lshl_add_u64 v[166:167], v[238:239], 0, s[22:23]
	s_mov_b32 m0, s73
	v_lshl_add_u64 v[240:241], v[134:135], 0, s[50:51]
	ds_read_b128 v[186:189], v155
	ds_read_b128 v[190:193], v155 offset:1024
	ds_read_b128 v[194:197], v154
	ds_read_b128 v[198:201], v154 offset:1024
	ds_read_b128 v[202:205], v153
	ds_read_b128 v[206:209], v153 offset:1024
	ds_read_b128 v[210:213], v152
	ds_read_b128 v[214:217], v152 offset:1024
	global_load_lds_dwordx4 v[166:167], off
	s_bitset1_b32 m0, 13
	v_lshl_add_u64 v[166:167], v[240:241], 0, s[22:23]
	global_load_lds_dwordx4 v[166:167], off
	s_waitcnt lgkmcnt(8)
	s_barrier
	s_waitcnt lgkmcnt(0)
	s_waitcnt lgkmcnt(0)
	v_mfma_f32_16x16x32_bf16 v[124:127], v[168:171], v[186:189], v[124:127]
	v_mfma_f32_16x16x32_bf16 v[120:123], v[178:181], v[186:189], v[120:123]
	v_mfma_f32_16x16x32_bf16 v[116:119], v[168:171], v[194:197], v[116:119]
	v_mfma_f32_16x16x32_bf16 v[112:115], v[178:181], v[194:197], v[112:115]
	v_mfma_f32_16x16x32_bf16 v[108:111], v[168:171], v[202:205], v[108:111]
	v_mfma_f32_16x16x32_bf16 v[104:107], v[178:181], v[202:205], v[104:107]
	v_mfma_f32_16x16x32_bf16 v[100:103], v[168:171], v[210:213], v[100:103]
	v_mfma_f32_16x16x32_bf16 v[96:99], v[178:181], v[210:213], v[96:99]
	v_mfma_f32_16x16x32_bf16 v[124:127], v[174:177], v[190:193], v[124:127]
	v_mfma_f32_16x16x32_bf16 v[120:123], v[182:185], v[190:193], v[120:123]
	v_mfma_f32_16x16x32_bf16 v[116:119], v[174:177], v[198:201], v[116:119]
	v_mfma_f32_16x16x32_bf16 v[112:115], v[182:185], v[198:201], v[112:115]
	v_mfma_f32_16x16x32_bf16 v[108:111], v[174:177], v[206:209], v[108:111]
	v_mfma_f32_16x16x32_bf16 v[104:107], v[182:185], v[206:209], v[104:107]
	v_mfma_f32_16x16x32_bf16 v[100:103], v[174:177], v[214:217], v[100:103]
	v_mfma_f32_16x16x32_bf16 v[96:99], v[182:185], v[214:217], v[96:99]
	s_barrier
	v_add_u32_e32 v165, s63, v156
	v_lshl_add_u64 v[242:243], v[144:145], 0, s[50:51]
	v_readfirstlane_b32 s73, v165
	v_lshl_add_u64 v[166:167], v[242:243], 0, s[24:25]
	s_mov_b32 m0, s73
	ds_read_b128 v[218:221], v163
	ds_read_b128 v[222:225], v163 offset:1024
	ds_read_b128 v[226:229], v163 offset:2048
	ds_read_b128 v[230:233], v163 offset:3072
	global_load_lds_dwordx4 v[166:167], off
	s_bitset1_b32 m0, 13
	v_add_u32_e32 v166, 0x2000, v165
	v_lshl_add_u64 v[244:245], v[142:143], 0, s[50:51]
	v_lshl_add_u64 v[234:235], v[244:245], 0, s[24:25]
	global_load_lds_dwordx4 v[234:235], off
	s_barrier
	s_waitcnt lgkmcnt(0)
	s_waitcnt lgkmcnt(0)
	v_mfma_f32_16x16x32_bf16 v[92:95], v[218:221], v[186:189], v[92:95]
	v_mfma_f32_16x16x32_bf16 v[88:91], v[226:229], v[186:189], v[88:91]
	v_mfma_f32_16x16x32_bf16 v[84:87], v[218:221], v[194:197], v[84:87]
	v_mfma_f32_16x16x32_bf16 v[80:83], v[226:229], v[194:197], v[80:83]
	v_mfma_f32_16x16x32_bf16 v[76:79], v[218:221], v[202:205], v[76:79]
	v_mfma_f32_16x16x32_bf16 v[72:75], v[226:229], v[202:205], v[72:75]
	v_mfma_f32_16x16x32_bf16 v[68:71], v[218:221], v[210:213], v[68:71]
	v_mfma_f32_16x16x32_bf16 v[64:67], v[226:229], v[210:213], v[64:67]
	v_mfma_f32_16x16x32_bf16 v[92:95], v[222:225], v[190:193], v[92:95]
	v_mfma_f32_16x16x32_bf16 v[88:91], v[230:233], v[190:193], v[88:91]
	v_mfma_f32_16x16x32_bf16 v[84:87], v[222:225], v[198:201], v[84:87]
	v_mfma_f32_16x16x32_bf16 v[80:83], v[230:233], v[198:201], v[80:83]
	v_mfma_f32_16x16x32_bf16 v[76:79], v[222:225], v[206:209], v[76:79]
	v_mfma_f32_16x16x32_bf16 v[72:75], v[230:233], v[206:209], v[72:75]
	v_mfma_f32_16x16x32_bf16 v[68:71], v[222:225], v[214:217], v[68:71]
	v_mfma_f32_16x16x32_bf16 v[64:67], v[230:233], v[214:217], v[64:67]
	v_readfirstlane_b32 s73, v147
	v_add_u32_e32 v167, 0x2000, v147
	v_lshl_add_u64 v[234:235], v[238:239], 0, s[26:27]
	s_mov_b32 m0, s73
	s_barrier
	ds_read_b128 v[186:189], v155 offset:16384
	ds_read_b128 v[190:193], v155 offset:17408
	ds_read_b128 v[194:197], v154 offset:16384
	ds_read_b128 v[198:201], v154 offset:17408
	ds_read_b128 v[202:205], v153 offset:16384
	ds_read_b128 v[206:209], v153 offset:17408
	ds_read_b128 v[210:213], v152 offset:16384
	ds_read_b128 v[214:217], v152 offset:17408
	global_load_lds_dwordx4 v[234:235], off
	s_bitset1_b32 m0, 13
	v_lshl_add_u64 v[234:235], v[240:241], 0, s[26:27]
	global_load_lds_dwordx4 v[234:235], off
	s_barrier
	s_waitcnt lgkmcnt(0)
	s_waitcnt lgkmcnt(0)
	v_mfma_f32_16x16x32_bf16 v[60:63], v[168:171], v[186:189], v[60:63]
	v_mfma_f32_16x16x32_bf16 v[56:59], v[178:181], v[186:189], v[56:59]
	v_mfma_f32_16x16x32_bf16 v[52:55], v[168:171], v[194:197], v[52:55]
	v_mfma_f32_16x16x32_bf16 v[48:51], v[178:181], v[194:197], v[48:51]
	v_mfma_f32_16x16x32_bf16 v[44:47], v[168:171], v[202:205], v[44:47]
	v_mfma_f32_16x16x32_bf16 v[40:43], v[178:181], v[202:205], v[40:43]
	v_mfma_f32_16x16x32_bf16 v[36:39], v[168:171], v[210:213], v[36:39]
	v_mfma_f32_16x16x32_bf16 v[32:35], v[178:181], v[210:213], v[32:35]
	v_mfma_f32_16x16x32_bf16 v[60:63], v[174:177], v[190:193], v[60:63]
	v_mfma_f32_16x16x32_bf16 v[56:59], v[182:185], v[190:193], v[56:59]
	v_mfma_f32_16x16x32_bf16 v[52:55], v[174:177], v[198:201], v[52:55]
	v_mfma_f32_16x16x32_bf16 v[48:51], v[182:185], v[198:201], v[48:51]
	v_mfma_f32_16x16x32_bf16 v[44:47], v[174:177], v[206:209], v[44:47]
	v_mfma_f32_16x16x32_bf16 v[40:43], v[182:185], v[206:209], v[40:43]
	v_mfma_f32_16x16x32_bf16 v[36:39], v[174:177], v[214:217], v[36:39]
	v_mfma_f32_16x16x32_bf16 v[32:35], v[182:185], v[214:217], v[32:35]
	s_barrier
; #define STAGE(P, BASE, LD, br, kt) do { const char* _g = (const char*)((BASE) + (size_t)(br) * (LD) + (size_t)(kt) * 64); \
;     for (int _i = 0; _i < 2; ++_i) { int _b = tidx * 16 + _i * 8192; int _r, _c; stage_rc(_b, _r, _c); \
;       __builtin_amdgcn_global_load_lds((const unsigned*)(_g + (unsigned)((_r * (LD) + _c) * 2)), (unsigned*)((char*)(P) + _b), 16, 0, 0); } } while (0)
; #define LDA(dst, b, h) for (int m = 0; m < 4; ++m) for (int k = 0; k < 2; ++k) \
;     dst[m][k] = *reinterpret_cast<const bf16x8*>((char*)SA(b, h) + lds_byte(wr * 64 + m * 16 + fr, k * 32 + fq * 8))
; #define LDB(dst, b, h) for (int n = 0; n < 2; ++n) for (int k = 0; k < 2; ++k) \
;     dst[n][k] = *reinterpret_cast<const bf16x8*>((char*)SB(b, h) + lds_byte(wc * 32 + n * 16 + fr, k * 32 + fq * 8))
; #define MMA(ai, bj, At_, Bt_) do { __builtin_amdgcn_s_setprio(1); \
;     for (int k = 0; k < 2; ++k) for (int m = 0; m < 4; ++m) for (int n = 0; n < 2; ++n) \
;       acc[ai][bj][m][n] = __builtin_amdgcn_mfma_f32_16x16x32_bf16(At_[m][k], Bt_[n][k], acc[ai][bj][m][n], 0, 0, 0); \
;     __builtin_amdgcn_s_setprio(0); } while (0)
; #define WAIT_V(n) asm volatile("s_waitcnt vmcnt(" #n ")" ::: "memory")
; #define WAIT_L(n) asm volatile("s_waitcnt lgkmcnt(" #n ")" ::: "memory")
; #define BAR __builtin_amdgcn_s_barrier()
; #define SCHED __builtin_amdgcn_sched_barrier(0)
; template <int EPI, int lda, int ldb, int N, int K>
; __device__ __forceinline__ void gemm_phase(const u16* __restrict__ A, const u16* __restrict__ Bt, const GemmEpi ep, int wv) {
;     ...
;       STAGE(SB(0, 1), Bt, ldb, bcol + HALF, t + 2);
;       WAIT_V(6); BAR; MMA(1, 1, At, B1); BAR;
;       LDB(B0, 1, 0); SCHED; LDA(At, 1, 0); STAGE(SA(0, 1), Ab, lda, brow + HALF, t + 2);
;       WAIT_L(8); BAR; WAIT_L(0); MMA(0, 0, At, B0); BAR; SCHED;
;       LDB(B1, 1, 1); STAGE(SB(1, 0), Bt, ldb, bcol, t + 3);
;       BAR; WAIT_L(0); MMA(0, 1, At, B1); BAR;
;       LDA(At, 1, 1); STAGE(SA(1, 0), Ab, lda, brow, t + 3);
	v_add_u32_e32 v168, s64, v156
	v_lshl_add_u64 v[246:247], v[140:141], 0, s[50:51]
	v_readfirstlane_b32 s73, v168
	v_add_u32_e32 v169, 0x2000, v168
	v_lshl_add_u64 v[170:171], v[246:247], 0, s[40:41]
	s_mov_b32 m0, s73
	v_lshl_add_u64 v[248:249], v[138:139], 0, s[50:51]
	global_load_lds_dwordx4 v[170:171], off
	s_bitset1_b32 m0, 13
	v_lshl_add_u64 v[170:171], v[248:249], 0, s[40:41]
	global_load_lds_dwordx4 v[170:171], off
	s_waitcnt vmcnt(6)
	s_barrier
	v_mfma_f32_16x16x32_bf16 v[28:31], v[218:221], v[186:189], v[28:31]
	v_mfma_f32_16x16x32_bf16 v[24:27], v[226:229], v[186:189], v[24:27]
	v_mfma_f32_16x16x32_bf16 v[20:23], v[218:221], v[194:197], v[20:23]
	v_mfma_f32_16x16x32_bf16 v[16:19], v[226:229], v[194:197], v[16:19]
	v_mfma_f32_16x16x32_bf16 v[12:15], v[218:221], v[202:205], v[12:15]
	v_mfma_f32_16x16x32_bf16 v[8:11], v[226:229], v[202:205], v[8:11]
	v_mfma_f32_16x16x32_bf16 v[4:7], v[218:221], v[210:213], v[4:7]
	v_mfma_f32_16x16x32_bf16 v[0:3], v[226:229], v[210:213], v[0:3]
	v_mfma_f32_16x16x32_bf16 v[28:31], v[222:225], v[190:193], v[28:31]
	v_mfma_f32_16x16x32_bf16 v[24:27], v[230:233], v[190:193], v[24:27]
	v_mfma_f32_16x16x32_bf16 v[20:23], v[222:225], v[198:201], v[20:23]
	v_mfma_f32_16x16x32_bf16 v[16:19], v[230:233], v[198:201], v[16:19]
	v_mfma_f32_16x16x32_bf16 v[12:15], v[222:225], v[206:209], v[12:15]
	v_mfma_f32_16x16x32_bf16 v[8:11], v[230:233], v[206:209], v[8:11]
	v_mfma_f32_16x16x32_bf16 v[4:7], v[222:225], v[214:217], v[4:7]
	v_mfma_f32_16x16x32_bf16 v[0:3], v[230:233], v[214:217], v[0:3]
	s_barrier
	ds_read_b128 v[174:177], v159
	ds_read_b128 v[178:181], v159 offset:1024
	ds_read_b128 v[182:185], v159 offset:2048
	ds_read_b128 v[186:189], v159 offset:3072
	v_add_u32_e32 v170, 0x4000, v147
	v_add_u32_e32 v171, 0x6000, v147
	v_readfirstlane_b32 s73, v170
	v_lshl_add_u64 v[222:223], v[238:239], 0, s[42:43]
	s_mov_b32 m0, s73
	ds_read_b128 v[190:193], v155 offset:32768
	ds_read_b128 v[194:197], v155 offset:33792
	ds_read_b128 v[198:201], v154 offset:32768
	ds_read_b128 v[202:205], v154 offset:33792
	ds_read_b128 v[206:209], v153 offset:32768
	ds_read_b128 v[210:213], v153 offset:33792
	ds_read_b128 v[214:217], v152 offset:32768
	ds_read_b128 v[218:221], v152 offset:33792
	global_load_lds_dwordx4 v[222:223], off
	s_bitset1_b32 m0, 13
	v_lshl_add_u64 v[222:223], v[240:241], 0, s[42:43]
	global_load_lds_dwordx4 v[222:223], off
	s_waitcnt lgkmcnt(8)
	s_barrier
	s_waitcnt lgkmcnt(0)
	s_waitcnt lgkmcnt(0)
	v_mfma_f32_16x16x32_bf16 v[124:127], v[174:177], v[190:193], v[124:127]
	v_mfma_f32_16x16x32_bf16 v[120:123], v[182:185], v[190:193], v[120:123]
	v_mfma_f32_16x16x32_bf16 v[116:119], v[174:177], v[198:201], v[116:119]
	v_mfma_f32_16x16x32_bf16 v[112:115], v[182:185], v[198:201], v[112:115]
	v_mfma_f32_16x16x32_bf16 v[108:111], v[174:177], v[206:209], v[108:111]
	v_mfma_f32_16x16x32_bf16 v[104:107], v[182:185], v[206:209], v[104:107]
	v_mfma_f32_16x16x32_bf16 v[100:103], v[174:177], v[214:217], v[100:103]
	v_mfma_f32_16x16x32_bf16 v[96:99], v[182:185], v[214:217], v[96:99]
	v_mfma_f32_16x16x32_bf16 v[124:127], v[178:181], v[194:197], v[124:127]
	v_mfma_f32_16x16x32_bf16 v[120:123], v[186:189], v[194:197], v[120:123]
	v_mfma_f32_16x16x32_bf16 v[116:119], v[178:181], v[202:205], v[116:119]
	v_mfma_f32_16x16x32_bf16 v[112:115], v[186:189], v[202:205], v[112:115]
	v_mfma_f32_16x16x32_bf16 v[108:111], v[178:181], v[210:213], v[108:111]
	v_mfma_f32_16x16x32_bf16 v[104:107], v[186:189], v[210:213], v[104:107]
	v_mfma_f32_16x16x32_bf16 v[100:103], v[178:181], v[218:221], v[100:103]
	v_mfma_f32_16x16x32_bf16 v[96:99], v[186:189], v[218:221], v[96:99]
	s_barrier
	v_readfirstlane_b32 s73, v158
	v_lshl_add_u64 v[242:243], v[242:243], 0, s[44:45]
	s_mov_b32 m0, s73
	ds_read_b128 v[222:225], v157
	ds_read_b128 v[226:229], v157 offset:1024
	ds_read_b128 v[230:233], v157 offset:2048
	ds_read_b128 v[234:237], v157 offset:3072
	global_load_lds_dwordx4 v[242:243], off
	s_bitset1_b32 m0, 13
	v_lshl_add_u64 v[242:243], v[244:245], 0, s[44:45]
	v_add_u32_e32 v244, 0x2000, v158
	global_load_lds_dwordx4 v[242:243], off
	s_barrier
	s_waitcnt lgkmcnt(0)
	s_waitcnt lgkmcnt(0)
	v_mfma_f32_16x16x32_bf16 v[92:95], v[222:225], v[190:193], v[92:95]
	v_mfma_f32_16x16x32_bf16 v[88:91], v[230:233], v[190:193], v[88:91]
	v_mfma_f32_16x16x32_bf16 v[84:87], v[222:225], v[198:201], v[84:87]
	v_mfma_f32_16x16x32_bf16 v[80:83], v[230:233], v[198:201], v[80:83]
	v_mfma_f32_16x16x32_bf16 v[76:79], v[222:225], v[206:209], v[76:79]
	v_mfma_f32_16x16x32_bf16 v[72:75], v[230:233], v[206:209], v[72:75]
	v_mfma_f32_16x16x32_bf16 v[68:71], v[222:225], v[214:217], v[68:71]
	v_mfma_f32_16x16x32_bf16 v[64:67], v[230:233], v[214:217], v[64:67]
	v_mfma_f32_16x16x32_bf16 v[92:95], v[226:229], v[194:197], v[92:95]
	v_mfma_f32_16x16x32_bf16 v[88:91], v[234:237], v[194:197], v[88:91]
	v_mfma_f32_16x16x32_bf16 v[84:87], v[226:229], v[202:205], v[84:87]
	v_mfma_f32_16x16x32_bf16 v[80:83], v[234:237], v[202:205], v[80:83]
	v_mfma_f32_16x16x32_bf16 v[76:79], v[226:229], v[210:213], v[76:79]
	v_mfma_f32_16x16x32_bf16 v[72:75], v[234:237], v[210:213], v[72:75]
	v_mfma_f32_16x16x32_bf16 v[68:71], v[226:229], v[218:221], v[68:71]
	v_mfma_f32_16x16x32_bf16 v[64:67], v[234:237], v[218:221], v[64:67]
	v_readfirstlane_b32 s73, v160
	v_lshl_add_u64 v[238:239], v[238:239], 0, s[46:47]
	s_mov_b32 m0, s73
	s_barrier
	ds_read_b128 v[190:193], v155 offset:49152
	ds_read_b128 v[194:197], v155 offset:50176
	ds_read_b128 v[198:201], v154 offset:49152
	ds_read_b128 v[202:205], v154 offset:50176
	ds_read_b128 v[206:209], v153 offset:49152
	ds_read_b128 v[210:213], v153 offset:50176
	ds_read_b128 v[214:217], v152 offset:49152
	ds_read_b128 v[218:221], v152 offset:50176
	global_load_lds_dwordx4 v[238:239], off
	s_bitset1_b32 m0, 13
	v_lshl_add_u64 v[238:239], v[240:241], 0, s[46:47]
	global_load_lds_dwordx4 v[238:239], off
	s_barrier
; #define STAGE(P, BASE, LD, br, kt) do { const char* _g = (const char*)((BASE) + (size_t)(br) * (LD) + (size_t)(kt) * 64); \
;     for (int _i = 0; _i < 2; ++_i) { int _b = tidx * 16 + _i * 8192; int _r, _c; stage_rc(_b, _r, _c); \
;       __builtin_amdgcn_global_load_lds((const unsigned*)(_g + (unsigned)((_r * (LD) + _c) * 2)), (unsigned*)((char*)(P) + _b), 16, 0, 0); } } while (0)
; #define LDA(dst, b, h) for (int m = 0; m < 4; ++m) for (int k = 0; k < 2; ++k) \
;     dst[m][k] = *reinterpret_cast<const bf16x8*>((char*)SA(b, h) + lds_byte(wr * 64 + m * 16 + fr, k * 32 + fq * 8))
; #define LDB(dst, b, h) for (int n = 0; n < 2; ++n) for (int k = 0; k < 2; ++k) \
;     dst[n][k] = *reinterpret_cast<const bf16x8*>((char*)SB(b, h) + lds_byte(wc * 32 + n * 16 + fr, k * 32 + fq * 8))
; #define MMA(ai, bj, At_, Bt_) do { __builtin_amdgcn_s_setprio(1); \
;     for (int k = 0; k < 2; ++k) for (int m = 0; m < 4; ++m) for (int n = 0; n < 2; ++n) \
;       acc[ai][bj][m][n] = __builtin_amdgcn_mfma_f32_16x16x32_bf16(At_[m][k], Bt_[n][k], acc[ai][bj][m][n], 0, 0, 0); \
;     __builtin_amdgcn_s_setprio(0); } while (0)
; #define WAIT_V(n) asm volatile("s_waitcnt vmcnt(" #n ")" ::: "memory")
; #define WAIT_L(n) asm volatile("s_waitcnt lgkmcnt(" #n ")" ::: "memory")
; #define BAR __builtin_amdgcn_s_barrier()
; #define SCHED __builtin_amdgcn_sched_barrier(0)
; template <int EPI, int lda, int ldb, int N, int K>
; __device__ __forceinline__ void gemm_phase(const u16* __restrict__ A, const u16* __restrict__ Bt, const GemmEpi ep, int wv) {
;     ...
;       BAR; WAIT_L(0); MMA(1, 0, At, B0); BAR; SCHED;
;       STAGE(SB(1, 1), Bt, ldb, bcol + HALF, t + 3);
;       WAIT_V(6); BAR; MMA(1, 1, At, B1); BAR;
;     }
;     { LDB(B0, 0, 0); LDA(At, 0, 0); STAGE(SA(1, 1), Ab, lda, brow + HALF, nt - 1);
;       BAR; WAIT_L(0); MMA(0, 0, At, B0); BAR;
;       LDB(B1, 0, 1); BAR; WAIT_L(0); MMA(0, 1, At, B1); BAR;
	s_waitcnt lgkmcnt(0)
	s_waitcnt lgkmcnt(0)
	v_mfma_f32_16x16x32_bf16 v[60:63], v[174:177], v[190:193], v[60:63]
	v_mfma_f32_16x16x32_bf16 v[56:59], v[182:185], v[190:193], v[56:59]
	v_mfma_f32_16x16x32_bf16 v[52:55], v[174:177], v[198:201], v[52:55]
	v_mfma_f32_16x16x32_bf16 v[48:51], v[182:185], v[198:201], v[48:51]
	v_mfma_f32_16x16x32_bf16 v[44:47], v[174:177], v[206:209], v[44:47]
	v_mfma_f32_16x16x32_bf16 v[40:43], v[182:185], v[206:209], v[40:43]
	v_mfma_f32_16x16x32_bf16 v[36:39], v[174:177], v[214:217], v[36:39]
	v_mfma_f32_16x16x32_bf16 v[32:35], v[182:185], v[214:217], v[32:35]
	v_mfma_f32_16x16x32_bf16 v[60:63], v[178:181], v[194:197], v[60:63]
	v_mfma_f32_16x16x32_bf16 v[56:59], v[186:189], v[194:197], v[56:59]
	v_mfma_f32_16x16x32_bf16 v[52:55], v[178:181], v[202:205], v[52:55]
	v_mfma_f32_16x16x32_bf16 v[48:51], v[186:189], v[202:205], v[48:51]
	v_mfma_f32_16x16x32_bf16 v[44:47], v[178:181], v[210:213], v[44:47]
	v_mfma_f32_16x16x32_bf16 v[40:43], v[186:189], v[210:213], v[40:43]
	v_mfma_f32_16x16x32_bf16 v[36:39], v[178:181], v[218:221], v[36:39]
	v_mfma_f32_16x16x32_bf16 v[32:35], v[186:189], v[218:221], v[32:35]
	s_barrier
	v_readfirstlane_b32 s73, v162
	v_add_u32_e32 v176, 0x2000, v162
	v_lshl_add_u64 v[174:175], v[246:247], 0, s[48:49]
	s_mov_b32 m0, s73
	global_load_lds_dwordx4 v[174:175], off
	s_bitset1_b32 m0, 13
	v_lshl_add_u64 v[174:175], v[248:249], 0, s[48:49]
	global_load_lds_dwordx4 v[174:175], off
	s_waitcnt vmcnt(6)
	s_barrier
	v_mfma_f32_16x16x32_bf16 v[28:31], v[222:225], v[190:193], v[28:31]
	v_mfma_f32_16x16x32_bf16 v[24:27], v[230:233], v[190:193], v[24:27]
	v_mfma_f32_16x16x32_bf16 v[20:23], v[222:225], v[198:201], v[20:23]
	v_mfma_f32_16x16x32_bf16 v[16:19], v[230:233], v[198:201], v[16:19]
	v_mfma_f32_16x16x32_bf16 v[12:15], v[222:225], v[206:209], v[12:15]
	v_mfma_f32_16x16x32_bf16 v[8:11], v[230:233], v[206:209], v[8:11]
	v_mfma_f32_16x16x32_bf16 v[4:7], v[222:225], v[214:217], v[4:7]
	v_mfma_f32_16x16x32_bf16 v[0:3], v[230:233], v[214:217], v[0:3]
	v_mfma_f32_16x16x32_bf16 v[28:31], v[226:229], v[194:197], v[28:31]
	v_mfma_f32_16x16x32_bf16 v[24:27], v[234:237], v[194:197], v[24:27]
	v_mfma_f32_16x16x32_bf16 v[20:23], v[226:229], v[202:205], v[20:23]
	v_mfma_f32_16x16x32_bf16 v[16:19], v[234:237], v[202:205], v[16:19]
	v_mfma_f32_16x16x32_bf16 v[12:15], v[226:229], v[210:213], v[12:15]
	v_mfma_f32_16x16x32_bf16 v[8:11], v[234:237], v[210:213], v[8:11]
	v_mfma_f32_16x16x32_bf16 v[4:7], v[226:229], v[218:221], v[4:7]
	v_mfma_f32_16x16x32_bf16 v[0:3], v[234:237], v[218:221], v[0:3]
	s_add_i32 s72, s72, 2
	s_add_u32 s50, s50, 0x100
	s_addc_u32 s51, s51, 0
	s_cmpk_gt_u32 s72, 0x51
	s_barrier
	s_cbranch_scc0 .LBB0_838
	s_add_i32 s50, s18, 0x80
	s_mul_hi_i32 s51, s50, 0x2b00
	s_mulk_i32 s50, 0x2b00
	s_add_u32 s50, s56, s50
	s_addc_u32 s51, s57, s51
	s_add_u32 s50, s50, 0x2a80
	s_addc_u32 s51, s51, 0
	v_readfirstlane_b32 s72, v172
	v_lshl_add_u64 v[160:161], s[50:51], 0, v[128:129]
	s_mov_b32 m0, s72
	ds_read_b128 v[134:137], v164
	ds_read_b128 v[138:141], v164 offset:1024
	ds_read_b128 v[142:145], v164 offset:2048
	ds_read_b128 v[174:177], v164 offset:3072
	ds_read_b128 v[178:181], v155
	ds_read_b128 v[182:185], v155 offset:1024
	ds_read_b128 v[186:189], v154
	ds_read_b128 v[190:193], v154 offset:1024
	ds_read_b128 v[194:197], v153
	ds_read_b128 v[198:201], v153 offset:1024
	ds_read_b128 v[202:205], v152
	ds_read_b128 v[206:209], v152 offset:1024
	global_load_lds_dwordx4 v[160:161], off
	v_lshl_add_u64 v[160:161], s[50:51], 0, v[132:133]
	v_readfirstlane_b32 s50, v173
	s_mov_b32 m0, s50
	s_nop 0
	global_load_lds_dwordx4 v[160:161], off
	s_barrier
	s_waitcnt lgkmcnt(0)
	s_waitcnt lgkmcnt(0)
	v_mfma_f32_16x16x32_bf16 v[124:127], v[134:137], v[178:181], v[124:127]
	v_mfma_f32_16x16x32_bf16 v[120:123], v[142:145], v[178:181], v[120:123]
	v_mfma_f32_16x16x32_bf16 v[116:119], v[134:137], v[186:189], v[116:119]
	v_mfma_f32_16x16x32_bf16 v[112:115], v[142:145], v[186:189], v[112:115]
	v_mfma_f32_16x16x32_bf16 v[108:111], v[134:137], v[194:197], v[108:111]
	v_mfma_f32_16x16x32_bf16 v[104:107], v[142:145], v[194:197], v[104:107]
	v_mfma_f32_16x16x32_bf16 v[100:103], v[134:137], v[202:205], v[100:103]
	v_mfma_f32_16x16x32_bf16 v[96:99], v[142:145], v[202:205], v[96:99]
	v_mfma_f32_16x16x32_bf16 v[124:127], v[138:141], v[182:185], v[124:127]
	v_mfma_f32_16x16x32_bf16 v[120:123], v[174:177], v[182:185], v[120:123]
	v_mfma_f32_16x16x32_bf16 v[116:119], v[138:141], v[190:193], v[116:119]
	v_mfma_f32_16x16x32_bf16 v[112:115], v[174:177], v[190:193], v[112:115]
	v_mfma_f32_16x16x32_bf16 v[108:111], v[138:141], v[198:201], v[108:111]
	v_mfma_f32_16x16x32_bf16 v[104:107], v[174:177], v[198:201], v[104:107]
	v_mfma_f32_16x16x32_bf16 v[100:103], v[138:141], v[206:209], v[100:103]
	v_mfma_f32_16x16x32_bf16 v[96:99], v[174:177], v[206:209], v[96:99]
	s_barrier
	ds_read_b128 v[210:213], v163
	ds_read_b128 v[214:217], v163 offset:1024
	ds_read_b128 v[218:221], v163 offset:2048
	ds_read_b128 v[160:163], v163 offset:3072
	s_barrier
	s_waitcnt lgkmcnt(0)
	s_waitcnt lgkmcnt(0)
	v_mfma_f32_16x16x32_bf16 v[92:95], v[210:213], v[178:181], v[92:95]
	v_mfma_f32_16x16x32_bf16 v[88:91], v[218:221], v[178:181], v[88:91]
	v_mfma_f32_16x16x32_bf16 v[76:79], v[210:213], v[194:197], v[76:79]
	v_mfma_f32_16x16x32_bf16 v[72:75], v[218:221], v[194:197], v[72:75]
	v_mfma_f32_16x16x32_bf16 v[84:87], v[210:213], v[186:189], v[84:87]
	v_mfma_f32_16x16x32_bf16 v[80:83], v[218:221], v[186:189], v[80:83]
	v_mfma_f32_16x16x32_bf16 v[68:71], v[210:213], v[202:205], v[68:71]
	v_mfma_f32_16x16x32_bf16 v[64:67], v[218:221], v[202:205], v[64:67]
	v_mfma_f32_16x16x32_bf16 v[92:95], v[214:217], v[182:185], v[92:95]
	v_mfma_f32_16x16x32_bf16 v[88:91], v[160:163], v[182:185], v[88:91]
	v_mfma_f32_16x16x32_bf16 v[76:79], v[214:217], v[198:201], v[76:79]
	v_mfma_f32_16x16x32_bf16 v[72:75], v[160:163], v[198:201], v[72:75]
	v_mfma_f32_16x16x32_bf16 v[178:181], v[214:217], v[190:193], v[84:87]
	v_mfma_f32_16x16x32_bf16 v[182:185], v[160:163], v[190:193], v[80:83]
	v_mfma_f32_16x16x32_bf16 v[186:189], v[214:217], v[206:209], v[68:71]
	v_mfma_f32_16x16x32_bf16 v[190:193], v[160:163], v[206:209], v[64:67]
	s_barrier
; #define LDA(dst, b, h) for (int m = 0; m < 4; ++m) for (int k = 0; k < 2; ++k) \
;     dst[m][k] = *reinterpret_cast<const bf16x8*>((char*)SA(b, h) + lds_byte(wr * 64 + m * 16 + fr, k * 32 + fq * 8))
; #define LDB(dst, b, h) for (int n = 0; n < 2; ++n) for (int k = 0; k < 2; ++k) \
;     dst[n][k] = *reinterpret_cast<const bf16x8*>((char*)SB(b, h) + lds_byte(wc * 32 + n * 16 + fr, k * 32 + fq * 8))
; #define MMA(ai, bj, At_, Bt_) do { __builtin_amdgcn_s_setprio(1); \
;     for (int k = 0; k < 2; ++k) for (int m = 0; m < 4; ++m) for (int n = 0; n < 2; ++n) \
;       acc[ai][bj][m][n] = __builtin_amdgcn_mfma_f32_16x16x32_bf16(At_[m][k], Bt_[n][k], acc[ai][bj][m][n], 0, 0, 0); \
;     __builtin_amdgcn_s_setprio(0); } while (0)
; #define WAIT_V(n) asm volatile("s_waitcnt vmcnt(" #n ")" ::: "memory")
; #define WAIT_L(n) asm volatile("s_waitcnt lgkmcnt(" #n ")" ::: "memory")
; #define BAR __builtin_amdgcn_s_barrier()
; template <int EPI, int lda, int ldb, int N, int K>
; __device__ __forceinline__ void gemm_phase(const u16* __restrict__ A, const u16* __restrict__ Bt, const GemmEpi ep, int wv) {
;     ...
;       LDA(At, 0, 1); WAIT_V(4); BAR; WAIT_L(0); MMA(1, 0, At, B0); MMA(1, 1, At, B1); BAR; }
;     { LDB(B0, 1, 0); LDA(At, 1, 0); WAIT_V(2); BAR; WAIT_L(0); MMA(0, 0, At, B0); BAR;
	s_nop 0
	ds_read_b128 v[64:67], v155 offset:16384
	ds_read_b128 v[68:71], v155 offset:17408
	ds_read_b128 v[80:83], v154 offset:16384
	ds_read_b128 v[84:87], v154 offset:17408
	ds_read_b128 v[194:197], v153 offset:16384
	ds_read_b128 v[198:201], v153 offset:17408
	ds_read_b128 v[202:205], v152 offset:16384
	ds_read_b128 v[206:209], v152 offset:17408
	s_waitcnt vmcnt(4)
	s_barrier
	s_waitcnt lgkmcnt(0)
	s_waitcnt lgkmcnt(0)
	v_mfma_f32_16x16x32_bf16 v[60:63], v[134:137], v[64:67], v[60:63]
	v_mfma_f32_16x16x32_bf16 v[56:59], v[142:145], v[64:67], v[56:59]
	v_mfma_f32_16x16x32_bf16 v[52:55], v[134:137], v[80:83], v[52:55]
	v_mfma_f32_16x16x32_bf16 v[48:51], v[142:145], v[80:83], v[48:51]
	v_mfma_f32_16x16x32_bf16 v[44:47], v[134:137], v[194:197], v[44:47]
	v_mfma_f32_16x16x32_bf16 v[40:43], v[142:145], v[194:197], v[40:43]
	v_mfma_f32_16x16x32_bf16 v[36:39], v[134:137], v[202:205], v[36:39]
	v_mfma_f32_16x16x32_bf16 v[32:35], v[142:145], v[202:205], v[32:35]
	v_mfma_f32_16x16x32_bf16 v[60:63], v[138:141], v[68:71], v[60:63]
	v_mfma_f32_16x16x32_bf16 v[56:59], v[174:177], v[68:71], v[56:59]
	v_mfma_f32_16x16x32_bf16 v[52:55], v[138:141], v[84:87], v[52:55]
	v_mfma_f32_16x16x32_bf16 v[48:51], v[174:177], v[84:87], v[48:51]
	v_mfma_f32_16x16x32_bf16 v[44:47], v[138:141], v[198:201], v[44:47]
	v_mfma_f32_16x16x32_bf16 v[40:43], v[174:177], v[198:201], v[40:43]
	v_mfma_f32_16x16x32_bf16 v[36:39], v[138:141], v[206:209], v[36:39]
	v_mfma_f32_16x16x32_bf16 v[32:35], v[174:177], v[206:209], v[32:35]
	v_mfma_f32_16x16x32_bf16 v[28:31], v[210:213], v[64:67], v[28:31]
	v_mfma_f32_16x16x32_bf16 v[16:19], v[218:221], v[80:83], v[16:19]
	v_mfma_f32_16x16x32_bf16 v[12:15], v[210:213], v[194:197], v[12:15]
	v_mfma_f32_16x16x32_bf16 v[0:3], v[218:221], v[202:205], v[0:3]
	v_mfma_f32_16x16x32_bf16 v[24:27], v[218:221], v[64:67], v[24:27]
	v_mfma_f32_16x16x32_bf16 v[20:23], v[210:213], v[80:83], v[20:23]
	v_mfma_f32_16x16x32_bf16 v[8:11], v[218:221], v[194:197], v[8:11]
	v_mfma_f32_16x16x32_bf16 v[4:7], v[210:213], v[202:205], v[4:7]
	v_mfma_f32_16x16x32_bf16 v[28:31], v[214:217], v[68:71], v[28:31]
	v_mfma_f32_16x16x32_bf16 v[16:19], v[160:163], v[84:87], v[16:19]
	v_mfma_f32_16x16x32_bf16 v[12:15], v[214:217], v[198:201], v[12:15]
	v_mfma_f32_16x16x32_bf16 v[0:3], v[160:163], v[206:209], v[0:3]
	v_mfma_f32_16x16x32_bf16 v[134:137], v[160:163], v[68:71], v[24:27]
	v_mfma_f32_16x16x32_bf16 v[138:141], v[214:217], v[84:87], v[20:23]
	v_mfma_f32_16x16x32_bf16 v[142:145], v[160:163], v[198:201], v[8:11]
	v_mfma_f32_16x16x32_bf16 v[172:175], v[214:217], v[206:209], v[4:7]
	s_barrier
	s_nop 0
	ds_read_b128 v[4:7], v159
	ds_read_b128 v[8:11], v159 offset:1024
	ds_read_b128 v[20:23], v159 offset:2048
	ds_read_b128 v[158:161], v159 offset:3072
	ds_read_b128 v[24:27], v155 offset:32768
	ds_read_b128 v[194:197], v155 offset:33792
	ds_read_b128 v[198:201], v154 offset:32768
	ds_read_b128 v[202:205], v154 offset:33792
	ds_read_b128 v[206:209], v153 offset:32768
	ds_read_b128 v[210:213], v153 offset:33792
	ds_read_b128 v[214:217], v152 offset:32768
	ds_read_b128 v[218:221], v152 offset:33792
	s_waitcnt vmcnt(2)
	s_barrier
	s_waitcnt lgkmcnt(0)
	s_waitcnt lgkmcnt(0)
	v_mfma_f32_16x16x32_bf16 v[64:67], v[4:7], v[24:27], v[124:127]
	v_mfma_f32_16x16x32_bf16 v[68:71], v[20:23], v[24:27], v[120:123]
	v_mfma_f32_16x16x32_bf16 v[80:83], v[4:7], v[198:201], v[116:119]
	v_mfma_f32_16x16x32_bf16 v[84:87], v[20:23], v[198:201], v[112:115]
	v_mfma_f32_16x16x32_bf16 v[108:111], v[4:7], v[206:209], v[108:111]
	v_mfma_f32_16x16x32_bf16 v[104:107], v[20:23], v[206:209], v[104:107]
	v_mfma_f32_16x16x32_bf16 v[120:123], v[4:7], v[214:217], v[100:103]
	v_mfma_f32_16x16x32_bf16 v[124:127], v[20:23], v[214:217], v[96:99]
	v_mfma_f32_16x16x32_bf16 v[116:119], v[8:11], v[194:197], v[64:67]
	v_mfma_f32_16x16x32_bf16 v[112:115], v[158:161], v[194:197], v[68:71]
	v_mfma_f32_16x16x32_bf16 v[100:103], v[8:11], v[202:205], v[80:83]
	v_mfma_f32_16x16x32_bf16 v[96:99], v[158:161], v[202:205], v[84:87]
	v_mfma_f32_16x16x32_bf16 v[84:87], v[8:11], v[210:213], v[108:111]
	v_mfma_f32_16x16x32_bf16 v[80:83], v[158:161], v[210:213], v[104:107]
	v_mfma_f32_16x16x32_bf16 v[68:71], v[8:11], v[218:221], v[120:123]
	v_mfma_f32_16x16x32_bf16 v[64:67], v[158:161], v[218:221], v[124:127]
	s_barrier
; #define LDA(dst, b, h) for (int m = 0; m < 4; ++m) for (int k = 0; k < 2; ++k) \
;     dst[m][k] = *reinterpret_cast<const bf16x8*>((char*)SA(b, h) + lds_byte(wr * 64 + m * 16 + fr, k * 32 + fq * 8))
; #define LDB(dst, b, h) for (int n = 0; n < 2; ++n) for (int k = 0; k < 2; ++k) \
;     dst[n][k] = *reinterpret_cast<const bf16x8*>((char*)SB(b, h) + lds_byte(wc * 32 + n * 16 + fr, k * 32 + fq * 8))
; #define MMA(ai, bj, At_, Bt_) do { __builtin_amdgcn_s_setprio(1); \
;     for (int k = 0; k < 2; ++k) for (int m = 0; m < 4; ++m) for (int n = 0; n < 2; ++n) \
;       acc[ai][bj][m][n] = __builtin_amdgcn_mfma_f32_16x16x32_bf16(At_[m][k], Bt_[n][k], acc[ai][bj][m][n], 0, 0, 0); \
;     __builtin_amdgcn_s_setprio(0); } while (0)
; #define WAIT_V(n) asm volatile("s_waitcnt vmcnt(" #n ")" ::: "memory")
; #define WAIT_L(n) asm volatile("s_waitcnt lgkmcnt(" #n ")" ::: "memory")
; #define BAR __builtin_amdgcn_s_barrier()
; template <int EPI, int lda, int ldb, int N, int K>
; __device__ __forceinline__ void gemm_phase(const u16* __restrict__ A, const u16* __restrict__ Bt, const GemmEpi ep, int wv) {
;     ...
;       LDB(B1, 1, 1); WAIT_V(0); BAR; WAIT_L(0); MMA(0, 1, At, B1); BAR;
;       LDA(At, 1, 1); BAR; WAIT_L(0); MMA(1, 0, At, B0); MMA(1, 1, At, B1); BAR; }
;     if (wr == 0) BAR;
	ds_read_b128 v[222:225], v157
	ds_read_b128 v[226:229], v157 offset:1024
	ds_read_b128 v[230:233], v157 offset:2048
	ds_read_b128 v[234:237], v157 offset:3072
	s_waitcnt vmcnt(0)
	s_barrier
	s_waitcnt lgkmcnt(0)
	s_waitcnt lgkmcnt(0)
	v_mfma_f32_16x16x32_bf16 v[92:95], v[222:225], v[24:27], v[92:95]
	v_mfma_f32_16x16x32_bf16 v[24:27], v[230:233], v[24:27], v[88:91]
	v_mfma_f32_16x16x32_bf16 v[88:91], v[222:225], v[198:201], v[178:181]
	v_mfma_f32_16x16x32_bf16 v[104:107], v[230:233], v[198:201], v[182:185]
	v_mfma_f32_16x16x32_bf16 v[76:79], v[222:225], v[206:209], v[76:79]
	v_mfma_f32_16x16x32_bf16 v[72:75], v[230:233], v[206:209], v[72:75]
	v_mfma_f32_16x16x32_bf16 v[176:179], v[222:225], v[214:217], v[186:189]
	v_mfma_f32_16x16x32_bf16 v[180:183], v[230:233], v[214:217], v[190:193]
	v_mfma_f32_16x16x32_bf16 v[124:127], v[226:229], v[194:197], v[92:95]
	v_mfma_f32_16x16x32_bf16 v[120:123], v[234:237], v[194:197], v[24:27]
	v_mfma_f32_16x16x32_bf16 v[108:111], v[226:229], v[202:205], v[88:91]
	v_mfma_f32_16x16x32_bf16 v[104:107], v[234:237], v[202:205], v[104:107]
	v_mfma_f32_16x16x32_bf16 v[92:95], v[226:229], v[210:213], v[76:79]
	v_mfma_f32_16x16x32_bf16 v[88:91], v[234:237], v[210:213], v[72:75]
	v_mfma_f32_16x16x32_bf16 v[76:79], v[226:229], v[218:221], v[176:179]
	v_mfma_f32_16x16x32_bf16 v[72:75], v[234:237], v[218:221], v[180:183]
	s_barrier
	ds_read_b128 v[176:179], v155 offset:49152
	ds_read_b128 v[180:183], v155 offset:50176
	ds_read_b128 v[184:187], v154 offset:49152
	ds_read_b128 v[154:157], v154 offset:50176
	ds_read_b128 v[188:191], v153 offset:49152
	ds_read_b128 v[192:195], v153 offset:50176
	ds_read_b128 v[196:199], v152 offset:49152
	ds_read_b128 v[200:203], v152 offset:50176
	s_barrier
	s_waitcnt lgkmcnt(0)
	s_waitcnt lgkmcnt(0)
	v_mfma_f32_16x16x32_bf16 v[24:27], v[4:7], v[176:179], v[60:63]
	v_mfma_f32_16x16x32_bf16 v[60:63], v[20:23], v[176:179], v[56:59]
	v_mfma_f32_16x16x32_bf16 v[204:207], v[4:7], v[184:187], v[52:55]
	v_mfma_f32_16x16x32_bf16 v[48:51], v[20:23], v[184:187], v[48:51]
	v_mfma_f32_16x16x32_bf16 v[44:47], v[4:7], v[188:191], v[44:47]
	v_mfma_f32_16x16x32_bf16 v[208:211], v[20:23], v[188:191], v[40:43]
	v_mfma_f32_16x16x32_bf16 v[4:7], v[4:7], v[196:199], v[36:39]
	v_mfma_f32_16x16x32_bf16 v[32:35], v[20:23], v[196:199], v[32:35]
	v_mfma_f32_16x16x32_bf16 v[56:59], v[8:11], v[180:183], v[24:27]
	v_mfma_f32_16x16x32_bf16 v[52:55], v[158:161], v[180:183], v[60:63]
	v_mfma_f32_16x16x32_bf16 v[40:43], v[8:11], v[154:157], v[204:207]
	v_mfma_f32_16x16x32_bf16 v[36:39], v[158:161], v[154:157], v[48:51]
	v_mfma_f32_16x16x32_bf16 v[24:27], v[8:11], v[192:195], v[44:47]
	v_mfma_f32_16x16x32_bf16 v[20:23], v[158:161], v[192:195], v[208:211]
	v_mfma_f32_16x16x32_bf16 v[8:11], v[8:11], v[200:203], v[4:7]
	v_mfma_f32_16x16x32_bf16 v[4:7], v[158:161], v[200:203], v[32:35]
	v_mfma_f32_16x16x32_bf16 v[28:31], v[222:225], v[176:179], v[28:31]
	v_mfma_f32_16x16x32_bf16 v[32:35], v[230:233], v[176:179], v[134:137]
	v_mfma_f32_16x16x32_bf16 v[44:47], v[222:225], v[184:187], v[138:141]
	v_mfma_f32_16x16x32_bf16 v[16:19], v[230:233], v[184:187], v[16:19]
	v_mfma_f32_16x16x32_bf16 v[12:15], v[222:225], v[188:191], v[12:15]
	v_mfma_f32_16x16x32_bf16 v[134:137], v[230:233], v[188:191], v[142:145]
	v_mfma_f32_16x16x32_bf16 v[138:141], v[222:225], v[196:199], v[172:175]
	v_mfma_f32_16x16x32_bf16 v[0:3], v[230:233], v[196:199], v[0:3]
	v_mfma_f32_16x16x32_bf16 v[60:63], v[226:229], v[180:183], v[28:31]
	v_mfma_f32_16x16x32_bf16 v[48:51], v[234:237], v[180:183], v[32:35]
	v_mfma_f32_16x16x32_bf16 v[44:47], v[226:229], v[154:157], v[44:47]
	v_mfma_f32_16x16x32_bf16 v[32:35], v[234:237], v[154:157], v[16:19]
	v_mfma_f32_16x16x32_bf16 v[28:31], v[226:229], v[192:195], v[12:15]
	v_mfma_f32_16x16x32_bf16 v[16:19], v[234:237], v[192:195], v[134:137]
	v_mfma_f32_16x16x32_bf16 v[12:15], v[226:229], v[200:203], v[138:141]
	v_mfma_f32_16x16x32_bf16 v[0:3], v[234:237], v[200:203], v[0:3]
	v_cmp_gt_u32_e32 vcc, s69, v130
	s_barrier
	s_and_saveexec_b64 s[50:51], vcc
	s_cbranch_execz .LBB0_841
	s_barrier

; #define STAGE(P, BASE, LD, br, kt) do { const char* _g = (const char*)((BASE) + (size_t)(br) * (LD) + (size_t)(kt) * 64); \
;     for (int _i = 0; _i < 2; ++_i) { int _b = tidx * 16 + _i * 8192; int _r, _c; stage_rc(_b, _r, _c); \
;       __builtin_amdgcn_global_load_lds((const unsigned*)(_g + (unsigned)((_r * (LD) + _c) * 2)), (unsigned*)((char*)(P) + _b), 16, 0, 0); } } while (0)
; #define LDA(dst, b, h) for (int m = 0; m < 4; ++m) for (int k = 0; k < 2; ++k) \
;     dst[m][k] = *reinterpret_cast<const bf16x8*>((char*)SA(b, h) + lds_byte(wr * 64 + m * 16 + fr, k * 32 + fq * 8))
; #define LDB(dst, b, h) for (int n = 0; n < 2; ++n) for (int k = 0; k < 2; ++k) \
;     dst[n][k] = *reinterpret_cast<const bf16x8*>((char*)SB(b, h) + lds_byte(wc * 32 + n * 16 + fr, k * 32 + fq * 8))
; #define MMA(ai, bj, At_, Bt_) do { __builtin_amdgcn_s_setprio(1); \
;     for (int k = 0; k < 2; ++k) for (int m = 0; m < 4; ++m) for (int n = 0; n < 2; ++n) \
;       acc[ai][bj][m][n] = __builtin_amdgcn_mfma_f32_16x16x32_bf16(At_[m][k], Bt_[n][k], acc[ai][bj][m][n], 0, 0, 0); \
;     __builtin_amdgcn_s_setprio(0); } while (0)
; #define WAIT_L(n) asm volatile("s_waitcnt lgkmcnt(" #n ")" ::: "memory")
; #define BAR __builtin_amdgcn_s_barrier()
; #define SCHED __builtin_amdgcn_sched_barrier(0)
; template <int EPI, int lda, int ldb, int N, int K>
; __device__ __forceinline__ void gemm_phase(const u16* __restrict__ A, const u16* __restrict__ Bt, const GemmEpi ep, int wv) {
;     ...
;       LDB(B0, 0, 0); SCHED; LDA(At, 0, 0); STAGE(SA(1, 1), Ab, lda, brow + HALF, t + 1);
;       WAIT_L(8); BAR; WAIT_L(0); MMA(0, 0, At, B0); BAR; SCHED;
;       LDB(B1, 0, 1); STAGE(SB(0, 0), Bt, ldb, bcol, t + 2);
;       BAR; WAIT_L(0); MMA(0, 1, At, B1); BAR;
;       LDA(At, 0, 1); STAGE(SA(0, 0), Ab, lda, brow, t + 2);
;       BAR; WAIT_L(0); MMA(1, 0, At, B0); BAR; SCHED;
.LBB0_1147:
	ds_read_b128 v[172:175], v161
	ds_read_b128 v[176:179], v161 offset:1024
	ds_read_b128 v[180:183], v161 offset:2048
	ds_read_b128 v[184:187], v161 offset:3072
	v_add_u32_e32 v169, 0xc000, v148
	v_lshl_add_u64 v[236:237], v[138:139], 0, s[60:61]
	v_readfirstlane_b32 s63, v169
	v_add_u32_e32 v170, 0xe000, v148
	v_lshl_add_u64 v[162:163], v[236:237], 0, s[22:23]
	s_mov_b32 m0, s63
	v_lshl_add_u64 v[238:239], v[140:141], 0, s[60:61]
	ds_read_b128 v[164:167], v152
	ds_read_b128 v[188:191], v152 offset:1024
	ds_read_b128 v[192:195], v151
	ds_read_b128 v[196:199], v151 offset:1024
	ds_read_b128 v[200:203], v150
	ds_read_b128 v[204:207], v150 offset:1024
	ds_read_b128 v[208:211], v149
	ds_read_b128 v[212:215], v149 offset:1024
	global_load_lds_dwordx4 v[162:163], off
	s_bitset1_b32 m0, 13
	v_lshl_add_u64 v[162:163], v[238:239], 0, s[22:23]
	global_load_lds_dwordx4 v[162:163], off
	s_waitcnt lgkmcnt(8)
	s_barrier
	s_waitcnt lgkmcnt(0)
	s_waitcnt lgkmcnt(0)
	v_mfma_f32_16x16x32_bf16 v[124:127], v[164:167], v[172:175], v[124:127]
	v_mfma_f32_16x16x32_bf16 v[120:123], v[164:167], v[180:183], v[120:123]
	v_mfma_f32_16x16x32_bf16 v[116:119], v[192:195], v[172:175], v[116:119]
	v_mfma_f32_16x16x32_bf16 v[112:115], v[192:195], v[180:183], v[112:115]
	v_mfma_f32_16x16x32_bf16 v[108:111], v[200:203], v[172:175], v[108:111]
	v_mfma_f32_16x16x32_bf16 v[104:107], v[200:203], v[180:183], v[104:107]
	v_mfma_f32_16x16x32_bf16 v[100:103], v[208:211], v[172:175], v[100:103]
	v_mfma_f32_16x16x32_bf16 v[96:99], v[208:211], v[180:183], v[96:99]
	v_mfma_f32_16x16x32_bf16 v[124:127], v[188:191], v[176:179], v[124:127]
	v_mfma_f32_16x16x32_bf16 v[120:123], v[188:191], v[184:187], v[120:123]
	v_mfma_f32_16x16x32_bf16 v[116:119], v[196:199], v[176:179], v[116:119]
	v_mfma_f32_16x16x32_bf16 v[112:115], v[196:199], v[184:187], v[112:115]
	v_mfma_f32_16x16x32_bf16 v[108:111], v[204:207], v[176:179], v[108:111]
	v_mfma_f32_16x16x32_bf16 v[104:107], v[204:207], v[184:187], v[104:107]
	v_mfma_f32_16x16x32_bf16 v[100:103], v[212:215], v[176:179], v[100:103]
	v_mfma_f32_16x16x32_bf16 v[96:99], v[212:215], v[184:187], v[96:99]
	s_barrier
	v_add_u32_e32 v162, s75, v154
	v_lshl_add_u64 v[240:241], v[134:135], 0, s[60:61]
	v_readfirstlane_b32 s63, v162
	v_add_u32_e32 v163, 0x2000, v162
	v_lshl_add_u64 v[232:233], v[240:241], 0, s[24:25]
	s_mov_b32 m0, s63
	v_lshl_add_u64 v[242:243], v[136:137], 0, s[60:61]
	ds_read_b128 v[216:219], v160
	ds_read_b128 v[220:223], v160 offset:1024
	ds_read_b128 v[224:227], v160 offset:2048
	ds_read_b128 v[228:231], v160 offset:3072
	global_load_lds_dwordx4 v[232:233], off
	s_bitset1_b32 m0, 13
	v_lshl_add_u64 v[232:233], v[242:243], 0, s[24:25]
	global_load_lds_dwordx4 v[232:233], off
	s_barrier
	s_waitcnt lgkmcnt(0)
	s_waitcnt lgkmcnt(0)
	v_mfma_f32_16x16x32_bf16 v[92:95], v[164:167], v[216:219], v[92:95]
	v_mfma_f32_16x16x32_bf16 v[88:91], v[164:167], v[224:227], v[88:91]
	v_mfma_f32_16x16x32_bf16 v[84:87], v[192:195], v[216:219], v[84:87]
	v_mfma_f32_16x16x32_bf16 v[80:83], v[192:195], v[224:227], v[80:83]
	v_mfma_f32_16x16x32_bf16 v[76:79], v[200:203], v[216:219], v[76:79]
	v_mfma_f32_16x16x32_bf16 v[72:75], v[200:203], v[224:227], v[72:75]
	v_mfma_f32_16x16x32_bf16 v[68:71], v[208:211], v[216:219], v[68:71]
	v_mfma_f32_16x16x32_bf16 v[64:67], v[208:211], v[224:227], v[64:67]
	v_mfma_f32_16x16x32_bf16 v[92:95], v[188:191], v[220:223], v[92:95]
	v_mfma_f32_16x16x32_bf16 v[88:91], v[188:191], v[228:231], v[88:91]
	v_mfma_f32_16x16x32_bf16 v[84:87], v[196:199], v[220:223], v[84:87]
	v_mfma_f32_16x16x32_bf16 v[80:83], v[196:199], v[228:231], v[80:83]
	v_mfma_f32_16x16x32_bf16 v[76:79], v[204:207], v[220:223], v[76:79]
	v_mfma_f32_16x16x32_bf16 v[72:75], v[204:207], v[228:231], v[72:75]
	v_mfma_f32_16x16x32_bf16 v[68:71], v[212:215], v[220:223], v[68:71]
	v_mfma_f32_16x16x32_bf16 v[64:67], v[212:215], v[228:231], v[64:67]
	v_readfirstlane_b32 s63, v148
	v_lshl_add_u64 v[164:165], v[236:237], 0, s[26:27]
	s_mov_b32 m0, s63
	s_barrier
	ds_read_b128 v[188:191], v152 offset:16384
	ds_read_b128 v[192:195], v152 offset:17408
	ds_read_b128 v[196:199], v151 offset:16384
	ds_read_b128 v[200:203], v151 offset:17408
	ds_read_b128 v[204:207], v150 offset:16384
	ds_read_b128 v[208:211], v150 offset:17408
	ds_read_b128 v[212:215], v149 offset:16384
	ds_read_b128 v[232:235], v149 offset:17408
	global_load_lds_dwordx4 v[164:165], off
	s_bitset1_b32 m0, 13
	v_add_u32_e32 v164, 0x2000, v148
	v_lshl_add_u64 v[166:167], v[238:239], 0, s[26:27]
	global_load_lds_dwordx4 v[166:167], off
	s_barrier
	s_waitcnt lgkmcnt(0)
	s_waitcnt lgkmcnt(0)
	v_mfma_f32_16x16x32_bf16 v[60:63], v[188:191], v[172:175], v[60:63]
	v_mfma_f32_16x16x32_bf16 v[56:59], v[188:191], v[180:183], v[56:59]
	v_mfma_f32_16x16x32_bf16 v[52:55], v[196:199], v[172:175], v[52:55]
	v_mfma_f32_16x16x32_bf16 v[48:51], v[196:199], v[180:183], v[48:51]
	v_mfma_f32_16x16x32_bf16 v[44:47], v[204:207], v[172:175], v[44:47]
	v_mfma_f32_16x16x32_bf16 v[40:43], v[204:207], v[180:183], v[40:43]
	v_mfma_f32_16x16x32_bf16 v[36:39], v[212:215], v[172:175], v[36:39]
	v_mfma_f32_16x16x32_bf16 v[32:35], v[212:215], v[180:183], v[32:35]
	v_mfma_f32_16x16x32_bf16 v[60:63], v[192:195], v[176:179], v[60:63]
	v_mfma_f32_16x16x32_bf16 v[56:59], v[192:195], v[184:187], v[56:59]
	v_mfma_f32_16x16x32_bf16 v[52:55], v[200:203], v[176:179], v[52:55]
	v_mfma_f32_16x16x32_bf16 v[48:51], v[200:203], v[184:187], v[48:51]
	v_mfma_f32_16x16x32_bf16 v[44:47], v[208:211], v[176:179], v[44:47]
	v_mfma_f32_16x16x32_bf16 v[40:43], v[208:211], v[184:187], v[40:43]
	v_mfma_f32_16x16x32_bf16 v[36:39], v[232:235], v[176:179], v[36:39]
	v_mfma_f32_16x16x32_bf16 v[32:35], v[232:235], v[184:187], v[32:35]
	s_barrier
; #define STAGE(P, BASE, LD, br, kt) do { const char* _g = (const char*)((BASE) + (size_t)(br) * (LD) + (size_t)(kt) * 64); \
;     for (int _i = 0; _i < 2; ++_i) { int _b = tidx * 16 + _i * 8192; int _r, _c; stage_rc(_b, _r, _c); \
;       __builtin_amdgcn_global_load_lds((const unsigned*)(_g + (unsigned)((_r * (LD) + _c) * 2)), (unsigned*)((char*)(P) + _b), 16, 0, 0); } } while (0)
; #define LDA(dst, b, h) for (int m = 0; m < 4; ++m) for (int k = 0; k < 2; ++k) \
;     dst[m][k] = *reinterpret_cast<const bf16x8*>((char*)SA(b, h) + lds_byte(wr * 64 + m * 16 + fr, k * 32 + fq * 8))
; #define LDB(dst, b, h) for (int n = 0; n < 2; ++n) for (int k = 0; k < 2; ++k) \
;     dst[n][k] = *reinterpret_cast<const bf16x8*>((char*)SB(b, h) + lds_byte(wc * 32 + n * 16 + fr, k * 32 + fq * 8))
; #define MMA(ai, bj, At_, Bt_) do { __builtin_amdgcn_s_setprio(1); \
;     for (int k = 0; k < 2; ++k) for (int m = 0; m < 4; ++m) for (int n = 0; n < 2; ++n) \
;       acc[ai][bj][m][n] = __builtin_amdgcn_mfma_f32_16x16x32_bf16(At_[m][k], Bt_[n][k], acc[ai][bj][m][n], 0, 0, 0); \
;     __builtin_amdgcn_s_setprio(0); } while (0)
; #define WAIT_V(n) asm volatile("s_waitcnt vmcnt(" #n ")" ::: "memory")
; #define WAIT_L(n) asm volatile("s_waitcnt lgkmcnt(" #n ")" ::: "memory")
; #define BAR __builtin_amdgcn_s_barrier()
; #define SCHED __builtin_amdgcn_sched_barrier(0)
; template <int EPI, int lda, int ldb, int N, int K>
; __device__ __forceinline__ void gemm_phase(const u16* __restrict__ A, const u16* __restrict__ Bt, const GemmEpi ep, int wv) {
;     ...
;       STAGE(SB(0, 1), Bt, ldb, bcol + HALF, t + 2);
;       WAIT_V(6); BAR; MMA(1, 1, At, B1); BAR;
;       LDB(B0, 1, 0); SCHED; LDA(At, 1, 0); STAGE(SA(0, 1), Ab, lda, brow + HALF, t + 2);
;       WAIT_L(8); BAR; WAIT_L(0); MMA(0, 0, At, B0); BAR; SCHED;
;       LDB(B1, 1, 1); STAGE(SB(1, 0), Bt, ldb, bcol, t + 3);
;       BAR; WAIT_L(0); MMA(0, 1, At, B1); BAR;
;       LDA(At, 1, 1); STAGE(SA(1, 0), Ab, lda, brow, t + 3);
	v_add_u32_e32 v165, s76, v154
	v_lshl_add_u64 v[166:167], v[240:241], 0, s[40:41]
	v_readfirstlane_b32 s63, v165
	s_mov_b32 m0, s63
	v_lshl_add_u64 v[172:173], v[242:243], 0, s[40:41]
	global_load_lds_dwordx4 v[166:167], off
	s_bitset1_b32 m0, 13
	v_add_u32_e32 v166, 0x2000, v165
	global_load_lds_dwordx4 v[172:173], off
	s_waitcnt vmcnt(6)
	s_barrier
	v_mfma_f32_16x16x32_bf16 v[28:31], v[188:191], v[216:219], v[28:31]
	v_mfma_f32_16x16x32_bf16 v[24:27], v[188:191], v[224:227], v[24:27]
	v_mfma_f32_16x16x32_bf16 v[20:23], v[196:199], v[216:219], v[20:23]
	v_mfma_f32_16x16x32_bf16 v[16:19], v[196:199], v[224:227], v[16:19]
	v_mfma_f32_16x16x32_bf16 v[12:15], v[204:207], v[216:219], v[12:15]
	v_mfma_f32_16x16x32_bf16 v[8:11], v[204:207], v[224:227], v[8:11]
	v_mfma_f32_16x16x32_bf16 v[4:7], v[212:215], v[216:219], v[4:7]
	v_mfma_f32_16x16x32_bf16 v[0:3], v[212:215], v[224:227], v[0:3]
	v_mfma_f32_16x16x32_bf16 v[28:31], v[192:195], v[220:223], v[28:31]
	v_mfma_f32_16x16x32_bf16 v[24:27], v[192:195], v[228:231], v[24:27]
	v_mfma_f32_16x16x32_bf16 v[20:23], v[200:203], v[220:223], v[20:23]
	v_mfma_f32_16x16x32_bf16 v[16:19], v[200:203], v[228:231], v[16:19]
	v_mfma_f32_16x16x32_bf16 v[12:15], v[208:211], v[220:223], v[12:15]
	v_mfma_f32_16x16x32_bf16 v[8:11], v[208:211], v[228:231], v[8:11]
	v_mfma_f32_16x16x32_bf16 v[4:7], v[232:235], v[220:223], v[4:7]
	v_mfma_f32_16x16x32_bf16 v[0:3], v[232:235], v[228:231], v[0:3]
	s_barrier
	ds_read_b128 v[172:175], v155
	ds_read_b128 v[176:179], v155 offset:1024
	ds_read_b128 v[180:183], v155 offset:2048
	ds_read_b128 v[184:187], v155 offset:3072
	v_add_u32_e32 v167, 0x4000, v148
	v_add_u32_e32 v168, 0x6000, v148
	v_readfirstlane_b32 s63, v167
	v_lshl_add_u64 v[220:221], v[236:237], 0, s[42:43]
	s_mov_b32 m0, s63
	ds_read_b128 v[188:191], v152 offset:32768
	ds_read_b128 v[192:195], v152 offset:33792
	ds_read_b128 v[196:199], v151 offset:32768
	ds_read_b128 v[200:203], v151 offset:33792
	ds_read_b128 v[204:207], v150 offset:32768
	ds_read_b128 v[208:211], v150 offset:33792
	ds_read_b128 v[212:215], v149 offset:32768
	ds_read_b128 v[216:219], v149 offset:33792
	global_load_lds_dwordx4 v[220:221], off
	s_bitset1_b32 m0, 13
	v_lshl_add_u64 v[220:221], v[238:239], 0, s[42:43]
	global_load_lds_dwordx4 v[220:221], off
	s_waitcnt lgkmcnt(8)
	s_barrier
	s_waitcnt lgkmcnt(0)
	s_waitcnt lgkmcnt(0)
	v_mfma_f32_16x16x32_bf16 v[124:127], v[188:191], v[172:175], v[124:127]
	v_mfma_f32_16x16x32_bf16 v[120:123], v[188:191], v[180:183], v[120:123]
	v_mfma_f32_16x16x32_bf16 v[116:119], v[196:199], v[172:175], v[116:119]
	v_mfma_f32_16x16x32_bf16 v[112:115], v[196:199], v[180:183], v[112:115]
	v_mfma_f32_16x16x32_bf16 v[108:111], v[204:207], v[172:175], v[108:111]
	v_mfma_f32_16x16x32_bf16 v[104:107], v[204:207], v[180:183], v[104:107]
	v_mfma_f32_16x16x32_bf16 v[100:103], v[212:215], v[172:175], v[100:103]
	v_mfma_f32_16x16x32_bf16 v[96:99], v[212:215], v[180:183], v[96:99]
	v_mfma_f32_16x16x32_bf16 v[124:127], v[192:195], v[176:179], v[124:127]
	v_mfma_f32_16x16x32_bf16 v[120:123], v[192:195], v[184:187], v[120:123]
	v_mfma_f32_16x16x32_bf16 v[116:119], v[200:203], v[176:179], v[116:119]
	v_mfma_f32_16x16x32_bf16 v[112:115], v[200:203], v[184:187], v[112:115]
	v_mfma_f32_16x16x32_bf16 v[108:111], v[208:211], v[176:179], v[108:111]
	v_mfma_f32_16x16x32_bf16 v[104:107], v[208:211], v[184:187], v[104:107]
	v_mfma_f32_16x16x32_bf16 v[100:103], v[216:219], v[176:179], v[100:103]
	v_mfma_f32_16x16x32_bf16 v[96:99], v[216:219], v[184:187], v[96:99]
	s_barrier
	v_readfirstlane_b32 s63, v156
	v_add_u32_e32 v171, 0x2000, v156
	v_lshl_add_u64 v[244:245], v[240:241], 0, s[44:45]
	s_mov_b32 m0, s63
	ds_read_b128 v[220:223], v153
	ds_read_b128 v[224:227], v153 offset:1024
	ds_read_b128 v[228:231], v153 offset:2048
	ds_read_b128 v[232:235], v153 offset:3072
	global_load_lds_dwordx4 v[244:245], off
	s_bitset1_b32 m0, 13
	v_lshl_add_u64 v[244:245], v[242:243], 0, s[44:45]
	global_load_lds_dwordx4 v[244:245], off
	s_barrier
	s_waitcnt lgkmcnt(0)
	s_waitcnt lgkmcnt(0)
	v_mfma_f32_16x16x32_bf16 v[92:95], v[188:191], v[220:223], v[92:95]
	v_mfma_f32_16x16x32_bf16 v[88:91], v[188:191], v[228:231], v[88:91]
	v_mfma_f32_16x16x32_bf16 v[84:87], v[196:199], v[220:223], v[84:87]
	v_mfma_f32_16x16x32_bf16 v[80:83], v[196:199], v[228:231], v[80:83]
	v_mfma_f32_16x16x32_bf16 v[76:79], v[204:207], v[220:223], v[76:79]
	v_mfma_f32_16x16x32_bf16 v[72:75], v[204:207], v[228:231], v[72:75]
	v_mfma_f32_16x16x32_bf16 v[68:71], v[212:215], v[220:223], v[68:71]
	v_mfma_f32_16x16x32_bf16 v[64:67], v[212:215], v[228:231], v[64:67]
	v_mfma_f32_16x16x32_bf16 v[92:95], v[192:195], v[224:227], v[92:95]
	v_mfma_f32_16x16x32_bf16 v[88:91], v[192:195], v[232:235], v[88:91]
	v_mfma_f32_16x16x32_bf16 v[84:87], v[200:203], v[224:227], v[84:87]
	v_mfma_f32_16x16x32_bf16 v[80:83], v[200:203], v[232:235], v[80:83]
	v_mfma_f32_16x16x32_bf16 v[76:79], v[208:211], v[224:227], v[76:79]
	v_mfma_f32_16x16x32_bf16 v[72:75], v[208:211], v[232:235], v[72:75]
	v_mfma_f32_16x16x32_bf16 v[68:71], v[216:219], v[224:227], v[68:71]
	v_mfma_f32_16x16x32_bf16 v[64:67], v[216:219], v[232:235], v[64:67]
	v_readfirstlane_b32 s63, v157
	v_lshl_add_u64 v[236:237], v[236:237], 0, s[46:47]
	s_mov_b32 m0, s63
	s_barrier
	ds_read_b128 v[188:191], v152 offset:49152
	ds_read_b128 v[192:195], v152 offset:50176
	ds_read_b128 v[196:199], v151 offset:49152
	ds_read_b128 v[200:203], v151 offset:50176
	ds_read_b128 v[204:207], v150 offset:49152
	ds_read_b128 v[208:211], v150 offset:50176
	ds_read_b128 v[212:215], v149 offset:49152
	ds_read_b128 v[216:219], v149 offset:50176
	global_load_lds_dwordx4 v[236:237], off
	s_bitset1_b32 m0, 13
	v_lshl_add_u64 v[236:237], v[238:239], 0, s[46:47]
	global_load_lds_dwordx4 v[236:237], off
	s_barrier
; #define STAGE(P, BASE, LD, br, kt) do { const char* _g = (const char*)((BASE) + (size_t)(br) * (LD) + (size_t)(kt) * 64); \
;     for (int _i = 0; _i < 2; ++_i) { int _b = tidx * 16 + _i * 8192; int _r, _c; stage_rc(_b, _r, _c); \
;       __builtin_amdgcn_global_load_lds((const unsigned*)(_g + (unsigned)((_r * (LD) + _c) * 2)), (unsigned*)((char*)(P) + _b), 16, 0, 0); } } while (0)
; #define LDA(dst, b, h) for (int m = 0; m < 4; ++m) for (int k = 0; k < 2; ++k) \
;     dst[m][k] = *reinterpret_cast<const bf16x8*>((char*)SA(b, h) + lds_byte(wr * 64 + m * 16 + fr, k * 32 + fq * 8))
; #define LDB(dst, b, h) for (int n = 0; n < 2; ++n) for (int k = 0; k < 2; ++k) \
;     dst[n][k] = *reinterpret_cast<const bf16x8*>((char*)SB(b, h) + lds_byte(wc * 32 + n * 16 + fr, k * 32 + fq * 8))
; #define MMA(ai, bj, At_, Bt_) do { __builtin_amdgcn_s_setprio(1); \
;     for (int k = 0; k < 2; ++k) for (int m = 0; m < 4; ++m) for (int n = 0; n < 2; ++n) \
;       acc[ai][bj][m][n] = __builtin_amdgcn_mfma_f32_16x16x32_bf16(At_[m][k], Bt_[n][k], acc[ai][bj][m][n], 0, 0, 0); \
;     __builtin_amdgcn_s_setprio(0); } while (0)
; #define WAIT_V(n) asm volatile("s_waitcnt vmcnt(" #n ")" ::: "memory")
; #define WAIT_L(n) asm volatile("s_waitcnt lgkmcnt(" #n ")" ::: "memory")
; #define BAR __builtin_amdgcn_s_barrier()
; #define SCHED __builtin_amdgcn_sched_barrier(0)
; template <int EPI, int lda, int ldb, int N, int K>
; __device__ __forceinline__ void gemm_phase(const u16* __restrict__ A, const u16* __restrict__ Bt, const GemmEpi ep, int wv) {
;     ...
;       BAR; WAIT_L(0); MMA(1, 0, At, B0); BAR; SCHED;
;       STAGE(SB(1, 1), Bt, ldb, bcol + HALF, t + 3);
;       WAIT_V(6); BAR; MMA(1, 1, At, B1); BAR;
;     }
;     { LDB(B0, 0, 0); LDA(At, 0, 0); STAGE(SA(1, 1), Ab, lda, brow + HALF, nt - 1);
;       BAR; WAIT_L(0); MMA(0, 0, At, B0); BAR;
;       LDB(B1, 0, 1); BAR; WAIT_L(0); MMA(0, 1, At, B1); BAR;
	s_waitcnt lgkmcnt(0)
	s_waitcnt lgkmcnt(0)
	v_mfma_f32_16x16x32_bf16 v[60:63], v[188:191], v[172:175], v[60:63]
	v_mfma_f32_16x16x32_bf16 v[56:59], v[188:191], v[180:183], v[56:59]
	v_mfma_f32_16x16x32_bf16 v[52:55], v[196:199], v[172:175], v[52:55]
	v_mfma_f32_16x16x32_bf16 v[48:51], v[196:199], v[180:183], v[48:51]
	v_mfma_f32_16x16x32_bf16 v[44:47], v[204:207], v[172:175], v[44:47]
	v_mfma_f32_16x16x32_bf16 v[40:43], v[204:207], v[180:183], v[40:43]
	v_mfma_f32_16x16x32_bf16 v[36:39], v[212:215], v[172:175], v[36:39]
	v_mfma_f32_16x16x32_bf16 v[32:35], v[212:215], v[180:183], v[32:35]
	v_mfma_f32_16x16x32_bf16 v[60:63], v[192:195], v[176:179], v[60:63]
	v_mfma_f32_16x16x32_bf16 v[56:59], v[192:195], v[184:187], v[56:59]
	v_mfma_f32_16x16x32_bf16 v[52:55], v[200:203], v[176:179], v[52:55]
	v_mfma_f32_16x16x32_bf16 v[48:51], v[200:203], v[184:187], v[48:51]
	v_mfma_f32_16x16x32_bf16 v[44:47], v[208:211], v[176:179], v[44:47]
	v_mfma_f32_16x16x32_bf16 v[40:43], v[208:211], v[184:187], v[40:43]
	v_mfma_f32_16x16x32_bf16 v[36:39], v[216:219], v[176:179], v[36:39]
	v_mfma_f32_16x16x32_bf16 v[32:35], v[216:219], v[184:187], v[32:35]
	s_barrier
	v_readfirstlane_b32 s63, v159
	v_add_u32_e32 v171, 0x2000, v159
	v_lshl_add_u64 v[172:173], v[240:241], 0, s[48:49]
	s_mov_b32 m0, s63
	global_load_lds_dwordx4 v[172:173], off
	s_bitset1_b32 m0, 13
	v_lshl_add_u64 v[172:173], v[242:243], 0, s[48:49]
	global_load_lds_dwordx4 v[172:173], off
	s_waitcnt vmcnt(6)
	s_barrier
	v_mfma_f32_16x16x32_bf16 v[28:31], v[188:191], v[220:223], v[28:31]
	v_mfma_f32_16x16x32_bf16 v[24:27], v[188:191], v[228:231], v[24:27]
	v_mfma_f32_16x16x32_bf16 v[20:23], v[196:199], v[220:223], v[20:23]
	v_mfma_f32_16x16x32_bf16 v[16:19], v[196:199], v[228:231], v[16:19]
	v_mfma_f32_16x16x32_bf16 v[12:15], v[204:207], v[220:223], v[12:15]
	v_mfma_f32_16x16x32_bf16 v[8:11], v[204:207], v[228:231], v[8:11]
	v_mfma_f32_16x16x32_bf16 v[4:7], v[212:215], v[220:223], v[4:7]
	v_mfma_f32_16x16x32_bf16 v[0:3], v[212:215], v[228:231], v[0:3]
	v_mfma_f32_16x16x32_bf16 v[28:31], v[192:195], v[224:227], v[28:31]
	v_mfma_f32_16x16x32_bf16 v[24:27], v[192:195], v[232:235], v[24:27]
	v_mfma_f32_16x16x32_bf16 v[20:23], v[200:203], v[224:227], v[20:23]
	v_mfma_f32_16x16x32_bf16 v[16:19], v[200:203], v[232:235], v[16:19]
	v_mfma_f32_16x16x32_bf16 v[12:15], v[208:211], v[224:227], v[12:15]
	v_mfma_f32_16x16x32_bf16 v[8:11], v[208:211], v[232:235], v[8:11]
	v_mfma_f32_16x16x32_bf16 v[4:7], v[216:219], v[224:227], v[4:7]
	v_mfma_f32_16x16x32_bf16 v[0:3], v[216:219], v[232:235], v[0:3]
	s_add_i32 s62, s62, 2
	s_add_u32 s60, s60, 0x100
	s_addc_u32 s61, s61, 0
	s_cmp_gt_u32 s62, 27
	s_barrier
	s_cbranch_scc0 .LBB0_1147
	s_add_i32 s60, s58, 0x80
	s_mul_hi_i32 s61, s60, 0x1080
	s_mulk_i32 s60, 0x1080
	s_add_u32 s60, s69, s60
	s_addc_u32 s61, s70, s61
	v_lshl_add_u64 v[208:209], s[60:61], 0, v[128:129]
	v_readfirstlane_b32 s62, v169
	v_lshl_add_u64 v[208:209], v[208:209], 0, s[50:51]
	s_mov_b32 m0, s62
	ds_read_b128 v[134:137], v161
	ds_read_b128 v[138:141], v161 offset:1024
	ds_read_b128 v[156:159], v161 offset:2048
	ds_read_b128 v[172:175], v161 offset:3072
	ds_read_b128 v[176:179], v152
	ds_read_b128 v[180:183], v152 offset:1024
	ds_read_b128 v[184:187], v151
	ds_read_b128 v[188:191], v151 offset:1024
	ds_read_b128 v[192:195], v150
	ds_read_b128 v[196:199], v150 offset:1024
	ds_read_b128 v[200:203], v149
	ds_read_b128 v[204:207], v149 offset:1024
	global_load_lds_dwordx4 v[208:209], off
	v_lshl_add_u64 v[208:209], s[60:61], 0, v[132:133]
	v_readfirstlane_b32 s60, v170
	v_lshl_add_u64 v[208:209], v[208:209], 0, s[50:51]
	s_mov_b32 m0, s60
	s_nop 0
	global_load_lds_dwordx4 v[208:209], off
	s_barrier
	s_waitcnt lgkmcnt(0)
	s_waitcnt lgkmcnt(0)
	v_mfma_f32_16x16x32_bf16 v[124:127], v[176:179], v[134:137], v[124:127]
	v_mfma_f32_16x16x32_bf16 v[120:123], v[176:179], v[156:159], v[120:123]
	v_mfma_f32_16x16x32_bf16 v[116:119], v[184:187], v[134:137], v[116:119]
	v_mfma_f32_16x16x32_bf16 v[112:115], v[184:187], v[156:159], v[112:115]
	v_mfma_f32_16x16x32_bf16 v[108:111], v[192:195], v[134:137], v[108:111]
	v_mfma_f32_16x16x32_bf16 v[104:107], v[192:195], v[156:159], v[104:107]
	v_mfma_f32_16x16x32_bf16 v[100:103], v[200:203], v[134:137], v[100:103]
	v_mfma_f32_16x16x32_bf16 v[96:99], v[200:203], v[156:159], v[96:99]
	v_mfma_f32_16x16x32_bf16 v[124:127], v[180:183], v[138:141], v[124:127]
	v_mfma_f32_16x16x32_bf16 v[120:123], v[180:183], v[172:175], v[120:123]
	v_mfma_f32_16x16x32_bf16 v[116:119], v[188:191], v[138:141], v[116:119]
	v_mfma_f32_16x16x32_bf16 v[112:115], v[188:191], v[172:175], v[112:115]
	v_mfma_f32_16x16x32_bf16 v[108:111], v[196:199], v[138:141], v[108:111]
	v_mfma_f32_16x16x32_bf16 v[104:107], v[196:199], v[172:175], v[104:107]
	v_mfma_f32_16x16x32_bf16 v[100:103], v[204:207], v[138:141], v[100:103]
	v_mfma_f32_16x16x32_bf16 v[96:99], v[204:207], v[172:175], v[96:99]
	s_barrier
	ds_read_b128 v[208:211], v160
	ds_read_b128 v[212:215], v160 offset:1024
	ds_read_b128 v[216:219], v160 offset:2048
	ds_read_b128 v[220:223], v160 offset:3072
	s_barrier
; #define LDA(dst, b, h) for (int m = 0; m < 4; ++m) for (int k = 0; k < 2; ++k) \
;     dst[m][k] = *reinterpret_cast<const bf16x8*>((char*)SA(b, h) + lds_byte(wr * 64 + m * 16 + fr, k * 32 + fq * 8))
; #define LDB(dst, b, h) for (int n = 0; n < 2; ++n) for (int k = 0; k < 2; ++k) \
;     dst[n][k] = *reinterpret_cast<const bf16x8*>((char*)SB(b, h) + lds_byte(wc * 32 + n * 16 + fr, k * 32 + fq * 8))
; #define MMA(ai, bj, At_, Bt_) do { __builtin_amdgcn_s_setprio(1); \
;     for (int k = 0; k < 2; ++k) for (int m = 0; m < 4; ++m) for (int n = 0; n < 2; ++n) \
;       acc[ai][bj][m][n] = __builtin_amdgcn_mfma_f32_16x16x32_bf16(At_[m][k], Bt_[n][k], acc[ai][bj][m][n], 0, 0, 0); \
;     __builtin_amdgcn_s_setprio(0); } while (0)
; #define WAIT_V(n) asm volatile("s_waitcnt vmcnt(" #n ")" ::: "memory")
; #define WAIT_L(n) asm volatile("s_waitcnt lgkmcnt(" #n ")" ::: "memory")
; #define BAR __builtin_amdgcn_s_barrier()
; template <int EPI, int lda, int ldb, int N, int K>
; __device__ __forceinline__ void gemm_phase(const u16* __restrict__ A, const u16* __restrict__ Bt, const GemmEpi ep, int wv) {
;     ...
;       LDB(B1, 0, 1); BAR; WAIT_L(0); MMA(0, 1, At, B1); BAR;
;       LDA(At, 0, 1); WAIT_V(4); BAR; WAIT_L(0); MMA(1, 0, At, B0); MMA(1, 1, At, B1); BAR; }
;     { LDB(B0, 1, 0); LDA(At, 1, 0); WAIT_V(2); BAR; WAIT_L(0); MMA(0, 0, At, B0); BAR;
	s_waitcnt lgkmcnt(0)
	s_waitcnt lgkmcnt(0)
	v_mfma_f32_16x16x32_bf16 v[92:95], v[176:179], v[208:211], v[92:95]
	v_mfma_f32_16x16x32_bf16 v[88:91], v[176:179], v[216:219], v[88:91]
	v_mfma_f32_16x16x32_bf16 v[76:79], v[192:195], v[208:211], v[76:79]
	v_mfma_f32_16x16x32_bf16 v[72:75], v[192:195], v[216:219], v[72:75]
	v_mfma_f32_16x16x32_bf16 v[84:87], v[184:187], v[208:211], v[84:87]
	v_mfma_f32_16x16x32_bf16 v[80:83], v[184:187], v[216:219], v[80:83]
	v_mfma_f32_16x16x32_bf16 v[68:71], v[200:203], v[208:211], v[68:71]
	v_mfma_f32_16x16x32_bf16 v[64:67], v[200:203], v[216:219], v[64:67]
	v_mfma_f32_16x16x32_bf16 v[92:95], v[180:183], v[212:215], v[92:95]
	v_mfma_f32_16x16x32_bf16 v[88:91], v[180:183], v[220:223], v[88:91]
	v_mfma_f32_16x16x32_bf16 v[76:79], v[196:199], v[212:215], v[76:79]
	v_mfma_f32_16x16x32_bf16 v[72:75], v[196:199], v[220:223], v[72:75]
	v_mfma_f32_16x16x32_bf16 v[176:179], v[188:191], v[212:215], v[84:87]
	v_mfma_f32_16x16x32_bf16 v[180:183], v[188:191], v[220:223], v[80:83]
	v_mfma_f32_16x16x32_bf16 v[184:187], v[204:207], v[212:215], v[68:71]
	v_mfma_f32_16x16x32_bf16 v[188:191], v[204:207], v[220:223], v[64:67]
	s_barrier
	s_nop 0
	ds_read_b128 v[64:67], v152 offset:16384
	ds_read_b128 v[68:71], v152 offset:17408
	ds_read_b128 v[80:83], v151 offset:16384
	ds_read_b128 v[84:87], v151 offset:17408
	ds_read_b128 v[192:195], v150 offset:16384
	ds_read_b128 v[196:199], v150 offset:17408
	ds_read_b128 v[200:203], v149 offset:16384
	ds_read_b128 v[204:207], v149 offset:17408
	s_waitcnt vmcnt(4)
	s_barrier
	s_waitcnt lgkmcnt(0)
	s_waitcnt lgkmcnt(0)
	v_mfma_f32_16x16x32_bf16 v[60:63], v[64:67], v[134:137], v[60:63]
	v_mfma_f32_16x16x32_bf16 v[56:59], v[64:67], v[156:159], v[56:59]
	v_mfma_f32_16x16x32_bf16 v[52:55], v[80:83], v[134:137], v[52:55]
	v_mfma_f32_16x16x32_bf16 v[48:51], v[80:83], v[156:159], v[48:51]
	v_mfma_f32_16x16x32_bf16 v[44:47], v[192:195], v[134:137], v[44:47]
	v_mfma_f32_16x16x32_bf16 v[40:43], v[192:195], v[156:159], v[40:43]
	v_mfma_f32_16x16x32_bf16 v[36:39], v[200:203], v[134:137], v[36:39]
	v_mfma_f32_16x16x32_bf16 v[32:35], v[200:203], v[156:159], v[32:35]
	v_mfma_f32_16x16x32_bf16 v[60:63], v[68:71], v[138:141], v[60:63]
	v_mfma_f32_16x16x32_bf16 v[56:59], v[68:71], v[172:175], v[56:59]
	v_mfma_f32_16x16x32_bf16 v[52:55], v[84:87], v[138:141], v[52:55]
	v_mfma_f32_16x16x32_bf16 v[48:51], v[84:87], v[172:175], v[48:51]
	v_mfma_f32_16x16x32_bf16 v[44:47], v[196:199], v[138:141], v[44:47]
	v_mfma_f32_16x16x32_bf16 v[40:43], v[196:199], v[172:175], v[40:43]
	v_mfma_f32_16x16x32_bf16 v[36:39], v[204:207], v[138:141], v[36:39]
	v_mfma_f32_16x16x32_bf16 v[32:35], v[204:207], v[172:175], v[32:35]
	v_mfma_f32_16x16x32_bf16 v[28:31], v[64:67], v[208:211], v[28:31]
	v_mfma_f32_16x16x32_bf16 v[24:27], v[64:67], v[216:219], v[24:27]
	v_mfma_f32_16x16x32_bf16 v[12:15], v[192:195], v[208:211], v[12:15]
	v_mfma_f32_16x16x32_bf16 v[8:11], v[192:195], v[216:219], v[8:11]
	v_mfma_f32_16x16x32_bf16 v[20:23], v[80:83], v[208:211], v[20:23]
	v_mfma_f32_16x16x32_bf16 v[16:19], v[80:83], v[216:219], v[16:19]
	v_mfma_f32_16x16x32_bf16 v[4:7], v[200:203], v[208:211], v[4:7]
	v_mfma_f32_16x16x32_bf16 v[0:3], v[200:203], v[216:219], v[0:3]
	v_mfma_f32_16x16x32_bf16 v[28:31], v[68:71], v[212:215], v[28:31]
	v_mfma_f32_16x16x32_bf16 v[24:27], v[68:71], v[220:223], v[24:27]
	v_mfma_f32_16x16x32_bf16 v[12:15], v[196:199], v[212:215], v[12:15]
	v_mfma_f32_16x16x32_bf16 v[8:11], v[196:199], v[220:223], v[8:11]
	v_mfma_f32_16x16x32_bf16 v[134:137], v[84:87], v[212:215], v[20:23]
	v_mfma_f32_16x16x32_bf16 v[138:141], v[84:87], v[220:223], v[16:19]
	v_mfma_f32_16x16x32_bf16 v[156:159], v[204:207], v[212:215], v[4:7]
	v_mfma_f32_16x16x32_bf16 v[170:173], v[204:207], v[220:223], v[0:3]
	s_barrier
	s_nop 0
	ds_read_b128 v[0:3], v155
	ds_read_b128 v[4:7], v155 offset:1024
	ds_read_b128 v[16:19], v155 offset:2048
	ds_read_b128 v[192:195], v155 offset:3072
	ds_read_b128 v[20:23], v152 offset:32768
	ds_read_b128 v[196:199], v152 offset:33792
	ds_read_b128 v[200:203], v151 offset:32768
	ds_read_b128 v[204:207], v151 offset:33792
	ds_read_b128 v[208:211], v150 offset:32768
	ds_read_b128 v[212:215], v150 offset:33792
	ds_read_b128 v[216:219], v149 offset:32768
	ds_read_b128 v[220:223], v149 offset:33792
	s_waitcnt vmcnt(2)
	s_barrier
; #define LDA(dst, b, h) for (int m = 0; m < 4; ++m) for (int k = 0; k < 2; ++k) \
;     dst[m][k] = *reinterpret_cast<const bf16x8*>((char*)SA(b, h) + lds_byte(wr * 64 + m * 16 + fr, k * 32 + fq * 8))
; #define LDB(dst, b, h) for (int n = 0; n < 2; ++n) for (int k = 0; k < 2; ++k) \
;     dst[n][k] = *reinterpret_cast<const bf16x8*>((char*)SB(b, h) + lds_byte(wc * 32 + n * 16 + fr, k * 32 + fq * 8))
; #define MMA(ai, bj, At_, Bt_) do { __builtin_amdgcn_s_setprio(1); \
;     for (int k = 0; k < 2; ++k) for (int m = 0; m < 4; ++m) for (int n = 0; n < 2; ++n) \
;       acc[ai][bj][m][n] = __builtin_amdgcn_mfma_f32_16x16x32_bf16(At_[m][k], Bt_[n][k], acc[ai][bj][m][n], 0, 0, 0); \
;     __builtin_amdgcn_s_setprio(0); } while (0)
; #define WAIT_V(n) asm volatile("s_waitcnt vmcnt(" #n ")" ::: "memory")
; #define WAIT_L(n) asm volatile("s_waitcnt lgkmcnt(" #n ")" ::: "memory")
; #define BAR __builtin_amdgcn_s_barrier()
; template <int EPI, int lda, int ldb, int N, int K>
; __device__ __forceinline__ void gemm_phase(const u16* __restrict__ A, const u16* __restrict__ Bt, const GemmEpi ep, int wv) {
;     ...
;     { LDB(B0, 1, 0); LDA(At, 1, 0); WAIT_V(2); BAR; WAIT_L(0); MMA(0, 0, At, B0); BAR;
;       LDB(B1, 1, 1); WAIT_V(0); BAR; WAIT_L(0); MMA(0, 1, At, B1); BAR;
;       LDA(At, 1, 1); BAR; WAIT_L(0); MMA(1, 0, At, B0); MMA(1, 1, At, B1); BAR; }
;     if (wr == 0) BAR;
	s_waitcnt lgkmcnt(0)
	s_waitcnt lgkmcnt(0)
	v_mfma_f32_16x16x32_bf16 v[64:67], v[20:23], v[0:3], v[124:127]
	v_mfma_f32_16x16x32_bf16 v[68:71], v[20:23], v[16:19], v[120:123]
	v_mfma_f32_16x16x32_bf16 v[80:83], v[200:203], v[0:3], v[116:119]
	v_mfma_f32_16x16x32_bf16 v[84:87], v[200:203], v[16:19], v[112:115]
	v_mfma_f32_16x16x32_bf16 v[108:111], v[208:211], v[0:3], v[108:111]
	v_mfma_f32_16x16x32_bf16 v[104:107], v[208:211], v[16:19], v[104:107]
	v_mfma_f32_16x16x32_bf16 v[120:123], v[216:219], v[0:3], v[100:103]
	v_mfma_f32_16x16x32_bf16 v[124:127], v[216:219], v[16:19], v[96:99]
	v_mfma_f32_16x16x32_bf16 v[116:119], v[196:199], v[4:7], v[64:67]
	v_mfma_f32_16x16x32_bf16 v[112:115], v[196:199], v[192:195], v[68:71]
	v_mfma_f32_16x16x32_bf16 v[100:103], v[204:207], v[4:7], v[80:83]
	v_mfma_f32_16x16x32_bf16 v[96:99], v[204:207], v[192:195], v[84:87]
	v_mfma_f32_16x16x32_bf16 v[84:87], v[212:215], v[4:7], v[108:111]
	v_mfma_f32_16x16x32_bf16 v[80:83], v[212:215], v[192:195], v[104:107]
	v_mfma_f32_16x16x32_bf16 v[68:71], v[220:223], v[4:7], v[120:123]
	v_mfma_f32_16x16x32_bf16 v[64:67], v[220:223], v[192:195], v[124:127]
	s_barrier
	ds_read_b128 v[224:227], v153
	ds_read_b128 v[228:231], v153 offset:1024
	ds_read_b128 v[232:235], v153 offset:2048
	ds_read_b128 v[236:239], v153 offset:3072
	s_waitcnt vmcnt(0)
	s_barrier
	s_waitcnt lgkmcnt(0)
	s_waitcnt lgkmcnt(0)
	v_mfma_f32_16x16x32_bf16 v[92:95], v[20:23], v[224:227], v[92:95]
	v_mfma_f32_16x16x32_bf16 v[20:23], v[20:23], v[232:235], v[88:91]
	v_mfma_f32_16x16x32_bf16 v[88:91], v[200:203], v[224:227], v[176:179]
	v_mfma_f32_16x16x32_bf16 v[104:107], v[200:203], v[232:235], v[180:183]
	v_mfma_f32_16x16x32_bf16 v[76:79], v[208:211], v[224:227], v[76:79]
	v_mfma_f32_16x16x32_bf16 v[72:75], v[208:211], v[232:235], v[72:75]
	v_mfma_f32_16x16x32_bf16 v[174:177], v[216:219], v[224:227], v[184:187]
	v_mfma_f32_16x16x32_bf16 v[178:181], v[216:219], v[232:235], v[188:191]
	v_mfma_f32_16x16x32_bf16 v[124:127], v[196:199], v[228:231], v[92:95]
	v_mfma_f32_16x16x32_bf16 v[120:123], v[196:199], v[236:239], v[20:23]
	v_mfma_f32_16x16x32_bf16 v[108:111], v[204:207], v[228:231], v[88:91]
	v_mfma_f32_16x16x32_bf16 v[104:107], v[204:207], v[236:239], v[104:107]
	v_mfma_f32_16x16x32_bf16 v[92:95], v[212:215], v[228:231], v[76:79]
	v_mfma_f32_16x16x32_bf16 v[88:91], v[212:215], v[236:239], v[72:75]
	v_mfma_f32_16x16x32_bf16 v[76:79], v[220:223], v[228:231], v[174:177]
	v_mfma_f32_16x16x32_bf16 v[72:75], v[220:223], v[236:239], v[178:181]
	s_barrier
	ds_read_b128 v[174:177], v152 offset:49152
	ds_read_b128 v[152:155], v152 offset:50176
	ds_read_b128 v[178:181], v151 offset:49152
	ds_read_b128 v[182:185], v151 offset:50176
	ds_read_b128 v[186:189], v150 offset:49152
	ds_read_b128 v[196:199], v150 offset:50176
	ds_read_b128 v[200:203], v149 offset:49152
	ds_read_b128 v[204:207], v149 offset:50176
	s_barrier
	s_waitcnt lgkmcnt(0)
	s_waitcnt lgkmcnt(0)
	v_mfma_f32_16x16x32_bf16 v[20:23], v[174:177], v[0:3], v[60:63]
	v_mfma_f32_16x16x32_bf16 v[56:59], v[174:177], v[16:19], v[56:59]
	v_mfma_f32_16x16x32_bf16 v[60:63], v[178:181], v[0:3], v[52:55]
	v_mfma_f32_16x16x32_bf16 v[208:211], v[178:181], v[16:19], v[48:51]
	v_mfma_f32_16x16x32_bf16 v[44:47], v[186:189], v[0:3], v[44:47]
	v_mfma_f32_16x16x32_bf16 v[40:43], v[186:189], v[16:19], v[40:43]
	v_mfma_f32_16x16x32_bf16 v[0:3], v[200:203], v[0:3], v[36:39]
	v_mfma_f32_16x16x32_bf16 v[212:215], v[200:203], v[16:19], v[32:35]
	v_mfma_f32_16x16x32_bf16 v[52:55], v[152:155], v[4:7], v[20:23]
	v_mfma_f32_16x16x32_bf16 v[48:51], v[152:155], v[192:195], v[56:59]
	v_mfma_f32_16x16x32_bf16 v[36:39], v[182:185], v[4:7], v[60:63]
	v_mfma_f32_16x16x32_bf16 v[32:35], v[182:185], v[192:195], v[208:211]
	v_mfma_f32_16x16x32_bf16 v[20:23], v[196:199], v[4:7], v[44:47]
	v_mfma_f32_16x16x32_bf16 v[16:19], v[196:199], v[192:195], v[40:43]
	v_mfma_f32_16x16x32_bf16 v[4:7], v[204:207], v[4:7], v[0:3]
	v_mfma_f32_16x16x32_bf16 v[0:3], v[204:207], v[192:195], v[212:215]
	v_mfma_f32_16x16x32_bf16 v[28:31], v[174:177], v[224:227], v[28:31]
	v_mfma_f32_16x16x32_bf16 v[24:27], v[174:177], v[232:235], v[24:27]
	v_mfma_f32_16x16x32_bf16 v[40:43], v[178:181], v[224:227], v[134:137]
	v_mfma_f32_16x16x32_bf16 v[134:137], v[178:181], v[232:235], v[138:141]
	v_mfma_f32_16x16x32_bf16 v[12:15], v[186:189], v[224:227], v[12:15]
	v_mfma_f32_16x16x32_bf16 v[8:11], v[186:189], v[232:235], v[8:11]
	v_mfma_f32_16x16x32_bf16 v[138:141], v[200:203], v[224:227], v[156:159]
	v_mfma_f32_16x16x32_bf16 v[156:159], v[200:203], v[232:235], v[170:173]
	v_mfma_f32_16x16x32_bf16 v[60:63], v[152:155], v[228:231], v[28:31]
	v_mfma_f32_16x16x32_bf16 v[56:59], v[152:155], v[236:239], v[24:27]
	v_mfma_f32_16x16x32_bf16 v[44:47], v[182:185], v[228:231], v[40:43]
	v_mfma_f32_16x16x32_bf16 v[40:43], v[182:185], v[236:239], v[134:137]
	v_mfma_f32_16x16x32_bf16 v[28:31], v[196:199], v[228:231], v[12:15]
	v_mfma_f32_16x16x32_bf16 v[24:27], v[196:199], v[236:239], v[8:11]
	v_mfma_f32_16x16x32_bf16 v[12:15], v[204:207], v[228:231], v[138:141]
	v_mfma_f32_16x16x32_bf16 v[8:11], v[204:207], v[236:239], v[156:159]
	v_cmp_gt_u32_e32 vcc, s80, v130
	s_barrier
	s_and_saveexec_b64 s[60:61], vcc
	s_cbranch_execz .LBB0_1150
	s_barrier

; #define STAGE(P, BASE, LD, br, kt) do { const char* _g = (const char*)((BASE) + (size_t)(br) * (LD) + (size_t)(kt) * 64); \
;     for (int _i = 0; _i < 2; ++_i) { int _b = tidx * 16 + _i * 8192; int _r, _c; stage_rc(_b, _r, _c); \
;       __builtin_amdgcn_global_load_lds((const unsigned*)(_g + (unsigned)((_r * (LD) + _c) * 2)), (unsigned*)((char*)(P) + _b), 16, 0, 0); } } while (0)
; #define LDA(dst, b, h) for (int m = 0; m < 4; ++m) for (int k = 0; k < 2; ++k) \
;     dst[m][k] = *reinterpret_cast<const bf16x8*>((char*)SA(b, h) + lds_byte(wr * 64 + m * 16 + fr, k * 32 + fq * 8))
; #define LDB(dst, b, h) for (int n = 0; n < 2; ++n) for (int k = 0; k < 2; ++k) \
;     dst[n][k] = *reinterpret_cast<const bf16x8*>((char*)SB(b, h) + lds_byte(wc * 32 + n * 16 + fr, k * 32 + fq * 8))
; #define MMA(ai, bj, At_, Bt_) do { __builtin_amdgcn_s_setprio(1); \
;     for (int k = 0; k < 2; ++k) for (int m = 0; m < 4; ++m) for (int n = 0; n < 2; ++n) \
;       acc[ai][bj][m][n] = __builtin_amdgcn_mfma_f32_16x16x32_bf16(At_[m][k], Bt_[n][k], acc[ai][bj][m][n], 0, 0, 0); \
;     __builtin_amdgcn_s_setprio(0); } while (0)
; #define WAIT_V(n) asm volatile("s_waitcnt vmcnt(" #n ")" ::: "memory")
; #define WAIT_L(n) asm volatile("s_waitcnt lgkmcnt(" #n ")" ::: "memory")
; #define BAR __builtin_amdgcn_s_barrier()
; #define SCHED __builtin_amdgcn_sched_barrier(0)
; template <int EPI, int lda, int ldb, int N, int K>
; __device__ __forceinline__ void gemm_phase(const u16* __restrict__ A, const u16* __restrict__ Bt, const GemmEpi ep, int wv) {
;     ...
;     f32x4 acc[2][2][4][2] = {};
;     bf16x8 At[4][2], B0[2][2], B1[2][2];
;     constexpr int nt = K / 64;
;     if (wr == 1) BAR;
;     WAIT_V(4); BAR;
;     STAGE(SB(1, 0), Bt, ldb, bcol, 1); STAGE(SA(1, 0), Ab, lda, brow, 1); STAGE(SB(1, 1), Bt, ldb, bcol + HALF, 1);
;     WAIT_V(6); BAR;
;     for (int t = 0; t < nt - 2; t += 2) {
;       LDB(B0, 0, 0); SCHED; LDA(At, 0, 0); STAGE(SA(1, 1), Ab, lda, brow + HALF, t + 1);
;       WAIT_L(8); BAR; WAIT_L(0); MMA(0, 0, At, B0); BAR; SCHED;
;       LDB(B1, 0, 1); STAGE(SB(0, 0), Bt, ldb, bcol, t + 2);
;       BAR; WAIT_L(0); MMA(0, 1, At, B1); BAR;
;       LDA(At, 0, 1); STAGE(SA(0, 0), Ab, lda, brow, t + 2);
.LBB0_1248:
	s_or_b64 exec, exec, s[54:55]
	v_mov_b32_e32 v1, v129
	v_add_u32_e32 v7, s60, v6
	v_lshl_add_u64 v[12:13], s[46:47], 0, v[128:129]
	v_lshl_add_u64 v[14:15], s[46:47], 0, v[0:1]
	v_lshl_add_u64 v[2:3], s[52:53], 0, v[128:129]
	v_lshl_add_u64 v[0:1], s[52:53], 0, v[0:1]
	v_readfirstlane_b32 s53, v7
	v_add_u32_e32 v7, 0x2000, v7
	v_mov_b32_e32 v5, v129
	v_mov_b32_e32 v17, v129
	v_lshl_add_u64 v[26:27], v[12:13], 0, s[40:41]
	s_mov_b32 m0, s53
	v_readfirstlane_b32 s52, v7
	v_add_u32_e32 v7, 0x8000, v23
	v_lshl_add_u64 v[8:9], s[50:51], 0, v[4:5]
	v_lshl_add_u64 v[10:11], s[50:51], 0, v[16:17]
	s_waitcnt vmcnt(4)
	s_barrier
	global_load_lds_dwordx4 v[26:27], off
	v_lshl_add_u64 v[26:27], v[14:15], 0, s[40:41]
	s_mov_b32 m0, s52
	v_readfirstlane_b32 s51, v7
	v_add_u32_e32 v7, 0xa000, v23
	global_load_lds_dwordx4 v[26:27], off
	v_lshl_add_u64 v[26:27], v[8:9], 0, s[40:41]
	s_mov_b32 m0, s51
	v_readfirstlane_b32 s50, v7
	v_add_u32_e32 v25, s61, v6
	global_load_lds_dwordx4 v[26:27], off
	v_lshl_add_u64 v[26:27], v[10:11], 0, s[40:41]
	s_mov_b32 m0, s50
	v_readfirstlane_b32 s13, v25
	v_add_u32_e32 v25, 0x2000, v25
	global_load_lds_dwordx4 v[26:27], off
	v_lshl_add_u64 v[26:27], v[2:3], 0, s[40:41]
	s_mov_b32 m0, s13
	v_readfirstlane_b32 s11, v25
	global_load_lds_dwordx4 v[26:27], off
	v_lshl_add_u64 v[6:7], v[0:1], 0, s[40:41]
	s_mov_b32 m0, s11
	v_and_b32_e32 v132, 15, v20
	global_load_lds_dwordx4 v[6:7], off
	v_bfe_u32 v128, v20, 4, 2
	v_lshlrev_b32_e32 v7, 2, v20
	v_bfe_u32 v131, v130, 6, 2
	v_lshlrev_b32_e32 v25, 4, v128
	v_lshlrev_b32_e32 v6, 6, v132
	v_and_b32_e32 v50, 32, v7
	v_lshlrev_b32_e32 v126, 12, v131
	v_bitop3_b32 v127, v25, v50, v6 bitop3:0x36
	v_add3_u32 v133, s58, v127, v126
	s_waitcnt vmcnt(6)
	s_barrier
	ds_read_b128 v[26:29], v133
	ds_read_b128 v[30:33], v133 offset:1024
	ds_read_b128 v[34:37], v133 offset:2048
	ds_read_b128 v[38:41], v133 offset:3072
	v_lshl_add_u64 v[6:7], s[48:49], 0, v[4:5]
	v_lshl_add_u64 v[4:5], s[48:49], 0, v[16:17]
	v_lshlrev_b32_e32 v17, 6, v20
	v_and_b32_e32 v17, 0x3c0, v17
	v_add_u32_e32 v20, 0xc000, v23
	v_lshlrev_b32_e32 v16, 13, v143
	v_bitop3_b32 v17, v17, v50, v25 bitop3:0x36
	v_readfirstlane_b32 s47, v20
	v_add_u32_e32 v20, 0xe000, v23
	v_add3_u32 v228, 0, v127, v16
	v_add3_u32 v229, 0, v17, v16
	v_lshl_add_u64 v[16:17], v[6:7], 0, s[40:41]
	s_mov_b32 m0, s47
	v_readfirstlane_b32 s46, v20
	ds_read_b128 v[42:45], v228
	ds_read_b128 v[46:49], v228 offset:1024
	ds_read_b128 v[50:53], v229 offset:2048
	ds_read_b128 v[54:57], v229 offset:3072
	ds_read_b128 v[58:61], v229 offset:4096
	ds_read_b128 v[62:65], v229 offset:5120
	ds_read_b128 v[66:69], v229 offset:6144
	ds_read_b128 v[70:73], v229 offset:7168
	global_load_lds_dwordx4 v[16:17], off
	v_lshl_add_u64 v[16:17], v[4:5], 0, s[40:41]
	s_mov_b32 m0, s46
	s_nop 0
	global_load_lds_dwordx4 v[16:17], off
	s_waitcnt lgkmcnt(8)
	s_barrier
	s_waitcnt lgkmcnt(0)
	s_waitcnt lgkmcnt(0)
	v_mfma_f32_16x16x32_bf16 v[74:77], v[42:45], v[26:29], 0
	v_mfma_f32_16x16x32_bf16 v[78:81], v[42:45], v[34:37], 0
	v_mfma_f32_16x16x32_bf16 v[82:85], v[50:53], v[26:29], 0
	v_mfma_f32_16x16x32_bf16 v[86:89], v[50:53], v[34:37], 0
	v_mfma_f32_16x16x32_bf16 v[90:93], v[58:61], v[26:29], 0
	v_mfma_f32_16x16x32_bf16 v[94:97], v[58:61], v[34:37], 0
	v_mfma_f32_16x16x32_bf16 v[98:101], v[66:69], v[26:29], 0
	v_mfma_f32_16x16x32_bf16 v[102:105], v[66:69], v[34:37], 0
	v_mfma_f32_16x16x32_bf16 v[74:77], v[46:49], v[30:33], v[74:77]
	v_mfma_f32_16x16x32_bf16 v[78:81], v[46:49], v[38:41], v[78:81]
	v_mfma_f32_16x16x32_bf16 v[82:85], v[54:57], v[30:33], v[82:85]
	v_mfma_f32_16x16x32_bf16 v[86:89], v[54:57], v[38:41], v[86:89]
	v_mfma_f32_16x16x32_bf16 v[90:93], v[62:65], v[30:33], v[90:93]
	v_mfma_f32_16x16x32_bf16 v[94:97], v[62:65], v[38:41], v[94:97]
	v_mfma_f32_16x16x32_bf16 v[98:101], v[70:73], v[30:33], v[98:101]
	v_mfma_f32_16x16x32_bf16 v[102:105], v[70:73], v[38:41], v[102:105]
	s_barrier
	v_readfirstlane_b32 s48, v21
	v_add_u32_e32 v20, 0x2000, v21
	v_add3_u32 v224, s59, v127, v126
	v_lshl_add_u64 v[16:17], v[12:13], 0, s[42:43]
	s_mov_b32 m0, s48
	ds_read_b128 v[106:109], v224
	ds_read_b128 v[110:113], v224 offset:1024
	ds_read_b128 v[114:117], v224 offset:2048
	ds_read_b128 v[118:121], v224 offset:3072
	global_load_lds_dwordx4 v[16:17], off
	s_bitset1_b32 m0, 13
	v_lshl_add_u64 v[16:17], v[14:15], 0, s[42:43]
	global_load_lds_dwordx4 v[16:17], off
	s_barrier
	s_waitcnt lgkmcnt(0)
	s_waitcnt lgkmcnt(0)
	v_mfma_f32_16x16x32_bf16 v[122:125], v[42:45], v[106:109], 0
	v_mfma_f32_16x16x32_bf16 v[42:45], v[42:45], v[114:117], 0
	v_mfma_f32_16x16x32_bf16 v[134:137], v[50:53], v[106:109], 0
	v_mfma_f32_16x16x32_bf16 v[50:53], v[50:53], v[114:117], 0
	v_mfma_f32_16x16x32_bf16 v[144:147], v[58:61], v[106:109], 0
	v_mfma_f32_16x16x32_bf16 v[58:61], v[58:61], v[114:117], 0
	v_mfma_f32_16x16x32_bf16 v[148:151], v[66:69], v[106:109], 0
	v_mfma_f32_16x16x32_bf16 v[66:69], v[66:69], v[114:117], 0
	v_mfma_f32_16x16x32_bf16 v[122:125], v[46:49], v[110:113], v[122:125]
	v_mfma_f32_16x16x32_bf16 v[42:45], v[46:49], v[118:121], v[42:45]
	v_mfma_f32_16x16x32_bf16 v[46:49], v[54:57], v[110:113], v[134:137]
	v_mfma_f32_16x16x32_bf16 v[50:53], v[54:57], v[118:121], v[50:53]
	v_mfma_f32_16x16x32_bf16 v[54:57], v[62:65], v[110:113], v[144:147]
	v_mfma_f32_16x16x32_bf16 v[58:61], v[62:65], v[118:121], v[58:61]
	v_mfma_f32_16x16x32_bf16 v[62:65], v[70:73], v[110:113], v[148:151]
	v_mfma_f32_16x16x32_bf16 v[66:69], v[70:73], v[118:121], v[66:69]
	v_readfirstlane_b32 s48, v23
	v_lshl_add_u64 v[16:17], v[8:9], 0, s[42:43]
	s_mov_b32 m0, s48
	s_barrier
; #define STAGE(P, BASE, LD, br, kt) do { const char* _g = (const char*)((BASE) + (size_t)(br) * (LD) + (size_t)(kt) * 64); \
;     for (int _i = 0; _i < 2; ++_i) { int _b = tidx * 16 + _i * 8192; int _r, _c; stage_rc(_b, _r, _c); \
;       __builtin_amdgcn_global_load_lds((const unsigned*)(_g + (unsigned)((_r * (LD) + _c) * 2)), (unsigned*)((char*)(P) + _b), 16, 0, 0); } } while (0)
; #define LDA(dst, b, h) for (int m = 0; m < 4; ++m) for (int k = 0; k < 2; ++k) \
;     dst[m][k] = *reinterpret_cast<const bf16x8*>((char*)SA(b, h) + lds_byte(wr * 64 + m * 16 + fr, k * 32 + fq * 8))
; #define LDB(dst, b, h) for (int n = 0; n < 2; ++n) for (int k = 0; k < 2; ++k) \
;     dst[n][k] = *reinterpret_cast<const bf16x8*>((char*)SB(b, h) + lds_byte(wc * 32 + n * 16 + fr, k * 32 + fq * 8))
; #define MMA(ai, bj, At_, Bt_) do { __builtin_amdgcn_s_setprio(1); \
;     for (int k = 0; k < 2; ++k) for (int m = 0; m < 4; ++m) for (int n = 0; n < 2; ++n) \
;       acc[ai][bj][m][n] = __builtin_amdgcn_mfma_f32_16x16x32_bf16(At_[m][k], Bt_[n][k], acc[ai][bj][m][n], 0, 0, 0); \
;     __builtin_amdgcn_s_setprio(0); } while (0)
; #define WAIT_V(n) asm volatile("s_waitcnt vmcnt(" #n ")" ::: "memory")
; #define WAIT_L(n) asm volatile("s_waitcnt lgkmcnt(" #n ")" ::: "memory")
; #define BAR __builtin_amdgcn_s_barrier()
; #define SCHED __builtin_amdgcn_sched_barrier(0)
; template <int EPI, int lda, int ldb, int N, int K>
; __device__ __forceinline__ void gemm_phase(const u16* __restrict__ A, const u16* __restrict__ Bt, const GemmEpi ep, int wv) {
;     ...
;       LDA(At, 0, 1); STAGE(SA(0, 0), Ab, lda, brow, t + 2);
;       BAR; WAIT_L(0); MMA(1, 0, At, B0); BAR; SCHED;
;       STAGE(SB(0, 1), Bt, ldb, bcol + HALF, t + 2);
;       WAIT_V(6); BAR; MMA(1, 1, At, B1); BAR;
;       LDB(B0, 1, 0); SCHED; LDA(At, 1, 0); STAGE(SA(0, 1), Ab, lda, brow + HALF, t + 2);
;       WAIT_L(8); BAR; WAIT_L(0); MMA(0, 0, At, B0); BAR; SCHED;
;       LDB(B1, 1, 1); STAGE(SB(1, 0), Bt, ldb, bcol, t + 3);
	ds_read_b128 v[70:73], v228 offset:16384
	ds_read_b128 v[134:137], v228 offset:17408
	ds_read_b128 v[144:147], v229 offset:18432
	ds_read_b128 v[148:151], v229 offset:19456
	ds_read_b128 v[152:155], v229 offset:20480
	ds_read_b128 v[156:159], v229 offset:21504
	ds_read_b128 v[160:163], v229 offset:22528
	ds_read_b128 v[164:167], v229 offset:23552
	global_load_lds_dwordx4 v[16:17], off
	s_bitset1_b32 m0, 13
	v_lshl_add_u64 v[16:17], v[10:11], 0, s[42:43]
	global_load_lds_dwordx4 v[16:17], off
	s_barrier
	s_waitcnt lgkmcnt(0)
	s_waitcnt lgkmcnt(0)
	v_mfma_f32_16x16x32_bf16 v[168:171], v[70:73], v[26:29], 0
	v_mfma_f32_16x16x32_bf16 v[172:175], v[70:73], v[34:37], 0
	v_mfma_f32_16x16x32_bf16 v[176:179], v[144:147], v[26:29], 0
	v_mfma_f32_16x16x32_bf16 v[180:183], v[144:147], v[34:37], 0
	v_mfma_f32_16x16x32_bf16 v[184:187], v[152:155], v[26:29], 0
	v_mfma_f32_16x16x32_bf16 v[188:191], v[152:155], v[34:37], 0
	v_mfma_f32_16x16x32_bf16 v[24:27], v[160:163], v[26:29], 0
	v_mfma_f32_16x16x32_bf16 v[34:37], v[160:163], v[34:37], 0
	v_mfma_f32_16x16x32_bf16 v[168:171], v[134:137], v[30:33], v[168:171]
	v_mfma_f32_16x16x32_bf16 v[176:179], v[148:151], v[30:33], v[176:179]
	v_mfma_f32_16x16x32_bf16 v[184:187], v[156:159], v[30:33], v[184:187]
	v_mfma_f32_16x16x32_bf16 v[24:27], v[164:167], v[30:33], v[24:27]
	v_mfma_f32_16x16x32_bf16 v[28:31], v[164:167], v[38:41], v[34:37]
	v_mfma_f32_16x16x32_bf16 v[172:175], v[134:137], v[38:41], v[172:175]
	v_mfma_f32_16x16x32_bf16 v[180:183], v[148:151], v[38:41], v[180:183]
	v_mfma_f32_16x16x32_bf16 v[188:191], v[156:159], v[38:41], v[188:191]
	s_barrier
	v_readfirstlane_b32 s48, v22
	v_add_u32_e32 v20, 0x2000, v22
	v_lshl_add_u64 v[16:17], v[2:3], 0, s[42:43]
	s_mov_b32 m0, s48
	global_load_lds_dwordx4 v[16:17], off
	s_bitset1_b32 m0, 13
	v_lshl_add_u64 v[16:17], v[0:1], 0, s[42:43]
	global_load_lds_dwordx4 v[16:17], off
	s_waitcnt vmcnt(6)
	s_barrier
	v_mfma_f32_16x16x32_bf16 v[20:23], v[70:73], v[106:109], 0
	v_mfma_f32_16x16x32_bf16 v[32:35], v[70:73], v[114:117], 0
	v_mfma_f32_16x16x32_bf16 v[36:39], v[144:147], v[106:109], 0
	v_mfma_f32_16x16x32_bf16 v[70:73], v[144:147], v[114:117], 0
	v_mfma_f32_16x16x32_bf16 v[144:147], v[152:155], v[106:109], 0
	v_mfma_f32_16x16x32_bf16 v[152:155], v[152:155], v[114:117], 0
	v_mfma_f32_16x16x32_bf16 v[106:109], v[160:163], v[106:109], 0
	v_mfma_f32_16x16x32_bf16 v[114:117], v[160:163], v[114:117], 0
	v_mfma_f32_16x16x32_bf16 v[20:23], v[134:137], v[110:113], v[20:23]
	v_mfma_f32_16x16x32_bf16 v[32:35], v[134:137], v[118:121], v[32:35]
	v_mfma_f32_16x16x32_bf16 v[36:39], v[148:151], v[110:113], v[36:39]
	v_mfma_f32_16x16x32_bf16 v[70:73], v[148:151], v[118:121], v[70:73]
	v_mfma_f32_16x16x32_bf16 v[134:137], v[156:159], v[110:113], v[144:147]
	v_mfma_f32_16x16x32_bf16 v[106:109], v[164:167], v[110:113], v[106:109]
	v_mfma_f32_16x16x32_bf16 v[110:113], v[164:167], v[118:121], v[114:117]
	v_mfma_f32_16x16x32_bf16 v[144:147], v[156:159], v[118:121], v[152:155]
	v_add3_u32 v225, s60, v127, v126
	s_barrier
	ds_read_b128 v[114:117], v225
	ds_read_b128 v[118:121], v225 offset:1024
	ds_read_b128 v[148:151], v225 offset:2048
	ds_read_b128 v[152:155], v225 offset:3072
	v_readfirstlane_b32 s48, v18
	v_lshl_add_u64 v[16:17], v[6:7], 0, s[42:43]
	s_mov_b32 m0, s48
	ds_read_b128 v[156:159], v228 offset:32768
	ds_read_b128 v[160:163], v228 offset:33792
	ds_read_b128 v[164:167], v229 offset:34816
	ds_read_b128 v[192:195], v229 offset:35840
	ds_read_b128 v[196:199], v229 offset:36864
	ds_read_b128 v[200:203], v229 offset:37888
	ds_read_b128 v[204:207], v229 offset:38912
	ds_read_b128 v[208:211], v229 offset:39936
	global_load_lds_dwordx4 v[16:17], off
	s_bitset1_b32 m0, 13
	v_lshl_add_u64 v[16:17], v[4:5], 0, s[42:43]
	global_load_lds_dwordx4 v[16:17], off
	s_waitcnt lgkmcnt(8)
	s_barrier
	s_waitcnt lgkmcnt(0)
	s_waitcnt lgkmcnt(0)
	v_mfma_f32_16x16x32_bf16 v[16:19], v[156:159], v[114:117], v[74:77]
	v_mfma_f32_16x16x32_bf16 v[74:77], v[156:159], v[148:151], v[78:81]
	v_mfma_f32_16x16x32_bf16 v[78:81], v[164:167], v[114:117], v[82:85]
	v_mfma_f32_16x16x32_bf16 v[82:85], v[164:167], v[148:151], v[86:89]
	v_mfma_f32_16x16x32_bf16 v[86:89], v[196:199], v[114:117], v[90:93]
	v_mfma_f32_16x16x32_bf16 v[90:93], v[196:199], v[148:151], v[94:97]
	v_mfma_f32_16x16x32_bf16 v[94:97], v[204:207], v[114:117], v[98:101]
	v_mfma_f32_16x16x32_bf16 v[98:101], v[204:207], v[148:151], v[102:105]
	v_mfma_f32_16x16x32_bf16 v[16:19], v[160:163], v[118:121], v[16:19]
	v_mfma_f32_16x16x32_bf16 v[74:77], v[160:163], v[152:155], v[74:77]
	v_mfma_f32_16x16x32_bf16 v[78:81], v[192:195], v[118:121], v[78:81]
	v_mfma_f32_16x16x32_bf16 v[82:85], v[192:195], v[152:155], v[82:85]
	v_mfma_f32_16x16x32_bf16 v[86:89], v[200:203], v[118:121], v[86:89]
	v_mfma_f32_16x16x32_bf16 v[90:93], v[200:203], v[152:155], v[90:93]
	v_mfma_f32_16x16x32_bf16 v[94:97], v[208:211], v[118:121], v[94:97]
	v_mfma_f32_16x16x32_bf16 v[98:101], v[208:211], v[152:155], v[98:101]
	s_barrier
	s_mov_b32 m0, s53
	v_add3_u32 v226, s61, v127, v126
	v_lshl_add_u64 v[12:13], v[12:13], 0, s[44:45]
	ds_read_b128 v[102:105], v226
	ds_read_b128 v[212:215], v226 offset:1024
	ds_read_b128 v[216:219], v226 offset:2048
	ds_read_b128 v[220:223], v226 offset:3072
	global_load_lds_dwordx4 v[12:13], off
	v_lshl_add_u64 v[12:13], v[14:15], 0, s[44:45]
	s_mov_b32 m0, s52
	s_nop 0
	global_load_lds_dwordx4 v[12:13], off
	s_barrier
; #define STAGE(P, BASE, LD, br, kt) do { const char* _g = (const char*)((BASE) + (size_t)(br) * (LD) + (size_t)(kt) * 64); \
;     for (int _i = 0; _i < 2; ++_i) { int _b = tidx * 16 + _i * 8192; int _r, _c; stage_rc(_b, _r, _c); \
;       __builtin_amdgcn_global_load_lds((const unsigned*)(_g + (unsigned)((_r * (LD) + _c) * 2)), (unsigned*)((char*)(P) + _b), 16, 0, 0); } } while (0)
; #define LDA(dst, b, h) for (int m = 0; m < 4; ++m) for (int k = 0; k < 2; ++k) \
;     dst[m][k] = *reinterpret_cast<const bf16x8*>((char*)SA(b, h) + lds_byte(wr * 64 + m * 16 + fr, k * 32 + fq * 8))
; #define LDB(dst, b, h) for (int n = 0; n < 2; ++n) for (int k = 0; k < 2; ++k) \
;     dst[n][k] = *reinterpret_cast<const bf16x8*>((char*)SB(b, h) + lds_byte(wc * 32 + n * 16 + fr, k * 32 + fq * 8))
; #define MMA(ai, bj, At_, Bt_) do { __builtin_amdgcn_s_setprio(1); \
;     for (int k = 0; k < 2; ++k) for (int m = 0; m < 4; ++m) for (int n = 0; n < 2; ++n) \
;       acc[ai][bj][m][n] = __builtin_amdgcn_mfma_f32_16x16x32_bf16(At_[m][k], Bt_[n][k], acc[ai][bj][m][n], 0, 0, 0); \
;     __builtin_amdgcn_s_setprio(0); } while (0)
; #define WAIT_V(n) asm volatile("s_waitcnt vmcnt(" #n ")" ::: "memory")
; #define WAIT_L(n) asm volatile("s_waitcnt lgkmcnt(" #n ")" ::: "memory")
; #define BAR __builtin_amdgcn_s_barrier()
; #define SCHED __builtin_amdgcn_sched_barrier(0)
; template <int EPI, int lda, int ldb, int N, int K>
; __device__ __forceinline__ void gemm_phase(const u16* __restrict__ A, const u16* __restrict__ Bt, const GemmEpi ep, int wv) {
;     ...
;       BAR; WAIT_L(0); MMA(0, 1, At, B1); BAR;
;       LDA(At, 1, 1); STAGE(SA(1, 0), Ab, lda, brow, t + 3);
;       BAR; WAIT_L(0); MMA(1, 0, At, B0); BAR; SCHED;
;       STAGE(SB(1, 1), Bt, ldb, bcol + HALF, t + 3);
;       WAIT_V(6); BAR; MMA(1, 1, At, B1); BAR;
;     }
;     { LDB(B0, 0, 0); LDA(At, 0, 0); STAGE(SA(1, 1), Ab, lda, brow + HALF, nt - 1);
;       BAR; WAIT_L(0); MMA(0, 0, At, B0); BAR;
	s_waitcnt lgkmcnt(0)
	s_waitcnt lgkmcnt(0)
	v_mfma_f32_16x16x32_bf16 v[12:15], v[156:159], v[102:105], v[122:125]
	v_mfma_f32_16x16x32_bf16 v[40:43], v[156:159], v[216:219], v[42:45]
	v_mfma_f32_16x16x32_bf16 v[44:47], v[164:167], v[102:105], v[46:49]
	v_mfma_f32_16x16x32_bf16 v[48:51], v[164:167], v[216:219], v[50:53]
	v_mfma_f32_16x16x32_bf16 v[52:55], v[196:199], v[102:105], v[54:57]
	v_mfma_f32_16x16x32_bf16 v[56:59], v[196:199], v[216:219], v[58:61]
	v_mfma_f32_16x16x32_bf16 v[60:63], v[204:207], v[102:105], v[62:65]
	v_mfma_f32_16x16x32_bf16 v[64:67], v[204:207], v[216:219], v[66:69]
	v_mfma_f32_16x16x32_bf16 v[12:15], v[160:163], v[212:215], v[12:15]
	v_mfma_f32_16x16x32_bf16 v[40:43], v[160:163], v[220:223], v[40:43]
	v_mfma_f32_16x16x32_bf16 v[44:47], v[192:195], v[212:215], v[44:47]
	v_mfma_f32_16x16x32_bf16 v[48:51], v[192:195], v[220:223], v[48:51]
	v_mfma_f32_16x16x32_bf16 v[52:55], v[200:203], v[212:215], v[52:55]
	v_mfma_f32_16x16x32_bf16 v[56:59], v[200:203], v[220:223], v[56:59]
	v_mfma_f32_16x16x32_bf16 v[60:63], v[208:211], v[212:215], v[60:63]
	v_mfma_f32_16x16x32_bf16 v[64:67], v[208:211], v[220:223], v[64:67]
	s_mov_b32 m0, s51
	v_lshl_add_u64 v[8:9], v[8:9], 0, s[44:45]
	s_barrier
	ds_read_b128 v[122:125], v228 offset:49152
	ds_read_b128 v[156:159], v228 offset:50176
	ds_read_b128 v[160:163], v229 offset:51200
	ds_read_b128 v[164:167], v229 offset:52224
	ds_read_b128 v[192:195], v229 offset:53248
	ds_read_b128 v[196:199], v229 offset:54272
	ds_read_b128 v[200:203], v229 offset:55296
	ds_read_b128 v[204:207], v229 offset:56320
	global_load_lds_dwordx4 v[8:9], off
	v_lshl_add_u64 v[8:9], v[10:11], 0, s[44:45]
	s_mov_b32 m0, s50
	s_nop 0
	global_load_lds_dwordx4 v[8:9], off
	s_barrier
	s_waitcnt lgkmcnt(0)
	s_waitcnt lgkmcnt(0)
	v_mfma_f32_16x16x32_bf16 v[8:11], v[122:125], v[114:117], v[168:171]
	v_mfma_f32_16x16x32_bf16 v[168:171], v[122:125], v[148:151], v[172:175]
	v_mfma_f32_16x16x32_bf16 v[24:27], v[200:203], v[114:117], v[24:27]
	v_mfma_f32_16x16x32_bf16 v[28:31], v[200:203], v[148:151], v[28:31]
	v_mfma_f32_16x16x32_bf16 v[172:175], v[160:163], v[114:117], v[176:179]
	v_mfma_f32_16x16x32_bf16 v[176:179], v[160:163], v[148:151], v[180:183]
	v_mfma_f32_16x16x32_bf16 v[180:183], v[192:195], v[114:117], v[184:187]
	v_mfma_f32_16x16x32_bf16 v[184:187], v[192:195], v[148:151], v[188:191]
	v_mfma_f32_16x16x32_bf16 v[8:11], v[156:159], v[118:121], v[8:11]
	v_mfma_f32_16x16x32_bf16 v[114:117], v[156:159], v[152:155], v[168:171]
	v_mfma_f32_16x16x32_bf16 v[24:27], v[204:207], v[118:121], v[24:27]
	v_mfma_f32_16x16x32_bf16 v[28:31], v[204:207], v[152:155], v[28:31]
	v_mfma_f32_16x16x32_bf16 v[148:151], v[164:167], v[118:121], v[172:175]
	v_mfma_f32_16x16x32_bf16 v[168:171], v[164:167], v[152:155], v[176:179]
	v_mfma_f32_16x16x32_bf16 v[172:175], v[196:199], v[118:121], v[180:183]
	v_mfma_f32_16x16x32_bf16 v[176:179], v[196:199], v[152:155], v[184:187]
	s_barrier
	s_mov_b32 m0, s13
	v_lshl_add_u64 v[2:3], v[2:3], 0, s[44:45]
	global_load_lds_dwordx4 v[2:3], off
	v_lshl_add_u64 v[0:1], v[0:1], 0, s[44:45]
	s_mov_b32 m0, s11
	s_nop 0
	global_load_lds_dwordx4 v[0:1], off
	s_waitcnt vmcnt(6)
	s_barrier
	v_mfma_f32_16x16x32_bf16 v[0:3], v[122:125], v[102:105], v[20:23]
	v_mfma_f32_16x16x32_bf16 v[20:23], v[122:125], v[216:219], v[32:35]
	v_mfma_f32_16x16x32_bf16 v[32:35], v[160:163], v[102:105], v[36:39]
	v_mfma_f32_16x16x32_bf16 v[36:39], v[160:163], v[216:219], v[70:73]
	v_mfma_f32_16x16x32_bf16 v[68:71], v[192:195], v[102:105], v[134:137]
	v_mfma_f32_16x16x32_bf16 v[118:121], v[192:195], v[216:219], v[144:147]
	v_mfma_f32_16x16x32_bf16 v[102:105], v[200:203], v[102:105], v[106:109]
	v_mfma_f32_16x16x32_bf16 v[106:109], v[200:203], v[216:219], v[110:113]
	v_mfma_f32_16x16x32_bf16 v[0:3], v[156:159], v[212:215], v[0:3]
	v_mfma_f32_16x16x32_bf16 v[20:23], v[156:159], v[220:223], v[20:23]
	v_mfma_f32_16x16x32_bf16 v[32:35], v[164:167], v[212:215], v[32:35]
	v_mfma_f32_16x16x32_bf16 v[36:39], v[164:167], v[220:223], v[36:39]
	v_mfma_f32_16x16x32_bf16 v[68:71], v[196:199], v[212:215], v[68:71]
	v_mfma_f32_16x16x32_bf16 v[110:113], v[196:199], v[220:223], v[118:121]
	v_mfma_f32_16x16x32_bf16 v[102:105], v[204:207], v[212:215], v[102:105]
	v_mfma_f32_16x16x32_bf16 v[106:109], v[204:207], v[220:223], v[106:109]
	s_mov_b32 m0, s47
	v_lshl_add_u64 v[6:7], v[6:7], 0, s[44:45]
	s_barrier
	ds_read_b128 v[118:121], v133
	ds_read_b128 v[122:125], v133 offset:1024
	ds_read_b128 v[134:137], v133 offset:2048
	ds_read_b128 v[144:147], v133 offset:3072
	ds_read_b128 v[152:155], v228
	ds_read_b128 v[156:159], v228 offset:1024
	ds_read_b128 v[160:163], v229 offset:2048
	ds_read_b128 v[164:167], v229 offset:3072
	ds_read_b128 v[180:183], v229 offset:4096
	ds_read_b128 v[184:187], v229 offset:5120
	ds_read_b128 v[188:191], v229 offset:6144
	ds_read_b128 v[192:195], v229 offset:7168
	global_load_lds_dwordx4 v[6:7], off
	v_lshl_add_u64 v[4:5], v[4:5], 0, s[44:45]
	s_mov_b32 m0, s46
	s_nop 0
	global_load_lds_dwordx4 v[4:5], off
	s_barrier
	s_waitcnt lgkmcnt(0)
	s_waitcnt lgkmcnt(0)
	v_mfma_f32_16x16x32_bf16 v[4:7], v[152:155], v[118:121], v[16:19]
	v_mfma_f32_16x16x32_bf16 v[16:19], v[152:155], v[134:137], v[74:77]
	v_mfma_f32_16x16x32_bf16 v[72:75], v[160:163], v[118:121], v[78:81]
	v_mfma_f32_16x16x32_bf16 v[76:79], v[160:163], v[134:137], v[82:85]
	v_mfma_f32_16x16x32_bf16 v[80:83], v[180:183], v[118:121], v[86:89]
	v_mfma_f32_16x16x32_bf16 v[84:87], v[180:183], v[134:137], v[90:93]
	v_mfma_f32_16x16x32_bf16 v[88:91], v[188:191], v[118:121], v[94:97]
	v_mfma_f32_16x16x32_bf16 v[92:95], v[188:191], v[134:137], v[98:101]
	v_mfma_f32_16x16x32_bf16 v[4:7], v[156:159], v[122:125], v[4:7]
	v_mfma_f32_16x16x32_bf16 v[16:19], v[156:159], v[144:147], v[16:19]
	v_mfma_f32_16x16x32_bf16 v[72:75], v[164:167], v[122:125], v[72:75]
	v_mfma_f32_16x16x32_bf16 v[76:79], v[164:167], v[144:147], v[76:79]
	v_mfma_f32_16x16x32_bf16 v[80:83], v[184:187], v[122:125], v[80:83]
	v_mfma_f32_16x16x32_bf16 v[84:87], v[184:187], v[144:147], v[84:87]
	v_mfma_f32_16x16x32_bf16 v[88:91], v[192:195], v[122:125], v[88:91]
	v_mfma_f32_16x16x32_bf16 v[92:95], v[192:195], v[144:147], v[92:95]
	s_barrier
; #define LDA(dst, b, h) for (int m = 0; m < 4; ++m) for (int k = 0; k < 2; ++k) \
;     dst[m][k] = *reinterpret_cast<const bf16x8*>((char*)SA(b, h) + lds_byte(wr * 64 + m * 16 + fr, k * 32 + fq * 8))
; #define LDB(dst, b, h) for (int n = 0; n < 2; ++n) for (int k = 0; k < 2; ++k) \
;     dst[n][k] = *reinterpret_cast<const bf16x8*>((char*)SB(b, h) + lds_byte(wc * 32 + n * 16 + fr, k * 32 + fq * 8))
; #define MMA(ai, bj, At_, Bt_) do { __builtin_amdgcn_s_setprio(1); \
;     for (int k = 0; k < 2; ++k) for (int m = 0; m < 4; ++m) for (int n = 0; n < 2; ++n) \
;       acc[ai][bj][m][n] = __builtin_amdgcn_mfma_f32_16x16x32_bf16(At_[m][k], Bt_[n][k], acc[ai][bj][m][n], 0, 0, 0); \
;     __builtin_amdgcn_s_setprio(0); } while (0)
; #define WAIT_V(n) asm volatile("s_waitcnt vmcnt(" #n ")" ::: "memory")
; #define WAIT_L(n) asm volatile("s_waitcnt lgkmcnt(" #n ")" ::: "memory")
; #define BAR __builtin_amdgcn_s_barrier()
; template <int EPI, int lda, int ldb, int N, int K>
; __device__ __forceinline__ void gemm_phase(const u16* __restrict__ A, const u16* __restrict__ Bt, const GemmEpi ep, int wv) {
;     ...
;       LDB(B1, 0, 1); BAR; WAIT_L(0); MMA(0, 1, At, B1); BAR;
;       LDA(At, 0, 1); WAIT_V(4); BAR; WAIT_L(0); MMA(1, 0, At, B0); MMA(1, 1, At, B1); BAR; }
;     { LDB(B0, 1, 0); LDA(At, 1, 0); WAIT_V(2); BAR; WAIT_L(0); MMA(0, 0, At, B0); BAR;
	ds_read_b128 v[96:99], v224
	ds_read_b128 v[196:199], v224 offset:1024
	ds_read_b128 v[200:203], v224 offset:2048
	ds_read_b128 v[204:207], v224 offset:3072
	s_barrier
	s_waitcnt lgkmcnt(0)
	s_waitcnt lgkmcnt(0)
	v_mfma_f32_16x16x32_bf16 v[12:15], v[152:155], v[96:99], v[12:15]
	v_mfma_f32_16x16x32_bf16 v[40:43], v[152:155], v[200:203], v[40:43]
	v_mfma_f32_16x16x32_bf16 v[52:55], v[180:183], v[96:99], v[52:55]
	v_mfma_f32_16x16x32_bf16 v[56:59], v[180:183], v[200:203], v[56:59]
	v_mfma_f32_16x16x32_bf16 v[64:67], v[188:191], v[200:203], v[64:67]
	v_mfma_f32_16x16x32_bf16 v[44:47], v[160:163], v[96:99], v[44:47]
	v_mfma_f32_16x16x32_bf16 v[48:51], v[160:163], v[200:203], v[48:51]
	v_mfma_f32_16x16x32_bf16 v[60:63], v[188:191], v[96:99], v[60:63]
	v_mfma_f32_16x16x32_bf16 v[12:15], v[156:159], v[196:199], v[12:15]
	v_mfma_f32_16x16x32_bf16 v[40:43], v[156:159], v[204:207], v[40:43]
	v_mfma_f32_16x16x32_bf16 v[52:55], v[184:187], v[196:199], v[52:55]
	v_mfma_f32_16x16x32_bf16 v[56:59], v[184:187], v[204:207], v[56:59]
	v_mfma_f32_16x16x32_bf16 v[64:67], v[192:195], v[204:207], v[64:67]
	v_mfma_f32_16x16x32_bf16 v[152:155], v[164:167], v[196:199], v[44:47]
	v_mfma_f32_16x16x32_bf16 v[156:159], v[164:167], v[204:207], v[48:51]
	v_mfma_f32_16x16x32_bf16 v[160:163], v[192:195], v[196:199], v[60:63]
	s_barrier
	ds_read_b128 v[44:47], v228 offset:16384
	ds_read_b128 v[48:51], v228 offset:17408
	ds_read_b128 v[60:63], v229 offset:18432
	ds_read_b128 v[164:167], v229 offset:19456
	ds_read_b128 v[180:183], v229 offset:20480
	ds_read_b128 v[184:187], v229 offset:21504
	ds_read_b128 v[188:191], v229 offset:22528
	ds_read_b128 v[192:195], v229 offset:23552
	s_waitcnt vmcnt(4)
	s_barrier
	s_waitcnt lgkmcnt(0)
	s_waitcnt lgkmcnt(0)
	v_mfma_f32_16x16x32_bf16 v[8:11], v[44:47], v[118:121], v[8:11]
	v_mfma_f32_16x16x32_bf16 v[24:27], v[188:191], v[118:121], v[24:27]
	v_mfma_f32_16x16x32_bf16 v[28:31], v[188:191], v[134:137], v[28:31]
	v_mfma_f32_16x16x32_bf16 v[114:117], v[44:47], v[134:137], v[114:117]
	v_mfma_f32_16x16x32_bf16 v[148:151], v[60:63], v[118:121], v[148:151]
	v_mfma_f32_16x16x32_bf16 v[168:171], v[60:63], v[134:137], v[168:171]
	v_mfma_f32_16x16x32_bf16 v[172:175], v[180:183], v[118:121], v[172:175]
	v_mfma_f32_16x16x32_bf16 v[176:179], v[180:183], v[134:137], v[176:179]
	v_mfma_f32_16x16x32_bf16 v[8:11], v[48:51], v[122:125], v[8:11]
	v_mfma_f32_16x16x32_bf16 v[24:27], v[192:195], v[122:125], v[24:27]
	v_mfma_f32_16x16x32_bf16 v[28:31], v[192:195], v[144:147], v[28:31]
	v_mfma_f32_16x16x32_bf16 v[134:137], v[48:51], v[144:147], v[114:117]
	v_mfma_f32_16x16x32_bf16 v[148:151], v[164:167], v[122:125], v[148:151]
	v_mfma_f32_16x16x32_bf16 v[168:171], v[164:167], v[144:147], v[168:171]
	v_mfma_f32_16x16x32_bf16 v[172:175], v[184:187], v[122:125], v[172:175]
	v_mfma_f32_16x16x32_bf16 v[176:179], v[184:187], v[144:147], v[176:179]
	v_mfma_f32_16x16x32_bf16 v[0:3], v[44:47], v[96:99], v[0:3]
	v_mfma_f32_16x16x32_bf16 v[20:23], v[44:47], v[200:203], v[20:23]
	v_mfma_f32_16x16x32_bf16 v[44:47], v[180:183], v[96:99], v[68:71]
	v_mfma_f32_16x16x32_bf16 v[68:71], v[188:191], v[96:99], v[102:105]
	v_mfma_f32_16x16x32_bf16 v[32:35], v[60:63], v[96:99], v[32:35]
	v_mfma_f32_16x16x32_bf16 v[36:39], v[60:63], v[200:203], v[36:39]
	v_mfma_f32_16x16x32_bf16 v[60:63], v[180:183], v[200:203], v[110:113]
	v_mfma_f32_16x16x32_bf16 v[96:99], v[188:191], v[200:203], v[106:109]
	v_mfma_f32_16x16x32_bf16 v[20:23], v[48:51], v[204:207], v[20:23]
	v_mfma_f32_16x16x32_bf16 v[68:71], v[192:195], v[196:199], v[68:71]
	v_mfma_f32_16x16x32_bf16 v[144:147], v[48:51], v[196:199], v[0:3]
	v_mfma_f32_16x16x32_bf16 v[180:183], v[164:167], v[196:199], v[32:35]
	v_mfma_f32_16x16x32_bf16 v[164:167], v[164:167], v[204:207], v[36:39]
	v_mfma_f32_16x16x32_bf16 v[188:191], v[184:187], v[196:199], v[44:47]
	v_mfma_f32_16x16x32_bf16 v[184:187], v[184:187], v[204:207], v[60:63]
	v_mfma_f32_16x16x32_bf16 v[192:195], v[192:195], v[204:207], v[96:99]
	s_barrier
	ds_read_b128 v[0:3], v225
	ds_read_b128 v[196:199], v225 offset:1024
	ds_read_b128 v[200:203], v225 offset:2048
	ds_read_b128 v[204:207], v225 offset:3072
	ds_read_b128 v[36:39], v228 offset:32768
	ds_read_b128 v[100:103], v228 offset:33792
	ds_read_b128 v[108:111], v229 offset:34816
	ds_read_b128 v[208:211], v229 offset:35840
	ds_read_b128 v[116:119], v229 offset:36864
	ds_read_b128 v[212:215], v229 offset:37888
	ds_read_b128 v[124:127], v229 offset:38912
	ds_read_b128 v[216:219], v229 offset:39936
	s_waitcnt vmcnt(2)
	s_barrier
; #define LDA(dst, b, h) for (int m = 0; m < 4; ++m) for (int k = 0; k < 2; ++k) \
;     dst[m][k] = *reinterpret_cast<const bf16x8*>((char*)SA(b, h) + lds_byte(wr * 64 + m * 16 + fr, k * 32 + fq * 8))
; #define LDB(dst, b, h) for (int n = 0; n < 2; ++n) for (int k = 0; k < 2; ++k) \
;     dst[n][k] = *reinterpret_cast<const bf16x8*>((char*)SB(b, h) + lds_byte(wc * 32 + n * 16 + fr, k * 32 + fq * 8))
; #define MMA(ai, bj, At_, Bt_) do { __builtin_amdgcn_s_setprio(1); \
;     for (int k = 0; k < 2; ++k) for (int m = 0; m < 4; ++m) for (int n = 0; n < 2; ++n) \
;       acc[ai][bj][m][n] = __builtin_amdgcn_mfma_f32_16x16x32_bf16(At_[m][k], Bt_[n][k], acc[ai][bj][m][n], 0, 0, 0); \
;     __builtin_amdgcn_s_setprio(0); } while (0)
; #define WAIT_V(n) asm volatile("s_waitcnt vmcnt(" #n ")" ::: "memory")
; #define WAIT_L(n) asm volatile("s_waitcnt lgkmcnt(" #n ")" ::: "memory")
; #define BAR __builtin_amdgcn_s_barrier()
; template <int EPI, int lda, int ldb, int N, int K>
; __device__ __forceinline__ void gemm_phase(const u16* __restrict__ A, const u16* __restrict__ Bt, const GemmEpi ep, int wv) {
;     ...
;     { LDB(B0, 1, 0); LDA(At, 1, 0); WAIT_V(2); BAR; WAIT_L(0); MMA(0, 0, At, B0); BAR;
;       LDB(B1, 1, 1); WAIT_V(0); BAR; WAIT_L(0); MMA(0, 1, At, B1); BAR;
;       LDA(At, 1, 1); BAR; WAIT_L(0); MMA(1, 0, At, B0); MMA(1, 1, At, B1); BAR; }
;     if (wr == 0) BAR;
	s_waitcnt lgkmcnt(0)
	s_waitcnt lgkmcnt(0)
	v_mfma_f32_16x16x32_bf16 v[4:7], v[36:39], v[0:3], v[4:7]
	v_mfma_f32_16x16x32_bf16 v[16:19], v[36:39], v[200:203], v[16:19]
	v_mfma_f32_16x16x32_bf16 v[32:35], v[108:111], v[0:3], v[72:75]
	v_mfma_f32_16x16x32_bf16 v[44:47], v[108:111], v[200:203], v[76:79]
	v_mfma_f32_16x16x32_bf16 v[72:75], v[116:119], v[0:3], v[80:83]
	v_mfma_f32_16x16x32_bf16 v[76:79], v[116:119], v[200:203], v[84:87]
	v_mfma_f32_16x16x32_bf16 v[80:83], v[124:127], v[0:3], v[88:91]
	v_mfma_f32_16x16x32_bf16 v[84:87], v[124:127], v[200:203], v[92:95]
	v_mfma_f32_16x16x32_bf16 v[120:123], v[100:103], v[196:199], v[4:7]
	v_mfma_f32_16x16x32_bf16 v[60:63], v[100:103], v[204:207], v[16:19]
	v_mfma_f32_16x16x32_bf16 v[112:115], v[208:211], v[196:199], v[32:35]
	v_mfma_f32_16x16x32_bf16 v[48:51], v[208:211], v[204:207], v[44:47]
	v_mfma_f32_16x16x32_bf16 v[104:107], v[212:215], v[196:199], v[72:75]
	v_mfma_f32_16x16x32_bf16 v[44:47], v[212:215], v[204:207], v[76:79]
	v_mfma_f32_16x16x32_bf16 v[96:99], v[216:219], v[196:199], v[80:83]
	v_mfma_f32_16x16x32_bf16 v[32:35], v[216:219], v[204:207], v[84:87]
	s_barrier
	ds_read_b128 v[4:7], v226
	ds_read_b128 v[220:223], v226 offset:1024
	ds_read_b128 v[76:79], v226 offset:2048
	ds_read_b128 v[224:227], v226 offset:3072
	s_waitcnt vmcnt(0)
	s_barrier
	s_waitcnt lgkmcnt(0)
	s_waitcnt lgkmcnt(0)
	v_mfma_f32_16x16x32_bf16 v[12:15], v[36:39], v[4:7], v[12:15]
	v_mfma_f32_16x16x32_bf16 v[16:19], v[36:39], v[76:79], v[40:43]
	v_mfma_f32_16x16x32_bf16 v[36:39], v[108:111], v[4:7], v[152:155]
	v_mfma_f32_16x16x32_bf16 v[40:43], v[108:111], v[76:79], v[156:159]
	v_mfma_f32_16x16x32_bf16 v[72:75], v[116:119], v[4:7], v[52:55]
	v_mfma_f32_16x16x32_bf16 v[80:83], v[116:119], v[76:79], v[56:59]
	v_mfma_f32_16x16x32_bf16 v[84:87], v[124:127], v[4:7], v[160:163]
	v_mfma_f32_16x16x32_bf16 v[64:67], v[124:127], v[76:79], v[64:67]
	v_mfma_f32_16x16x32_bf16 v[124:127], v[100:103], v[220:223], v[12:15]
	v_mfma_f32_16x16x32_bf16 v[56:59], v[100:103], v[224:227], v[16:19]
	v_mfma_f32_16x16x32_bf16 v[116:119], v[208:211], v[220:223], v[36:39]
	v_mfma_f32_16x16x32_bf16 v[52:55], v[208:211], v[224:227], v[40:43]
	v_mfma_f32_16x16x32_bf16 v[108:111], v[212:215], v[220:223], v[72:75]
	v_mfma_f32_16x16x32_bf16 v[40:43], v[212:215], v[224:227], v[80:83]
	v_mfma_f32_16x16x32_bf16 v[100:103], v[216:219], v[220:223], v[84:87]
	v_mfma_f32_16x16x32_bf16 v[36:39], v[216:219], v[224:227], v[64:67]
	s_barrier
	ds_read_b128 v[84:87], v228 offset:49152
	ds_read_b128 v[152:155], v228 offset:50176
	ds_read_b128 v[92:95], v229 offset:51200
	ds_read_b128 v[156:159], v229 offset:52224
	ds_read_b128 v[160:163], v229 offset:53248
	ds_read_b128 v[208:211], v229 offset:54272
	ds_read_b128 v[212:215], v229 offset:55296
	ds_read_b128 v[216:219], v229 offset:56320
	s_barrier
	s_waitcnt lgkmcnt(0)
	s_waitcnt lgkmcnt(0)
	v_mfma_f32_16x16x32_bf16 v[8:11], v[84:87], v[0:3], v[8:11]
	v_mfma_f32_16x16x32_bf16 v[12:15], v[84:87], v[200:203], v[134:137]
	v_mfma_f32_16x16x32_bf16 v[16:19], v[92:95], v[0:3], v[148:151]
	v_mfma_f32_16x16x32_bf16 v[64:67], v[92:95], v[200:203], v[168:171]
	v_mfma_f32_16x16x32_bf16 v[72:75], v[160:163], v[0:3], v[172:175]
	v_mfma_f32_16x16x32_bf16 v[134:137], v[160:163], v[200:203], v[176:179]
	v_mfma_f32_16x16x32_bf16 v[0:3], v[212:215], v[0:3], v[24:27]
	v_mfma_f32_16x16x32_bf16 v[24:27], v[212:215], v[200:203], v[28:31]
	v_mfma_f32_16x16x32_bf16 v[88:91], v[152:155], v[196:199], v[8:11]
	v_mfma_f32_16x16x32_bf16 v[28:31], v[152:155], v[204:207], v[12:15]
	v_mfma_f32_16x16x32_bf16 v[80:83], v[156:159], v[196:199], v[16:19]
	v_mfma_f32_16x16x32_bf16 v[16:19], v[156:159], v[204:207], v[64:67]
	v_mfma_f32_16x16x32_bf16 v[72:75], v[208:211], v[196:199], v[72:75]
	v_mfma_f32_16x16x32_bf16 v[12:15], v[208:211], v[204:207], v[134:137]
	v_mfma_f32_16x16x32_bf16 v[64:67], v[216:219], v[196:199], v[0:3]
	v_mfma_f32_16x16x32_bf16 v[0:3], v[216:219], v[204:207], v[24:27]
	v_mfma_f32_16x16x32_bf16 v[8:11], v[84:87], v[4:7], v[144:147]
	v_mfma_f32_16x16x32_bf16 v[20:23], v[84:87], v[76:79], v[20:23]
	v_mfma_f32_16x16x32_bf16 v[84:87], v[92:95], v[4:7], v[180:183]
	v_mfma_f32_16x16x32_bf16 v[134:137], v[92:95], v[76:79], v[164:167]
	v_mfma_f32_16x16x32_bf16 v[144:147], v[160:163], v[4:7], v[188:191]
	v_mfma_f32_16x16x32_bf16 v[148:151], v[160:163], v[76:79], v[184:187]
	v_mfma_f32_16x16x32_bf16 v[4:7], v[212:215], v[4:7], v[68:71]
	v_mfma_f32_16x16x32_bf16 v[160:163], v[212:215], v[76:79], v[192:195]
	v_mfma_f32_16x16x32_bf16 v[92:95], v[152:155], v[220:223], v[8:11]
	v_mfma_f32_16x16x32_bf16 v[24:27], v[152:155], v[224:227], v[20:23]
	v_mfma_f32_16x16x32_bf16 v[84:87], v[156:159], v[220:223], v[84:87]
	v_mfma_f32_16x16x32_bf16 v[20:23], v[156:159], v[224:227], v[134:137]
	v_mfma_f32_16x16x32_bf16 v[76:79], v[208:211], v[220:223], v[144:147]
	v_mfma_f32_16x16x32_bf16 v[8:11], v[208:211], v[224:227], v[148:151]
	v_mfma_f32_16x16x32_bf16 v[68:71], v[216:219], v[220:223], v[4:7]
	v_mfma_f32_16x16x32_bf16 v[4:7], v[216:219], v[224:227], v[160:163]
	v_cmp_gt_u32_e32 vcc, s62, v130
	s_barrier
	s_and_saveexec_b64 s[46:47], vcc
	s_cbranch_execz .LBB0_1245
	s_barrier
	s_branch .LBB0_1245

; #define STAGE(P, BASE, LD, br, kt) do { const char* _g = (const char*)((BASE) + (size_t)(br) * (LD) + (size_t)(kt) * 64); \
;     for (int _i = 0; _i < 2; ++_i) { int _b = tidx * 16 + _i * 8192; int _r, _c; stage_rc(_b, _r, _c); \
;       __builtin_amdgcn_global_load_lds((const unsigned*)(_g + (unsigned)((_r * (LD) + _c) * 2)), (unsigned*)((char*)(P) + _b), 16, 0, 0); } } while (0)
; #define LDA(dst, b, h) for (int m = 0; m < 4; ++m) for (int k = 0; k < 2; ++k) \
;     dst[m][k] = *reinterpret_cast<const bf16x8*>((char*)SA(b, h) + lds_byte(wr * 64 + m * 16 + fr, k * 32 + fq * 8))
; #define LDB(dst, b, h) for (int n = 0; n < 2; ++n) for (int k = 0; k < 2; ++k) \
;     dst[n][k] = *reinterpret_cast<const bf16x8*>((char*)SB(b, h) + lds_byte(wc * 32 + n * 16 + fr, k * 32 + fq * 8))
; #define MMA(ai, bj, At_, Bt_) do { __builtin_amdgcn_s_setprio(1); \
;     for (int k = 0; k < 2; ++k) for (int m = 0; m < 4; ++m) for (int n = 0; n < 2; ++n) \
;       acc[ai][bj][m][n] = __builtin_amdgcn_mfma_f32_16x16x32_bf16(At_[m][k], Bt_[n][k], acc[ai][bj][m][n], 0, 0, 0); \
;     __builtin_amdgcn_s_setprio(0); } while (0)
; #define WAIT_V(n) asm volatile("s_waitcnt vmcnt(" #n ")" ::: "memory")
; #define WAIT_L(n) asm volatile("s_waitcnt lgkmcnt(" #n ")" ::: "memory")
; #define BAR __builtin_amdgcn_s_barrier()
; #define SCHED __builtin_amdgcn_sched_barrier(0)
; template <int EPI, int lda, int ldb, int N, int K>
; __device__ __forceinline__ void gemm_phase(const u16* __restrict__ A, const u16* __restrict__ Bt, const GemmEpi ep, int wv) {
;     ...
;     f32x4 acc[2][2][4][2] = {};
;     bf16x8 At[4][2], B0[2][2], B1[2][2];
;     constexpr int nt = K / 64;
;     if (wr == 1) BAR;
;     WAIT_V(4); BAR;
;     STAGE(SB(1, 0), Bt, ldb, bcol, 1); STAGE(SA(1, 0), Ab, lda, brow, 1); STAGE(SB(1, 1), Bt, ldb, bcol + HALF, 1);
;     WAIT_V(6); BAR;
;     for (int t = 0; t < nt - 2; t += 2) {
;       LDB(B0, 0, 0); SCHED; LDA(At, 0, 0); STAGE(SA(1, 1), Ab, lda, brow + HALF, t + 1);
;       WAIT_L(8); BAR; WAIT_L(0); MMA(0, 0, At, B0); BAR; SCHED;
;       LDB(B1, 0, 1); STAGE(SB(0, 0), Bt, ldb, bcol, t + 2);
;       BAR; WAIT_L(0); MMA(0, 1, At, B1); BAR;
;       LDA(At, 0, 1); STAGE(SA(0, 0), Ab, lda, brow, t + 2);
.LBB0_1349:
	s_or_b64 exec, exec, s[54:55]
	v_mov_b32_e32 v1, v129
	v_add_u32_e32 v7, s58, v6
	v_lshl_add_u64 v[12:13], s[46:47], 0, v[128:129]
	v_lshl_add_u64 v[14:15], s[46:47], 0, v[0:1]
	v_lshl_add_u64 v[2:3], s[52:53], 0, v[128:129]
	v_lshl_add_u64 v[0:1], s[52:53], 0, v[0:1]
	v_readfirstlane_b32 s53, v7
	v_add_u32_e32 v7, 0x2000, v7
	v_mov_b32_e32 v5, v129
	v_mov_b32_e32 v17, v129
	v_lshl_add_u64 v[26:27], v[12:13], 0, s[36:37]
	s_mov_b32 m0, s53
	v_readfirstlane_b32 s52, v7
	v_add_u32_e32 v7, 0x8000, v23
	v_lshl_add_u64 v[8:9], s[50:51], 0, v[4:5]
	v_lshl_add_u64 v[10:11], s[50:51], 0, v[16:17]
	s_waitcnt vmcnt(4)
	s_barrier
	global_load_lds_dwordx4 v[26:27], off
	v_lshl_add_u64 v[26:27], v[14:15], 0, s[36:37]
	s_mov_b32 m0, s52
	v_readfirstlane_b32 s51, v7
	v_add_u32_e32 v7, 0xa000, v23
	global_load_lds_dwordx4 v[26:27], off
	v_lshl_add_u64 v[26:27], v[8:9], 0, s[36:37]
	s_mov_b32 m0, s51
	v_readfirstlane_b32 s50, v7
	v_add_u32_e32 v25, s59, v6
	global_load_lds_dwordx4 v[26:27], off
	v_lshl_add_u64 v[26:27], v[10:11], 0, s[36:37]
	s_mov_b32 m0, s50
	v_readfirstlane_b32 s11, v25
	v_add_u32_e32 v25, 0x2000, v25
	global_load_lds_dwordx4 v[26:27], off
	v_lshl_add_u64 v[26:27], v[2:3], 0, s[36:37]
	s_mov_b32 m0, s11
	v_readfirstlane_b32 s5, v25
	global_load_lds_dwordx4 v[26:27], off
	v_lshl_add_u64 v[6:7], v[0:1], 0, s[36:37]
	s_mov_b32 m0, s5
	v_and_b32_e32 v132, 15, v20
	global_load_lds_dwordx4 v[6:7], off
	v_bfe_u32 v128, v20, 4, 2
	v_lshlrev_b32_e32 v7, 2, v20
	v_bfe_u32 v131, v130, 6, 2
	v_lshlrev_b32_e32 v25, 4, v128
	v_lshlrev_b32_e32 v6, 6, v132
	v_and_b32_e32 v50, 32, v7
	v_lshlrev_b32_e32 v126, 12, v131
	v_bitop3_b32 v127, v25, v50, v6 bitop3:0x36
	v_add3_u32 v133, s56, v127, v126
	s_waitcnt vmcnt(6)
	s_barrier
	ds_read_b128 v[26:29], v133
	ds_read_b128 v[30:33], v133 offset:1024
	ds_read_b128 v[34:37], v133 offset:2048
	ds_read_b128 v[38:41], v133 offset:3072
	v_lshl_add_u64 v[6:7], s[48:49], 0, v[4:5]
	v_lshl_add_u64 v[4:5], s[48:49], 0, v[16:17]
	v_lshlrev_b32_e32 v17, 6, v20
	v_and_b32_e32 v17, 0x3c0, v17
	v_add_u32_e32 v20, 0xc000, v23
	v_lshlrev_b32_e32 v16, 13, v139
	v_bitop3_b32 v17, v17, v50, v25 bitop3:0x36
	v_readfirstlane_b32 s47, v20
	v_add_u32_e32 v20, 0xe000, v23
	v_add3_u32 v228, 0, v127, v16
	v_add3_u32 v229, 0, v17, v16
	v_lshl_add_u64 v[16:17], v[6:7], 0, s[36:37]
	s_mov_b32 m0, s47
	v_readfirstlane_b32 s46, v20
	ds_read_b128 v[42:45], v228
	ds_read_b128 v[46:49], v228 offset:1024
	ds_read_b128 v[50:53], v229 offset:2048
	ds_read_b128 v[54:57], v229 offset:3072
	ds_read_b128 v[58:61], v229 offset:4096
	ds_read_b128 v[62:65], v229 offset:5120
	ds_read_b128 v[66:69], v229 offset:6144
	ds_read_b128 v[70:73], v229 offset:7168
	global_load_lds_dwordx4 v[16:17], off
	v_lshl_add_u64 v[16:17], v[4:5], 0, s[36:37]
	s_mov_b32 m0, s46
	s_nop 0
	global_load_lds_dwordx4 v[16:17], off
	s_waitcnt lgkmcnt(8)
	s_barrier
	s_waitcnt lgkmcnt(0)
	s_waitcnt lgkmcnt(0)
	v_mfma_f32_16x16x32_bf16 v[74:77], v[42:45], v[26:29], 0
	v_mfma_f32_16x16x32_bf16 v[78:81], v[42:45], v[34:37], 0
	v_mfma_f32_16x16x32_bf16 v[82:85], v[50:53], v[26:29], 0
	v_mfma_f32_16x16x32_bf16 v[86:89], v[50:53], v[34:37], 0
	v_mfma_f32_16x16x32_bf16 v[90:93], v[58:61], v[26:29], 0
	v_mfma_f32_16x16x32_bf16 v[94:97], v[58:61], v[34:37], 0
	v_mfma_f32_16x16x32_bf16 v[98:101], v[66:69], v[26:29], 0
	v_mfma_f32_16x16x32_bf16 v[102:105], v[66:69], v[34:37], 0
	v_mfma_f32_16x16x32_bf16 v[74:77], v[46:49], v[30:33], v[74:77]
	v_mfma_f32_16x16x32_bf16 v[78:81], v[46:49], v[38:41], v[78:81]
	v_mfma_f32_16x16x32_bf16 v[82:85], v[54:57], v[30:33], v[82:85]
	v_mfma_f32_16x16x32_bf16 v[86:89], v[54:57], v[38:41], v[86:89]
	v_mfma_f32_16x16x32_bf16 v[90:93], v[62:65], v[30:33], v[90:93]
	v_mfma_f32_16x16x32_bf16 v[94:97], v[62:65], v[38:41], v[94:97]
	v_mfma_f32_16x16x32_bf16 v[98:101], v[70:73], v[30:33], v[98:101]
	v_mfma_f32_16x16x32_bf16 v[102:105], v[70:73], v[38:41], v[102:105]
	s_barrier
	v_readfirstlane_b32 s48, v21
	v_add_u32_e32 v20, 0x2000, v21
	v_add3_u32 v224, s57, v127, v126
	v_lshl_add_u64 v[16:17], v[12:13], 0, s[38:39]
	s_mov_b32 m0, s48
	ds_read_b128 v[106:109], v224
	ds_read_b128 v[110:113], v224 offset:1024
	ds_read_b128 v[114:117], v224 offset:2048
	ds_read_b128 v[118:121], v224 offset:3072
	global_load_lds_dwordx4 v[16:17], off
	s_bitset1_b32 m0, 13
	v_lshl_add_u64 v[16:17], v[14:15], 0, s[38:39]
	global_load_lds_dwordx4 v[16:17], off
	s_barrier
	s_waitcnt lgkmcnt(0)
	s_waitcnt lgkmcnt(0)
	v_mfma_f32_16x16x32_bf16 v[122:125], v[42:45], v[106:109], 0
	v_mfma_f32_16x16x32_bf16 v[42:45], v[42:45], v[114:117], 0
	v_mfma_f32_16x16x32_bf16 v[140:143], v[50:53], v[106:109], 0
	v_mfma_f32_16x16x32_bf16 v[50:53], v[50:53], v[114:117], 0
	v_mfma_f32_16x16x32_bf16 v[144:147], v[58:61], v[106:109], 0
	v_mfma_f32_16x16x32_bf16 v[58:61], v[58:61], v[114:117], 0
	v_mfma_f32_16x16x32_bf16 v[148:151], v[66:69], v[106:109], 0
	v_mfma_f32_16x16x32_bf16 v[66:69], v[66:69], v[114:117], 0
	v_mfma_f32_16x16x32_bf16 v[122:125], v[46:49], v[110:113], v[122:125]
	v_mfma_f32_16x16x32_bf16 v[42:45], v[46:49], v[118:121], v[42:45]
	v_mfma_f32_16x16x32_bf16 v[46:49], v[54:57], v[110:113], v[140:143]
	v_mfma_f32_16x16x32_bf16 v[50:53], v[54:57], v[118:121], v[50:53]
	v_mfma_f32_16x16x32_bf16 v[54:57], v[62:65], v[110:113], v[144:147]
	v_mfma_f32_16x16x32_bf16 v[58:61], v[62:65], v[118:121], v[58:61]
	v_mfma_f32_16x16x32_bf16 v[62:65], v[70:73], v[110:113], v[148:151]
	v_mfma_f32_16x16x32_bf16 v[66:69], v[70:73], v[118:121], v[66:69]
	v_readfirstlane_b32 s48, v23
	v_lshl_add_u64 v[16:17], v[8:9], 0, s[38:39]
	s_mov_b32 m0, s48
	s_barrier
; #define STAGE(P, BASE, LD, br, kt) do { const char* _g = (const char*)((BASE) + (size_t)(br) * (LD) + (size_t)(kt) * 64); \
;     for (int _i = 0; _i < 2; ++_i) { int _b = tidx * 16 + _i * 8192; int _r, _c; stage_rc(_b, _r, _c); \
;       __builtin_amdgcn_global_load_lds((const unsigned*)(_g + (unsigned)((_r * (LD) + _c) * 2)), (unsigned*)((char*)(P) + _b), 16, 0, 0); } } while (0)
; #define LDA(dst, b, h) for (int m = 0; m < 4; ++m) for (int k = 0; k < 2; ++k) \
;     dst[m][k] = *reinterpret_cast<const bf16x8*>((char*)SA(b, h) + lds_byte(wr * 64 + m * 16 + fr, k * 32 + fq * 8))
; #define LDB(dst, b, h) for (int n = 0; n < 2; ++n) for (int k = 0; k < 2; ++k) \
;     dst[n][k] = *reinterpret_cast<const bf16x8*>((char*)SB(b, h) + lds_byte(wc * 32 + n * 16 + fr, k * 32 + fq * 8))
; #define MMA(ai, bj, At_, Bt_) do { __builtin_amdgcn_s_setprio(1); \
;     for (int k = 0; k < 2; ++k) for (int m = 0; m < 4; ++m) for (int n = 0; n < 2; ++n) \
;       acc[ai][bj][m][n] = __builtin_amdgcn_mfma_f32_16x16x32_bf16(At_[m][k], Bt_[n][k], acc[ai][bj][m][n], 0, 0, 0); \
;     __builtin_amdgcn_s_setprio(0); } while (0)
; #define WAIT_V(n) asm volatile("s_waitcnt vmcnt(" #n ")" ::: "memory")
; #define WAIT_L(n) asm volatile("s_waitcnt lgkmcnt(" #n ")" ::: "memory")
; #define BAR __builtin_amdgcn_s_barrier()
; #define SCHED __builtin_amdgcn_sched_barrier(0)
; template <int EPI, int lda, int ldb, int N, int K>
; __device__ __forceinline__ void gemm_phase(const u16* __restrict__ A, const u16* __restrict__ Bt, const GemmEpi ep, int wv) {
;     ...
;       LDA(At, 0, 1); STAGE(SA(0, 0), Ab, lda, brow, t + 2);
;       BAR; WAIT_L(0); MMA(1, 0, At, B0); BAR; SCHED;
;       STAGE(SB(0, 1), Bt, ldb, bcol + HALF, t + 2);
;       WAIT_V(6); BAR; MMA(1, 1, At, B1); BAR;
;       LDB(B0, 1, 0); SCHED; LDA(At, 1, 0); STAGE(SA(0, 1), Ab, lda, brow + HALF, t + 2);
;       WAIT_L(8); BAR; WAIT_L(0); MMA(0, 0, At, B0); BAR; SCHED;
;       LDB(B1, 1, 1); STAGE(SB(1, 0), Bt, ldb, bcol, t + 3);
	ds_read_b128 v[70:73], v228 offset:16384
	ds_read_b128 v[140:143], v228 offset:17408
	ds_read_b128 v[144:147], v229 offset:18432
	ds_read_b128 v[148:151], v229 offset:19456
	ds_read_b128 v[152:155], v229 offset:20480
	ds_read_b128 v[156:159], v229 offset:21504
	ds_read_b128 v[160:163], v229 offset:22528
	ds_read_b128 v[164:167], v229 offset:23552
	global_load_lds_dwordx4 v[16:17], off
	s_bitset1_b32 m0, 13
	v_lshl_add_u64 v[16:17], v[10:11], 0, s[38:39]
	global_load_lds_dwordx4 v[16:17], off
	s_barrier
	s_waitcnt lgkmcnt(0)
	s_waitcnt lgkmcnt(0)
	v_mfma_f32_16x16x32_bf16 v[168:171], v[70:73], v[26:29], 0
	v_mfma_f32_16x16x32_bf16 v[172:175], v[70:73], v[34:37], 0
	v_mfma_f32_16x16x32_bf16 v[176:179], v[144:147], v[26:29], 0
	v_mfma_f32_16x16x32_bf16 v[180:183], v[144:147], v[34:37], 0
	v_mfma_f32_16x16x32_bf16 v[184:187], v[152:155], v[26:29], 0
	v_mfma_f32_16x16x32_bf16 v[188:191], v[152:155], v[34:37], 0
	v_mfma_f32_16x16x32_bf16 v[24:27], v[160:163], v[26:29], 0
	v_mfma_f32_16x16x32_bf16 v[34:37], v[160:163], v[34:37], 0
	v_mfma_f32_16x16x32_bf16 v[168:171], v[140:143], v[30:33], v[168:171]
	v_mfma_f32_16x16x32_bf16 v[176:179], v[148:151], v[30:33], v[176:179]
	v_mfma_f32_16x16x32_bf16 v[184:187], v[156:159], v[30:33], v[184:187]
	v_mfma_f32_16x16x32_bf16 v[24:27], v[164:167], v[30:33], v[24:27]
	v_mfma_f32_16x16x32_bf16 v[28:31], v[164:167], v[38:41], v[34:37]
	v_mfma_f32_16x16x32_bf16 v[172:175], v[140:143], v[38:41], v[172:175]
	v_mfma_f32_16x16x32_bf16 v[180:183], v[148:151], v[38:41], v[180:183]
	v_mfma_f32_16x16x32_bf16 v[188:191], v[156:159], v[38:41], v[188:191]
	s_barrier
	v_readfirstlane_b32 s48, v22
	v_add_u32_e32 v20, 0x2000, v22
	v_lshl_add_u64 v[16:17], v[2:3], 0, s[38:39]
	s_mov_b32 m0, s48
	global_load_lds_dwordx4 v[16:17], off
	s_bitset1_b32 m0, 13
	v_lshl_add_u64 v[16:17], v[0:1], 0, s[38:39]
	global_load_lds_dwordx4 v[16:17], off
	s_waitcnt vmcnt(6)
	s_barrier
	v_mfma_f32_16x16x32_bf16 v[20:23], v[70:73], v[106:109], 0
	v_mfma_f32_16x16x32_bf16 v[32:35], v[70:73], v[114:117], 0
	v_mfma_f32_16x16x32_bf16 v[36:39], v[144:147], v[106:109], 0
	v_mfma_f32_16x16x32_bf16 v[70:73], v[144:147], v[114:117], 0
	v_mfma_f32_16x16x32_bf16 v[144:147], v[152:155], v[106:109], 0
	v_mfma_f32_16x16x32_bf16 v[152:155], v[152:155], v[114:117], 0
	v_mfma_f32_16x16x32_bf16 v[106:109], v[160:163], v[106:109], 0
	v_mfma_f32_16x16x32_bf16 v[114:117], v[160:163], v[114:117], 0
	v_mfma_f32_16x16x32_bf16 v[20:23], v[140:143], v[110:113], v[20:23]
	v_mfma_f32_16x16x32_bf16 v[32:35], v[140:143], v[118:121], v[32:35]
	v_mfma_f32_16x16x32_bf16 v[36:39], v[148:151], v[110:113], v[36:39]
	v_mfma_f32_16x16x32_bf16 v[70:73], v[148:151], v[118:121], v[70:73]
	v_mfma_f32_16x16x32_bf16 v[140:143], v[156:159], v[110:113], v[144:147]
	v_mfma_f32_16x16x32_bf16 v[106:109], v[164:167], v[110:113], v[106:109]
	v_mfma_f32_16x16x32_bf16 v[110:113], v[164:167], v[118:121], v[114:117]
	v_mfma_f32_16x16x32_bf16 v[144:147], v[156:159], v[118:121], v[152:155]
	v_add3_u32 v225, s58, v127, v126
	s_barrier
	ds_read_b128 v[114:117], v225
	ds_read_b128 v[118:121], v225 offset:1024
	ds_read_b128 v[148:151], v225 offset:2048
	ds_read_b128 v[152:155], v225 offset:3072
	v_readfirstlane_b32 s48, v18
	v_lshl_add_u64 v[16:17], v[6:7], 0, s[38:39]
	s_mov_b32 m0, s48
	ds_read_b128 v[156:159], v228 offset:32768
	ds_read_b128 v[160:163], v228 offset:33792
	ds_read_b128 v[164:167], v229 offset:34816
	ds_read_b128 v[192:195], v229 offset:35840
	ds_read_b128 v[196:199], v229 offset:36864
	ds_read_b128 v[200:203], v229 offset:37888
	ds_read_b128 v[204:207], v229 offset:38912
	ds_read_b128 v[208:211], v229 offset:39936
	global_load_lds_dwordx4 v[16:17], off
	s_bitset1_b32 m0, 13
	v_lshl_add_u64 v[16:17], v[4:5], 0, s[38:39]
	global_load_lds_dwordx4 v[16:17], off
	s_waitcnt lgkmcnt(8)
	s_barrier
	s_waitcnt lgkmcnt(0)
	s_waitcnt lgkmcnt(0)
	v_mfma_f32_16x16x32_bf16 v[16:19], v[156:159], v[114:117], v[74:77]
	v_mfma_f32_16x16x32_bf16 v[74:77], v[156:159], v[148:151], v[78:81]
	v_mfma_f32_16x16x32_bf16 v[78:81], v[164:167], v[114:117], v[82:85]
	v_mfma_f32_16x16x32_bf16 v[82:85], v[164:167], v[148:151], v[86:89]
	v_mfma_f32_16x16x32_bf16 v[86:89], v[196:199], v[114:117], v[90:93]
	v_mfma_f32_16x16x32_bf16 v[90:93], v[196:199], v[148:151], v[94:97]
	v_mfma_f32_16x16x32_bf16 v[94:97], v[204:207], v[114:117], v[98:101]
	v_mfma_f32_16x16x32_bf16 v[98:101], v[204:207], v[148:151], v[102:105]
	v_mfma_f32_16x16x32_bf16 v[16:19], v[160:163], v[118:121], v[16:19]
	v_mfma_f32_16x16x32_bf16 v[74:77], v[160:163], v[152:155], v[74:77]
	v_mfma_f32_16x16x32_bf16 v[78:81], v[192:195], v[118:121], v[78:81]
	v_mfma_f32_16x16x32_bf16 v[82:85], v[192:195], v[152:155], v[82:85]
	v_mfma_f32_16x16x32_bf16 v[86:89], v[200:203], v[118:121], v[86:89]
	v_mfma_f32_16x16x32_bf16 v[90:93], v[200:203], v[152:155], v[90:93]
	v_mfma_f32_16x16x32_bf16 v[94:97], v[208:211], v[118:121], v[94:97]
	v_mfma_f32_16x16x32_bf16 v[98:101], v[208:211], v[152:155], v[98:101]
	s_barrier
	s_mov_b32 m0, s53
	v_add3_u32 v226, s59, v127, v126
	v_lshl_add_u64 v[12:13], v[12:13], 0, s[40:41]
	ds_read_b128 v[102:105], v226
	ds_read_b128 v[212:215], v226 offset:1024
	ds_read_b128 v[216:219], v226 offset:2048
	ds_read_b128 v[220:223], v226 offset:3072
	global_load_lds_dwordx4 v[12:13], off
	v_lshl_add_u64 v[12:13], v[14:15], 0, s[40:41]
	s_mov_b32 m0, s52
	s_nop 0
	global_load_lds_dwordx4 v[12:13], off
	s_barrier
; #define STAGE(P, BASE, LD, br, kt) do { const char* _g = (const char*)((BASE) + (size_t)(br) * (LD) + (size_t)(kt) * 64); \
;     for (int _i = 0; _i < 2; ++_i) { int _b = tidx * 16 + _i * 8192; int _r, _c; stage_rc(_b, _r, _c); \
;       __builtin_amdgcn_global_load_lds((const unsigned*)(_g + (unsigned)((_r * (LD) + _c) * 2)), (unsigned*)((char*)(P) + _b), 16, 0, 0); } } while (0)
; #define LDA(dst, b, h) for (int m = 0; m < 4; ++m) for (int k = 0; k < 2; ++k) \
;     dst[m][k] = *reinterpret_cast<const bf16x8*>((char*)SA(b, h) + lds_byte(wr * 64 + m * 16 + fr, k * 32 + fq * 8))
; #define LDB(dst, b, h) for (int n = 0; n < 2; ++n) for (int k = 0; k < 2; ++k) \
;     dst[n][k] = *reinterpret_cast<const bf16x8*>((char*)SB(b, h) + lds_byte(wc * 32 + n * 16 + fr, k * 32 + fq * 8))
; #define MMA(ai, bj, At_, Bt_) do { __builtin_amdgcn_s_setprio(1); \
;     for (int k = 0; k < 2; ++k) for (int m = 0; m < 4; ++m) for (int n = 0; n < 2; ++n) \
;       acc[ai][bj][m][n] = __builtin_amdgcn_mfma_f32_16x16x32_bf16(At_[m][k], Bt_[n][k], acc[ai][bj][m][n], 0, 0, 0); \
;     __builtin_amdgcn_s_setprio(0); } while (0)
; #define WAIT_V(n) asm volatile("s_waitcnt vmcnt(" #n ")" ::: "memory")
; #define WAIT_L(n) asm volatile("s_waitcnt lgkmcnt(" #n ")" ::: "memory")
; #define BAR __builtin_amdgcn_s_barrier()
; #define SCHED __builtin_amdgcn_sched_barrier(0)
; template <int EPI, int lda, int ldb, int N, int K>
; __device__ __forceinline__ void gemm_phase(const u16* __restrict__ A, const u16* __restrict__ Bt, const GemmEpi ep, int wv) {
;     ...
;       BAR; WAIT_L(0); MMA(0, 1, At, B1); BAR;
;       LDA(At, 1, 1); STAGE(SA(1, 0), Ab, lda, brow, t + 3);
;       BAR; WAIT_L(0); MMA(1, 0, At, B0); BAR; SCHED;
;       STAGE(SB(1, 1), Bt, ldb, bcol + HALF, t + 3);
;       WAIT_V(6); BAR; MMA(1, 1, At, B1); BAR;
;     }
;     { LDB(B0, 0, 0); LDA(At, 0, 0); STAGE(SA(1, 1), Ab, lda, brow + HALF, nt - 1);
;       BAR; WAIT_L(0); MMA(0, 0, At, B0); BAR;
	s_waitcnt lgkmcnt(0)
	s_waitcnt lgkmcnt(0)
	v_mfma_f32_16x16x32_bf16 v[12:15], v[156:159], v[102:105], v[122:125]
	v_mfma_f32_16x16x32_bf16 v[40:43], v[156:159], v[216:219], v[42:45]
	v_mfma_f32_16x16x32_bf16 v[44:47], v[164:167], v[102:105], v[46:49]
	v_mfma_f32_16x16x32_bf16 v[48:51], v[164:167], v[216:219], v[50:53]
	v_mfma_f32_16x16x32_bf16 v[52:55], v[196:199], v[102:105], v[54:57]
	v_mfma_f32_16x16x32_bf16 v[56:59], v[196:199], v[216:219], v[58:61]
	v_mfma_f32_16x16x32_bf16 v[60:63], v[204:207], v[102:105], v[62:65]
	v_mfma_f32_16x16x32_bf16 v[64:67], v[204:207], v[216:219], v[66:69]
	v_mfma_f32_16x16x32_bf16 v[12:15], v[160:163], v[212:215], v[12:15]
	v_mfma_f32_16x16x32_bf16 v[40:43], v[160:163], v[220:223], v[40:43]
	v_mfma_f32_16x16x32_bf16 v[44:47], v[192:195], v[212:215], v[44:47]
	v_mfma_f32_16x16x32_bf16 v[48:51], v[192:195], v[220:223], v[48:51]
	v_mfma_f32_16x16x32_bf16 v[52:55], v[200:203], v[212:215], v[52:55]
	v_mfma_f32_16x16x32_bf16 v[56:59], v[200:203], v[220:223], v[56:59]
	v_mfma_f32_16x16x32_bf16 v[60:63], v[208:211], v[212:215], v[60:63]
	v_mfma_f32_16x16x32_bf16 v[64:67], v[208:211], v[220:223], v[64:67]
	s_mov_b32 m0, s51
	v_lshl_add_u64 v[8:9], v[8:9], 0, s[40:41]
	s_barrier
	ds_read_b128 v[122:125], v228 offset:49152
	ds_read_b128 v[156:159], v228 offset:50176
	ds_read_b128 v[160:163], v229 offset:51200
	ds_read_b128 v[164:167], v229 offset:52224
	ds_read_b128 v[192:195], v229 offset:53248
	ds_read_b128 v[196:199], v229 offset:54272
	ds_read_b128 v[200:203], v229 offset:55296
	ds_read_b128 v[204:207], v229 offset:56320
	global_load_lds_dwordx4 v[8:9], off
	v_lshl_add_u64 v[8:9], v[10:11], 0, s[40:41]
	s_mov_b32 m0, s50
	s_nop 0
	global_load_lds_dwordx4 v[8:9], off
	s_barrier
	s_waitcnt lgkmcnt(0)
	s_waitcnt lgkmcnt(0)
	v_mfma_f32_16x16x32_bf16 v[8:11], v[122:125], v[114:117], v[168:171]
	v_mfma_f32_16x16x32_bf16 v[168:171], v[122:125], v[148:151], v[172:175]
	v_mfma_f32_16x16x32_bf16 v[24:27], v[200:203], v[114:117], v[24:27]
	v_mfma_f32_16x16x32_bf16 v[28:31], v[200:203], v[148:151], v[28:31]
	v_mfma_f32_16x16x32_bf16 v[172:175], v[160:163], v[114:117], v[176:179]
	v_mfma_f32_16x16x32_bf16 v[176:179], v[160:163], v[148:151], v[180:183]
	v_mfma_f32_16x16x32_bf16 v[180:183], v[192:195], v[114:117], v[184:187]
	v_mfma_f32_16x16x32_bf16 v[184:187], v[192:195], v[148:151], v[188:191]
	v_mfma_f32_16x16x32_bf16 v[8:11], v[156:159], v[118:121], v[8:11]
	v_mfma_f32_16x16x32_bf16 v[114:117], v[156:159], v[152:155], v[168:171]
	v_mfma_f32_16x16x32_bf16 v[24:27], v[204:207], v[118:121], v[24:27]
	v_mfma_f32_16x16x32_bf16 v[28:31], v[204:207], v[152:155], v[28:31]
	v_mfma_f32_16x16x32_bf16 v[148:151], v[164:167], v[118:121], v[172:175]
	v_mfma_f32_16x16x32_bf16 v[168:171], v[164:167], v[152:155], v[176:179]
	v_mfma_f32_16x16x32_bf16 v[172:175], v[196:199], v[118:121], v[180:183]
	v_mfma_f32_16x16x32_bf16 v[176:179], v[196:199], v[152:155], v[184:187]
	s_barrier
	s_mov_b32 m0, s11
	v_lshl_add_u64 v[2:3], v[2:3], 0, s[40:41]
	global_load_lds_dwordx4 v[2:3], off
	v_lshl_add_u64 v[0:1], v[0:1], 0, s[40:41]
	s_mov_b32 m0, s5
	s_nop 0
	global_load_lds_dwordx4 v[0:1], off
	s_waitcnt vmcnt(6)
	s_barrier
	v_mfma_f32_16x16x32_bf16 v[0:3], v[122:125], v[102:105], v[20:23]
	v_mfma_f32_16x16x32_bf16 v[20:23], v[122:125], v[216:219], v[32:35]
	v_mfma_f32_16x16x32_bf16 v[32:35], v[160:163], v[102:105], v[36:39]
	v_mfma_f32_16x16x32_bf16 v[36:39], v[160:163], v[216:219], v[70:73]
	v_mfma_f32_16x16x32_bf16 v[68:71], v[192:195], v[102:105], v[140:143]
	v_mfma_f32_16x16x32_bf16 v[118:121], v[192:195], v[216:219], v[144:147]
	v_mfma_f32_16x16x32_bf16 v[102:105], v[200:203], v[102:105], v[106:109]
	v_mfma_f32_16x16x32_bf16 v[106:109], v[200:203], v[216:219], v[110:113]
	v_mfma_f32_16x16x32_bf16 v[0:3], v[156:159], v[212:215], v[0:3]
	v_mfma_f32_16x16x32_bf16 v[20:23], v[156:159], v[220:223], v[20:23]
	v_mfma_f32_16x16x32_bf16 v[32:35], v[164:167], v[212:215], v[32:35]
	v_mfma_f32_16x16x32_bf16 v[36:39], v[164:167], v[220:223], v[36:39]
	v_mfma_f32_16x16x32_bf16 v[68:71], v[196:199], v[212:215], v[68:71]
	v_mfma_f32_16x16x32_bf16 v[110:113], v[196:199], v[220:223], v[118:121]
	v_mfma_f32_16x16x32_bf16 v[102:105], v[204:207], v[212:215], v[102:105]
	v_mfma_f32_16x16x32_bf16 v[106:109], v[204:207], v[220:223], v[106:109]
	s_mov_b32 m0, s47
	v_lshl_add_u64 v[6:7], v[6:7], 0, s[40:41]
	s_barrier
	ds_read_b128 v[118:121], v133
	ds_read_b128 v[122:125], v133 offset:1024
	ds_read_b128 v[140:143], v133 offset:2048
	ds_read_b128 v[144:147], v133 offset:3072
	ds_read_b128 v[152:155], v228
	ds_read_b128 v[156:159], v228 offset:1024
	ds_read_b128 v[160:163], v229 offset:2048
	ds_read_b128 v[164:167], v229 offset:3072
	ds_read_b128 v[180:183], v229 offset:4096
	ds_read_b128 v[184:187], v229 offset:5120
	ds_read_b128 v[188:191], v229 offset:6144
	ds_read_b128 v[192:195], v229 offset:7168
	global_load_lds_dwordx4 v[6:7], off
	v_lshl_add_u64 v[4:5], v[4:5], 0, s[40:41]
	s_mov_b32 m0, s46
	s_nop 0
	global_load_lds_dwordx4 v[4:5], off
	s_barrier
	s_waitcnt lgkmcnt(0)
	s_waitcnt lgkmcnt(0)
	v_mfma_f32_16x16x32_bf16 v[4:7], v[152:155], v[118:121], v[16:19]
	v_mfma_f32_16x16x32_bf16 v[16:19], v[152:155], v[140:143], v[74:77]
	v_mfma_f32_16x16x32_bf16 v[72:75], v[160:163], v[118:121], v[78:81]
	v_mfma_f32_16x16x32_bf16 v[76:79], v[160:163], v[140:143], v[82:85]
	v_mfma_f32_16x16x32_bf16 v[80:83], v[180:183], v[118:121], v[86:89]
	v_mfma_f32_16x16x32_bf16 v[84:87], v[180:183], v[140:143], v[90:93]
	v_mfma_f32_16x16x32_bf16 v[88:91], v[188:191], v[118:121], v[94:97]
	v_mfma_f32_16x16x32_bf16 v[92:95], v[188:191], v[140:143], v[98:101]
	v_mfma_f32_16x16x32_bf16 v[4:7], v[156:159], v[122:125], v[4:7]
	v_mfma_f32_16x16x32_bf16 v[16:19], v[156:159], v[144:147], v[16:19]
	v_mfma_f32_16x16x32_bf16 v[72:75], v[164:167], v[122:125], v[72:75]
	v_mfma_f32_16x16x32_bf16 v[76:79], v[164:167], v[144:147], v[76:79]
	v_mfma_f32_16x16x32_bf16 v[80:83], v[184:187], v[122:125], v[80:83]
	v_mfma_f32_16x16x32_bf16 v[84:87], v[184:187], v[144:147], v[84:87]
	v_mfma_f32_16x16x32_bf16 v[88:91], v[192:195], v[122:125], v[88:91]
	v_mfma_f32_16x16x32_bf16 v[92:95], v[192:195], v[144:147], v[92:95]
	s_barrier
; #define LDA(dst, b, h) for (int m = 0; m < 4; ++m) for (int k = 0; k < 2; ++k) \
;     dst[m][k] = *reinterpret_cast<const bf16x8*>((char*)SA(b, h) + lds_byte(wr * 64 + m * 16 + fr, k * 32 + fq * 8))
; #define LDB(dst, b, h) for (int n = 0; n < 2; ++n) for (int k = 0; k < 2; ++k) \
;     dst[n][k] = *reinterpret_cast<const bf16x8*>((char*)SB(b, h) + lds_byte(wc * 32 + n * 16 + fr, k * 32 + fq * 8))
; #define MMA(ai, bj, At_, Bt_) do { __builtin_amdgcn_s_setprio(1); \
;     for (int k = 0; k < 2; ++k) for (int m = 0; m < 4; ++m) for (int n = 0; n < 2; ++n) \
;       acc[ai][bj][m][n] = __builtin_amdgcn_mfma_f32_16x16x32_bf16(At_[m][k], Bt_[n][k], acc[ai][bj][m][n], 0, 0, 0); \
;     __builtin_amdgcn_s_setprio(0); } while (0)
; #define WAIT_V(n) asm volatile("s_waitcnt vmcnt(" #n ")" ::: "memory")
; #define WAIT_L(n) asm volatile("s_waitcnt lgkmcnt(" #n ")" ::: "memory")
; #define BAR __builtin_amdgcn_s_barrier()
; template <int EPI, int lda, int ldb, int N, int K>
; __device__ __forceinline__ void gemm_phase(const u16* __restrict__ A, const u16* __restrict__ Bt, const GemmEpi ep, int wv) {
;     ...
;       LDB(B1, 0, 1); BAR; WAIT_L(0); MMA(0, 1, At, B1); BAR;
;       LDA(At, 0, 1); WAIT_V(4); BAR; WAIT_L(0); MMA(1, 0, At, B0); MMA(1, 1, At, B1); BAR; }
;     { LDB(B0, 1, 0); LDA(At, 1, 0); WAIT_V(2); BAR; WAIT_L(0); MMA(0, 0, At, B0); BAR;
	ds_read_b128 v[96:99], v224
	ds_read_b128 v[196:199], v224 offset:1024
	ds_read_b128 v[200:203], v224 offset:2048
	ds_read_b128 v[204:207], v224 offset:3072
	s_barrier
	s_waitcnt lgkmcnt(0)
	s_waitcnt lgkmcnt(0)
	v_mfma_f32_16x16x32_bf16 v[12:15], v[152:155], v[96:99], v[12:15]
	v_mfma_f32_16x16x32_bf16 v[40:43], v[152:155], v[200:203], v[40:43]
	v_mfma_f32_16x16x32_bf16 v[52:55], v[180:183], v[96:99], v[52:55]
	v_mfma_f32_16x16x32_bf16 v[56:59], v[180:183], v[200:203], v[56:59]
	v_mfma_f32_16x16x32_bf16 v[64:67], v[188:191], v[200:203], v[64:67]
	v_mfma_f32_16x16x32_bf16 v[44:47], v[160:163], v[96:99], v[44:47]
	v_mfma_f32_16x16x32_bf16 v[48:51], v[160:163], v[200:203], v[48:51]
	v_mfma_f32_16x16x32_bf16 v[60:63], v[188:191], v[96:99], v[60:63]
	v_mfma_f32_16x16x32_bf16 v[12:15], v[156:159], v[196:199], v[12:15]
	v_mfma_f32_16x16x32_bf16 v[40:43], v[156:159], v[204:207], v[40:43]
	v_mfma_f32_16x16x32_bf16 v[52:55], v[184:187], v[196:199], v[52:55]
	v_mfma_f32_16x16x32_bf16 v[56:59], v[184:187], v[204:207], v[56:59]
	v_mfma_f32_16x16x32_bf16 v[64:67], v[192:195], v[204:207], v[64:67]
	v_mfma_f32_16x16x32_bf16 v[152:155], v[164:167], v[196:199], v[44:47]
	v_mfma_f32_16x16x32_bf16 v[156:159], v[164:167], v[204:207], v[48:51]
	v_mfma_f32_16x16x32_bf16 v[160:163], v[192:195], v[196:199], v[60:63]
	s_barrier
	ds_read_b128 v[44:47], v228 offset:16384
	ds_read_b128 v[48:51], v228 offset:17408
	ds_read_b128 v[60:63], v229 offset:18432
	ds_read_b128 v[164:167], v229 offset:19456
	ds_read_b128 v[180:183], v229 offset:20480
	ds_read_b128 v[184:187], v229 offset:21504
	ds_read_b128 v[188:191], v229 offset:22528
	ds_read_b128 v[192:195], v229 offset:23552
	s_waitcnt vmcnt(4)
	s_barrier
	s_waitcnt lgkmcnt(0)
	s_waitcnt lgkmcnt(0)
	v_mfma_f32_16x16x32_bf16 v[8:11], v[44:47], v[118:121], v[8:11]
	v_mfma_f32_16x16x32_bf16 v[24:27], v[188:191], v[118:121], v[24:27]
	v_mfma_f32_16x16x32_bf16 v[28:31], v[188:191], v[140:143], v[28:31]
	v_mfma_f32_16x16x32_bf16 v[114:117], v[44:47], v[140:143], v[114:117]
	v_mfma_f32_16x16x32_bf16 v[148:151], v[60:63], v[118:121], v[148:151]
	v_mfma_f32_16x16x32_bf16 v[168:171], v[60:63], v[140:143], v[168:171]
	v_mfma_f32_16x16x32_bf16 v[172:175], v[180:183], v[118:121], v[172:175]
	v_mfma_f32_16x16x32_bf16 v[176:179], v[180:183], v[140:143], v[176:179]
	v_mfma_f32_16x16x32_bf16 v[8:11], v[48:51], v[122:125], v[8:11]
	v_mfma_f32_16x16x32_bf16 v[24:27], v[192:195], v[122:125], v[24:27]
	v_mfma_f32_16x16x32_bf16 v[28:31], v[192:195], v[144:147], v[28:31]
	v_mfma_f32_16x16x32_bf16 v[140:143], v[48:51], v[144:147], v[114:117]
	v_mfma_f32_16x16x32_bf16 v[148:151], v[164:167], v[122:125], v[148:151]
	v_mfma_f32_16x16x32_bf16 v[168:171], v[164:167], v[144:147], v[168:171]
	v_mfma_f32_16x16x32_bf16 v[172:175], v[184:187], v[122:125], v[172:175]
	v_mfma_f32_16x16x32_bf16 v[176:179], v[184:187], v[144:147], v[176:179]
	v_mfma_f32_16x16x32_bf16 v[0:3], v[44:47], v[96:99], v[0:3]
	v_mfma_f32_16x16x32_bf16 v[20:23], v[44:47], v[200:203], v[20:23]
	v_mfma_f32_16x16x32_bf16 v[44:47], v[180:183], v[96:99], v[68:71]
	v_mfma_f32_16x16x32_bf16 v[68:71], v[188:191], v[96:99], v[102:105]
	v_mfma_f32_16x16x32_bf16 v[32:35], v[60:63], v[96:99], v[32:35]
	v_mfma_f32_16x16x32_bf16 v[36:39], v[60:63], v[200:203], v[36:39]
	v_mfma_f32_16x16x32_bf16 v[60:63], v[180:183], v[200:203], v[110:113]
	v_mfma_f32_16x16x32_bf16 v[96:99], v[188:191], v[200:203], v[106:109]
	v_mfma_f32_16x16x32_bf16 v[20:23], v[48:51], v[204:207], v[20:23]
	v_mfma_f32_16x16x32_bf16 v[68:71], v[192:195], v[196:199], v[68:71]
	v_mfma_f32_16x16x32_bf16 v[144:147], v[48:51], v[196:199], v[0:3]
	v_mfma_f32_16x16x32_bf16 v[180:183], v[164:167], v[196:199], v[32:35]
	v_mfma_f32_16x16x32_bf16 v[164:167], v[164:167], v[204:207], v[36:39]
	v_mfma_f32_16x16x32_bf16 v[188:191], v[184:187], v[196:199], v[44:47]
	v_mfma_f32_16x16x32_bf16 v[184:187], v[184:187], v[204:207], v[60:63]
	v_mfma_f32_16x16x32_bf16 v[192:195], v[192:195], v[204:207], v[96:99]
	s_barrier
	ds_read_b128 v[0:3], v225
	ds_read_b128 v[196:199], v225 offset:1024
	ds_read_b128 v[200:203], v225 offset:2048
	ds_read_b128 v[204:207], v225 offset:3072
	ds_read_b128 v[36:39], v228 offset:32768
	ds_read_b128 v[100:103], v228 offset:33792
	ds_read_b128 v[108:111], v229 offset:34816
	ds_read_b128 v[208:211], v229 offset:35840
	ds_read_b128 v[116:119], v229 offset:36864
	ds_read_b128 v[212:215], v229 offset:37888
	ds_read_b128 v[124:127], v229 offset:38912
	ds_read_b128 v[216:219], v229 offset:39936
	s_waitcnt vmcnt(2)
	s_barrier
; #define LDA(dst, b, h) for (int m = 0; m < 4; ++m) for (int k = 0; k < 2; ++k) \
;     dst[m][k] = *reinterpret_cast<const bf16x8*>((char*)SA(b, h) + lds_byte(wr * 64 + m * 16 + fr, k * 32 + fq * 8))
; #define LDB(dst, b, h) for (int n = 0; n < 2; ++n) for (int k = 0; k < 2; ++k) \
;     dst[n][k] = *reinterpret_cast<const bf16x8*>((char*)SB(b, h) + lds_byte(wc * 32 + n * 16 + fr, k * 32 + fq * 8))
; #define MMA(ai, bj, At_, Bt_) do { __builtin_amdgcn_s_setprio(1); \
;     for (int k = 0; k < 2; ++k) for (int m = 0; m < 4; ++m) for (int n = 0; n < 2; ++n) \
;       acc[ai][bj][m][n] = __builtin_amdgcn_mfma_f32_16x16x32_bf16(At_[m][k], Bt_[n][k], acc[ai][bj][m][n], 0, 0, 0); \
;     __builtin_amdgcn_s_setprio(0); } while (0)
; #define WAIT_V(n) asm volatile("s_waitcnt vmcnt(" #n ")" ::: "memory")
; #define WAIT_L(n) asm volatile("s_waitcnt lgkmcnt(" #n ")" ::: "memory")
; #define BAR __builtin_amdgcn_s_barrier()
; template <int EPI, int lda, int ldb, int N, int K>
; __device__ __forceinline__ void gemm_phase(const u16* __restrict__ A, const u16* __restrict__ Bt, const GemmEpi ep, int wv) {
;     ...
;     { LDB(B0, 1, 0); LDA(At, 1, 0); WAIT_V(2); BAR; WAIT_L(0); MMA(0, 0, At, B0); BAR;
;       LDB(B1, 1, 1); WAIT_V(0); BAR; WAIT_L(0); MMA(0, 1, At, B1); BAR;
;       LDA(At, 1, 1); BAR; WAIT_L(0); MMA(1, 0, At, B0); MMA(1, 1, At, B1); BAR; }
;     if (wr == 0) BAR;
	s_waitcnt lgkmcnt(0)
	s_waitcnt lgkmcnt(0)
	v_mfma_f32_16x16x32_bf16 v[4:7], v[36:39], v[0:3], v[4:7]
	v_mfma_f32_16x16x32_bf16 v[16:19], v[36:39], v[200:203], v[16:19]
	v_mfma_f32_16x16x32_bf16 v[32:35], v[108:111], v[0:3], v[72:75]
	v_mfma_f32_16x16x32_bf16 v[44:47], v[108:111], v[200:203], v[76:79]
	v_mfma_f32_16x16x32_bf16 v[72:75], v[116:119], v[0:3], v[80:83]
	v_mfma_f32_16x16x32_bf16 v[76:79], v[116:119], v[200:203], v[84:87]
	v_mfma_f32_16x16x32_bf16 v[80:83], v[124:127], v[0:3], v[88:91]
	v_mfma_f32_16x16x32_bf16 v[84:87], v[124:127], v[200:203], v[92:95]
	v_mfma_f32_16x16x32_bf16 v[120:123], v[100:103], v[196:199], v[4:7]
	v_mfma_f32_16x16x32_bf16 v[60:63], v[100:103], v[204:207], v[16:19]
	v_mfma_f32_16x16x32_bf16 v[112:115], v[208:211], v[196:199], v[32:35]
	v_mfma_f32_16x16x32_bf16 v[48:51], v[208:211], v[204:207], v[44:47]
	v_mfma_f32_16x16x32_bf16 v[104:107], v[212:215], v[196:199], v[72:75]
	v_mfma_f32_16x16x32_bf16 v[44:47], v[212:215], v[204:207], v[76:79]
	v_mfma_f32_16x16x32_bf16 v[96:99], v[216:219], v[196:199], v[80:83]
	v_mfma_f32_16x16x32_bf16 v[32:35], v[216:219], v[204:207], v[84:87]
	s_barrier
	ds_read_b128 v[4:7], v226
	ds_read_b128 v[220:223], v226 offset:1024
	ds_read_b128 v[76:79], v226 offset:2048
	ds_read_b128 v[224:227], v226 offset:3072
	s_waitcnt vmcnt(0)
	s_barrier
	s_waitcnt lgkmcnt(0)
	s_waitcnt lgkmcnt(0)
	v_mfma_f32_16x16x32_bf16 v[12:15], v[36:39], v[4:7], v[12:15]
	v_mfma_f32_16x16x32_bf16 v[16:19], v[36:39], v[76:79], v[40:43]
	v_mfma_f32_16x16x32_bf16 v[36:39], v[108:111], v[4:7], v[152:155]
	v_mfma_f32_16x16x32_bf16 v[40:43], v[108:111], v[76:79], v[156:159]
	v_mfma_f32_16x16x32_bf16 v[72:75], v[116:119], v[4:7], v[52:55]
	v_mfma_f32_16x16x32_bf16 v[80:83], v[116:119], v[76:79], v[56:59]
	v_mfma_f32_16x16x32_bf16 v[84:87], v[124:127], v[4:7], v[160:163]
	v_mfma_f32_16x16x32_bf16 v[64:67], v[124:127], v[76:79], v[64:67]
	v_mfma_f32_16x16x32_bf16 v[124:127], v[100:103], v[220:223], v[12:15]
	v_mfma_f32_16x16x32_bf16 v[56:59], v[100:103], v[224:227], v[16:19]
	v_mfma_f32_16x16x32_bf16 v[116:119], v[208:211], v[220:223], v[36:39]
	v_mfma_f32_16x16x32_bf16 v[52:55], v[208:211], v[224:227], v[40:43]
	v_mfma_f32_16x16x32_bf16 v[108:111], v[212:215], v[220:223], v[72:75]
	v_mfma_f32_16x16x32_bf16 v[40:43], v[212:215], v[224:227], v[80:83]
	v_mfma_f32_16x16x32_bf16 v[100:103], v[216:219], v[220:223], v[84:87]
	v_mfma_f32_16x16x32_bf16 v[36:39], v[216:219], v[224:227], v[64:67]
	s_barrier
	ds_read_b128 v[84:87], v228 offset:49152
	ds_read_b128 v[152:155], v228 offset:50176
	ds_read_b128 v[92:95], v229 offset:51200
	ds_read_b128 v[156:159], v229 offset:52224
	ds_read_b128 v[160:163], v229 offset:53248
	ds_read_b128 v[208:211], v229 offset:54272
	ds_read_b128 v[212:215], v229 offset:55296
	ds_read_b128 v[216:219], v229 offset:56320
	s_barrier
	s_waitcnt lgkmcnt(0)
	s_waitcnt lgkmcnt(0)
	v_mfma_f32_16x16x32_bf16 v[8:11], v[84:87], v[0:3], v[8:11]
	v_mfma_f32_16x16x32_bf16 v[12:15], v[84:87], v[200:203], v[140:143]
	v_mfma_f32_16x16x32_bf16 v[16:19], v[92:95], v[0:3], v[148:151]
	v_mfma_f32_16x16x32_bf16 v[64:67], v[92:95], v[200:203], v[168:171]
	v_mfma_f32_16x16x32_bf16 v[72:75], v[160:163], v[0:3], v[172:175]
	v_mfma_f32_16x16x32_bf16 v[140:143], v[160:163], v[200:203], v[176:179]
	v_mfma_f32_16x16x32_bf16 v[0:3], v[212:215], v[0:3], v[24:27]
	v_mfma_f32_16x16x32_bf16 v[24:27], v[212:215], v[200:203], v[28:31]
	v_mfma_f32_16x16x32_bf16 v[88:91], v[152:155], v[196:199], v[8:11]
	v_mfma_f32_16x16x32_bf16 v[28:31], v[152:155], v[204:207], v[12:15]
	v_mfma_f32_16x16x32_bf16 v[80:83], v[156:159], v[196:199], v[16:19]
	v_mfma_f32_16x16x32_bf16 v[16:19], v[156:159], v[204:207], v[64:67]
	v_mfma_f32_16x16x32_bf16 v[72:75], v[208:211], v[196:199], v[72:75]
	v_mfma_f32_16x16x32_bf16 v[12:15], v[208:211], v[204:207], v[140:143]
	v_mfma_f32_16x16x32_bf16 v[64:67], v[216:219], v[196:199], v[0:3]
	v_mfma_f32_16x16x32_bf16 v[0:3], v[216:219], v[204:207], v[24:27]
	v_mfma_f32_16x16x32_bf16 v[8:11], v[84:87], v[4:7], v[144:147]
	v_mfma_f32_16x16x32_bf16 v[20:23], v[84:87], v[76:79], v[20:23]
	v_mfma_f32_16x16x32_bf16 v[84:87], v[92:95], v[4:7], v[180:183]
	v_mfma_f32_16x16x32_bf16 v[140:143], v[92:95], v[76:79], v[164:167]
	v_mfma_f32_16x16x32_bf16 v[144:147], v[160:163], v[4:7], v[188:191]
	v_mfma_f32_16x16x32_bf16 v[148:151], v[160:163], v[76:79], v[184:187]
	v_mfma_f32_16x16x32_bf16 v[4:7], v[212:215], v[4:7], v[68:71]
	v_mfma_f32_16x16x32_bf16 v[160:163], v[212:215], v[76:79], v[192:195]
	v_mfma_f32_16x16x32_bf16 v[92:95], v[152:155], v[220:223], v[8:11]
	v_mfma_f32_16x16x32_bf16 v[24:27], v[152:155], v[224:227], v[20:23]
	v_mfma_f32_16x16x32_bf16 v[84:87], v[156:159], v[220:223], v[84:87]
	v_mfma_f32_16x16x32_bf16 v[20:23], v[156:159], v[224:227], v[140:143]
	v_mfma_f32_16x16x32_bf16 v[76:79], v[208:211], v[220:223], v[144:147]
	v_mfma_f32_16x16x32_bf16 v[8:11], v[208:211], v[224:227], v[148:151]
	v_mfma_f32_16x16x32_bf16 v[68:71], v[216:219], v[220:223], v[4:7]
	v_mfma_f32_16x16x32_bf16 v[4:7], v[216:219], v[224:227], v[160:163]
	v_cmp_gt_u32_e32 vcc, s60, v130
	s_barrier
	s_and_saveexec_b64 s[46:47], vcc
	s_cbranch_execz .LBB0_1346
	s_barrier
	s_branch .LBB0_1346

; #define STAGE(P, BASE, LD, br, kt) do { const char* _g = (const char*)((BASE) + (size_t)(br) * (LD) + (size_t)(kt) * 64); \
;     for (int _i = 0; _i < 2; ++_i) { int _b = tidx * 16 + _i * 8192; int _r, _c; stage_rc(_b, _r, _c); \
;       __builtin_amdgcn_global_load_lds((const unsigned*)(_g + (unsigned)((_r * (LD) + _c) * 2)), (unsigned*)((char*)(P) + _b), 16, 0, 0); } } while (0)
; #define LDA(dst, b, h) for (int m = 0; m < 4; ++m) for (int k = 0; k < 2; ++k) \
;     dst[m][k] = *reinterpret_cast<const bf16x8*>((char*)SA(b, h) + lds_byte(wr * 64 + m * 16 + fr, k * 32 + fq * 8))
; #define LDB(dst, b, h) for (int n = 0; n < 2; ++n) for (int k = 0; k < 2; ++k) \
;     dst[n][k] = *reinterpret_cast<const bf16x8*>((char*)SB(b, h) + lds_byte(wc * 32 + n * 16 + fr, k * 32 + fq * 8))
; #define MMA(ai, bj, At_, Bt_) do { __builtin_amdgcn_s_setprio(1); \
;     for (int k = 0; k < 2; ++k) for (int m = 0; m < 4; ++m) for (int n = 0; n < 2; ++n) \
;       acc[ai][bj][m][n] = __builtin_amdgcn_mfma_f32_16x16x32_bf16(At_[m][k], Bt_[n][k], acc[ai][bj][m][n], 0, 0, 0); \
;     __builtin_amdgcn_s_setprio(0); } while (0)
; #define WAIT_L(n) asm volatile("s_waitcnt lgkmcnt(" #n ")" ::: "memory")
; #define BAR __builtin_amdgcn_s_barrier()
; #define SCHED __builtin_amdgcn_sched_barrier(0)
; template <int EPI, int lda, int ldb, int N, int K>
; __device__ __forceinline__ void gemm_phase(const u16* __restrict__ A, const u16* __restrict__ Bt, const GemmEpi ep, int wv) {
;     ...
;       LDB(B0, 0, 0); SCHED; LDA(At, 0, 0); STAGE(SA(1, 1), Ab, lda, brow + HALF, t + 1);
;       WAIT_L(8); BAR; WAIT_L(0); MMA(0, 0, At, B0); BAR; SCHED;
;       LDB(B1, 0, 1); STAGE(SB(0, 0), Bt, ldb, bcol, t + 2);
;       BAR; WAIT_L(0); MMA(0, 1, At, B1); BAR;
;       LDA(At, 0, 1); STAGE(SA(0, 0), Ab, lda, brow, t + 2);
;       BAR; WAIT_L(0); MMA(1, 0, At, B0); BAR; SCHED;
.LBB0_1448:
	ds_read_b128 v[164:167], v160
	ds_read_b128 v[170:173], v160 offset:1024
	ds_read_b128 v[174:177], v160 offset:2048
	ds_read_b128 v[178:181], v160 offset:3072
	v_add_u32_e32 v168, 0xc000, v143
	v_lshl_add_u64 v[234:235], v[138:139], 0, s[44:45]
	v_readfirstlane_b32 s47, v168
	v_add_u32_e32 v169, 0xe000, v143
	v_lshl_add_u64 v[162:163], v[234:235], 0, s[20:21]
	s_mov_b32 m0, s47
	v_lshl_add_u64 v[236:237], v[140:141], 0, s[44:45]
	ds_read_b128 v[182:185], v151
	ds_read_b128 v[186:189], v151 offset:1024
	ds_read_b128 v[190:193], v150
	ds_read_b128 v[194:197], v150 offset:1024
	ds_read_b128 v[198:201], v149
	ds_read_b128 v[202:205], v149 offset:1024
	ds_read_b128 v[206:209], v148
	ds_read_b128 v[210:213], v148 offset:1024
	global_load_lds_dwordx4 v[162:163], off
	s_bitset1_b32 m0, 13
	v_lshl_add_u64 v[162:163], v[236:237], 0, s[20:21]
	global_load_lds_dwordx4 v[162:163], off
	s_waitcnt lgkmcnt(8)
	s_barrier
	s_waitcnt lgkmcnt(0)
	s_waitcnt lgkmcnt(0)
	v_mfma_f32_16x16x32_bf16 v[124:127], v[164:167], v[182:185], v[124:127]
	v_mfma_f32_16x16x32_bf16 v[120:123], v[174:177], v[182:185], v[120:123]
	v_mfma_f32_16x16x32_bf16 v[116:119], v[164:167], v[190:193], v[116:119]
	v_mfma_f32_16x16x32_bf16 v[112:115], v[174:177], v[190:193], v[112:115]
	v_mfma_f32_16x16x32_bf16 v[108:111], v[164:167], v[198:201], v[108:111]
	v_mfma_f32_16x16x32_bf16 v[104:107], v[174:177], v[198:201], v[104:107]
	v_mfma_f32_16x16x32_bf16 v[100:103], v[164:167], v[206:209], v[100:103]
	v_mfma_f32_16x16x32_bf16 v[96:99], v[174:177], v[206:209], v[96:99]
	v_mfma_f32_16x16x32_bf16 v[124:127], v[170:173], v[186:189], v[124:127]
	v_mfma_f32_16x16x32_bf16 v[120:123], v[178:181], v[186:189], v[120:123]
	v_mfma_f32_16x16x32_bf16 v[116:119], v[170:173], v[194:197], v[116:119]
	v_mfma_f32_16x16x32_bf16 v[112:115], v[178:181], v[194:197], v[112:115]
	v_mfma_f32_16x16x32_bf16 v[108:111], v[170:173], v[202:205], v[108:111]
	v_mfma_f32_16x16x32_bf16 v[104:107], v[178:181], v[202:205], v[104:107]
	v_mfma_f32_16x16x32_bf16 v[100:103], v[170:173], v[210:213], v[100:103]
	v_mfma_f32_16x16x32_bf16 v[96:99], v[178:181], v[210:213], v[96:99]
	s_barrier
	v_add_u32_e32 v161, s55, v153
	v_lshl_add_u64 v[238:239], v[134:135], 0, s[44:45]
	v_readfirstlane_b32 s47, v161
	v_lshl_add_u64 v[162:163], v[238:239], 0, s[22:23]
	s_mov_b32 m0, s47
	ds_read_b128 v[214:217], v159
	ds_read_b128 v[218:221], v159 offset:1024
	ds_read_b128 v[222:225], v159 offset:2048
	ds_read_b128 v[226:229], v159 offset:3072
	global_load_lds_dwordx4 v[162:163], off
	s_bitset1_b32 m0, 13
	v_add_u32_e32 v162, 0x2000, v161
	v_lshl_add_u64 v[240:241], v[136:137], 0, s[44:45]
	v_lshl_add_u64 v[230:231], v[240:241], 0, s[22:23]
	global_load_lds_dwordx4 v[230:231], off
	s_barrier
	s_waitcnt lgkmcnt(0)
	s_waitcnt lgkmcnt(0)
	v_mfma_f32_16x16x32_bf16 v[92:95], v[214:217], v[182:185], v[92:95]
	v_mfma_f32_16x16x32_bf16 v[88:91], v[222:225], v[182:185], v[88:91]
	v_mfma_f32_16x16x32_bf16 v[84:87], v[214:217], v[190:193], v[84:87]
	v_mfma_f32_16x16x32_bf16 v[80:83], v[222:225], v[190:193], v[80:83]
	v_mfma_f32_16x16x32_bf16 v[76:79], v[214:217], v[198:201], v[76:79]
	v_mfma_f32_16x16x32_bf16 v[72:75], v[222:225], v[198:201], v[72:75]
	v_mfma_f32_16x16x32_bf16 v[68:71], v[214:217], v[206:209], v[68:71]
	v_mfma_f32_16x16x32_bf16 v[64:67], v[222:225], v[206:209], v[64:67]
	v_mfma_f32_16x16x32_bf16 v[92:95], v[218:221], v[186:189], v[92:95]
	v_mfma_f32_16x16x32_bf16 v[88:91], v[226:229], v[186:189], v[88:91]
	v_mfma_f32_16x16x32_bf16 v[84:87], v[218:221], v[194:197], v[84:87]
	v_mfma_f32_16x16x32_bf16 v[80:83], v[226:229], v[194:197], v[80:83]
	v_mfma_f32_16x16x32_bf16 v[76:79], v[218:221], v[202:205], v[76:79]
	v_mfma_f32_16x16x32_bf16 v[72:75], v[226:229], v[202:205], v[72:75]
	v_mfma_f32_16x16x32_bf16 v[68:71], v[218:221], v[210:213], v[68:71]
	v_mfma_f32_16x16x32_bf16 v[64:67], v[226:229], v[210:213], v[64:67]
	v_readfirstlane_b32 s47, v143
	v_add_u32_e32 v163, 0x2000, v143
	v_lshl_add_u64 v[230:231], v[234:235], 0, s[24:25]
	s_mov_b32 m0, s47
	s_barrier
	ds_read_b128 v[182:185], v151 offset:16384
	ds_read_b128 v[186:189], v151 offset:17408
	ds_read_b128 v[190:193], v150 offset:16384
	ds_read_b128 v[194:197], v150 offset:17408
	ds_read_b128 v[198:201], v149 offset:16384
	ds_read_b128 v[202:205], v149 offset:17408
	ds_read_b128 v[206:209], v148 offset:16384
	ds_read_b128 v[210:213], v148 offset:17408
	global_load_lds_dwordx4 v[230:231], off
	s_bitset1_b32 m0, 13
	v_lshl_add_u64 v[230:231], v[236:237], 0, s[24:25]
	global_load_lds_dwordx4 v[230:231], off
	s_barrier
	s_waitcnt lgkmcnt(0)
	s_waitcnt lgkmcnt(0)
	v_mfma_f32_16x16x32_bf16 v[60:63], v[164:167], v[182:185], v[60:63]
	v_mfma_f32_16x16x32_bf16 v[56:59], v[174:177], v[182:185], v[56:59]
	v_mfma_f32_16x16x32_bf16 v[52:55], v[164:167], v[190:193], v[52:55]
	v_mfma_f32_16x16x32_bf16 v[48:51], v[174:177], v[190:193], v[48:51]
	v_mfma_f32_16x16x32_bf16 v[44:47], v[164:167], v[198:201], v[44:47]
	v_mfma_f32_16x16x32_bf16 v[40:43], v[174:177], v[198:201], v[40:43]
	v_mfma_f32_16x16x32_bf16 v[36:39], v[164:167], v[206:209], v[36:39]
	v_mfma_f32_16x16x32_bf16 v[32:35], v[174:177], v[206:209], v[32:35]
	v_mfma_f32_16x16x32_bf16 v[60:63], v[170:173], v[186:189], v[60:63]
	v_mfma_f32_16x16x32_bf16 v[56:59], v[178:181], v[186:189], v[56:59]
	v_mfma_f32_16x16x32_bf16 v[52:55], v[170:173], v[194:197], v[52:55]
	v_mfma_f32_16x16x32_bf16 v[48:51], v[178:181], v[194:197], v[48:51]
	v_mfma_f32_16x16x32_bf16 v[44:47], v[170:173], v[202:205], v[44:47]
	v_mfma_f32_16x16x32_bf16 v[40:43], v[178:181], v[202:205], v[40:43]
	v_mfma_f32_16x16x32_bf16 v[36:39], v[170:173], v[210:213], v[36:39]
	v_mfma_f32_16x16x32_bf16 v[32:35], v[178:181], v[210:213], v[32:35]
	s_barrier
; #define STAGE(P, BASE, LD, br, kt) do { const char* _g = (const char*)((BASE) + (size_t)(br) * (LD) + (size_t)(kt) * 64); \
;     for (int _i = 0; _i < 2; ++_i) { int _b = tidx * 16 + _i * 8192; int _r, _c; stage_rc(_b, _r, _c); \
;       __builtin_amdgcn_global_load_lds((const unsigned*)(_g + (unsigned)((_r * (LD) + _c) * 2)), (unsigned*)((char*)(P) + _b), 16, 0, 0); } } while (0)
; #define LDA(dst, b, h) for (int m = 0; m < 4; ++m) for (int k = 0; k < 2; ++k) \
;     dst[m][k] = *reinterpret_cast<const bf16x8*>((char*)SA(b, h) + lds_byte(wr * 64 + m * 16 + fr, k * 32 + fq * 8))
; #define LDB(dst, b, h) for (int n = 0; n < 2; ++n) for (int k = 0; k < 2; ++k) \
;     dst[n][k] = *reinterpret_cast<const bf16x8*>((char*)SB(b, h) + lds_byte(wc * 32 + n * 16 + fr, k * 32 + fq * 8))
; #define MMA(ai, bj, At_, Bt_) do { __builtin_amdgcn_s_setprio(1); \
;     for (int k = 0; k < 2; ++k) for (int m = 0; m < 4; ++m) for (int n = 0; n < 2; ++n) \
;       acc[ai][bj][m][n] = __builtin_amdgcn_mfma_f32_16x16x32_bf16(At_[m][k], Bt_[n][k], acc[ai][bj][m][n], 0, 0, 0); \
;     __builtin_amdgcn_s_setprio(0); } while (0)
; #define WAIT_V(n) asm volatile("s_waitcnt vmcnt(" #n ")" ::: "memory")
; #define WAIT_L(n) asm volatile("s_waitcnt lgkmcnt(" #n ")" ::: "memory")
; #define BAR __builtin_amdgcn_s_barrier()
; #define SCHED __builtin_amdgcn_sched_barrier(0)
; template <int EPI, int lda, int ldb, int N, int K>
; __device__ __forceinline__ void gemm_phase(const u16* __restrict__ A, const u16* __restrict__ Bt, const GemmEpi ep, int wv) {
;     ...
;       WAIT_V(6); BAR; MMA(1, 1, At, B1); BAR;
;       LDB(B0, 1, 0); SCHED; LDA(At, 1, 0); STAGE(SA(0, 1), Ab, lda, brow + HALF, t + 2);
;       WAIT_L(8); BAR; WAIT_L(0); MMA(0, 0, At, B0); BAR; SCHED;
;       LDB(B1, 1, 1); STAGE(SB(1, 0), Bt, ldb, bcol, t + 3);
;       BAR; WAIT_L(0); MMA(0, 1, At, B1); BAR;
;       LDA(At, 1, 1); STAGE(SA(1, 0), Ab, lda, brow, t + 3);
;       BAR; WAIT_L(0); MMA(1, 0, At, B0); BAR; SCHED;
;       STAGE(SB(1, 1), Bt, ldb, bcol + HALF, t + 3);
;       WAIT_V(6); BAR; MMA(1, 1, At, B1); BAR;
	v_add_u32_e32 v164, s56, v153
	v_add_u32_e32 v165, 0x2000, v164
	v_readfirstlane_b32 s47, v164
	v_lshl_add_u64 v[166:167], v[238:239], 0, s[26:27]
	s_mov_b32 m0, s47
	global_load_lds_dwordx4 v[166:167], off
	s_bitset1_b32 m0, 13
	v_lshl_add_u64 v[166:167], v[240:241], 0, s[26:27]
	global_load_lds_dwordx4 v[166:167], off
	s_waitcnt vmcnt(6)
	s_barrier
	v_mfma_f32_16x16x32_bf16 v[28:31], v[214:217], v[182:185], v[28:31]
	v_mfma_f32_16x16x32_bf16 v[24:27], v[222:225], v[182:185], v[24:27]
	v_mfma_f32_16x16x32_bf16 v[20:23], v[214:217], v[190:193], v[20:23]
	v_mfma_f32_16x16x32_bf16 v[16:19], v[222:225], v[190:193], v[16:19]
	v_mfma_f32_16x16x32_bf16 v[12:15], v[214:217], v[198:201], v[12:15]
	v_mfma_f32_16x16x32_bf16 v[8:11], v[222:225], v[198:201], v[8:11]
	v_mfma_f32_16x16x32_bf16 v[4:7], v[214:217], v[206:209], v[4:7]
	v_mfma_f32_16x16x32_bf16 v[0:3], v[222:225], v[206:209], v[0:3]
	v_mfma_f32_16x16x32_bf16 v[28:31], v[218:221], v[186:189], v[28:31]
	v_mfma_f32_16x16x32_bf16 v[24:27], v[226:229], v[186:189], v[24:27]
	v_mfma_f32_16x16x32_bf16 v[20:23], v[218:221], v[194:197], v[20:23]
	v_mfma_f32_16x16x32_bf16 v[16:19], v[226:229], v[194:197], v[16:19]
	v_mfma_f32_16x16x32_bf16 v[12:15], v[218:221], v[202:205], v[12:15]
	v_mfma_f32_16x16x32_bf16 v[8:11], v[226:229], v[202:205], v[8:11]
	v_mfma_f32_16x16x32_bf16 v[4:7], v[218:221], v[210:213], v[4:7]
	v_mfma_f32_16x16x32_bf16 v[0:3], v[226:229], v[210:213], v[0:3]
	s_barrier
	ds_read_b128 v[170:173], v154
	ds_read_b128 v[174:177], v154 offset:1024
	ds_read_b128 v[178:181], v154 offset:2048
	ds_read_b128 v[182:185], v154 offset:3072
	v_add_u32_e32 v166, 0x4000, v143
	v_add_u32_e32 v167, 0x6000, v143
	v_readfirstlane_b32 s47, v166
	v_lshl_add_u64 v[218:219], v[234:235], 0, s[34:35]
	s_mov_b32 m0, s47
	ds_read_b128 v[186:189], v151 offset:32768
	ds_read_b128 v[190:193], v151 offset:33792
	ds_read_b128 v[194:197], v150 offset:32768
	ds_read_b128 v[198:201], v150 offset:33792
	ds_read_b128 v[202:205], v149 offset:32768
	ds_read_b128 v[206:209], v149 offset:33792
	ds_read_b128 v[210:213], v148 offset:32768
	ds_read_b128 v[214:217], v148 offset:33792
	global_load_lds_dwordx4 v[218:219], off
	s_bitset1_b32 m0, 13
	v_lshl_add_u64 v[218:219], v[236:237], 0, s[34:35]
	global_load_lds_dwordx4 v[218:219], off
	s_waitcnt lgkmcnt(8)
	s_barrier
	s_waitcnt lgkmcnt(0)
	s_waitcnt lgkmcnt(0)
	v_mfma_f32_16x16x32_bf16 v[124:127], v[170:173], v[186:189], v[124:127]
	v_mfma_f32_16x16x32_bf16 v[120:123], v[178:181], v[186:189], v[120:123]
	v_mfma_f32_16x16x32_bf16 v[116:119], v[170:173], v[194:197], v[116:119]
	v_mfma_f32_16x16x32_bf16 v[112:115], v[178:181], v[194:197], v[112:115]
	v_mfma_f32_16x16x32_bf16 v[108:111], v[170:173], v[202:205], v[108:111]
	v_mfma_f32_16x16x32_bf16 v[104:107], v[178:181], v[202:205], v[104:107]
	v_mfma_f32_16x16x32_bf16 v[100:103], v[170:173], v[210:213], v[100:103]
	v_mfma_f32_16x16x32_bf16 v[96:99], v[178:181], v[210:213], v[96:99]
	v_mfma_f32_16x16x32_bf16 v[124:127], v[174:177], v[190:193], v[124:127]
	v_mfma_f32_16x16x32_bf16 v[120:123], v[182:185], v[190:193], v[120:123]
	v_mfma_f32_16x16x32_bf16 v[116:119], v[174:177], v[198:201], v[116:119]
	v_mfma_f32_16x16x32_bf16 v[112:115], v[182:185], v[198:201], v[112:115]
	v_mfma_f32_16x16x32_bf16 v[108:111], v[174:177], v[206:209], v[108:111]
	v_mfma_f32_16x16x32_bf16 v[104:107], v[182:185], v[206:209], v[104:107]
	v_mfma_f32_16x16x32_bf16 v[100:103], v[174:177], v[214:217], v[100:103]
	v_mfma_f32_16x16x32_bf16 v[96:99], v[182:185], v[214:217], v[96:99]
	s_barrier
	v_readfirstlane_b32 s47, v155
	v_add_u32_e32 v244, 0x2000, v155
	v_lshl_add_u64 v[242:243], v[238:239], 0, s[36:37]
	s_mov_b32 m0, s47
	ds_read_b128 v[218:221], v152
	ds_read_b128 v[222:225], v152 offset:1024
	ds_read_b128 v[226:229], v152 offset:2048
	ds_read_b128 v[230:233], v152 offset:3072
	global_load_lds_dwordx4 v[242:243], off
	s_bitset1_b32 m0, 13
	v_lshl_add_u64 v[242:243], v[240:241], 0, s[36:37]
	global_load_lds_dwordx4 v[242:243], off
	s_barrier
	s_waitcnt lgkmcnt(0)
	s_waitcnt lgkmcnt(0)
	v_mfma_f32_16x16x32_bf16 v[92:95], v[218:221], v[186:189], v[92:95]
	v_mfma_f32_16x16x32_bf16 v[88:91], v[226:229], v[186:189], v[88:91]
	v_mfma_f32_16x16x32_bf16 v[84:87], v[218:221], v[194:197], v[84:87]
	v_mfma_f32_16x16x32_bf16 v[80:83], v[226:229], v[194:197], v[80:83]
	v_mfma_f32_16x16x32_bf16 v[76:79], v[218:221], v[202:205], v[76:79]
	v_mfma_f32_16x16x32_bf16 v[72:75], v[226:229], v[202:205], v[72:75]
	v_mfma_f32_16x16x32_bf16 v[68:71], v[218:221], v[210:213], v[68:71]
	v_mfma_f32_16x16x32_bf16 v[64:67], v[226:229], v[210:213], v[64:67]
	v_mfma_f32_16x16x32_bf16 v[92:95], v[222:225], v[190:193], v[92:95]
	v_mfma_f32_16x16x32_bf16 v[88:91], v[230:233], v[190:193], v[88:91]
	v_mfma_f32_16x16x32_bf16 v[84:87], v[222:225], v[198:201], v[84:87]
	v_mfma_f32_16x16x32_bf16 v[80:83], v[230:233], v[198:201], v[80:83]
	v_mfma_f32_16x16x32_bf16 v[76:79], v[222:225], v[206:209], v[76:79]
	v_mfma_f32_16x16x32_bf16 v[72:75], v[230:233], v[206:209], v[72:75]
	v_mfma_f32_16x16x32_bf16 v[68:71], v[222:225], v[214:217], v[68:71]
	v_mfma_f32_16x16x32_bf16 v[64:67], v[230:233], v[214:217], v[64:67]
	v_readfirstlane_b32 s47, v156
	v_lshl_add_u64 v[234:235], v[234:235], 0, s[38:39]
	s_mov_b32 m0, s47
	s_barrier
	ds_read_b128 v[186:189], v151 offset:49152
	ds_read_b128 v[190:193], v151 offset:50176
	ds_read_b128 v[194:197], v150 offset:49152
	ds_read_b128 v[198:201], v150 offset:50176
	ds_read_b128 v[202:205], v149 offset:49152
	ds_read_b128 v[206:209], v149 offset:50176
	ds_read_b128 v[210:213], v148 offset:49152
	ds_read_b128 v[214:217], v148 offset:50176
	global_load_lds_dwordx4 v[234:235], off
	s_bitset1_b32 m0, 13
	v_lshl_add_u64 v[234:235], v[236:237], 0, s[38:39]
	global_load_lds_dwordx4 v[234:235], off
	s_barrier
; #define STAGE(P, BASE, LD, br, kt) do { const char* _g = (const char*)((BASE) + (size_t)(br) * (LD) + (size_t)(kt) * 64); \
;     for (int _i = 0; _i < 2; ++_i) { int _b = tidx * 16 + _i * 8192; int _r, _c; stage_rc(_b, _r, _c); \
;       __builtin_amdgcn_global_load_lds((const unsigned*)(_g + (unsigned)((_r * (LD) + _c) * 2)), (unsigned*)((char*)(P) + _b), 16, 0, 0); } } while (0)
; #define LDA(dst, b, h) for (int m = 0; m < 4; ++m) for (int k = 0; k < 2; ++k) \
;     dst[m][k] = *reinterpret_cast<const bf16x8*>((char*)SA(b, h) + lds_byte(wr * 64 + m * 16 + fr, k * 32 + fq * 8))
; #define LDB(dst, b, h) for (int n = 0; n < 2; ++n) for (int k = 0; k < 2; ++k) \
;     dst[n][k] = *reinterpret_cast<const bf16x8*>((char*)SB(b, h) + lds_byte(wc * 32 + n * 16 + fr, k * 32 + fq * 8))
; #define MMA(ai, bj, At_, Bt_) do { __builtin_amdgcn_s_setprio(1); \
;     for (int k = 0; k < 2; ++k) for (int m = 0; m < 4; ++m) for (int n = 0; n < 2; ++n) \
;       acc[ai][bj][m][n] = __builtin_amdgcn_mfma_f32_16x16x32_bf16(At_[m][k], Bt_[n][k], acc[ai][bj][m][n], 0, 0, 0); \
;     __builtin_amdgcn_s_setprio(0); } while (0)
; #define WAIT_V(n) asm volatile("s_waitcnt vmcnt(" #n ")" ::: "memory")
; #define WAIT_L(n) asm volatile("s_waitcnt lgkmcnt(" #n ")" ::: "memory")
; #define BAR __builtin_amdgcn_s_barrier()
; #define SCHED __builtin_amdgcn_sched_barrier(0)
; template <int EPI, int lda, int ldb, int N, int K>
; __device__ __forceinline__ void gemm_phase(const u16* __restrict__ A, const u16* __restrict__ Bt, const GemmEpi ep, int wv) {
;     ...
;       BAR; WAIT_L(0); MMA(0, 1, At, B1); BAR;
;       LDA(At, 1, 1); STAGE(SA(1, 0), Ab, lda, brow, t + 3);
;       BAR; WAIT_L(0); MMA(1, 0, At, B0); BAR; SCHED;
;       STAGE(SB(1, 1), Bt, ldb, bcol + HALF, t + 3);
;       WAIT_V(6); BAR; MMA(1, 1, At, B1); BAR;
;     }
;     { LDB(B0, 0, 0); LDA(At, 0, 0); STAGE(SA(1, 1), Ab, lda, brow + HALF, nt - 1);
;       BAR; WAIT_L(0); MMA(0, 0, At, B0); BAR;
;       LDB(B1, 0, 1); BAR; WAIT_L(0); MMA(0, 1, At, B1); BAR;
	s_waitcnt lgkmcnt(0)
	s_waitcnt lgkmcnt(0)
	v_mfma_f32_16x16x32_bf16 v[60:63], v[170:173], v[186:189], v[60:63]
	v_mfma_f32_16x16x32_bf16 v[56:59], v[178:181], v[186:189], v[56:59]
	v_mfma_f32_16x16x32_bf16 v[52:55], v[170:173], v[194:197], v[52:55]
	v_mfma_f32_16x16x32_bf16 v[48:51], v[178:181], v[194:197], v[48:51]
	v_mfma_f32_16x16x32_bf16 v[44:47], v[170:173], v[202:205], v[44:47]
	v_mfma_f32_16x16x32_bf16 v[40:43], v[178:181], v[202:205], v[40:43]
	v_mfma_f32_16x16x32_bf16 v[36:39], v[170:173], v[210:213], v[36:39]
	v_mfma_f32_16x16x32_bf16 v[32:35], v[178:181], v[210:213], v[32:35]
	v_mfma_f32_16x16x32_bf16 v[60:63], v[174:177], v[190:193], v[60:63]
	v_mfma_f32_16x16x32_bf16 v[56:59], v[182:185], v[190:193], v[56:59]
	v_mfma_f32_16x16x32_bf16 v[52:55], v[174:177], v[198:201], v[52:55]
	v_mfma_f32_16x16x32_bf16 v[48:51], v[182:185], v[198:201], v[48:51]
	v_mfma_f32_16x16x32_bf16 v[44:47], v[174:177], v[206:209], v[44:47]
	v_mfma_f32_16x16x32_bf16 v[40:43], v[182:185], v[206:209], v[40:43]
	v_mfma_f32_16x16x32_bf16 v[36:39], v[174:177], v[214:217], v[36:39]
	v_mfma_f32_16x16x32_bf16 v[32:35], v[182:185], v[214:217], v[32:35]
	s_barrier
	v_readfirstlane_b32 s47, v158
	v_add_u32_e32 v172, 0x2000, v158
	v_lshl_add_u64 v[170:171], v[238:239], 0, s[40:41]
	s_mov_b32 m0, s47
	global_load_lds_dwordx4 v[170:171], off
	s_bitset1_b32 m0, 13
	v_lshl_add_u64 v[170:171], v[240:241], 0, s[40:41]
	global_load_lds_dwordx4 v[170:171], off
	s_waitcnt vmcnt(6)
	s_barrier
	v_mfma_f32_16x16x32_bf16 v[28:31], v[218:221], v[186:189], v[28:31]
	v_mfma_f32_16x16x32_bf16 v[24:27], v[226:229], v[186:189], v[24:27]
	v_mfma_f32_16x16x32_bf16 v[20:23], v[218:221], v[194:197], v[20:23]
	v_mfma_f32_16x16x32_bf16 v[16:19], v[226:229], v[194:197], v[16:19]
	v_mfma_f32_16x16x32_bf16 v[12:15], v[218:221], v[202:205], v[12:15]
	v_mfma_f32_16x16x32_bf16 v[8:11], v[226:229], v[202:205], v[8:11]
	v_mfma_f32_16x16x32_bf16 v[4:7], v[218:221], v[210:213], v[4:7]
	v_mfma_f32_16x16x32_bf16 v[0:3], v[226:229], v[210:213], v[0:3]
	v_mfma_f32_16x16x32_bf16 v[28:31], v[222:225], v[190:193], v[28:31]
	v_mfma_f32_16x16x32_bf16 v[24:27], v[230:233], v[190:193], v[24:27]
	v_mfma_f32_16x16x32_bf16 v[20:23], v[222:225], v[198:201], v[20:23]
	v_mfma_f32_16x16x32_bf16 v[16:19], v[230:233], v[198:201], v[16:19]
	v_mfma_f32_16x16x32_bf16 v[12:15], v[222:225], v[206:209], v[12:15]
	v_mfma_f32_16x16x32_bf16 v[8:11], v[230:233], v[206:209], v[8:11]
	v_mfma_f32_16x16x32_bf16 v[4:7], v[222:225], v[214:217], v[4:7]
	v_mfma_f32_16x16x32_bf16 v[0:3], v[230:233], v[214:217], v[0:3]
	s_add_i32 s46, s46, 2
	s_add_u32 s44, s44, 0x100
	s_addc_u32 s45, s45, 0
	s_cmp_gt_u32 s46, 27
	s_barrier
	s_cbranch_scc0 .LBB0_1448
	s_lshl_b64 s[44:45], s[16:17], 12
	s_add_u32 s44, s14, s44
	s_addc_u32 s45, s15, s45
	s_add_u32 s44, s44, 0x80000
	s_addc_u32 s45, s45, 0
	v_lshl_add_u64 v[156:157], s[44:45], 0, v[128:129]
	v_readfirstlane_b32 s46, v168
	v_lshl_add_u64 v[156:157], v[156:157], 0, s[42:43]
	s_mov_b32 m0, s46
	ds_read_b128 v[134:137], v160
	ds_read_b128 v[138:141], v160 offset:1024
	ds_read_b128 v[170:173], v160 offset:2048
	ds_read_b128 v[174:177], v160 offset:3072
	ds_read_b128 v[178:181], v151
	ds_read_b128 v[182:185], v151 offset:1024
	ds_read_b128 v[186:189], v150
	ds_read_b128 v[190:193], v150 offset:1024
	ds_read_b128 v[194:197], v149
	ds_read_b128 v[198:201], v149 offset:1024
	ds_read_b128 v[202:205], v148
	ds_read_b128 v[206:209], v148 offset:1024
	global_load_lds_dwordx4 v[156:157], off
	v_lshl_add_u64 v[156:157], s[44:45], 0, v[132:133]
	v_readfirstlane_b32 s44, v169
	v_lshl_add_u64 v[156:157], v[156:157], 0, s[42:43]
	s_mov_b32 m0, s44
	s_nop 0
	global_load_lds_dwordx4 v[156:157], off
	s_barrier
	s_waitcnt lgkmcnt(0)
	s_waitcnt lgkmcnt(0)
	v_mfma_f32_16x16x32_bf16 v[124:127], v[134:137], v[178:181], v[124:127]
	v_mfma_f32_16x16x32_bf16 v[120:123], v[170:173], v[178:181], v[120:123]
	v_mfma_f32_16x16x32_bf16 v[116:119], v[134:137], v[186:189], v[116:119]
	v_mfma_f32_16x16x32_bf16 v[112:115], v[170:173], v[186:189], v[112:115]
	v_mfma_f32_16x16x32_bf16 v[108:111], v[134:137], v[194:197], v[108:111]
	v_mfma_f32_16x16x32_bf16 v[104:107], v[170:173], v[194:197], v[104:107]
	v_mfma_f32_16x16x32_bf16 v[100:103], v[134:137], v[202:205], v[100:103]
	v_mfma_f32_16x16x32_bf16 v[96:99], v[170:173], v[202:205], v[96:99]
	v_mfma_f32_16x16x32_bf16 v[124:127], v[138:141], v[182:185], v[124:127]
	v_mfma_f32_16x16x32_bf16 v[120:123], v[174:177], v[182:185], v[120:123]
	v_mfma_f32_16x16x32_bf16 v[116:119], v[138:141], v[190:193], v[116:119]
	v_mfma_f32_16x16x32_bf16 v[112:115], v[174:177], v[190:193], v[112:115]
	v_mfma_f32_16x16x32_bf16 v[108:111], v[138:141], v[198:201], v[108:111]
	v_mfma_f32_16x16x32_bf16 v[104:107], v[174:177], v[198:201], v[104:107]
	v_mfma_f32_16x16x32_bf16 v[100:103], v[138:141], v[206:209], v[100:103]
	v_mfma_f32_16x16x32_bf16 v[96:99], v[174:177], v[206:209], v[96:99]
	s_barrier
	ds_read_b128 v[210:213], v159
	ds_read_b128 v[214:217], v159 offset:1024
	ds_read_b128 v[218:221], v159 offset:2048
	ds_read_b128 v[156:159], v159 offset:3072
	s_barrier
; #define LDA(dst, b, h) for (int m = 0; m < 4; ++m) for (int k = 0; k < 2; ++k) \
;     dst[m][k] = *reinterpret_cast<const bf16x8*>((char*)SA(b, h) + lds_byte(wr * 64 + m * 16 + fr, k * 32 + fq * 8))
; #define LDB(dst, b, h) for (int n = 0; n < 2; ++n) for (int k = 0; k < 2; ++k) \
;     dst[n][k] = *reinterpret_cast<const bf16x8*>((char*)SB(b, h) + lds_byte(wc * 32 + n * 16 + fr, k * 32 + fq * 8))
; #define MMA(ai, bj, At_, Bt_) do { __builtin_amdgcn_s_setprio(1); \
;     for (int k = 0; k < 2; ++k) for (int m = 0; m < 4; ++m) for (int n = 0; n < 2; ++n) \
;       acc[ai][bj][m][n] = __builtin_amdgcn_mfma_f32_16x16x32_bf16(At_[m][k], Bt_[n][k], acc[ai][bj][m][n], 0, 0, 0); \
;     __builtin_amdgcn_s_setprio(0); } while (0)
; #define WAIT_V(n) asm volatile("s_waitcnt vmcnt(" #n ")" ::: "memory")
; #define WAIT_L(n) asm volatile("s_waitcnt lgkmcnt(" #n ")" ::: "memory")
; #define BAR __builtin_amdgcn_s_barrier()
; template <int EPI, int lda, int ldb, int N, int K>
; __device__ __forceinline__ void gemm_phase(const u16* __restrict__ A, const u16* __restrict__ Bt, const GemmEpi ep, int wv) {
;     ...
;       LDB(B1, 0, 1); BAR; WAIT_L(0); MMA(0, 1, At, B1); BAR;
;       LDA(At, 0, 1); WAIT_V(4); BAR; WAIT_L(0); MMA(1, 0, At, B0); MMA(1, 1, At, B1); BAR; }
;     { LDB(B0, 1, 0); LDA(At, 1, 0); WAIT_V(2); BAR; WAIT_L(0); MMA(0, 0, At, B0); BAR;
	s_waitcnt lgkmcnt(0)
	s_waitcnt lgkmcnt(0)
	v_mfma_f32_16x16x32_bf16 v[92:95], v[210:213], v[178:181], v[92:95]
	v_mfma_f32_16x16x32_bf16 v[88:91], v[218:221], v[178:181], v[88:91]
	v_mfma_f32_16x16x32_bf16 v[76:79], v[210:213], v[194:197], v[76:79]
	v_mfma_f32_16x16x32_bf16 v[72:75], v[218:221], v[194:197], v[72:75]
	v_mfma_f32_16x16x32_bf16 v[84:87], v[210:213], v[186:189], v[84:87]
	v_mfma_f32_16x16x32_bf16 v[80:83], v[218:221], v[186:189], v[80:83]
	v_mfma_f32_16x16x32_bf16 v[68:71], v[210:213], v[202:205], v[68:71]
	v_mfma_f32_16x16x32_bf16 v[64:67], v[218:221], v[202:205], v[64:67]
	v_mfma_f32_16x16x32_bf16 v[92:95], v[214:217], v[182:185], v[92:95]
	v_mfma_f32_16x16x32_bf16 v[88:91], v[156:159], v[182:185], v[88:91]
	v_mfma_f32_16x16x32_bf16 v[76:79], v[214:217], v[198:201], v[76:79]
	v_mfma_f32_16x16x32_bf16 v[72:75], v[156:159], v[198:201], v[72:75]
	v_mfma_f32_16x16x32_bf16 v[178:181], v[214:217], v[190:193], v[84:87]
	v_mfma_f32_16x16x32_bf16 v[182:185], v[156:159], v[190:193], v[80:83]
	v_mfma_f32_16x16x32_bf16 v[186:189], v[214:217], v[206:209], v[68:71]
	v_mfma_f32_16x16x32_bf16 v[190:193], v[156:159], v[206:209], v[64:67]
	s_barrier
	s_nop 0
	ds_read_b128 v[64:67], v151 offset:16384
	ds_read_b128 v[68:71], v151 offset:17408
	ds_read_b128 v[80:83], v150 offset:16384
	ds_read_b128 v[84:87], v150 offset:17408
	ds_read_b128 v[194:197], v149 offset:16384
	ds_read_b128 v[198:201], v149 offset:17408
	ds_read_b128 v[202:205], v148 offset:16384
	ds_read_b128 v[206:209], v148 offset:17408
	s_waitcnt vmcnt(4)
	s_barrier
	s_waitcnt lgkmcnt(0)
	s_waitcnt lgkmcnt(0)
	v_mfma_f32_16x16x32_bf16 v[60:63], v[134:137], v[64:67], v[60:63]
	v_mfma_f32_16x16x32_bf16 v[56:59], v[170:173], v[64:67], v[56:59]
	v_mfma_f32_16x16x32_bf16 v[52:55], v[134:137], v[80:83], v[52:55]
	v_mfma_f32_16x16x32_bf16 v[48:51], v[170:173], v[80:83], v[48:51]
	v_mfma_f32_16x16x32_bf16 v[44:47], v[134:137], v[194:197], v[44:47]
	v_mfma_f32_16x16x32_bf16 v[40:43], v[170:173], v[194:197], v[40:43]
	v_mfma_f32_16x16x32_bf16 v[36:39], v[134:137], v[202:205], v[36:39]
	v_mfma_f32_16x16x32_bf16 v[32:35], v[170:173], v[202:205], v[32:35]
	v_mfma_f32_16x16x32_bf16 v[60:63], v[138:141], v[68:71], v[60:63]
	v_mfma_f32_16x16x32_bf16 v[56:59], v[174:177], v[68:71], v[56:59]
	v_mfma_f32_16x16x32_bf16 v[52:55], v[138:141], v[84:87], v[52:55]
	v_mfma_f32_16x16x32_bf16 v[48:51], v[174:177], v[84:87], v[48:51]
	v_mfma_f32_16x16x32_bf16 v[44:47], v[138:141], v[198:201], v[44:47]
	v_mfma_f32_16x16x32_bf16 v[40:43], v[174:177], v[198:201], v[40:43]
	v_mfma_f32_16x16x32_bf16 v[36:39], v[138:141], v[206:209], v[36:39]
	v_mfma_f32_16x16x32_bf16 v[32:35], v[174:177], v[206:209], v[32:35]
	v_mfma_f32_16x16x32_bf16 v[28:31], v[210:213], v[64:67], v[28:31]
	v_mfma_f32_16x16x32_bf16 v[20:23], v[210:213], v[80:83], v[20:23]
	v_mfma_f32_16x16x32_bf16 v[12:15], v[210:213], v[194:197], v[12:15]
	v_mfma_f32_16x16x32_bf16 v[4:7], v[210:213], v[202:205], v[4:7]
	v_mfma_f32_16x16x32_bf16 v[24:27], v[218:221], v[64:67], v[24:27]
	v_mfma_f32_16x16x32_bf16 v[16:19], v[218:221], v[80:83], v[16:19]
	v_mfma_f32_16x16x32_bf16 v[8:11], v[218:221], v[194:197], v[8:11]
	v_mfma_f32_16x16x32_bf16 v[0:3], v[218:221], v[202:205], v[0:3]
	v_mfma_f32_16x16x32_bf16 v[28:31], v[214:217], v[68:71], v[28:31]
	v_mfma_f32_16x16x32_bf16 v[20:23], v[214:217], v[84:87], v[20:23]
	v_mfma_f32_16x16x32_bf16 v[12:15], v[214:217], v[198:201], v[12:15]
	v_mfma_f32_16x16x32_bf16 v[4:7], v[214:217], v[206:209], v[4:7]
	v_mfma_f32_16x16x32_bf16 v[134:137], v[156:159], v[68:71], v[24:27]
	v_mfma_f32_16x16x32_bf16 v[138:141], v[156:159], v[84:87], v[16:19]
	v_mfma_f32_16x16x32_bf16 v[168:171], v[156:159], v[198:201], v[8:11]
	v_mfma_f32_16x16x32_bf16 v[156:159], v[156:159], v[206:209], v[0:3]
	s_barrier
	s_nop 0
	ds_read_b128 v[0:3], v154
	ds_read_b128 v[8:11], v154 offset:1024
	ds_read_b128 v[16:19], v154 offset:2048
	ds_read_b128 v[172:175], v154 offset:3072
	ds_read_b128 v[24:27], v151 offset:32768
	ds_read_b128 v[194:197], v151 offset:33792
	ds_read_b128 v[198:201], v150 offset:32768
	ds_read_b128 v[202:205], v150 offset:33792
	ds_read_b128 v[206:209], v149 offset:32768
	ds_read_b128 v[210:213], v149 offset:33792
	ds_read_b128 v[214:217], v148 offset:32768
	ds_read_b128 v[218:221], v148 offset:33792
	s_waitcnt vmcnt(2)
	s_barrier
; #define LDA(dst, b, h) for (int m = 0; m < 4; ++m) for (int k = 0; k < 2; ++k) \
;     dst[m][k] = *reinterpret_cast<const bf16x8*>((char*)SA(b, h) + lds_byte(wr * 64 + m * 16 + fr, k * 32 + fq * 8))
; #define LDB(dst, b, h) for (int n = 0; n < 2; ++n) for (int k = 0; k < 2; ++k) \
;     dst[n][k] = *reinterpret_cast<const bf16x8*>((char*)SB(b, h) + lds_byte(wc * 32 + n * 16 + fr, k * 32 + fq * 8))
; #define MMA(ai, bj, At_, Bt_) do { __builtin_amdgcn_s_setprio(1); \
;     for (int k = 0; k < 2; ++k) for (int m = 0; m < 4; ++m) for (int n = 0; n < 2; ++n) \
;       acc[ai][bj][m][n] = __builtin_amdgcn_mfma_f32_16x16x32_bf16(At_[m][k], Bt_[n][k], acc[ai][bj][m][n], 0, 0, 0); \
;     __builtin_amdgcn_s_setprio(0); } while (0)
; #define WAIT_V(n) asm volatile("s_waitcnt vmcnt(" #n ")" ::: "memory")
; #define WAIT_L(n) asm volatile("s_waitcnt lgkmcnt(" #n ")" ::: "memory")
; #define BAR __builtin_amdgcn_s_barrier()
; template <int EPI, int lda, int ldb, int N, int K>
; __device__ __forceinline__ void gemm_phase(const u16* __restrict__ A, const u16* __restrict__ Bt, const GemmEpi ep, int wv) {
;     ...
;     { LDB(B0, 1, 0); LDA(At, 1, 0); WAIT_V(2); BAR; WAIT_L(0); MMA(0, 0, At, B0); BAR;
;       LDB(B1, 1, 1); WAIT_V(0); BAR; WAIT_L(0); MMA(0, 1, At, B1); BAR;
;       LDA(At, 1, 1); BAR; WAIT_L(0); MMA(1, 0, At, B0); MMA(1, 1, At, B1); BAR; }
;     if (wr == 0) BAR;
	s_waitcnt lgkmcnt(0)
	s_waitcnt lgkmcnt(0)
	v_mfma_f32_16x16x32_bf16 v[64:67], v[0:3], v[24:27], v[124:127]
	v_mfma_f32_16x16x32_bf16 v[68:71], v[16:19], v[24:27], v[120:123]
	v_mfma_f32_16x16x32_bf16 v[80:83], v[0:3], v[198:201], v[116:119]
	v_mfma_f32_16x16x32_bf16 v[84:87], v[16:19], v[198:201], v[112:115]
	v_mfma_f32_16x16x32_bf16 v[108:111], v[0:3], v[206:209], v[108:111]
	v_mfma_f32_16x16x32_bf16 v[104:107], v[16:19], v[206:209], v[104:107]
	v_mfma_f32_16x16x32_bf16 v[120:123], v[0:3], v[214:217], v[100:103]
	v_mfma_f32_16x16x32_bf16 v[124:127], v[16:19], v[214:217], v[96:99]
	v_mfma_f32_16x16x32_bf16 v[116:119], v[8:11], v[194:197], v[64:67]
	v_mfma_f32_16x16x32_bf16 v[112:115], v[172:175], v[194:197], v[68:71]
	v_mfma_f32_16x16x32_bf16 v[100:103], v[8:11], v[202:205], v[80:83]
	v_mfma_f32_16x16x32_bf16 v[96:99], v[172:175], v[202:205], v[84:87]
	v_mfma_f32_16x16x32_bf16 v[84:87], v[8:11], v[210:213], v[108:111]
	v_mfma_f32_16x16x32_bf16 v[80:83], v[172:175], v[210:213], v[104:107]
	v_mfma_f32_16x16x32_bf16 v[68:71], v[8:11], v[218:221], v[120:123]
	v_mfma_f32_16x16x32_bf16 v[64:67], v[172:175], v[218:221], v[124:127]
	s_barrier
	ds_read_b128 v[222:225], v152
	ds_read_b128 v[226:229], v152 offset:1024
	ds_read_b128 v[230:233], v152 offset:2048
	ds_read_b128 v[152:155], v152 offset:3072
	s_waitcnt vmcnt(0)
	s_barrier
	s_waitcnt lgkmcnt(0)
	s_waitcnt lgkmcnt(0)
	v_mfma_f32_16x16x32_bf16 v[92:95], v[222:225], v[24:27], v[92:95]
	v_mfma_f32_16x16x32_bf16 v[24:27], v[230:233], v[24:27], v[88:91]
	v_mfma_f32_16x16x32_bf16 v[88:91], v[222:225], v[198:201], v[178:181]
	v_mfma_f32_16x16x32_bf16 v[104:107], v[230:233], v[198:201], v[182:185]
	v_mfma_f32_16x16x32_bf16 v[76:79], v[222:225], v[206:209], v[76:79]
	v_mfma_f32_16x16x32_bf16 v[72:75], v[230:233], v[206:209], v[72:75]
	v_mfma_f32_16x16x32_bf16 v[176:179], v[222:225], v[214:217], v[186:189]
	v_mfma_f32_16x16x32_bf16 v[180:183], v[230:233], v[214:217], v[190:193]
	v_mfma_f32_16x16x32_bf16 v[124:127], v[226:229], v[194:197], v[92:95]
	v_mfma_f32_16x16x32_bf16 v[120:123], v[152:155], v[194:197], v[24:27]
	v_mfma_f32_16x16x32_bf16 v[108:111], v[226:229], v[202:205], v[88:91]
	v_mfma_f32_16x16x32_bf16 v[104:107], v[152:155], v[202:205], v[104:107]
	v_mfma_f32_16x16x32_bf16 v[92:95], v[226:229], v[210:213], v[76:79]
	v_mfma_f32_16x16x32_bf16 v[88:91], v[152:155], v[210:213], v[72:75]
	v_mfma_f32_16x16x32_bf16 v[76:79], v[226:229], v[218:221], v[176:179]
	v_mfma_f32_16x16x32_bf16 v[72:75], v[152:155], v[218:221], v[180:183]
	s_barrier
	ds_read_b128 v[176:179], v151 offset:49152
	ds_read_b128 v[180:183], v151 offset:50176
	ds_read_b128 v[184:187], v150 offset:49152
	ds_read_b128 v[188:191], v150 offset:50176
	ds_read_b128 v[192:195], v149 offset:49152
	ds_read_b128 v[196:199], v149 offset:50176
	ds_read_b128 v[200:203], v148 offset:49152
	ds_read_b128 v[148:151], v148 offset:50176
	s_barrier
	s_waitcnt lgkmcnt(0)
	s_waitcnt lgkmcnt(0)
	v_mfma_f32_16x16x32_bf16 v[24:27], v[0:3], v[176:179], v[60:63]
	v_mfma_f32_16x16x32_bf16 v[60:63], v[16:19], v[176:179], v[56:59]
	v_mfma_f32_16x16x32_bf16 v[52:55], v[0:3], v[184:187], v[52:55]
	v_mfma_f32_16x16x32_bf16 v[204:207], v[16:19], v[184:187], v[48:51]
	v_mfma_f32_16x16x32_bf16 v[44:47], v[0:3], v[192:195], v[44:47]
	v_mfma_f32_16x16x32_bf16 v[208:211], v[16:19], v[192:195], v[40:43]
	v_mfma_f32_16x16x32_bf16 v[0:3], v[0:3], v[200:203], v[36:39]
	v_mfma_f32_16x16x32_bf16 v[36:39], v[16:19], v[200:203], v[32:35]
	v_mfma_f32_16x16x32_bf16 v[56:59], v[8:11], v[180:183], v[24:27]
	v_mfma_f32_16x16x32_bf16 v[48:51], v[172:175], v[180:183], v[60:63]
	v_mfma_f32_16x16x32_bf16 v[40:43], v[8:11], v[188:191], v[52:55]
	v_mfma_f32_16x16x32_bf16 v[32:35], v[172:175], v[188:191], v[204:207]
	v_mfma_f32_16x16x32_bf16 v[24:27], v[8:11], v[196:199], v[44:47]
	v_mfma_f32_16x16x32_bf16 v[16:19], v[172:175], v[196:199], v[208:211]
	v_mfma_f32_16x16x32_bf16 v[8:11], v[8:11], v[148:151], v[0:3]
	v_mfma_f32_16x16x32_bf16 v[0:3], v[172:175], v[148:151], v[36:39]
	v_mfma_f32_16x16x32_bf16 v[28:31], v[222:225], v[176:179], v[28:31]
	v_mfma_f32_16x16x32_bf16 v[36:39], v[230:233], v[176:179], v[134:137]
	v_mfma_f32_16x16x32_bf16 v[20:23], v[222:225], v[184:187], v[20:23]
	v_mfma_f32_16x16x32_bf16 v[134:137], v[230:233], v[184:187], v[138:141]
	v_mfma_f32_16x16x32_bf16 v[12:15], v[222:225], v[192:195], v[12:15]
	v_mfma_f32_16x16x32_bf16 v[138:141], v[230:233], v[192:195], v[168:171]
	v_mfma_f32_16x16x32_bf16 v[4:7], v[222:225], v[200:203], v[4:7]
	v_mfma_f32_16x16x32_bf16 v[156:159], v[230:233], v[200:203], v[156:159]
	v_mfma_f32_16x16x32_bf16 v[60:63], v[226:229], v[180:183], v[28:31]
	v_mfma_f32_16x16x32_bf16 v[52:55], v[152:155], v[180:183], v[36:39]
	v_mfma_f32_16x16x32_bf16 v[44:47], v[226:229], v[188:191], v[20:23]
	v_mfma_f32_16x16x32_bf16 v[36:39], v[152:155], v[188:191], v[134:137]
	v_mfma_f32_16x16x32_bf16 v[28:31], v[226:229], v[196:199], v[12:15]
	v_mfma_f32_16x16x32_bf16 v[20:23], v[152:155], v[196:199], v[138:141]
	v_mfma_f32_16x16x32_bf16 v[12:15], v[226:229], v[148:151], v[4:7]
	v_mfma_f32_16x16x32_bf16 v[4:7], v[152:155], v[148:151], v[156:159]
	v_cmp_gt_u32_e32 vcc, s60, v130
	s_barrier
	s_and_saveexec_b64 s[44:45], vcc
	s_cbranch_execz .LBB0_1451
	s_barrier

; #define STAGE(P, BASE, LD, br, kt) do { const char* _g = (const char*)((BASE) + (size_t)(br) * (LD) + (size_t)(kt) * 64); \
;     for (int _i = 0; _i < 2; ++_i) { int _b = tidx * 16 + _i * 8192; int _r, _c; stage_rc(_b, _r, _c); \
;       __builtin_amdgcn_global_load_lds((const unsigned*)(_g + (unsigned)((_r * (LD) + _c) * 2)), (unsigned*)((char*)(P) + _b), 16, 0, 0); } } while (0)
; #define LDA(dst, b, h) for (int m = 0; m < 4; ++m) for (int k = 0; k < 2; ++k) \
;     dst[m][k] = *reinterpret_cast<const bf16x8*>((char*)SA(b, h) + lds_byte(wr * 64 + m * 16 + fr, k * 32 + fq * 8))
; #define LDB(dst, b, h) for (int n = 0; n < 2; ++n) for (int k = 0; k < 2; ++k) \
;     dst[n][k] = *reinterpret_cast<const bf16x8*>((char*)SB(b, h) + lds_byte(wc * 32 + n * 16 + fr, k * 32 + fq * 8))
; #define MMA(ai, bj, At_, Bt_) do { __builtin_amdgcn_s_setprio(1); \
;     for (int k = 0; k < 2; ++k) for (int m = 0; m < 4; ++m) for (int n = 0; n < 2; ++n) \
;       acc[ai][bj][m][n] = __builtin_amdgcn_mfma_f32_16x16x32_bf16(At_[m][k], Bt_[n][k], acc[ai][bj][m][n], 0, 0, 0); \
;     __builtin_amdgcn_s_setprio(0); } while (0)
; #define WAIT_L(n) asm volatile("s_waitcnt lgkmcnt(" #n ")" ::: "memory")
; #define BAR __builtin_amdgcn_s_barrier()
; #define SCHED __builtin_amdgcn_sched_barrier(0)
; template <int EPI, int lda, int ldb, int N, int K>
; __device__ __forceinline__ void gemm_phase(const u16* __restrict__ A, const u16* __restrict__ Bt, const GemmEpi ep, int wv) {
;     ...
;     for (int t = 0; t < nt - 2; t += 2) {
;       LDB(B0, 0, 0); SCHED; LDA(At, 0, 0); STAGE(SA(1, 1), Ab, lda, brow + HALF, t + 1);
;       WAIT_L(8); BAR; WAIT_L(0); MMA(0, 0, At, B0); BAR; SCHED;
;       LDB(B1, 0, 1); STAGE(SB(0, 0), Bt, ldb, bcol, t + 2);
;       BAR; WAIT_L(0); MMA(0, 1, At, B1); BAR;
;       LDA(At, 0, 1); STAGE(SA(0, 0), Ab, lda, brow, t + 2);
;       BAR; WAIT_L(0); MMA(1, 0, At, B0); BAR; SCHED;
.LBB0_1564:
	ds_read_b128 v[172:175], v161
	ds_read_b128 v[176:179], v161 offset:1024
	ds_read_b128 v[180:183], v161 offset:2048
	ds_read_b128 v[184:187], v161 offset:3072
	v_add_u32_e32 v169, 0xc000, v148
	v_lshl_add_u64 v[236:237], v[136:137], 0, s[40:41]
	v_readfirstlane_b32 s43, v169
	v_add_u32_e32 v170, 0xe000, v148
	v_lshl_add_u64 v[162:163], v[236:237], 0, s[14:15]
	s_mov_b32 m0, s43
	v_lshl_add_u64 v[238:239], v[134:135], 0, s[40:41]
	ds_read_b128 v[164:167], v152
	ds_read_b128 v[188:191], v152 offset:1024
	ds_read_b128 v[192:195], v151
	ds_read_b128 v[196:199], v151 offset:1024
	ds_read_b128 v[200:203], v150
	ds_read_b128 v[204:207], v150 offset:1024
	ds_read_b128 v[208:211], v149
	ds_read_b128 v[212:215], v149 offset:1024
	global_load_lds_dwordx4 v[162:163], off
	s_bitset1_b32 m0, 13
	v_lshl_add_u64 v[162:163], v[238:239], 0, s[14:15]
	global_load_lds_dwordx4 v[162:163], off
	s_waitcnt lgkmcnt(8)
	s_barrier
	s_waitcnt lgkmcnt(0)
	s_waitcnt lgkmcnt(0)
	v_mfma_f32_16x16x32_bf16 v[124:127], v[172:175], v[164:167], v[124:127]
	v_mfma_f32_16x16x32_bf16 v[120:123], v[180:183], v[164:167], v[120:123]
	v_mfma_f32_16x16x32_bf16 v[116:119], v[172:175], v[192:195], v[116:119]
	v_mfma_f32_16x16x32_bf16 v[112:115], v[180:183], v[192:195], v[112:115]
	v_mfma_f32_16x16x32_bf16 v[108:111], v[172:175], v[200:203], v[108:111]
	v_mfma_f32_16x16x32_bf16 v[104:107], v[180:183], v[200:203], v[104:107]
	v_mfma_f32_16x16x32_bf16 v[100:103], v[172:175], v[208:211], v[100:103]
	v_mfma_f32_16x16x32_bf16 v[96:99], v[180:183], v[208:211], v[96:99]
	v_mfma_f32_16x16x32_bf16 v[124:127], v[176:179], v[188:191], v[124:127]
	v_mfma_f32_16x16x32_bf16 v[120:123], v[184:187], v[188:191], v[120:123]
	v_mfma_f32_16x16x32_bf16 v[116:119], v[176:179], v[196:199], v[116:119]
	v_mfma_f32_16x16x32_bf16 v[112:115], v[184:187], v[196:199], v[112:115]
	v_mfma_f32_16x16x32_bf16 v[108:111], v[176:179], v[204:207], v[108:111]
	v_mfma_f32_16x16x32_bf16 v[104:107], v[184:187], v[204:207], v[104:107]
	v_mfma_f32_16x16x32_bf16 v[100:103], v[176:179], v[212:215], v[100:103]
	v_mfma_f32_16x16x32_bf16 v[96:99], v[184:187], v[212:215], v[96:99]
	s_barrier
	v_add_u32_e32 v162, s52, v153
	v_lshl_add_u64 v[240:241], v[140:141], 0, s[40:41]
	v_readfirstlane_b32 s43, v162
	v_add_u32_e32 v163, 0x2000, v162
	v_lshl_add_u64 v[232:233], v[240:241], 0, s[16:17]
	s_mov_b32 m0, s43
	v_lshl_add_u64 v[242:243], v[138:139], 0, s[40:41]
	ds_read_b128 v[216:219], v160
	ds_read_b128 v[220:223], v160 offset:1024
	ds_read_b128 v[224:227], v160 offset:2048
	ds_read_b128 v[228:231], v160 offset:3072
	global_load_lds_dwordx4 v[232:233], off
	s_bitset1_b32 m0, 13
	v_lshl_add_u64 v[232:233], v[242:243], 0, s[16:17]
	global_load_lds_dwordx4 v[232:233], off
	s_barrier
	s_waitcnt lgkmcnt(0)
	s_waitcnt lgkmcnt(0)
	v_mfma_f32_16x16x32_bf16 v[92:95], v[216:219], v[164:167], v[92:95]
	v_mfma_f32_16x16x32_bf16 v[88:91], v[224:227], v[164:167], v[88:91]
	v_mfma_f32_16x16x32_bf16 v[84:87], v[216:219], v[192:195], v[84:87]
	v_mfma_f32_16x16x32_bf16 v[80:83], v[224:227], v[192:195], v[80:83]
	v_mfma_f32_16x16x32_bf16 v[76:79], v[216:219], v[200:203], v[76:79]
	v_mfma_f32_16x16x32_bf16 v[72:75], v[224:227], v[200:203], v[72:75]
	v_mfma_f32_16x16x32_bf16 v[68:71], v[216:219], v[208:211], v[68:71]
	v_mfma_f32_16x16x32_bf16 v[64:67], v[224:227], v[208:211], v[64:67]
	v_mfma_f32_16x16x32_bf16 v[92:95], v[220:223], v[188:191], v[92:95]
	v_mfma_f32_16x16x32_bf16 v[88:91], v[228:231], v[188:191], v[88:91]
	v_mfma_f32_16x16x32_bf16 v[84:87], v[220:223], v[196:199], v[84:87]
	v_mfma_f32_16x16x32_bf16 v[80:83], v[228:231], v[196:199], v[80:83]
	v_mfma_f32_16x16x32_bf16 v[76:79], v[220:223], v[204:207], v[76:79]
	v_mfma_f32_16x16x32_bf16 v[72:75], v[228:231], v[204:207], v[72:75]
	v_mfma_f32_16x16x32_bf16 v[68:71], v[220:223], v[212:215], v[68:71]
	v_mfma_f32_16x16x32_bf16 v[64:67], v[228:231], v[212:215], v[64:67]
	v_readfirstlane_b32 s43, v148
	v_lshl_add_u64 v[164:165], v[236:237], 0, s[18:19]
	s_mov_b32 m0, s43
	s_barrier
	ds_read_b128 v[188:191], v152 offset:16384
	ds_read_b128 v[192:195], v152 offset:17408
	ds_read_b128 v[196:199], v151 offset:16384
	ds_read_b128 v[200:203], v151 offset:17408
	ds_read_b128 v[204:207], v150 offset:16384
	ds_read_b128 v[208:211], v150 offset:17408
	ds_read_b128 v[212:215], v149 offset:16384
	ds_read_b128 v[232:235], v149 offset:17408
	global_load_lds_dwordx4 v[164:165], off
	s_bitset1_b32 m0, 13
	v_add_u32_e32 v164, 0x2000, v148
	v_lshl_add_u64 v[166:167], v[238:239], 0, s[18:19]
	global_load_lds_dwordx4 v[166:167], off
	s_barrier
	s_waitcnt lgkmcnt(0)
	s_waitcnt lgkmcnt(0)
	v_mfma_f32_16x16x32_bf16 v[60:63], v[172:175], v[188:191], v[60:63]
	v_mfma_f32_16x16x32_bf16 v[56:59], v[180:183], v[188:191], v[56:59]
	v_mfma_f32_16x16x32_bf16 v[52:55], v[172:175], v[196:199], v[52:55]
	v_mfma_f32_16x16x32_bf16 v[48:51], v[180:183], v[196:199], v[48:51]
	v_mfma_f32_16x16x32_bf16 v[44:47], v[172:175], v[204:207], v[44:47]
	v_mfma_f32_16x16x32_bf16 v[40:43], v[180:183], v[204:207], v[40:43]
	v_mfma_f32_16x16x32_bf16 v[36:39], v[172:175], v[212:215], v[36:39]
	v_mfma_f32_16x16x32_bf16 v[32:35], v[180:183], v[212:215], v[32:35]
	v_mfma_f32_16x16x32_bf16 v[60:63], v[176:179], v[192:195], v[60:63]
	v_mfma_f32_16x16x32_bf16 v[56:59], v[184:187], v[192:195], v[56:59]
	v_mfma_f32_16x16x32_bf16 v[52:55], v[176:179], v[200:203], v[52:55]
	v_mfma_f32_16x16x32_bf16 v[48:51], v[184:187], v[200:203], v[48:51]
	v_mfma_f32_16x16x32_bf16 v[44:47], v[176:179], v[208:211], v[44:47]
	v_mfma_f32_16x16x32_bf16 v[40:43], v[184:187], v[208:211], v[40:43]
	v_mfma_f32_16x16x32_bf16 v[36:39], v[176:179], v[232:235], v[36:39]
	v_mfma_f32_16x16x32_bf16 v[32:35], v[184:187], v[232:235], v[32:35]
	s_barrier
; #define STAGE(P, BASE, LD, br, kt) do { const char* _g = (const char*)((BASE) + (size_t)(br) * (LD) + (size_t)(kt) * 64); \
;     for (int _i = 0; _i < 2; ++_i) { int _b = tidx * 16 + _i * 8192; int _r, _c; stage_rc(_b, _r, _c); \
;       __builtin_amdgcn_global_load_lds((const unsigned*)(_g + (unsigned)((_r * (LD) + _c) * 2)), (unsigned*)((char*)(P) + _b), 16, 0, 0); } } while (0)
; #define LDA(dst, b, h) for (int m = 0; m < 4; ++m) for (int k = 0; k < 2; ++k) \
;     dst[m][k] = *reinterpret_cast<const bf16x8*>((char*)SA(b, h) + lds_byte(wr * 64 + m * 16 + fr, k * 32 + fq * 8))
; #define LDB(dst, b, h) for (int n = 0; n < 2; ++n) for (int k = 0; k < 2; ++k) \
;     dst[n][k] = *reinterpret_cast<const bf16x8*>((char*)SB(b, h) + lds_byte(wc * 32 + n * 16 + fr, k * 32 + fq * 8))
; #define MMA(ai, bj, At_, Bt_) do { __builtin_amdgcn_s_setprio(1); \
;     for (int k = 0; k < 2; ++k) for (int m = 0; m < 4; ++m) for (int n = 0; n < 2; ++n) \
;       acc[ai][bj][m][n] = __builtin_amdgcn_mfma_f32_16x16x32_bf16(At_[m][k], Bt_[n][k], acc[ai][bj][m][n], 0, 0, 0); \
;     __builtin_amdgcn_s_setprio(0); } while (0)
; #define WAIT_V(n) asm volatile("s_waitcnt vmcnt(" #n ")" ::: "memory")
; #define WAIT_L(n) asm volatile("s_waitcnt lgkmcnt(" #n ")" ::: "memory")
; #define BAR __builtin_amdgcn_s_barrier()
; #define SCHED __builtin_amdgcn_sched_barrier(0)
; template <int EPI, int lda, int ldb, int N, int K>
; __device__ __forceinline__ void gemm_phase(const u16* __restrict__ A, const u16* __restrict__ Bt, const GemmEpi ep, int wv) {
;     ...
;       STAGE(SB(0, 1), Bt, ldb, bcol + HALF, t + 2);
;       WAIT_V(6); BAR; MMA(1, 1, At, B1); BAR;
;       LDB(B0, 1, 0); SCHED; LDA(At, 1, 0); STAGE(SA(0, 1), Ab, lda, brow + HALF, t + 2);
;       WAIT_L(8); BAR; WAIT_L(0); MMA(0, 0, At, B0); BAR; SCHED;
;       LDB(B1, 1, 1); STAGE(SB(1, 0), Bt, ldb, bcol, t + 3);
;       BAR; WAIT_L(0); MMA(0, 1, At, B1); BAR;
;       LDA(At, 1, 1); STAGE(SA(1, 0), Ab, lda, brow, t + 3);
	v_add_u32_e32 v165, s53, v153
	v_lshl_add_u64 v[166:167], v[240:241], 0, s[20:21]
	v_readfirstlane_b32 s43, v165
	s_mov_b32 m0, s43
	v_lshl_add_u64 v[172:173], v[242:243], 0, s[20:21]
	global_load_lds_dwordx4 v[166:167], off
	s_bitset1_b32 m0, 13
	v_add_u32_e32 v166, 0x2000, v165
	global_load_lds_dwordx4 v[172:173], off
	s_waitcnt vmcnt(6)
	s_barrier
	v_mfma_f32_16x16x32_bf16 v[28:31], v[216:219], v[188:191], v[28:31]
	v_mfma_f32_16x16x32_bf16 v[24:27], v[224:227], v[188:191], v[24:27]
	v_mfma_f32_16x16x32_bf16 v[20:23], v[216:219], v[196:199], v[20:23]
	v_mfma_f32_16x16x32_bf16 v[16:19], v[224:227], v[196:199], v[16:19]
	v_mfma_f32_16x16x32_bf16 v[12:15], v[216:219], v[204:207], v[12:15]
	v_mfma_f32_16x16x32_bf16 v[8:11], v[224:227], v[204:207], v[8:11]
	v_mfma_f32_16x16x32_bf16 v[4:7], v[216:219], v[212:215], v[4:7]
	v_mfma_f32_16x16x32_bf16 v[0:3], v[224:227], v[212:215], v[0:3]
	v_mfma_f32_16x16x32_bf16 v[28:31], v[220:223], v[192:195], v[28:31]
	v_mfma_f32_16x16x32_bf16 v[24:27], v[228:231], v[192:195], v[24:27]
	v_mfma_f32_16x16x32_bf16 v[20:23], v[220:223], v[200:203], v[20:23]
	v_mfma_f32_16x16x32_bf16 v[16:19], v[228:231], v[200:203], v[16:19]
	v_mfma_f32_16x16x32_bf16 v[12:15], v[220:223], v[208:211], v[12:15]
	v_mfma_f32_16x16x32_bf16 v[8:11], v[228:231], v[208:211], v[8:11]
	v_mfma_f32_16x16x32_bf16 v[4:7], v[220:223], v[232:235], v[4:7]
	v_mfma_f32_16x16x32_bf16 v[0:3], v[228:231], v[232:235], v[0:3]
	s_barrier
	ds_read_b128 v[172:175], v156
	ds_read_b128 v[176:179], v156 offset:1024
	ds_read_b128 v[180:183], v156 offset:2048
	ds_read_b128 v[184:187], v156 offset:3072
	v_add_u32_e32 v167, 0x4000, v148
	v_add_u32_e32 v168, 0x6000, v148
	v_readfirstlane_b32 s43, v167
	v_lshl_add_u64 v[220:221], v[236:237], 0, s[22:23]
	s_mov_b32 m0, s43
	ds_read_b128 v[188:191], v152 offset:32768
	ds_read_b128 v[192:195], v152 offset:33792
	ds_read_b128 v[196:199], v151 offset:32768
	ds_read_b128 v[200:203], v151 offset:33792
	ds_read_b128 v[204:207], v150 offset:32768
	ds_read_b128 v[208:211], v150 offset:33792
	ds_read_b128 v[212:215], v149 offset:32768
	ds_read_b128 v[216:219], v149 offset:33792
	global_load_lds_dwordx4 v[220:221], off
	s_bitset1_b32 m0, 13
	v_lshl_add_u64 v[220:221], v[238:239], 0, s[22:23]
	global_load_lds_dwordx4 v[220:221], off
	s_waitcnt lgkmcnt(8)
	s_barrier
	s_waitcnt lgkmcnt(0)
	s_waitcnt lgkmcnt(0)
	v_mfma_f32_16x16x32_bf16 v[124:127], v[172:175], v[188:191], v[124:127]
	v_mfma_f32_16x16x32_bf16 v[120:123], v[180:183], v[188:191], v[120:123]
	v_mfma_f32_16x16x32_bf16 v[116:119], v[172:175], v[196:199], v[116:119]
	v_mfma_f32_16x16x32_bf16 v[112:115], v[180:183], v[196:199], v[112:115]
	v_mfma_f32_16x16x32_bf16 v[108:111], v[172:175], v[204:207], v[108:111]
	v_mfma_f32_16x16x32_bf16 v[104:107], v[180:183], v[204:207], v[104:107]
	v_mfma_f32_16x16x32_bf16 v[100:103], v[172:175], v[212:215], v[100:103]
	v_mfma_f32_16x16x32_bf16 v[96:99], v[180:183], v[212:215], v[96:99]
	v_mfma_f32_16x16x32_bf16 v[124:127], v[176:179], v[192:195], v[124:127]
	v_mfma_f32_16x16x32_bf16 v[120:123], v[184:187], v[192:195], v[120:123]
	v_mfma_f32_16x16x32_bf16 v[116:119], v[176:179], v[200:203], v[116:119]
	v_mfma_f32_16x16x32_bf16 v[112:115], v[184:187], v[200:203], v[112:115]
	v_mfma_f32_16x16x32_bf16 v[108:111], v[176:179], v[208:211], v[108:111]
	v_mfma_f32_16x16x32_bf16 v[104:107], v[184:187], v[208:211], v[104:107]
	v_mfma_f32_16x16x32_bf16 v[100:103], v[176:179], v[216:219], v[100:103]
	v_mfma_f32_16x16x32_bf16 v[96:99], v[184:187], v[216:219], v[96:99]
	s_barrier
	v_readfirstlane_b32 s43, v155
	v_add_u32_e32 v171, 0x2000, v155
	v_lshl_add_u64 v[244:245], v[240:241], 0, s[24:25]
	s_mov_b32 m0, s43
	ds_read_b128 v[220:223], v154
	ds_read_b128 v[224:227], v154 offset:1024
	ds_read_b128 v[228:231], v154 offset:2048
	ds_read_b128 v[232:235], v154 offset:3072
	global_load_lds_dwordx4 v[244:245], off
	s_bitset1_b32 m0, 13
	v_lshl_add_u64 v[244:245], v[242:243], 0, s[24:25]
	global_load_lds_dwordx4 v[244:245], off
	s_barrier
	s_waitcnt lgkmcnt(0)
	s_waitcnt lgkmcnt(0)
	v_mfma_f32_16x16x32_bf16 v[92:95], v[220:223], v[188:191], v[92:95]
	v_mfma_f32_16x16x32_bf16 v[88:91], v[228:231], v[188:191], v[88:91]
	v_mfma_f32_16x16x32_bf16 v[84:87], v[220:223], v[196:199], v[84:87]
	v_mfma_f32_16x16x32_bf16 v[80:83], v[228:231], v[196:199], v[80:83]
	v_mfma_f32_16x16x32_bf16 v[76:79], v[220:223], v[204:207], v[76:79]
	v_mfma_f32_16x16x32_bf16 v[72:75], v[228:231], v[204:207], v[72:75]
	v_mfma_f32_16x16x32_bf16 v[68:71], v[220:223], v[212:215], v[68:71]
	v_mfma_f32_16x16x32_bf16 v[64:67], v[228:231], v[212:215], v[64:67]
	v_mfma_f32_16x16x32_bf16 v[92:95], v[224:227], v[192:195], v[92:95]
	v_mfma_f32_16x16x32_bf16 v[88:91], v[232:235], v[192:195], v[88:91]
	v_mfma_f32_16x16x32_bf16 v[84:87], v[224:227], v[200:203], v[84:87]
	v_mfma_f32_16x16x32_bf16 v[80:83], v[232:235], v[200:203], v[80:83]
	v_mfma_f32_16x16x32_bf16 v[76:79], v[224:227], v[208:211], v[76:79]
	v_mfma_f32_16x16x32_bf16 v[72:75], v[232:235], v[208:211], v[72:75]
	v_mfma_f32_16x16x32_bf16 v[68:71], v[224:227], v[216:219], v[68:71]
	v_mfma_f32_16x16x32_bf16 v[64:67], v[232:235], v[216:219], v[64:67]
	v_readfirstlane_b32 s43, v157
	v_lshl_add_u64 v[236:237], v[236:237], 0, s[26:27]
	s_mov_b32 m0, s43
	s_barrier
	ds_read_b128 v[188:191], v152 offset:49152
	ds_read_b128 v[192:195], v152 offset:50176
	ds_read_b128 v[196:199], v151 offset:49152
	ds_read_b128 v[200:203], v151 offset:50176
	ds_read_b128 v[204:207], v150 offset:49152
	ds_read_b128 v[208:211], v150 offset:50176
	ds_read_b128 v[212:215], v149 offset:49152
	ds_read_b128 v[216:219], v149 offset:50176
	global_load_lds_dwordx4 v[236:237], off
	s_bitset1_b32 m0, 13
	v_lshl_add_u64 v[236:237], v[238:239], 0, s[26:27]
	global_load_lds_dwordx4 v[236:237], off
	s_barrier
; #define STAGE(P, BASE, LD, br, kt) do { const char* _g = (const char*)((BASE) + (size_t)(br) * (LD) + (size_t)(kt) * 64); \
;     for (int _i = 0; _i < 2; ++_i) { int _b = tidx * 16 + _i * 8192; int _r, _c; stage_rc(_b, _r, _c); \
;       __builtin_amdgcn_global_load_lds((const unsigned*)(_g + (unsigned)((_r * (LD) + _c) * 2)), (unsigned*)((char*)(P) + _b), 16, 0, 0); } } while (0)
; #define LDA(dst, b, h) for (int m = 0; m < 4; ++m) for (int k = 0; k < 2; ++k) \
;     dst[m][k] = *reinterpret_cast<const bf16x8*>((char*)SA(b, h) + lds_byte(wr * 64 + m * 16 + fr, k * 32 + fq * 8))
; #define LDB(dst, b, h) for (int n = 0; n < 2; ++n) for (int k = 0; k < 2; ++k) \
;     dst[n][k] = *reinterpret_cast<const bf16x8*>((char*)SB(b, h) + lds_byte(wc * 32 + n * 16 + fr, k * 32 + fq * 8))
; #define MMA(ai, bj, At_, Bt_) do { __builtin_amdgcn_s_setprio(1); \
;     for (int k = 0; k < 2; ++k) for (int m = 0; m < 4; ++m) for (int n = 0; n < 2; ++n) \
;       acc[ai][bj][m][n] = __builtin_amdgcn_mfma_f32_16x16x32_bf16(At_[m][k], Bt_[n][k], acc[ai][bj][m][n], 0, 0, 0); \
;     __builtin_amdgcn_s_setprio(0); } while (0)
; #define WAIT_V(n) asm volatile("s_waitcnt vmcnt(" #n ")" ::: "memory")
; #define WAIT_L(n) asm volatile("s_waitcnt lgkmcnt(" #n ")" ::: "memory")
; #define BAR __builtin_amdgcn_s_barrier()
; #define SCHED __builtin_amdgcn_sched_barrier(0)
; template <int EPI, int lda, int ldb, int N, int K>
; __device__ __forceinline__ void gemm_phase(const u16* __restrict__ A, const u16* __restrict__ Bt, const GemmEpi ep, int wv) {
;     ...
;       BAR; WAIT_L(0); MMA(0, 1, At, B1); BAR;
;       LDA(At, 1, 1); STAGE(SA(1, 0), Ab, lda, brow, t + 3);
;       BAR; WAIT_L(0); MMA(1, 0, At, B0); BAR; SCHED;
;       STAGE(SB(1, 1), Bt, ldb, bcol + HALF, t + 3);
;       WAIT_V(6); BAR; MMA(1, 1, At, B1); BAR;
;     }
;     { LDB(B0, 0, 0); LDA(At, 0, 0); STAGE(SA(1, 1), Ab, lda, brow + HALF, nt - 1);
;       BAR; WAIT_L(0); MMA(0, 0, At, B0); BAR;
;       LDB(B1, 0, 1); BAR; WAIT_L(0); MMA(0, 1, At, B1); BAR;
	s_waitcnt lgkmcnt(0)
	s_waitcnt lgkmcnt(0)
	v_mfma_f32_16x16x32_bf16 v[60:63], v[172:175], v[188:191], v[60:63]
	v_mfma_f32_16x16x32_bf16 v[56:59], v[180:183], v[188:191], v[56:59]
	v_mfma_f32_16x16x32_bf16 v[52:55], v[172:175], v[196:199], v[52:55]
	v_mfma_f32_16x16x32_bf16 v[48:51], v[180:183], v[196:199], v[48:51]
	v_mfma_f32_16x16x32_bf16 v[44:47], v[172:175], v[204:207], v[44:47]
	v_mfma_f32_16x16x32_bf16 v[40:43], v[180:183], v[204:207], v[40:43]
	v_mfma_f32_16x16x32_bf16 v[36:39], v[172:175], v[212:215], v[36:39]
	v_mfma_f32_16x16x32_bf16 v[32:35], v[180:183], v[212:215], v[32:35]
	v_mfma_f32_16x16x32_bf16 v[60:63], v[176:179], v[192:195], v[60:63]
	v_mfma_f32_16x16x32_bf16 v[56:59], v[184:187], v[192:195], v[56:59]
	v_mfma_f32_16x16x32_bf16 v[52:55], v[176:179], v[200:203], v[52:55]
	v_mfma_f32_16x16x32_bf16 v[48:51], v[184:187], v[200:203], v[48:51]
	v_mfma_f32_16x16x32_bf16 v[44:47], v[176:179], v[208:211], v[44:47]
	v_mfma_f32_16x16x32_bf16 v[40:43], v[184:187], v[208:211], v[40:43]
	v_mfma_f32_16x16x32_bf16 v[36:39], v[176:179], v[216:219], v[36:39]
	v_mfma_f32_16x16x32_bf16 v[32:35], v[184:187], v[216:219], v[32:35]
	s_barrier
	v_readfirstlane_b32 s43, v159
	v_add_u32_e32 v171, 0x2000, v159
	v_lshl_add_u64 v[172:173], v[240:241], 0, s[34:35]
	s_mov_b32 m0, s43
	global_load_lds_dwordx4 v[172:173], off
	s_bitset1_b32 m0, 13
	v_lshl_add_u64 v[172:173], v[242:243], 0, s[34:35]
	global_load_lds_dwordx4 v[172:173], off
	s_waitcnt vmcnt(6)
	s_barrier
	v_mfma_f32_16x16x32_bf16 v[28:31], v[220:223], v[188:191], v[28:31]
	v_mfma_f32_16x16x32_bf16 v[24:27], v[228:231], v[188:191], v[24:27]
	v_mfma_f32_16x16x32_bf16 v[20:23], v[220:223], v[196:199], v[20:23]
	v_mfma_f32_16x16x32_bf16 v[16:19], v[228:231], v[196:199], v[16:19]
	v_mfma_f32_16x16x32_bf16 v[12:15], v[220:223], v[204:207], v[12:15]
	v_mfma_f32_16x16x32_bf16 v[8:11], v[228:231], v[204:207], v[8:11]
	v_mfma_f32_16x16x32_bf16 v[4:7], v[220:223], v[212:215], v[4:7]
	v_mfma_f32_16x16x32_bf16 v[0:3], v[228:231], v[212:215], v[0:3]
	v_mfma_f32_16x16x32_bf16 v[28:31], v[224:227], v[192:195], v[28:31]
	v_mfma_f32_16x16x32_bf16 v[24:27], v[232:235], v[192:195], v[24:27]
	v_mfma_f32_16x16x32_bf16 v[20:23], v[224:227], v[200:203], v[20:23]
	v_mfma_f32_16x16x32_bf16 v[16:19], v[232:235], v[200:203], v[16:19]
	v_mfma_f32_16x16x32_bf16 v[12:15], v[224:227], v[208:211], v[12:15]
	v_mfma_f32_16x16x32_bf16 v[8:11], v[232:235], v[208:211], v[8:11]
	v_mfma_f32_16x16x32_bf16 v[4:7], v[224:227], v[216:219], v[4:7]
	v_mfma_f32_16x16x32_bf16 v[0:3], v[232:235], v[216:219], v[0:3]
	s_add_i32 s42, s42, 2
	s_add_u32 s40, s40, 0x100
	s_addc_u32 s41, s41, 0
	s_cmp_gt_u32 s42, 27
	s_barrier
	s_cbranch_scc0 .LBB0_1564
	s_add_i32 s40, s38, 0x80
	s_mul_hi_i32 s41, s40, 0x1080
	s_mulk_i32 s40, 0x1080
	s_add_u32 s40, s49, s40
	s_addc_u32 s41, s50, s41
	v_lshl_add_u64 v[158:159], s[40:41], 0, v[128:129]
	v_readfirstlane_b32 s42, v169
	v_lshl_add_u64 v[158:159], v[158:159], 0, s[36:37]
	s_mov_b32 m0, s42
	ds_read_b128 v[134:137], v161
	ds_read_b128 v[138:141], v161 offset:1024
	ds_read_b128 v[172:175], v161 offset:2048
	ds_read_b128 v[176:179], v161 offset:3072
	ds_read_b128 v[180:183], v152
	ds_read_b128 v[184:187], v152 offset:1024
	ds_read_b128 v[188:191], v151
	ds_read_b128 v[192:195], v151 offset:1024
	ds_read_b128 v[196:199], v150
	ds_read_b128 v[200:203], v150 offset:1024
	ds_read_b128 v[204:207], v149
	ds_read_b128 v[208:211], v149 offset:1024
	global_load_lds_dwordx4 v[158:159], off
	v_lshl_add_u64 v[158:159], s[40:41], 0, v[132:133]
	v_readfirstlane_b32 s40, v170
	v_lshl_add_u64 v[158:159], v[158:159], 0, s[36:37]
	s_mov_b32 m0, s40
	s_nop 0
	global_load_lds_dwordx4 v[158:159], off
	s_barrier
	s_waitcnt lgkmcnt(0)
	s_waitcnt lgkmcnt(0)
	v_mfma_f32_16x16x32_bf16 v[124:127], v[134:137], v[180:183], v[124:127]
	v_mfma_f32_16x16x32_bf16 v[120:123], v[172:175], v[180:183], v[120:123]
	v_mfma_f32_16x16x32_bf16 v[116:119], v[134:137], v[188:191], v[116:119]
	v_mfma_f32_16x16x32_bf16 v[112:115], v[172:175], v[188:191], v[112:115]
	v_mfma_f32_16x16x32_bf16 v[108:111], v[134:137], v[196:199], v[108:111]
	v_mfma_f32_16x16x32_bf16 v[104:107], v[172:175], v[196:199], v[104:107]
	v_mfma_f32_16x16x32_bf16 v[100:103], v[134:137], v[204:207], v[100:103]
	v_mfma_f32_16x16x32_bf16 v[96:99], v[172:175], v[204:207], v[96:99]
	v_mfma_f32_16x16x32_bf16 v[124:127], v[138:141], v[184:187], v[124:127]
	v_mfma_f32_16x16x32_bf16 v[120:123], v[176:179], v[184:187], v[120:123]
	v_mfma_f32_16x16x32_bf16 v[116:119], v[138:141], v[192:195], v[116:119]
	v_mfma_f32_16x16x32_bf16 v[112:115], v[176:179], v[192:195], v[112:115]
	v_mfma_f32_16x16x32_bf16 v[108:111], v[138:141], v[200:203], v[108:111]
	v_mfma_f32_16x16x32_bf16 v[104:107], v[176:179], v[200:203], v[104:107]
	v_mfma_f32_16x16x32_bf16 v[100:103], v[138:141], v[208:211], v[100:103]
	v_mfma_f32_16x16x32_bf16 v[96:99], v[176:179], v[208:211], v[96:99]
	s_barrier
	ds_read_b128 v[212:215], v160
	ds_read_b128 v[216:219], v160 offset:1024
	ds_read_b128 v[220:223], v160 offset:2048
	ds_read_b128 v[158:161], v160 offset:3072
	s_barrier
; #define LDA(dst, b, h) for (int m = 0; m < 4; ++m) for (int k = 0; k < 2; ++k) \
;     dst[m][k] = *reinterpret_cast<const bf16x8*>((char*)SA(b, h) + lds_byte(wr * 64 + m * 16 + fr, k * 32 + fq * 8))
; #define LDB(dst, b, h) for (int n = 0; n < 2; ++n) for (int k = 0; k < 2; ++k) \
;     dst[n][k] = *reinterpret_cast<const bf16x8*>((char*)SB(b, h) + lds_byte(wc * 32 + n * 16 + fr, k * 32 + fq * 8))
; #define MMA(ai, bj, At_, Bt_) do { __builtin_amdgcn_s_setprio(1); \
;     for (int k = 0; k < 2; ++k) for (int m = 0; m < 4; ++m) for (int n = 0; n < 2; ++n) \
;       acc[ai][bj][m][n] = __builtin_amdgcn_mfma_f32_16x16x32_bf16(At_[m][k], Bt_[n][k], acc[ai][bj][m][n], 0, 0, 0); \
;     __builtin_amdgcn_s_setprio(0); } while (0)
; #define WAIT_V(n) asm volatile("s_waitcnt vmcnt(" #n ")" ::: "memory")
; #define WAIT_L(n) asm volatile("s_waitcnt lgkmcnt(" #n ")" ::: "memory")
; #define BAR __builtin_amdgcn_s_barrier()
; template <int EPI, int lda, int ldb, int N, int K>
; __device__ __forceinline__ void gemm_phase(const u16* __restrict__ A, const u16* __restrict__ Bt, const GemmEpi ep, int wv) {
;     ...
;       LDB(B1, 0, 1); BAR; WAIT_L(0); MMA(0, 1, At, B1); BAR;
;       LDA(At, 0, 1); WAIT_V(4); BAR; WAIT_L(0); MMA(1, 0, At, B0); MMA(1, 1, At, B1); BAR; }
;     { LDB(B0, 1, 0); LDA(At, 1, 0); WAIT_V(2); BAR; WAIT_L(0); MMA(0, 0, At, B0); BAR;
	s_waitcnt lgkmcnt(0)
	s_waitcnt lgkmcnt(0)
	v_mfma_f32_16x16x32_bf16 v[92:95], v[212:215], v[180:183], v[92:95]
	v_mfma_f32_16x16x32_bf16 v[88:91], v[220:223], v[180:183], v[88:91]
	v_mfma_f32_16x16x32_bf16 v[76:79], v[212:215], v[196:199], v[76:79]
	v_mfma_f32_16x16x32_bf16 v[72:75], v[220:223], v[196:199], v[72:75]
	v_mfma_f32_16x16x32_bf16 v[84:87], v[212:215], v[188:191], v[84:87]
	v_mfma_f32_16x16x32_bf16 v[80:83], v[220:223], v[188:191], v[80:83]
	v_mfma_f32_16x16x32_bf16 v[68:71], v[212:215], v[204:207], v[68:71]
	v_mfma_f32_16x16x32_bf16 v[64:67], v[220:223], v[204:207], v[64:67]
	v_mfma_f32_16x16x32_bf16 v[92:95], v[216:219], v[184:187], v[92:95]
	v_mfma_f32_16x16x32_bf16 v[88:91], v[158:161], v[184:187], v[88:91]
	v_mfma_f32_16x16x32_bf16 v[76:79], v[216:219], v[200:203], v[76:79]
	v_mfma_f32_16x16x32_bf16 v[72:75], v[158:161], v[200:203], v[72:75]
	v_mfma_f32_16x16x32_bf16 v[180:183], v[216:219], v[192:195], v[84:87]
	v_mfma_f32_16x16x32_bf16 v[184:187], v[158:161], v[192:195], v[80:83]
	v_mfma_f32_16x16x32_bf16 v[188:191], v[216:219], v[208:211], v[68:71]
	v_mfma_f32_16x16x32_bf16 v[192:195], v[158:161], v[208:211], v[64:67]
	s_barrier
	s_nop 0
	ds_read_b128 v[64:67], v152 offset:16384
	ds_read_b128 v[68:71], v152 offset:17408
	ds_read_b128 v[80:83], v151 offset:16384
	ds_read_b128 v[84:87], v151 offset:17408
	ds_read_b128 v[196:199], v150 offset:16384
	ds_read_b128 v[200:203], v150 offset:17408
	ds_read_b128 v[204:207], v149 offset:16384
	ds_read_b128 v[208:211], v149 offset:17408
	s_waitcnt vmcnt(4)
	s_barrier
	s_waitcnt lgkmcnt(0)
	s_waitcnt lgkmcnt(0)
	v_mfma_f32_16x16x32_bf16 v[60:63], v[134:137], v[64:67], v[60:63]
	v_mfma_f32_16x16x32_bf16 v[56:59], v[172:175], v[64:67], v[56:59]
	v_mfma_f32_16x16x32_bf16 v[52:55], v[134:137], v[80:83], v[52:55]
	v_mfma_f32_16x16x32_bf16 v[48:51], v[172:175], v[80:83], v[48:51]
	v_mfma_f32_16x16x32_bf16 v[44:47], v[134:137], v[196:199], v[44:47]
	v_mfma_f32_16x16x32_bf16 v[40:43], v[172:175], v[196:199], v[40:43]
	v_mfma_f32_16x16x32_bf16 v[36:39], v[134:137], v[204:207], v[36:39]
	v_mfma_f32_16x16x32_bf16 v[32:35], v[172:175], v[204:207], v[32:35]
	v_mfma_f32_16x16x32_bf16 v[60:63], v[138:141], v[68:71], v[60:63]
	v_mfma_f32_16x16x32_bf16 v[56:59], v[176:179], v[68:71], v[56:59]
	v_mfma_f32_16x16x32_bf16 v[52:55], v[138:141], v[84:87], v[52:55]
	v_mfma_f32_16x16x32_bf16 v[48:51], v[176:179], v[84:87], v[48:51]
	v_mfma_f32_16x16x32_bf16 v[44:47], v[138:141], v[200:203], v[44:47]
	v_mfma_f32_16x16x32_bf16 v[40:43], v[176:179], v[200:203], v[40:43]
	v_mfma_f32_16x16x32_bf16 v[36:39], v[138:141], v[208:211], v[36:39]
	v_mfma_f32_16x16x32_bf16 v[32:35], v[176:179], v[208:211], v[32:35]
	v_mfma_f32_16x16x32_bf16 v[28:31], v[212:215], v[64:67], v[28:31]
	v_mfma_f32_16x16x32_bf16 v[24:27], v[220:223], v[64:67], v[24:27]
	v_mfma_f32_16x16x32_bf16 v[12:15], v[212:215], v[196:199], v[12:15]
	v_mfma_f32_16x16x32_bf16 v[8:11], v[220:223], v[196:199], v[8:11]
	v_mfma_f32_16x16x32_bf16 v[20:23], v[212:215], v[80:83], v[20:23]
	v_mfma_f32_16x16x32_bf16 v[16:19], v[220:223], v[80:83], v[16:19]
	v_mfma_f32_16x16x32_bf16 v[4:7], v[212:215], v[204:207], v[4:7]
	v_mfma_f32_16x16x32_bf16 v[0:3], v[220:223], v[204:207], v[0:3]
	v_mfma_f32_16x16x32_bf16 v[28:31], v[216:219], v[68:71], v[28:31]
	v_mfma_f32_16x16x32_bf16 v[24:27], v[158:161], v[68:71], v[24:27]
	v_mfma_f32_16x16x32_bf16 v[12:15], v[216:219], v[200:203], v[12:15]
	v_mfma_f32_16x16x32_bf16 v[8:11], v[158:161], v[200:203], v[8:11]
	v_mfma_f32_16x16x32_bf16 v[134:137], v[216:219], v[84:87], v[20:23]
	v_mfma_f32_16x16x32_bf16 v[138:141], v[158:161], v[84:87], v[16:19]
	v_mfma_f32_16x16x32_bf16 v[170:173], v[216:219], v[208:211], v[4:7]
	v_mfma_f32_16x16x32_bf16 v[158:161], v[158:161], v[208:211], v[0:3]
	s_barrier
	s_nop 0
	ds_read_b128 v[0:3], v156
	ds_read_b128 v[4:7], v156 offset:1024
	ds_read_b128 v[16:19], v156 offset:2048
	ds_read_b128 v[174:177], v156 offset:3072
	ds_read_b128 v[20:23], v152 offset:32768
	ds_read_b128 v[196:199], v152 offset:33792
	ds_read_b128 v[200:203], v151 offset:32768
	ds_read_b128 v[204:207], v151 offset:33792
	ds_read_b128 v[208:211], v150 offset:32768
	ds_read_b128 v[212:215], v150 offset:33792
	ds_read_b128 v[216:219], v149 offset:32768
	ds_read_b128 v[220:223], v149 offset:33792
	s_waitcnt vmcnt(2)
	s_barrier
; #define LDA(dst, b, h) for (int m = 0; m < 4; ++m) for (int k = 0; k < 2; ++k) \
;     dst[m][k] = *reinterpret_cast<const bf16x8*>((char*)SA(b, h) + lds_byte(wr * 64 + m * 16 + fr, k * 32 + fq * 8))
; #define LDB(dst, b, h) for (int n = 0; n < 2; ++n) for (int k = 0; k < 2; ++k) \
;     dst[n][k] = *reinterpret_cast<const bf16x8*>((char*)SB(b, h) + lds_byte(wc * 32 + n * 16 + fr, k * 32 + fq * 8))
; #define MMA(ai, bj, At_, Bt_) do { __builtin_amdgcn_s_setprio(1); \
;     for (int k = 0; k < 2; ++k) for (int m = 0; m < 4; ++m) for (int n = 0; n < 2; ++n) \
;       acc[ai][bj][m][n] = __builtin_amdgcn_mfma_f32_16x16x32_bf16(At_[m][k], Bt_[n][k], acc[ai][bj][m][n], 0, 0, 0); \
;     __builtin_amdgcn_s_setprio(0); } while (0)
; #define WAIT_V(n) asm volatile("s_waitcnt vmcnt(" #n ")" ::: "memory")
; #define WAIT_L(n) asm volatile("s_waitcnt lgkmcnt(" #n ")" ::: "memory")
; #define BAR __builtin_amdgcn_s_barrier()
; template <int EPI, int lda, int ldb, int N, int K>
; __device__ __forceinline__ void gemm_phase(const u16* __restrict__ A, const u16* __restrict__ Bt, const GemmEpi ep, int wv) {
;     ...
;     { LDB(B0, 1, 0); LDA(At, 1, 0); WAIT_V(2); BAR; WAIT_L(0); MMA(0, 0, At, B0); BAR;
;       LDB(B1, 1, 1); WAIT_V(0); BAR; WAIT_L(0); MMA(0, 1, At, B1); BAR;
;       LDA(At, 1, 1); BAR; WAIT_L(0); MMA(1, 0, At, B0); MMA(1, 1, At, B1); BAR; }
;     if (wr == 0) BAR;
	s_waitcnt lgkmcnt(0)
	s_waitcnt lgkmcnt(0)
	v_mfma_f32_16x16x32_bf16 v[64:67], v[0:3], v[20:23], v[124:127]
	v_mfma_f32_16x16x32_bf16 v[68:71], v[16:19], v[20:23], v[120:123]
	v_mfma_f32_16x16x32_bf16 v[80:83], v[0:3], v[200:203], v[116:119]
	v_mfma_f32_16x16x32_bf16 v[84:87], v[16:19], v[200:203], v[112:115]
	v_mfma_f32_16x16x32_bf16 v[108:111], v[0:3], v[208:211], v[108:111]
	v_mfma_f32_16x16x32_bf16 v[104:107], v[16:19], v[208:211], v[104:107]
	v_mfma_f32_16x16x32_bf16 v[120:123], v[0:3], v[216:219], v[100:103]
	v_mfma_f32_16x16x32_bf16 v[124:127], v[16:19], v[216:219], v[96:99]
	v_mfma_f32_16x16x32_bf16 v[116:119], v[4:7], v[196:199], v[64:67]
	v_mfma_f32_16x16x32_bf16 v[112:115], v[174:177], v[196:199], v[68:71]
	v_mfma_f32_16x16x32_bf16 v[100:103], v[4:7], v[204:207], v[80:83]
	v_mfma_f32_16x16x32_bf16 v[96:99], v[174:177], v[204:207], v[84:87]
	v_mfma_f32_16x16x32_bf16 v[84:87], v[4:7], v[212:215], v[108:111]
	v_mfma_f32_16x16x32_bf16 v[80:83], v[174:177], v[212:215], v[104:107]
	v_mfma_f32_16x16x32_bf16 v[68:71], v[4:7], v[220:223], v[120:123]
	v_mfma_f32_16x16x32_bf16 v[64:67], v[174:177], v[220:223], v[124:127]
	s_barrier
	ds_read_b128 v[224:227], v154
	ds_read_b128 v[228:231], v154 offset:1024
	ds_read_b128 v[232:235], v154 offset:2048
	ds_read_b128 v[154:157], v154 offset:3072
	s_waitcnt vmcnt(0)
	s_barrier
	s_waitcnt lgkmcnt(0)
	s_waitcnt lgkmcnt(0)
	v_mfma_f32_16x16x32_bf16 v[92:95], v[224:227], v[20:23], v[92:95]
	v_mfma_f32_16x16x32_bf16 v[20:23], v[232:235], v[20:23], v[88:91]
	v_mfma_f32_16x16x32_bf16 v[88:91], v[224:227], v[200:203], v[180:183]
	v_mfma_f32_16x16x32_bf16 v[104:107], v[232:235], v[200:203], v[184:187]
	v_mfma_f32_16x16x32_bf16 v[76:79], v[224:227], v[208:211], v[76:79]
	v_mfma_f32_16x16x32_bf16 v[72:75], v[232:235], v[208:211], v[72:75]
	v_mfma_f32_16x16x32_bf16 v[178:181], v[224:227], v[216:219], v[188:191]
	v_mfma_f32_16x16x32_bf16 v[182:185], v[232:235], v[216:219], v[192:195]
	v_mfma_f32_16x16x32_bf16 v[124:127], v[228:231], v[196:199], v[92:95]
	v_mfma_f32_16x16x32_bf16 v[120:123], v[154:157], v[196:199], v[20:23]
	v_mfma_f32_16x16x32_bf16 v[108:111], v[228:231], v[204:207], v[88:91]
	v_mfma_f32_16x16x32_bf16 v[104:107], v[154:157], v[204:207], v[104:107]
	v_mfma_f32_16x16x32_bf16 v[92:95], v[228:231], v[212:215], v[76:79]
	v_mfma_f32_16x16x32_bf16 v[88:91], v[154:157], v[212:215], v[72:75]
	v_mfma_f32_16x16x32_bf16 v[76:79], v[228:231], v[220:223], v[178:181]
	v_mfma_f32_16x16x32_bf16 v[72:75], v[154:157], v[220:223], v[182:185]
	s_barrier
	ds_read_b128 v[178:181], v152 offset:49152
	ds_read_b128 v[182:185], v152 offset:50176
	ds_read_b128 v[186:189], v151 offset:49152
	ds_read_b128 v[190:193], v151 offset:50176
	ds_read_b128 v[194:197], v150 offset:49152
	ds_read_b128 v[150:153], v150 offset:50176
	ds_read_b128 v[198:201], v149 offset:49152
	ds_read_b128 v[202:205], v149 offset:50176
	s_barrier
	s_waitcnt lgkmcnt(0)
	s_waitcnt lgkmcnt(0)
	v_mfma_f32_16x16x32_bf16 v[20:23], v[0:3], v[178:181], v[60:63]
	v_mfma_f32_16x16x32_bf16 v[56:59], v[16:19], v[178:181], v[56:59]
	v_mfma_f32_16x16x32_bf16 v[60:63], v[0:3], v[186:189], v[52:55]
	v_mfma_f32_16x16x32_bf16 v[206:209], v[16:19], v[186:189], v[48:51]
	v_mfma_f32_16x16x32_bf16 v[44:47], v[0:3], v[194:197], v[44:47]
	v_mfma_f32_16x16x32_bf16 v[40:43], v[16:19], v[194:197], v[40:43]
	v_mfma_f32_16x16x32_bf16 v[0:3], v[0:3], v[198:201], v[36:39]
	v_mfma_f32_16x16x32_bf16 v[210:213], v[16:19], v[198:201], v[32:35]
	v_mfma_f32_16x16x32_bf16 v[52:55], v[4:7], v[182:185], v[20:23]
	v_mfma_f32_16x16x32_bf16 v[48:51], v[174:177], v[182:185], v[56:59]
	v_mfma_f32_16x16x32_bf16 v[36:39], v[4:7], v[190:193], v[60:63]
	v_mfma_f32_16x16x32_bf16 v[32:35], v[174:177], v[190:193], v[206:209]
	v_mfma_f32_16x16x32_bf16 v[20:23], v[4:7], v[150:153], v[44:47]
	v_mfma_f32_16x16x32_bf16 v[16:19], v[174:177], v[150:153], v[40:43]
	v_mfma_f32_16x16x32_bf16 v[4:7], v[4:7], v[202:205], v[0:3]
	v_mfma_f32_16x16x32_bf16 v[0:3], v[174:177], v[202:205], v[210:213]
	v_mfma_f32_16x16x32_bf16 v[28:31], v[224:227], v[178:181], v[28:31]
	v_mfma_f32_16x16x32_bf16 v[24:27], v[232:235], v[178:181], v[24:27]
	v_mfma_f32_16x16x32_bf16 v[40:43], v[224:227], v[186:189], v[134:137]
	v_mfma_f32_16x16x32_bf16 v[134:137], v[232:235], v[186:189], v[138:141]
	v_mfma_f32_16x16x32_bf16 v[12:15], v[224:227], v[194:197], v[12:15]
	v_mfma_f32_16x16x32_bf16 v[8:11], v[232:235], v[194:197], v[8:11]
	v_mfma_f32_16x16x32_bf16 v[138:141], v[224:227], v[198:201], v[170:173]
	v_mfma_f32_16x16x32_bf16 v[158:161], v[232:235], v[198:201], v[158:161]
	v_mfma_f32_16x16x32_bf16 v[60:63], v[228:231], v[182:185], v[28:31]
	v_mfma_f32_16x16x32_bf16 v[56:59], v[154:157], v[182:185], v[24:27]
	v_mfma_f32_16x16x32_bf16 v[44:47], v[228:231], v[190:193], v[40:43]
	v_mfma_f32_16x16x32_bf16 v[40:43], v[154:157], v[190:193], v[134:137]
	v_mfma_f32_16x16x32_bf16 v[28:31], v[228:231], v[150:153], v[12:15]
	v_mfma_f32_16x16x32_bf16 v[24:27], v[154:157], v[150:153], v[8:11]
	v_mfma_f32_16x16x32_bf16 v[12:15], v[228:231], v[202:205], v[138:141]
	v_mfma_f32_16x16x32_bf16 v[8:11], v[154:157], v[202:205], v[158:161]
	v_cmp_gt_u32_e32 vcc, s54, v130
	s_barrier
	s_and_saveexec_b64 s[40:41], vcc
	s_cbranch_execz .LBB0_1567
	s_barrier

; #define STAGE(P, BASE, LD, br, kt) do { const char* _g = (const char*)((BASE) + (size_t)(br) * (LD) + (size_t)(kt) * 64); \
;     for (int _i = 0; _i < 2; ++_i) { int _b = tidx * 16 + _i * 8192; int _r, _c; stage_rc(_b, _r, _c); \
;       __builtin_amdgcn_global_load_lds((const unsigned*)(_g + (unsigned)((_r * (LD) + _c) * 2)), (unsigned*)((char*)(P) + _b), 16, 0, 0); } } while (0)
; #define LDA(dst, b, h) for (int m = 0; m < 4; ++m) for (int k = 0; k < 2; ++k) \
;     dst[m][k] = *reinterpret_cast<const bf16x8*>((char*)SA(b, h) + lds_byte(wr * 64 + m * 16 + fr, k * 32 + fq * 8))
; #define LDB(dst, b, h) for (int n = 0; n < 2; ++n) for (int k = 0; k < 2; ++k) \
;     dst[n][k] = *reinterpret_cast<const bf16x8*>((char*)SB(b, h) + lds_byte(wc * 32 + n * 16 + fr, k * 32 + fq * 8))
; #define MMA(ai, bj, At_, Bt_) do { __builtin_amdgcn_s_setprio(1); \
;     for (int k = 0; k < 2; ++k) for (int m = 0; m < 4; ++m) for (int n = 0; n < 2; ++n) \
;       acc[ai][bj][m][n] = __builtin_amdgcn_mfma_f32_16x16x32_bf16(At_[m][k], Bt_[n][k], acc[ai][bj][m][n], 0, 0, 0); \
;     __builtin_amdgcn_s_setprio(0); } while (0)
; #define WAIT_L(n) asm volatile("s_waitcnt lgkmcnt(" #n ")" ::: "memory")
; #define BAR __builtin_amdgcn_s_barrier()
; #define SCHED __builtin_amdgcn_sched_barrier(0)
; template <int EPI, int lda, int ldb, int N, int K>
; __device__ __forceinline__ void gemm_phase(const u16* __restrict__ A, const u16* __restrict__ Bt, const GemmEpi ep, int wv) {
;     ...
;     for (int t = 0; t < nt - 2; t += 2) {
;       LDB(B0, 0, 0); SCHED; LDA(At, 0, 0); STAGE(SA(1, 1), Ab, lda, brow + HALF, t + 1);
;       WAIT_L(8); BAR; WAIT_L(0); MMA(0, 0, At, B0); BAR; SCHED;
;       LDB(B1, 0, 1); STAGE(SB(0, 0), Bt, ldb, bcol, t + 2);
;       BAR; WAIT_L(0); MMA(0, 1, At, B1); BAR;
;       LDA(At, 0, 1); STAGE(SA(0, 0), Ab, lda, brow, t + 2);
;       BAR; WAIT_L(0); MMA(1, 0, At, B0); BAR; SCHED;
.LBB0_1624:
	ds_read_b128 v[174:177], v163
	ds_read_b128 v[178:181], v163 offset:1024
	ds_read_b128 v[182:185], v163 offset:2048
	ds_read_b128 v[186:189], v163 offset:3072
	v_add_u32_e32 v171, 0xc000, v149
	v_lshl_add_u64 v[238:239], v[134:135], 0, s[28:29]
	v_readfirstlane_b32 s50, v171
	v_add_u32_e32 v172, 0xe000, v149
	v_lshl_add_u64 v[164:165], v[238:239], 0, s[10:11]
	s_mov_b32 m0, s50
	v_lshl_add_u64 v[240:241], v[132:133], 0, s[28:29]
	ds_read_b128 v[166:169], v154
	ds_read_b128 v[190:193], v154 offset:1024
	ds_read_b128 v[194:197], v153
	ds_read_b128 v[198:201], v153 offset:1024
	ds_read_b128 v[202:205], v151
	ds_read_b128 v[206:209], v151 offset:1024
	ds_read_b128 v[210:213], v150
	ds_read_b128 v[214:217], v150 offset:1024
	global_load_lds_dwordx4 v[164:165], off
	s_bitset1_b32 m0, 13
	v_lshl_add_u64 v[164:165], v[240:241], 0, s[10:11]
	global_load_lds_dwordx4 v[164:165], off
	s_waitcnt lgkmcnt(8)
	s_barrier
	s_waitcnt lgkmcnt(0)
	s_waitcnt lgkmcnt(0)
	v_mfma_f32_16x16x32_bf16 v[124:127], v[166:169], v[174:177], v[124:127]
	v_mfma_f32_16x16x32_bf16 v[120:123], v[166:169], v[182:185], v[120:123]
	v_mfma_f32_16x16x32_bf16 v[116:119], v[194:197], v[174:177], v[116:119]
	v_mfma_f32_16x16x32_bf16 v[112:115], v[194:197], v[182:185], v[112:115]
	v_mfma_f32_16x16x32_bf16 v[108:111], v[202:205], v[174:177], v[108:111]
	v_mfma_f32_16x16x32_bf16 v[104:107], v[202:205], v[182:185], v[104:107]
	v_mfma_f32_16x16x32_bf16 v[100:103], v[210:213], v[174:177], v[100:103]
	v_mfma_f32_16x16x32_bf16 v[96:99], v[210:213], v[182:185], v[96:99]
	v_mfma_f32_16x16x32_bf16 v[124:127], v[190:193], v[178:181], v[124:127]
	v_mfma_f32_16x16x32_bf16 v[120:123], v[190:193], v[186:189], v[120:123]
	v_mfma_f32_16x16x32_bf16 v[116:119], v[198:201], v[178:181], v[116:119]
	v_mfma_f32_16x16x32_bf16 v[112:115], v[198:201], v[186:189], v[112:115]
	v_mfma_f32_16x16x32_bf16 v[108:111], v[206:209], v[178:181], v[108:111]
	v_mfma_f32_16x16x32_bf16 v[104:107], v[206:209], v[186:189], v[104:107]
	v_mfma_f32_16x16x32_bf16 v[100:103], v[214:217], v[178:181], v[100:103]
	v_mfma_f32_16x16x32_bf16 v[96:99], v[214:217], v[186:189], v[96:99]
	s_barrier
	v_add_u32_e32 v164, s40, v155
	v_lshl_add_u64 v[242:243], v[142:143], 0, s[28:29]
	v_readfirstlane_b32 s50, v164
	v_add_u32_e32 v165, 0x2000, v164
	v_lshl_add_u64 v[234:235], v[242:243], 0, s[12:13]
	s_mov_b32 m0, s50
	v_lshl_add_u64 v[244:245], v[140:141], 0, s[28:29]
	ds_read_b128 v[218:221], v162
	ds_read_b128 v[222:225], v162 offset:1024
	ds_read_b128 v[226:229], v162 offset:2048
	ds_read_b128 v[230:233], v162 offset:3072
	global_load_lds_dwordx4 v[234:235], off
	s_bitset1_b32 m0, 13
	v_lshl_add_u64 v[234:235], v[244:245], 0, s[12:13]
	global_load_lds_dwordx4 v[234:235], off
	s_barrier
	s_waitcnt lgkmcnt(0)
	s_waitcnt lgkmcnt(0)
	v_mfma_f32_16x16x32_bf16 v[92:95], v[166:169], v[218:221], v[92:95]
	v_mfma_f32_16x16x32_bf16 v[88:91], v[166:169], v[226:229], v[88:91]
	v_mfma_f32_16x16x32_bf16 v[84:87], v[194:197], v[218:221], v[84:87]
	v_mfma_f32_16x16x32_bf16 v[80:83], v[194:197], v[226:229], v[80:83]
	v_mfma_f32_16x16x32_bf16 v[76:79], v[202:205], v[218:221], v[76:79]
	v_mfma_f32_16x16x32_bf16 v[72:75], v[202:205], v[226:229], v[72:75]
	v_mfma_f32_16x16x32_bf16 v[68:71], v[210:213], v[218:221], v[68:71]
	v_mfma_f32_16x16x32_bf16 v[64:67], v[210:213], v[226:229], v[64:67]
	v_mfma_f32_16x16x32_bf16 v[92:95], v[190:193], v[222:225], v[92:95]
	v_mfma_f32_16x16x32_bf16 v[88:91], v[190:193], v[230:233], v[88:91]
	v_mfma_f32_16x16x32_bf16 v[84:87], v[198:201], v[222:225], v[84:87]
	v_mfma_f32_16x16x32_bf16 v[80:83], v[198:201], v[230:233], v[80:83]
	v_mfma_f32_16x16x32_bf16 v[76:79], v[206:209], v[222:225], v[76:79]
	v_mfma_f32_16x16x32_bf16 v[72:75], v[206:209], v[230:233], v[72:75]
	v_mfma_f32_16x16x32_bf16 v[68:71], v[214:217], v[222:225], v[68:71]
	v_mfma_f32_16x16x32_bf16 v[64:67], v[214:217], v[230:233], v[64:67]
	v_readfirstlane_b32 s50, v149
	v_lshl_add_u64 v[166:167], v[238:239], 0, s[14:15]
	s_mov_b32 m0, s50
	s_barrier
	ds_read_b128 v[190:193], v154 offset:16384
	ds_read_b128 v[194:197], v154 offset:17408
	ds_read_b128 v[198:201], v153 offset:16384
	ds_read_b128 v[202:205], v153 offset:17408
	ds_read_b128 v[206:209], v151 offset:16384
	ds_read_b128 v[210:213], v151 offset:17408
	ds_read_b128 v[214:217], v150 offset:16384
	ds_read_b128 v[234:237], v150 offset:17408
	global_load_lds_dwordx4 v[166:167], off
	s_bitset1_b32 m0, 13
	v_add_u32_e32 v166, 0x2000, v149
	v_lshl_add_u64 v[168:169], v[240:241], 0, s[14:15]
	global_load_lds_dwordx4 v[168:169], off
	s_barrier
	s_waitcnt lgkmcnt(0)
	s_waitcnt lgkmcnt(0)
	v_mfma_f32_16x16x32_bf16 v[60:63], v[190:193], v[174:177], v[60:63]
	v_mfma_f32_16x16x32_bf16 v[56:59], v[190:193], v[182:185], v[56:59]
	v_mfma_f32_16x16x32_bf16 v[52:55], v[198:201], v[174:177], v[52:55]
	v_mfma_f32_16x16x32_bf16 v[48:51], v[198:201], v[182:185], v[48:51]
	v_mfma_f32_16x16x32_bf16 v[44:47], v[206:209], v[174:177], v[44:47]
	v_mfma_f32_16x16x32_bf16 v[40:43], v[206:209], v[182:185], v[40:43]
	v_mfma_f32_16x16x32_bf16 v[36:39], v[214:217], v[174:177], v[36:39]
	v_mfma_f32_16x16x32_bf16 v[32:35], v[214:217], v[182:185], v[32:35]
	v_mfma_f32_16x16x32_bf16 v[60:63], v[194:197], v[178:181], v[60:63]
	v_mfma_f32_16x16x32_bf16 v[56:59], v[194:197], v[186:189], v[56:59]
	v_mfma_f32_16x16x32_bf16 v[52:55], v[202:205], v[178:181], v[52:55]
	v_mfma_f32_16x16x32_bf16 v[48:51], v[202:205], v[186:189], v[48:51]
	v_mfma_f32_16x16x32_bf16 v[44:47], v[210:213], v[178:181], v[44:47]
	v_mfma_f32_16x16x32_bf16 v[40:43], v[210:213], v[186:189], v[40:43]
	v_mfma_f32_16x16x32_bf16 v[36:39], v[234:237], v[178:181], v[36:39]
	v_mfma_f32_16x16x32_bf16 v[32:35], v[234:237], v[186:189], v[32:35]
	s_barrier
; #define STAGE(P, BASE, LD, br, kt) do { const char* _g = (const char*)((BASE) + (size_t)(br) * (LD) + (size_t)(kt) * 64); \
;     for (int _i = 0; _i < 2; ++_i) { int _b = tidx * 16 + _i * 8192; int _r, _c; stage_rc(_b, _r, _c); \
;       __builtin_amdgcn_global_load_lds((const unsigned*)(_g + (unsigned)((_r * (LD) + _c) * 2)), (unsigned*)((char*)(P) + _b), 16, 0, 0); } } while (0)
; #define LDA(dst, b, h) for (int m = 0; m < 4; ++m) for (int k = 0; k < 2; ++k) \
;     dst[m][k] = *reinterpret_cast<const bf16x8*>((char*)SA(b, h) + lds_byte(wr * 64 + m * 16 + fr, k * 32 + fq * 8))
; #define LDB(dst, b, h) for (int n = 0; n < 2; ++n) for (int k = 0; k < 2; ++k) \
;     dst[n][k] = *reinterpret_cast<const bf16x8*>((char*)SB(b, h) + lds_byte(wc * 32 + n * 16 + fr, k * 32 + fq * 8))
; #define MMA(ai, bj, At_, Bt_) do { __builtin_amdgcn_s_setprio(1); \
;     for (int k = 0; k < 2; ++k) for (int m = 0; m < 4; ++m) for (int n = 0; n < 2; ++n) \
;       acc[ai][bj][m][n] = __builtin_amdgcn_mfma_f32_16x16x32_bf16(At_[m][k], Bt_[n][k], acc[ai][bj][m][n], 0, 0, 0); \
;     __builtin_amdgcn_s_setprio(0); } while (0)
; #define WAIT_V(n) asm volatile("s_waitcnt vmcnt(" #n ")" ::: "memory")
; #define WAIT_L(n) asm volatile("s_waitcnt lgkmcnt(" #n ")" ::: "memory")
; #define BAR __builtin_amdgcn_s_barrier()
; #define SCHED __builtin_amdgcn_sched_barrier(0)
; template <int EPI, int lda, int ldb, int N, int K>
; __device__ __forceinline__ void gemm_phase(const u16* __restrict__ A, const u16* __restrict__ Bt, const GemmEpi ep, int wv) {
;     ...
;       STAGE(SB(0, 1), Bt, ldb, bcol + HALF, t + 2);
;       WAIT_V(6); BAR; MMA(1, 1, At, B1); BAR;
;       LDB(B0, 1, 0); SCHED; LDA(At, 1, 0); STAGE(SA(0, 1), Ab, lda, brow + HALF, t + 2);
;       WAIT_L(8); BAR; WAIT_L(0); MMA(0, 0, At, B0); BAR; SCHED;
;       LDB(B1, 1, 1); STAGE(SB(1, 0), Bt, ldb, bcol, t + 3);
;       BAR; WAIT_L(0); MMA(0, 1, At, B1); BAR;
;       LDA(At, 1, 1); STAGE(SA(1, 0), Ab, lda, brow, t + 3);
	v_add_u32_e32 v167, s41, v155
	v_lshl_add_u64 v[246:247], v[138:139], 0, s[28:29]
	v_readfirstlane_b32 s50, v167
	v_lshl_add_u64 v[168:169], v[246:247], 0, s[16:17]
	s_mov_b32 m0, s50
	v_lshl_add_u64 v[248:249], v[136:137], 0, s[28:29]
	global_load_lds_dwordx4 v[168:169], off
	s_bitset1_b32 m0, 13
	v_add_u32_e32 v168, 0x2000, v167
	v_lshl_add_u64 v[174:175], v[248:249], 0, s[16:17]
	global_load_lds_dwordx4 v[174:175], off
	s_waitcnt vmcnt(6)
	s_barrier
	v_mfma_f32_16x16x32_bf16 v[28:31], v[190:193], v[218:221], v[28:31]
	v_mfma_f32_16x16x32_bf16 v[24:27], v[190:193], v[226:229], v[24:27]
	v_mfma_f32_16x16x32_bf16 v[20:23], v[198:201], v[218:221], v[20:23]
	v_mfma_f32_16x16x32_bf16 v[16:19], v[198:201], v[226:229], v[16:19]
	v_mfma_f32_16x16x32_bf16 v[12:15], v[206:209], v[218:221], v[12:15]
	v_mfma_f32_16x16x32_bf16 v[8:11], v[206:209], v[226:229], v[8:11]
	v_mfma_f32_16x16x32_bf16 v[4:7], v[214:217], v[218:221], v[4:7]
	v_mfma_f32_16x16x32_bf16 v[0:3], v[214:217], v[226:229], v[0:3]
	v_mfma_f32_16x16x32_bf16 v[28:31], v[194:197], v[222:225], v[28:31]
	v_mfma_f32_16x16x32_bf16 v[24:27], v[194:197], v[230:233], v[24:27]
	v_mfma_f32_16x16x32_bf16 v[20:23], v[202:205], v[222:225], v[20:23]
	v_mfma_f32_16x16x32_bf16 v[16:19], v[202:205], v[230:233], v[16:19]
	v_mfma_f32_16x16x32_bf16 v[12:15], v[210:213], v[222:225], v[12:15]
	v_mfma_f32_16x16x32_bf16 v[8:11], v[210:213], v[230:233], v[8:11]
	v_mfma_f32_16x16x32_bf16 v[4:7], v[234:237], v[222:225], v[4:7]
	v_mfma_f32_16x16x32_bf16 v[0:3], v[234:237], v[230:233], v[0:3]
	s_barrier
	ds_read_b128 v[174:177], v158
	ds_read_b128 v[178:181], v158 offset:1024
	ds_read_b128 v[182:185], v158 offset:2048
	ds_read_b128 v[186:189], v158 offset:3072
	v_add_u32_e32 v169, 0x4000, v149
	v_add_u32_e32 v170, 0x6000, v149
	v_readfirstlane_b32 s50, v169
	v_lshl_add_u64 v[222:223], v[238:239], 0, s[18:19]
	s_mov_b32 m0, s50
	ds_read_b128 v[190:193], v154 offset:32768
	ds_read_b128 v[194:197], v154 offset:33792
	ds_read_b128 v[198:201], v153 offset:32768
	ds_read_b128 v[202:205], v153 offset:33792
	ds_read_b128 v[206:209], v151 offset:32768
	ds_read_b128 v[210:213], v151 offset:33792
	ds_read_b128 v[214:217], v150 offset:32768
	ds_read_b128 v[218:221], v150 offset:33792
	global_load_lds_dwordx4 v[222:223], off
	s_bitset1_b32 m0, 13
	v_lshl_add_u64 v[222:223], v[240:241], 0, s[18:19]
	global_load_lds_dwordx4 v[222:223], off
	s_waitcnt lgkmcnt(8)
	s_barrier
	s_waitcnt lgkmcnt(0)
	s_waitcnt lgkmcnt(0)
	v_mfma_f32_16x16x32_bf16 v[124:127], v[190:193], v[174:177], v[124:127]
	v_mfma_f32_16x16x32_bf16 v[120:123], v[190:193], v[182:185], v[120:123]
	v_mfma_f32_16x16x32_bf16 v[116:119], v[198:201], v[174:177], v[116:119]
	v_mfma_f32_16x16x32_bf16 v[112:115], v[198:201], v[182:185], v[112:115]
	v_mfma_f32_16x16x32_bf16 v[108:111], v[206:209], v[174:177], v[108:111]
	v_mfma_f32_16x16x32_bf16 v[104:107], v[206:209], v[182:185], v[104:107]
	v_mfma_f32_16x16x32_bf16 v[100:103], v[214:217], v[174:177], v[100:103]
	v_mfma_f32_16x16x32_bf16 v[96:99], v[214:217], v[182:185], v[96:99]
	v_mfma_f32_16x16x32_bf16 v[124:127], v[194:197], v[178:181], v[124:127]
	v_mfma_f32_16x16x32_bf16 v[120:123], v[194:197], v[186:189], v[120:123]
	v_mfma_f32_16x16x32_bf16 v[116:119], v[202:205], v[178:181], v[116:119]
	v_mfma_f32_16x16x32_bf16 v[112:115], v[202:205], v[186:189], v[112:115]
	v_mfma_f32_16x16x32_bf16 v[108:111], v[210:213], v[178:181], v[108:111]
	v_mfma_f32_16x16x32_bf16 v[104:107], v[210:213], v[186:189], v[104:107]
	v_mfma_f32_16x16x32_bf16 v[100:103], v[218:221], v[178:181], v[100:103]
	v_mfma_f32_16x16x32_bf16 v[96:99], v[218:221], v[186:189], v[96:99]
	s_barrier
	v_readfirstlane_b32 s50, v157
	v_add_u32_e32 v173, 0x2000, v157
	v_lshl_add_u64 v[242:243], v[242:243], 0, s[20:21]
	s_mov_b32 m0, s50
	ds_read_b128 v[222:225], v156
	ds_read_b128 v[226:229], v156 offset:1024
	ds_read_b128 v[230:233], v156 offset:2048
	ds_read_b128 v[234:237], v156 offset:3072
	global_load_lds_dwordx4 v[242:243], off
	s_bitset1_b32 m0, 13
	v_lshl_add_u64 v[242:243], v[244:245], 0, s[20:21]
	global_load_lds_dwordx4 v[242:243], off
	s_barrier
	s_waitcnt lgkmcnt(0)
	s_waitcnt lgkmcnt(0)
	v_mfma_f32_16x16x32_bf16 v[92:95], v[190:193], v[222:225], v[92:95]
	v_mfma_f32_16x16x32_bf16 v[88:91], v[190:193], v[230:233], v[88:91]
	v_mfma_f32_16x16x32_bf16 v[84:87], v[198:201], v[222:225], v[84:87]
	v_mfma_f32_16x16x32_bf16 v[80:83], v[198:201], v[230:233], v[80:83]
	v_mfma_f32_16x16x32_bf16 v[76:79], v[206:209], v[222:225], v[76:79]
	v_mfma_f32_16x16x32_bf16 v[72:75], v[206:209], v[230:233], v[72:75]
	v_mfma_f32_16x16x32_bf16 v[68:71], v[214:217], v[222:225], v[68:71]
	v_mfma_f32_16x16x32_bf16 v[64:67], v[214:217], v[230:233], v[64:67]
	v_mfma_f32_16x16x32_bf16 v[92:95], v[194:197], v[226:229], v[92:95]
	v_mfma_f32_16x16x32_bf16 v[88:91], v[194:197], v[234:237], v[88:91]
	v_mfma_f32_16x16x32_bf16 v[84:87], v[202:205], v[226:229], v[84:87]
	v_mfma_f32_16x16x32_bf16 v[80:83], v[202:205], v[234:237], v[80:83]
	v_mfma_f32_16x16x32_bf16 v[76:79], v[210:213], v[226:229], v[76:79]
	v_mfma_f32_16x16x32_bf16 v[72:75], v[210:213], v[234:237], v[72:75]
	v_mfma_f32_16x16x32_bf16 v[68:71], v[218:221], v[226:229], v[68:71]
	v_mfma_f32_16x16x32_bf16 v[64:67], v[218:221], v[234:237], v[64:67]
	v_readfirstlane_b32 s50, v159
	v_lshl_add_u64 v[238:239], v[238:239], 0, s[22:23]
	s_mov_b32 m0, s50
	s_barrier
	ds_read_b128 v[190:193], v154 offset:49152
	ds_read_b128 v[194:197], v154 offset:50176
	ds_read_b128 v[198:201], v153 offset:49152
	ds_read_b128 v[202:205], v153 offset:50176
	ds_read_b128 v[206:209], v151 offset:49152
	ds_read_b128 v[210:213], v151 offset:50176
	ds_read_b128 v[214:217], v150 offset:49152
	ds_read_b128 v[218:221], v150 offset:50176
	global_load_lds_dwordx4 v[238:239], off
	s_bitset1_b32 m0, 13
	v_lshl_add_u64 v[238:239], v[240:241], 0, s[22:23]
	global_load_lds_dwordx4 v[238:239], off
	s_barrier
; #define STAGE(P, BASE, LD, br, kt) do { const char* _g = (const char*)((BASE) + (size_t)(br) * (LD) + (size_t)(kt) * 64); \
;     for (int _i = 0; _i < 2; ++_i) { int _b = tidx * 16 + _i * 8192; int _r, _c; stage_rc(_b, _r, _c); \
;       __builtin_amdgcn_global_load_lds((const unsigned*)(_g + (unsigned)((_r * (LD) + _c) * 2)), (unsigned*)((char*)(P) + _b), 16, 0, 0); } } while (0)
; #define LDA(dst, b, h) for (int m = 0; m < 4; ++m) for (int k = 0; k < 2; ++k) \
;     dst[m][k] = *reinterpret_cast<const bf16x8*>((char*)SA(b, h) + lds_byte(wr * 64 + m * 16 + fr, k * 32 + fq * 8))
; #define LDB(dst, b, h) for (int n = 0; n < 2; ++n) for (int k = 0; k < 2; ++k) \
;     dst[n][k] = *reinterpret_cast<const bf16x8*>((char*)SB(b, h) + lds_byte(wc * 32 + n * 16 + fr, k * 32 + fq * 8))
; #define MMA(ai, bj, At_, Bt_) do { __builtin_amdgcn_s_setprio(1); \
;     for (int k = 0; k < 2; ++k) for (int m = 0; m < 4; ++m) for (int n = 0; n < 2; ++n) \
;       acc[ai][bj][m][n] = __builtin_amdgcn_mfma_f32_16x16x32_bf16(At_[m][k], Bt_[n][k], acc[ai][bj][m][n], 0, 0, 0); \
;     __builtin_amdgcn_s_setprio(0); } while (0)
; #define WAIT_V(n) asm volatile("s_waitcnt vmcnt(" #n ")" ::: "memory")
; #define WAIT_L(n) asm volatile("s_waitcnt lgkmcnt(" #n ")" ::: "memory")
; #define BAR __builtin_amdgcn_s_barrier()
; #define SCHED __builtin_amdgcn_sched_barrier(0)
; template <int EPI, int lda, int ldb, int N, int K>
; __device__ __forceinline__ void gemm_phase(const u16* __restrict__ A, const u16* __restrict__ Bt, const GemmEpi ep, int wv) {
;     ...
;       BAR; WAIT_L(0); MMA(0, 1, At, B1); BAR;
;       LDA(At, 1, 1); STAGE(SA(1, 0), Ab, lda, brow, t + 3);
;       BAR; WAIT_L(0); MMA(1, 0, At, B0); BAR; SCHED;
;       STAGE(SB(1, 1), Bt, ldb, bcol + HALF, t + 3);
;       WAIT_V(6); BAR; MMA(1, 1, At, B1); BAR;
;     }
;     { LDB(B0, 0, 0); LDA(At, 0, 0); STAGE(SA(1, 1), Ab, lda, brow + HALF, nt - 1);
;       BAR; WAIT_L(0); MMA(0, 0, At, B0); BAR;
;       LDB(B1, 0, 1); BAR; WAIT_L(0); MMA(0, 1, At, B1); BAR;
	s_waitcnt lgkmcnt(0)
	s_waitcnt lgkmcnt(0)
	v_mfma_f32_16x16x32_bf16 v[60:63], v[190:193], v[174:177], v[60:63]
	v_mfma_f32_16x16x32_bf16 v[56:59], v[190:193], v[182:185], v[56:59]
	v_mfma_f32_16x16x32_bf16 v[52:55], v[198:201], v[174:177], v[52:55]
	v_mfma_f32_16x16x32_bf16 v[48:51], v[198:201], v[182:185], v[48:51]
	v_mfma_f32_16x16x32_bf16 v[44:47], v[206:209], v[174:177], v[44:47]
	v_mfma_f32_16x16x32_bf16 v[40:43], v[206:209], v[182:185], v[40:43]
	v_mfma_f32_16x16x32_bf16 v[36:39], v[214:217], v[174:177], v[36:39]
	v_mfma_f32_16x16x32_bf16 v[32:35], v[214:217], v[182:185], v[32:35]
	v_mfma_f32_16x16x32_bf16 v[60:63], v[194:197], v[178:181], v[60:63]
	v_mfma_f32_16x16x32_bf16 v[56:59], v[194:197], v[186:189], v[56:59]
	v_mfma_f32_16x16x32_bf16 v[52:55], v[202:205], v[178:181], v[52:55]
	v_mfma_f32_16x16x32_bf16 v[48:51], v[202:205], v[186:189], v[48:51]
	v_mfma_f32_16x16x32_bf16 v[44:47], v[210:213], v[178:181], v[44:47]
	v_mfma_f32_16x16x32_bf16 v[40:43], v[210:213], v[186:189], v[40:43]
	v_mfma_f32_16x16x32_bf16 v[36:39], v[218:221], v[178:181], v[36:39]
	v_mfma_f32_16x16x32_bf16 v[32:35], v[218:221], v[186:189], v[32:35]
	s_barrier
	v_readfirstlane_b32 s50, v161
	v_add_u32_e32 v173, 0x2000, v161
	v_lshl_add_u64 v[174:175], v[246:247], 0, s[24:25]
	s_mov_b32 m0, s50
	global_load_lds_dwordx4 v[174:175], off
	s_bitset1_b32 m0, 13
	v_lshl_add_u64 v[174:175], v[248:249], 0, s[24:25]
	global_load_lds_dwordx4 v[174:175], off
	s_waitcnt vmcnt(6)
	s_barrier
	v_mfma_f32_16x16x32_bf16 v[28:31], v[190:193], v[222:225], v[28:31]
	v_mfma_f32_16x16x32_bf16 v[24:27], v[190:193], v[230:233], v[24:27]
	v_mfma_f32_16x16x32_bf16 v[20:23], v[198:201], v[222:225], v[20:23]
	v_mfma_f32_16x16x32_bf16 v[16:19], v[198:201], v[230:233], v[16:19]
	v_mfma_f32_16x16x32_bf16 v[12:15], v[206:209], v[222:225], v[12:15]
	v_mfma_f32_16x16x32_bf16 v[8:11], v[206:209], v[230:233], v[8:11]
	v_mfma_f32_16x16x32_bf16 v[4:7], v[214:217], v[222:225], v[4:7]
	v_mfma_f32_16x16x32_bf16 v[0:3], v[214:217], v[230:233], v[0:3]
	v_mfma_f32_16x16x32_bf16 v[28:31], v[194:197], v[226:229], v[28:31]
	v_mfma_f32_16x16x32_bf16 v[24:27], v[194:197], v[234:237], v[24:27]
	v_mfma_f32_16x16x32_bf16 v[20:23], v[202:205], v[226:229], v[20:23]
	v_mfma_f32_16x16x32_bf16 v[16:19], v[202:205], v[234:237], v[16:19]
	v_mfma_f32_16x16x32_bf16 v[12:15], v[210:213], v[226:229], v[12:15]
	v_mfma_f32_16x16x32_bf16 v[8:11], v[210:213], v[234:237], v[8:11]
	v_mfma_f32_16x16x32_bf16 v[4:7], v[218:221], v[226:229], v[4:7]
	v_mfma_f32_16x16x32_bf16 v[0:3], v[218:221], v[234:237], v[0:3]
	s_add_i32 s49, s49, 2
	s_add_u32 s28, s28, 0x100
	s_addc_u32 s29, s29, 0
	s_cmpk_gt_u32 s49, 0x51
	s_barrier
	s_cbranch_scc0 .LBB0_1624
	s_add_i32 s28, s48, 0x80
	s_mul_hi_i32 s29, s28, 0x2b00
	s_mulk_i32 s28, 0x2b00
	s_add_u32 s28, s34, s28
	s_addc_u32 s29, s35, s29
	s_add_u32 s28, s28, 0x2a80
	s_addc_u32 s29, s29, 0
	v_readfirstlane_b32 s49, v171
	v_lshl_add_u64 v[160:161], s[28:29], 0, v[128:129]
	s_mov_b32 m0, s49
	ds_read_b128 v[132:135], v163
	ds_read_b128 v[136:139], v163 offset:1024
	ds_read_b128 v[140:143], v163 offset:2048
	ds_read_b128 v[174:177], v163 offset:3072
	ds_read_b128 v[178:181], v154
	ds_read_b128 v[182:185], v154 offset:1024
	ds_read_b128 v[186:189], v153
	ds_read_b128 v[190:193], v153 offset:1024
	ds_read_b128 v[194:197], v151
	ds_read_b128 v[198:201], v151 offset:1024
	ds_read_b128 v[202:205], v150
	ds_read_b128 v[206:209], v150 offset:1024
	global_load_lds_dwordx4 v[160:161], off
	v_lshl_add_u64 v[160:161], s[28:29], 0, v[130:131]
	v_readfirstlane_b32 s28, v172
	s_mov_b32 m0, s28
	s_nop 0
	global_load_lds_dwordx4 v[160:161], off
	s_barrier
	s_waitcnt lgkmcnt(0)
	s_waitcnt lgkmcnt(0)
	v_mfma_f32_16x16x32_bf16 v[124:127], v[178:181], v[132:135], v[124:127]
	v_mfma_f32_16x16x32_bf16 v[120:123], v[178:181], v[140:143], v[120:123]
	v_mfma_f32_16x16x32_bf16 v[116:119], v[186:189], v[132:135], v[116:119]
	v_mfma_f32_16x16x32_bf16 v[112:115], v[186:189], v[140:143], v[112:115]
	v_mfma_f32_16x16x32_bf16 v[108:111], v[194:197], v[132:135], v[108:111]
	v_mfma_f32_16x16x32_bf16 v[104:107], v[194:197], v[140:143], v[104:107]
	v_mfma_f32_16x16x32_bf16 v[100:103], v[202:205], v[132:135], v[100:103]
	v_mfma_f32_16x16x32_bf16 v[96:99], v[202:205], v[140:143], v[96:99]
	v_mfma_f32_16x16x32_bf16 v[124:127], v[182:185], v[136:139], v[124:127]
	v_mfma_f32_16x16x32_bf16 v[120:123], v[182:185], v[174:177], v[120:123]
	v_mfma_f32_16x16x32_bf16 v[116:119], v[190:193], v[136:139], v[116:119]
	v_mfma_f32_16x16x32_bf16 v[112:115], v[190:193], v[174:177], v[112:115]
	v_mfma_f32_16x16x32_bf16 v[108:111], v[198:201], v[136:139], v[108:111]
	v_mfma_f32_16x16x32_bf16 v[104:107], v[198:201], v[174:177], v[104:107]
	v_mfma_f32_16x16x32_bf16 v[100:103], v[206:209], v[136:139], v[100:103]
	v_mfma_f32_16x16x32_bf16 v[96:99], v[206:209], v[174:177], v[96:99]
	s_barrier
	ds_read_b128 v[210:213], v162
	ds_read_b128 v[214:217], v162 offset:1024
	ds_read_b128 v[218:221], v162 offset:2048
	ds_read_b128 v[160:163], v162 offset:3072
	s_barrier
	s_waitcnt lgkmcnt(0)
	s_waitcnt lgkmcnt(0)
	v_mfma_f32_16x16x32_bf16 v[92:95], v[178:181], v[210:213], v[92:95]
	v_mfma_f32_16x16x32_bf16 v[88:91], v[178:181], v[218:221], v[88:91]
	v_mfma_f32_16x16x32_bf16 v[72:75], v[194:197], v[218:221], v[72:75]
	v_mfma_f32_16x16x32_bf16 v[68:71], v[202:205], v[210:213], v[68:71]
	v_mfma_f32_16x16x32_bf16 v[84:87], v[186:189], v[210:213], v[84:87]
	v_mfma_f32_16x16x32_bf16 v[80:83], v[186:189], v[218:221], v[80:83]
	v_mfma_f32_16x16x32_bf16 v[76:79], v[194:197], v[210:213], v[76:79]
	v_mfma_f32_16x16x32_bf16 v[64:67], v[202:205], v[218:221], v[64:67]
	v_mfma_f32_16x16x32_bf16 v[92:95], v[182:185], v[214:217], v[92:95]
	v_mfma_f32_16x16x32_bf16 v[88:91], v[182:185], v[160:163], v[88:91]
	v_mfma_f32_16x16x32_bf16 v[72:75], v[198:201], v[160:163], v[72:75]
	v_mfma_f32_16x16x32_bf16 v[68:71], v[206:209], v[214:217], v[68:71]
	v_mfma_f32_16x16x32_bf16 v[178:181], v[190:193], v[214:217], v[84:87]
	v_mfma_f32_16x16x32_bf16 v[182:185], v[190:193], v[160:163], v[80:83]
	v_mfma_f32_16x16x32_bf16 v[186:189], v[198:201], v[214:217], v[76:79]
	v_mfma_f32_16x16x32_bf16 v[190:193], v[206:209], v[160:163], v[64:67]
	s_barrier
; #define LDA(dst, b, h) for (int m = 0; m < 4; ++m) for (int k = 0; k < 2; ++k) \
;     dst[m][k] = *reinterpret_cast<const bf16x8*>((char*)SA(b, h) + lds_byte(wr * 64 + m * 16 + fr, k * 32 + fq * 8))
; #define LDB(dst, b, h) for (int n = 0; n < 2; ++n) for (int k = 0; k < 2; ++k) \
;     dst[n][k] = *reinterpret_cast<const bf16x8*>((char*)SB(b, h) + lds_byte(wc * 32 + n * 16 + fr, k * 32 + fq * 8))
; #define MMA(ai, bj, At_, Bt_) do { __builtin_amdgcn_s_setprio(1); \
;     for (int k = 0; k < 2; ++k) for (int m = 0; m < 4; ++m) for (int n = 0; n < 2; ++n) \
;       acc[ai][bj][m][n] = __builtin_amdgcn_mfma_f32_16x16x32_bf16(At_[m][k], Bt_[n][k], acc[ai][bj][m][n], 0, 0, 0); \
;     __builtin_amdgcn_s_setprio(0); } while (0)
; #define WAIT_V(n) asm volatile("s_waitcnt vmcnt(" #n ")" ::: "memory")
; #define WAIT_L(n) asm volatile("s_waitcnt lgkmcnt(" #n ")" ::: "memory")
; #define BAR __builtin_amdgcn_s_barrier()
; template <int EPI, int lda, int ldb, int N, int K>
; __device__ __forceinline__ void gemm_phase(const u16* __restrict__ A, const u16* __restrict__ Bt, const GemmEpi ep, int wv) {
;     ...
;       LDA(At, 0, 1); WAIT_V(4); BAR; WAIT_L(0); MMA(1, 0, At, B0); MMA(1, 1, At, B1); BAR; }
;     { LDB(B0, 1, 0); LDA(At, 1, 0); WAIT_V(2); BAR; WAIT_L(0); MMA(0, 0, At, B0); BAR;
	s_nop 0
	ds_read_b128 v[64:67], v154 offset:16384
	ds_read_b128 v[76:79], v154 offset:17408
	ds_read_b128 v[80:83], v153 offset:16384
	ds_read_b128 v[84:87], v153 offset:17408
	ds_read_b128 v[194:197], v151 offset:16384
	ds_read_b128 v[198:201], v151 offset:17408
	ds_read_b128 v[202:205], v150 offset:16384
	ds_read_b128 v[206:209], v150 offset:17408
	s_waitcnt vmcnt(4)
	s_barrier
	s_waitcnt lgkmcnt(0)
	s_waitcnt lgkmcnt(0)
	v_mfma_f32_16x16x32_bf16 v[60:63], v[64:67], v[132:135], v[60:63]
	v_mfma_f32_16x16x32_bf16 v[56:59], v[64:67], v[140:143], v[56:59]
	v_mfma_f32_16x16x32_bf16 v[52:55], v[80:83], v[132:135], v[52:55]
	v_mfma_f32_16x16x32_bf16 v[48:51], v[80:83], v[140:143], v[48:51]
	v_mfma_f32_16x16x32_bf16 v[44:47], v[194:197], v[132:135], v[44:47]
	v_mfma_f32_16x16x32_bf16 v[40:43], v[194:197], v[140:143], v[40:43]
	v_mfma_f32_16x16x32_bf16 v[36:39], v[202:205], v[132:135], v[36:39]
	v_mfma_f32_16x16x32_bf16 v[32:35], v[202:205], v[140:143], v[32:35]
	v_mfma_f32_16x16x32_bf16 v[60:63], v[76:79], v[136:139], v[60:63]
	v_mfma_f32_16x16x32_bf16 v[56:59], v[76:79], v[174:177], v[56:59]
	v_mfma_f32_16x16x32_bf16 v[52:55], v[84:87], v[136:139], v[52:55]
	v_mfma_f32_16x16x32_bf16 v[48:51], v[84:87], v[174:177], v[48:51]
	v_mfma_f32_16x16x32_bf16 v[44:47], v[198:201], v[136:139], v[44:47]
	v_mfma_f32_16x16x32_bf16 v[40:43], v[198:201], v[174:177], v[40:43]
	v_mfma_f32_16x16x32_bf16 v[36:39], v[206:209], v[136:139], v[36:39]
	v_mfma_f32_16x16x32_bf16 v[32:35], v[206:209], v[174:177], v[32:35]
	v_mfma_f32_16x16x32_bf16 v[28:31], v[64:67], v[210:213], v[28:31]
	v_mfma_f32_16x16x32_bf16 v[24:27], v[64:67], v[218:221], v[24:27]
	v_mfma_f32_16x16x32_bf16 v[12:15], v[194:197], v[210:213], v[12:15]
	v_mfma_f32_16x16x32_bf16 v[8:11], v[194:197], v[218:221], v[8:11]
	v_mfma_f32_16x16x32_bf16 v[20:23], v[80:83], v[210:213], v[20:23]
	v_mfma_f32_16x16x32_bf16 v[16:19], v[80:83], v[218:221], v[16:19]
	v_mfma_f32_16x16x32_bf16 v[4:7], v[202:205], v[210:213], v[4:7]
	v_mfma_f32_16x16x32_bf16 v[0:3], v[202:205], v[218:221], v[0:3]
	v_mfma_f32_16x16x32_bf16 v[28:31], v[76:79], v[214:217], v[28:31]
	v_mfma_f32_16x16x32_bf16 v[24:27], v[76:79], v[160:163], v[24:27]
	v_mfma_f32_16x16x32_bf16 v[12:15], v[198:201], v[214:217], v[12:15]
	v_mfma_f32_16x16x32_bf16 v[8:11], v[198:201], v[160:163], v[8:11]
	v_mfma_f32_16x16x32_bf16 v[132:135], v[84:87], v[214:217], v[20:23]
	v_mfma_f32_16x16x32_bf16 v[136:139], v[84:87], v[160:163], v[16:19]
	v_mfma_f32_16x16x32_bf16 v[140:143], v[206:209], v[214:217], v[4:7]
	v_mfma_f32_16x16x32_bf16 v[160:163], v[206:209], v[160:163], v[0:3]
	s_barrier
	s_nop 0
	ds_read_b128 v[0:3], v158
	ds_read_b128 v[4:7], v158 offset:1024
	ds_read_b128 v[16:19], v158 offset:2048
	ds_read_b128 v[172:175], v158 offset:3072
	ds_read_b128 v[20:23], v154 offset:32768
	ds_read_b128 v[194:197], v154 offset:33792
	ds_read_b128 v[198:201], v153 offset:32768
	ds_read_b128 v[202:205], v153 offset:33792
	ds_read_b128 v[206:209], v151 offset:32768
	ds_read_b128 v[210:213], v151 offset:33792
	ds_read_b128 v[214:217], v150 offset:32768
	ds_read_b128 v[218:221], v150 offset:33792
	s_waitcnt vmcnt(2)
	s_barrier
	s_waitcnt lgkmcnt(0)
	s_waitcnt lgkmcnt(0)
	v_mfma_f32_16x16x32_bf16 v[64:67], v[20:23], v[0:3], v[124:127]
	v_mfma_f32_16x16x32_bf16 v[76:79], v[20:23], v[16:19], v[120:123]
	v_mfma_f32_16x16x32_bf16 v[80:83], v[198:201], v[0:3], v[116:119]
	v_mfma_f32_16x16x32_bf16 v[84:87], v[198:201], v[16:19], v[112:115]
	v_mfma_f32_16x16x32_bf16 v[108:111], v[206:209], v[0:3], v[108:111]
	v_mfma_f32_16x16x32_bf16 v[104:107], v[206:209], v[16:19], v[104:107]
	v_mfma_f32_16x16x32_bf16 v[120:123], v[214:217], v[0:3], v[100:103]
	v_mfma_f32_16x16x32_bf16 v[124:127], v[214:217], v[16:19], v[96:99]
	v_mfma_f32_16x16x32_bf16 v[116:119], v[194:197], v[4:7], v[64:67]
	v_mfma_f32_16x16x32_bf16 v[112:115], v[194:197], v[172:175], v[76:79]
	v_mfma_f32_16x16x32_bf16 v[100:103], v[202:205], v[4:7], v[80:83]
	v_mfma_f32_16x16x32_bf16 v[96:99], v[202:205], v[172:175], v[84:87]
	v_mfma_f32_16x16x32_bf16 v[84:87], v[210:213], v[4:7], v[108:111]
	v_mfma_f32_16x16x32_bf16 v[80:83], v[210:213], v[172:175], v[104:107]
	v_mfma_f32_16x16x32_bf16 v[76:79], v[218:221], v[4:7], v[120:123]
	v_mfma_f32_16x16x32_bf16 v[64:67], v[218:221], v[172:175], v[124:127]
	s_barrier
; #define LDA(dst, b, h) for (int m = 0; m < 4; ++m) for (int k = 0; k < 2; ++k) \
;     dst[m][k] = *reinterpret_cast<const bf16x8*>((char*)SA(b, h) + lds_byte(wr * 64 + m * 16 + fr, k * 32 + fq * 8))
; #define LDB(dst, b, h) for (int n = 0; n < 2; ++n) for (int k = 0; k < 2; ++k) \
;     dst[n][k] = *reinterpret_cast<const bf16x8*>((char*)SB(b, h) + lds_byte(wc * 32 + n * 16 + fr, k * 32 + fq * 8))
; #define MMA(ai, bj, At_, Bt_) do { __builtin_amdgcn_s_setprio(1); \
;     for (int k = 0; k < 2; ++k) for (int m = 0; m < 4; ++m) for (int n = 0; n < 2; ++n) \
;       acc[ai][bj][m][n] = __builtin_amdgcn_mfma_f32_16x16x32_bf16(At_[m][k], Bt_[n][k], acc[ai][bj][m][n], 0, 0, 0); \
;     __builtin_amdgcn_s_setprio(0); } while (0)
; #define WAIT_V(n) asm volatile("s_waitcnt vmcnt(" #n ")" ::: "memory")
; #define WAIT_L(n) asm volatile("s_waitcnt lgkmcnt(" #n ")" ::: "memory")
; #define BAR __builtin_amdgcn_s_barrier()
; template <int EPI, int lda, int ldb, int N, int K>
; __device__ __forceinline__ void gemm_phase(const u16* __restrict__ A, const u16* __restrict__ Bt, const GemmEpi ep, int wv) {
;     ...
;       LDB(B1, 1, 1); WAIT_V(0); BAR; WAIT_L(0); MMA(0, 1, At, B1); BAR;
;       LDA(At, 1, 1); BAR; WAIT_L(0); MMA(1, 0, At, B0); MMA(1, 1, At, B1); BAR; }
;     if (wr == 0) BAR;
	ds_read_b128 v[222:225], v156
	ds_read_b128 v[226:229], v156 offset:1024
	ds_read_b128 v[230:233], v156 offset:2048
	ds_read_b128 v[156:159], v156 offset:3072
	s_waitcnt vmcnt(0)
	s_barrier
	s_waitcnt lgkmcnt(0)
	s_waitcnt lgkmcnt(0)
	v_mfma_f32_16x16x32_bf16 v[92:95], v[20:23], v[222:225], v[92:95]
	v_mfma_f32_16x16x32_bf16 v[20:23], v[20:23], v[230:233], v[88:91]
	v_mfma_f32_16x16x32_bf16 v[88:91], v[198:201], v[222:225], v[178:181]
	v_mfma_f32_16x16x32_bf16 v[104:107], v[198:201], v[230:233], v[182:185]
	v_mfma_f32_16x16x32_bf16 v[176:179], v[206:209], v[222:225], v[186:189]
	v_mfma_f32_16x16x32_bf16 v[72:75], v[206:209], v[230:233], v[72:75]
	v_mfma_f32_16x16x32_bf16 v[68:71], v[214:217], v[222:225], v[68:71]
	v_mfma_f32_16x16x32_bf16 v[180:183], v[214:217], v[230:233], v[190:193]
	v_mfma_f32_16x16x32_bf16 v[124:127], v[194:197], v[226:229], v[92:95]
	v_mfma_f32_16x16x32_bf16 v[120:123], v[194:197], v[156:159], v[20:23]
	v_mfma_f32_16x16x32_bf16 v[108:111], v[202:205], v[226:229], v[88:91]
	v_mfma_f32_16x16x32_bf16 v[104:107], v[202:205], v[156:159], v[104:107]
	v_mfma_f32_16x16x32_bf16 v[92:95], v[210:213], v[226:229], v[176:179]
	v_mfma_f32_16x16x32_bf16 v[88:91], v[210:213], v[156:159], v[72:75]
	v_mfma_f32_16x16x32_bf16 v[72:75], v[218:221], v[226:229], v[68:71]
	v_mfma_f32_16x16x32_bf16 v[68:71], v[218:221], v[156:159], v[180:183]
	s_barrier
	ds_read_b128 v[176:179], v154 offset:49152
	ds_read_b128 v[180:183], v154 offset:50176
	ds_read_b128 v[184:187], v153 offset:49152
	ds_read_b128 v[188:191], v153 offset:50176
	ds_read_b128 v[192:195], v151 offset:49152
	ds_read_b128 v[196:199], v151 offset:50176
	ds_read_b128 v[200:203], v150 offset:49152
	ds_read_b128 v[204:207], v150 offset:50176
	s_barrier
	s_waitcnt lgkmcnt(0)
	s_waitcnt lgkmcnt(0)
	v_mfma_f32_16x16x32_bf16 v[20:23], v[176:179], v[0:3], v[60:63]
	v_mfma_f32_16x16x32_bf16 v[56:59], v[176:179], v[16:19], v[56:59]
	v_mfma_f32_16x16x32_bf16 v[60:63], v[184:187], v[0:3], v[52:55]
	v_mfma_f32_16x16x32_bf16 v[208:211], v[184:187], v[16:19], v[48:51]
	v_mfma_f32_16x16x32_bf16 v[44:47], v[192:195], v[0:3], v[44:47]
	v_mfma_f32_16x16x32_bf16 v[40:43], v[192:195], v[16:19], v[40:43]
	v_mfma_f32_16x16x32_bf16 v[0:3], v[200:203], v[0:3], v[36:39]
	v_mfma_f32_16x16x32_bf16 v[212:215], v[200:203], v[16:19], v[32:35]
	v_mfma_f32_16x16x32_bf16 v[52:55], v[180:183], v[4:7], v[20:23]
	v_mfma_f32_16x16x32_bf16 v[48:51], v[180:183], v[172:175], v[56:59]
	v_mfma_f32_16x16x32_bf16 v[36:39], v[188:191], v[4:7], v[60:63]
	v_mfma_f32_16x16x32_bf16 v[32:35], v[188:191], v[172:175], v[208:211]
	v_mfma_f32_16x16x32_bf16 v[20:23], v[196:199], v[4:7], v[44:47]
	v_mfma_f32_16x16x32_bf16 v[16:19], v[196:199], v[172:175], v[40:43]
	v_mfma_f32_16x16x32_bf16 v[4:7], v[204:207], v[4:7], v[0:3]
	v_mfma_f32_16x16x32_bf16 v[0:3], v[204:207], v[172:175], v[212:215]
	v_mfma_f32_16x16x32_bf16 v[28:31], v[176:179], v[222:225], v[28:31]
	v_mfma_f32_16x16x32_bf16 v[24:27], v[176:179], v[230:233], v[24:27]
	v_mfma_f32_16x16x32_bf16 v[40:43], v[184:187], v[222:225], v[132:135]
	v_mfma_f32_16x16x32_bf16 v[132:135], v[184:187], v[230:233], v[136:139]
	v_mfma_f32_16x16x32_bf16 v[12:15], v[192:195], v[222:225], v[12:15]
	v_mfma_f32_16x16x32_bf16 v[8:11], v[192:195], v[230:233], v[8:11]
	v_mfma_f32_16x16x32_bf16 v[136:139], v[200:203], v[222:225], v[140:143]
	v_mfma_f32_16x16x32_bf16 v[140:143], v[200:203], v[230:233], v[160:163]
	v_mfma_f32_16x16x32_bf16 v[60:63], v[180:183], v[226:229], v[28:31]
	v_mfma_f32_16x16x32_bf16 v[56:59], v[180:183], v[156:159], v[24:27]
	v_mfma_f32_16x16x32_bf16 v[44:47], v[188:191], v[226:229], v[40:43]
	v_mfma_f32_16x16x32_bf16 v[40:43], v[188:191], v[156:159], v[132:135]
	v_mfma_f32_16x16x32_bf16 v[28:31], v[196:199], v[226:229], v[12:15]
	v_mfma_f32_16x16x32_bf16 v[24:27], v[196:199], v[156:159], v[8:11]
	v_mfma_f32_16x16x32_bf16 v[12:15], v[204:207], v[226:229], v[136:139]
	v_mfma_f32_16x16x32_bf16 v[8:11], v[204:207], v[156:159], v[140:143]
	v_cmp_gt_u32_e32 vcc, s46, v147
	s_barrier
	s_and_saveexec_b64 s[28:29], vcc
	s_cbranch_execz .LBB0_1627
	s_barrier
